# row-wise norm phases: loop-invariant gain-vector loads hoisted out of the row loops (were load->drain serialised); deeper load prefetch in gate/sigmul GEMM epilogues
# speedup vs baseline: 1.0764x; 1.0073x over previous
; __device__ __forceinline__ float bflo(unsigned u) { return __uint_as_float(u << 16); }
; __device__ __forceinline__ float bfhi(unsigned u) { return __uint_as_float(u & 0xffff0000u); }
; __device__ __forceinline__ int o_tid() { int t = threadIdx.x; asm volatile("" : "+v"(t)); return t; }
; __device__ void phase_rows(int flags, const float* xin, bf16_t* XB, const bf16_t* mf, const float* g1, const float* g2, float* xout, bf16_t* U,
;                            const float* pin, bf16_t* Pb) {
;     const int tid = o_tid(), wave = tid >> 6, lane = tid & 63; const int bid = o_bid(), nblk = o_nblk();
;     const int stride = nblk * 8;
;     for (int r0 = bid * 8 + wave; r0 < TCH; r0 += 2 * stride) {
;         float4 x[2][4]; uint2 mq[2][4]; float4 pv[2];
; #pragma unroll
;         for (int k = 0; k < 2; ++k) { const int r = r0 + k * stride; if (r < TCH) {
;             if (flags & 16) { const uint2* xr = (const uint2*)(XB + (size_t)r * DM);
; #pragma unroll
;                 for (int i = 0; i < 4; ++i) { const uint2 q = xr[lane + 64 * i]; x[k][i] = make_float4(bflo(q.x), bfhi(q.x), bflo(q.y), bfhi(q.y)); } }
;             else { const float4* xr = (const float4*)(xin + (size_t)r * DM);
; #pragma unroll
;                 for (int i = 0; i < 4; ++i) x[k][i] = xr[lane + 64 * i]; }
;             if (flags & 1) { const uint2* mr = (const uint2*)(mf + (size_t)r * DM);
; #pragma unroll
;                 for (int i = 0; i < 4; ++i) { const unsigned long long t64 = __builtin_nontemporal_load((const unsigned long long*)(mr + lane + 64 * i)); mq[k][i] = make_uint2((unsigned)t64, (unsigned)(t64 >> 32)); } }
;             if (flags & 8) pv[k] = ((const float4*)(pin + (size_t)r * DPLE))[lane]; } }
; #pragma unroll
;         for (int k = 0; k < 2; ++k) { const int r = r0 + k * stride; if (r < TCH) {
;             if (flags & 1) {
;                 float ss = 0.f; float4 m[4];
; #pragma unroll
;                 for (int i = 0; i < 4; ++i) { m[i] = make_float4(bflo(mq[k][i].x), bfhi(mq[k][i].x), bflo(mq[k][i].y), bfhi(mq[k][i].y)); ss += m[i].x * m[i].x + m[i].y * m[i].y + m[i].z * m[i].z + m[i].w * m[i].w; }
;                 ss = wave_sum(ss); const float rs = rsqrtf(ss * (1.0f / DM) + 1e-6f);
; #pragma unroll
;                 for (int i = 0; i < 4; ++i) { const float4 g = ((const float4*)g1)[lane + 64 * i];
.LBB0_165:
	v_mov_b32_e32 v0, v180
	s_mov_b32 s19, s49
	s_mov_b32 s26, s64
	s_waitcnt vmcnt(0)
	v_ashrrev_i32_e32 v2, 6, v0
	v_lshl_add_u32 v40, s19, 3, v2
	s_mov_b32 s19, 0x8000
	v_cmp_gt_i32_e32 vcc, s19, v40
	s_and_saveexec_b64 s[22:23], vcc
	s_cbranch_execz .LBB0_180
	v_and_b32_e32 v2, 63, v0
	v_lshlrev_b32_e32 v0, 3, v2
	v_lshlrev_b32_e32 v44, 4, v2
	v_and_b32_e32 v2, 64, v191
	v_add_u32_e32 v2, 64, v2
	v_xor_b32_e32 v3, 32, v191
	v_cmp_lt_i32_e32 vcc, v3, v2
	s_load_dwordx4 s[40:43], s[82:83], 0x28
	s_lshl_b32 s19, s26, 3
	v_cndmask_b32_e32 v3, v191, v3, vcc
	v_lshlrev_b32_e32 v96, 2, v3
	v_xor_b32_e32 v3, 16, v191
	v_cmp_lt_i32_e32 vcc, v3, v2
	s_add_u32 s30, s16, 0x31400000
	s_addc_u32 s31, s17, 0
	v_cndmask_b32_e32 v3, v191, v3, vcc
	v_lshlrev_b32_e32 v97, 2, v3
	v_xor_b32_e32 v3, 8, v191
	v_cmp_lt_i32_e32 vcc, v3, v2
	s_and_b64 s[34:35], s[4:5], exec
	s_cselect_b32 s27, 0x1000, 0
	v_cndmask_b32_e32 v3, v191, v3, vcc
	v_lshlrev_b32_e32 v98, 2, v3
	v_xor_b32_e32 v3, 4, v191
	v_cmp_lt_i32_e32 vcc, v3, v2
	s_waitcnt lgkmcnt(0)
	s_add_u32 s34, s42, s27
	v_ashrrev_i32_e32 v41, 31, v40
	v_cndmask_b32_e32 v3, v191, v3, vcc
	v_lshlrev_b32_e32 v99, 2, v3
	v_xor_b32_e32 v3, 2, v191
	v_cmp_lt_i32_e32 vcc, v3, v2
	s_addc_u32 s35, s43, 0
	s_add_u32 s38, s40, s27
	v_cndmask_b32_e32 v3, v191, v3, vcc
	v_lshlrev_b32_e32 v100, 2, v3
	v_xor_b32_e32 v3, 1, v191
	v_cmp_lt_i32_e32 vcc, v3, v2
	s_addc_u32 s39, s41, 0
	s_lshl_b32 s26, s26, 4
	v_cndmask_b32_e32 v2, v191, v3, vcc
	v_lshlrev_b32_e32 v101, 2, v2
	v_lshlrev_b64 v[2:3], 11, v[40:41]
	v_lshl_add_u64 v[60:61], s[16:17], 0, v[2:3]
	v_lshlrev_b64 v[2:3], 9, v[40:41]
	v_lshl_add_u64 v[62:63], s[30:31], 0, v[2:3]
	v_lshlrev_b64 v[2:3], 10, v[40:41]
	v_mov_b32_e32 v45, v1
	s_ashr_i32 s27, s26, 31
	v_lshl_add_u64 v[64:65], s[6:7], 0, v[2:3]
	v_lshlrev_b64 v[2:3], 12, v[40:41]
	v_lshl_add_u64 v[42:43], s[14:15], 0, v[0:1]
	v_lshl_add_u64 v[46:47], s[6:7], 0, v[44:45]
	v_lshl_add_u64 v[48:49], s[30:31], 0, v[0:1]
	v_lshl_add_u64 v[50:51], s[38:39], 0, v[44:45]
	s_waitcnt vmcnt(0)
	v_lshl_add_u64 v[52:53], s[34:35], 0, v[44:45]
	v_lshl_add_u64 v[54:55], s[0:1], 0, v[44:45]
	v_lshl_add_u64 v[56:57], s[10:11], 0, v[0:1]
	v_lshl_add_u64 v[58:59], s[8:9], 0, v[0:1]
	s_lshl_b64 s[34:35], s[26:27], 11
	s_lshl_b64 s[50:51], s[26:27], 9
	s_lshl_b64 s[52:53], s[26:27], 10
	v_lshl_add_u64 v[66:67], s[0:1], 0, v[2:3]
	s_lshl_b64 s[54:55], s[26:27], 12
	s_mov_b64 s[56:57], 0
	global_load_dwordx4 v[136:139], v[52:53], off
	global_load_dwordx4 v[140:143], v[52:53], off offset:1024
	global_load_dwordx4 v[144:147], v[52:53], off offset:2048
	global_load_dwordx4 v[148:151], v[52:53], off offset:3072
	s_branch .LBB0_168

; __device__ __forceinline__ unsigned pack2(float lo, float hi) { return (unsigned)f2bf(lo) | ((unsigned)f2bf(hi) << 16); }
; __device__ __forceinline__ float bflo(unsigned u) { return __uint_as_float(u << 16); }
; __device__ __forceinline__ float bfhi(unsigned u) { return __uint_as_float(u & 0xffff0000u); }
; __device__ void phase_rows(int flags, const float* xin, bf16_t* XB, const bf16_t* mf, const float* g1, const float* g2, float* xout, bf16_t* U,
;                            const float* pin, bf16_t* Pb) {
;     ...
;         for (int k = 0; k < 2; ++k) { const int r = r0 + k * stride; if (r < TCH) {
;             if (flags & 1) {
;                 float ss = 0.f; float4 m[4];
; #pragma unroll
;                 for (int i = 0; i < 4; ++i) { m[i] = make_float4(bflo(mq[k][i].x), bfhi(mq[k][i].x), bflo(mq[k][i].y), bfhi(mq[k][i].y)); ss += m[i].x * m[i].x + m[i].y * m[i].y + m[i].z * m[i].z + m[i].w * m[i].w; }
;                 ss = wave_sum(ss); const float rs = rsqrtf(ss * (1.0f / DM) + 1e-6f);
; #pragma unroll
;                 for (int i = 0; i < 4; ++i) { const float4 g = ((const float4*)g1)[lane + 64 * i];
;                     x[k][i].x += m[i].x * rs * g.x; x[k][i].y += m[i].y * rs * g.y; x[k][i].z += m[i].z * rs * g.z; x[k][i].w += m[i].w * rs * g.w; }
;                 if (flags & 32) { float4* xo = (float4*)(xout + (size_t)r * DM);
; #pragma unroll
;                     for (int i = 0; i < 4; ++i) __builtin_nontemporal_store((f32x4){x[k][i].x, x[k][i].y, x[k][i].z, x[k][i].w}, (f32x4*)(xo + lane + 64 * i)); }
;                 else { uint2* xo = (uint2*)(XB + (size_t)r * DM);
; #pragma unroll
;                     for (int i = 0; i < 4; ++i) { uint2 o; o.x = pack2(x[k][i].x, x[k][i].y); o.y = pack2(x[k][i].z, x[k][i].w); xo[lane + 64 * i] = o; } }
;             }
.LBB0_178:
	s_or_b64 exec, exec, s[58:59]
	s_waitcnt vmcnt(3)
	v_lshlrev_b32_e32 v114, 16, v92
	v_and_b32_e32 v116, 0xffff0000, v92
	v_lshlrev_b32_e32 v115, 16, v93
	v_and_b32_e32 v117, 0xffff0000, v93
	s_waitcnt vmcnt(2)
	v_lshlrev_b32_e32 v118, 16, v90
	v_and_b32_e32 v120, 0xffff0000, v90
	v_lshlrev_b32_e32 v119, 16, v91
	v_and_b32_e32 v121, 0xffff0000, v91
	global_load_dwordx4 v[90:93], v[50:51], off
	global_load_dwordx4 v[102:105], v[50:51], off offset:1024
	v_lshlrev_b32_e32 v20, 16, v94
	v_and_b32_e32 v94, 0xffff0000, v94
	v_mov_b32_e32 v112, v94
	v_mov_b32_e32 v113, v116
	v_lshlrev_b32_e32 v21, 16, v95
	v_mov_b32_e32 v110, v20
	v_mov_b32_e32 v111, v114
	v_pk_mul_f32 v[112:113], v[112:113], v[112:113]
	v_and_b32_e32 v95, 0xffff0000, v95
	global_load_dwordx4 v[106:109], v[50:51], off offset:2048
	v_pk_fma_f32 v[110:111], v[110:111], v[110:111], v[112:113]
	v_mov_b32_e32 v112, v21
	v_mov_b32_e32 v113, v115
	v_pk_fma_f32 v[110:111], v[112:113], v[112:113], v[110:111]
	v_mov_b32_e32 v112, v95
	v_mov_b32_e32 v113, v117
	v_pk_fma_f32 v[124:125], v[112:113], v[112:113], v[110:111]
	global_load_dwordx4 v[110:113], v[50:51], off offset:3072
	s_waitcnt vmcnt(5)
	v_lshlrev_b32_e32 v122, 16, v88
	v_and_b32_e32 v88, 0xffff0000, v88
	v_mov_b32_e32 v128, v120
	v_mov_b32_e32 v129, v88
	v_lshlrev_b32_e32 v123, 16, v89
	v_mov_b32_e32 v126, v118
	v_mov_b32_e32 v127, v122
	v_pk_mul_f32 v[128:129], v[128:129], v[128:129]
	v_and_b32_e32 v89, 0xffff0000, v89
	v_pk_fma_f32 v[126:127], v[126:127], v[126:127], v[128:129]
	v_mov_b32_e32 v128, v119
	v_mov_b32_e32 v129, v123
	v_pk_fma_f32 v[126:127], v[128:129], v[128:129], v[126:127]
	v_mov_b32_e32 v128, v121
	v_mov_b32_e32 v129, v89
	v_pk_fma_f32 v[126:127], v[128:129], v[128:129], v[126:127]
	v_add_f32_e32 v41, v124, v125
	v_add_f32_e32 v41, v41, v126
	v_add_f32_e32 v41, v41, v127
	ds_bpermute_b32 v124, v96, v41
	s_waitcnt vmcnt(4)
	v_and_b32_sdwa v127, v38, v185 dst_sel:DWORD dst_unused:UNUSED_PAD src0_sel:WORD_1 src1_sel:DWORD
	s_mov_b32 s27, 0x3a400000
	v_and_b32_sdwa v130, v36, v185 dst_sel:DWORD dst_unused:UNUSED_PAD src0_sel:WORD_1 src1_sel:DWORD
	v_and_b32_sdwa v131, v39, v185 dst_sel:DWORD dst_unused:UNUSED_PAD src0_sel:WORD_1 src1_sel:DWORD
	s_waitcnt lgkmcnt(0)
	v_add_f32_e32 v41, v41, v124
	ds_bpermute_b32 v124, v97, v41
	v_and_b32_sdwa v132, v37, v185 dst_sel:DWORD dst_unused:UNUSED_PAD src0_sel:WORD_1 src1_sel:DWORD
	v_add3_u32 v37, v37, v132, s46
	v_and_b32_e32 v37, 0xffff0000, v37
	s_waitcnt lgkmcnt(0)
	v_add_f32_e32 v41, v41, v124
	ds_bpermute_b32 v124, v98, v41
	s_waitcnt lgkmcnt(0)
	v_add_f32_e32 v41, v41, v124
	ds_bpermute_b32 v124, v99, v41
	s_waitcnt lgkmcnt(0)
	v_add_f32_e32 v41, v41, v124
	ds_bpermute_b32 v124, v100, v41
	s_waitcnt lgkmcnt(0)
	v_add_f32_e32 v41, v41, v124
	ds_bpermute_b32 v124, v101, v41
	s_waitcnt lgkmcnt(0)
	v_add_f32_e32 v41, v41, v124
	v_fmamk_f32 v41, v41, 0x3a800000, v184
	v_mul_f32_e32 v124, 0x4b800000, v41
	v_cmp_gt_f32_e32 vcc, s67, v41
	s_waitcnt vmcnt(3)
	v_mov_b32_e32 v128, v90
	v_cndmask_b32_e32 v41, v41, v124, vcc
	v_rsq_f32_e32 v41, v41
	v_mov_b32_e32 v129, v92
	v_mov_b32_e32 v92, v91
	s_waitcnt vmcnt(2)
	v_mov_b32_e32 v90, v102
	v_mul_f32_e32 v126, 0x45800000, v41
	v_cndmask_b32_e32 v126, v41, v126, vcc
	v_pk_mul_f32 v[20:21], v[126:127], v[20:21] op_sel_hi:[0,1]
	v_pk_fma_f32 v[86:87], v[128:129], v[20:21], v[86:87]
	v_pk_mul_f32 v[20:21], v[126:127], v[94:95] op_sel_hi:[0,1]
	v_mov_b32_e32 v91, v104
	v_pk_fma_f32 v[92:93], v[92:93], v[20:21], v[34:35]
	v_pk_mul_f32 v[20:21], v[126:127], v[114:115] op_sel_hi:[0,1]
	v_mov_b32_e32 v104, v103
	v_pk_fma_f32 v[84:85], v[90:91], v[20:21], v[84:85]
	v_pk_mul_f32 v[20:21], v[126:127], v[116:117] op_sel_hi:[0,1]
	s_waitcnt vmcnt(1)
	v_mov_b32_e32 v102, v106
	v_mov_b32_e32 v103, v108
	v_pk_fma_f32 v[30:31], v[104:105], v[20:21], v[30:31]
	v_pk_mul_f32 v[20:21], v[126:127], v[118:119] op_sel_hi:[0,1]
	v_mov_b32_e32 v108, v107
	v_pk_fma_f32 v[82:83], v[102:103], v[20:21], v[82:83]
	v_pk_mul_f32 v[20:21], v[126:127], v[120:121] op_sel_hi:[0,1]
	v_pk_fma_f32 v[26:27], v[108:109], v[20:21], v[26:27]
	v_pk_mul_f32 v[20:21], v[126:127], v[122:123] op_sel_hi:[0,1]
	s_waitcnt vmcnt(0)
	v_mov_b32_e32 v34, v110
	v_mov_b32_e32 v35, v112
	v_pk_fma_f32 v[20:21], v[20:21], v[34:35], v[80:81]
	v_pk_mul_f32 v[34:35], v[126:127], v[88:89] op_sel_hi:[0,1]
	v_mov_b32_e32 v112, v111
	v_pk_fma_f32 v[22:23], v[34:35], v[112:113], v[22:23]
	v_and_b32_sdwa v35, v86, v185 dst_sel:DWORD dst_unused:UNUSED_PAD src0_sel:WORD_1 src1_sel:DWORD
	v_add3_u32 v41, v86, v35, s46
	v_and_b32_sdwa v35, v93, v185 dst_sel:DWORD dst_unused:UNUSED_PAD src0_sel:WORD_1 src1_sel:DWORD
	v_and_b32_sdwa v80, v92, v185 dst_sel:DWORD dst_unused:UNUSED_PAD src0_sel:WORD_1 src1_sel:DWORD
	v_and_b32_sdwa v34, v87, v185 dst_sel:DWORD dst_unused:UNUSED_PAD src0_sel:WORD_1 src1_sel:DWORD
	v_add3_u32 v35, v93, v35, s46
	v_add3_u32 v80, v92, v80, s46
	v_add3_u32 v34, v87, v34, s46
	v_and_b32_e32 v35, 0xffff0000, v35
	v_and_b32_e32 v80, 0xffff0000, v80
	v_or_b32_sdwa v35, v35, v34 dst_sel:DWORD dst_unused:UNUSED_PAD src0_sel:DWORD src1_sel:WORD_1
	v_or_b32_sdwa v34, v80, v41 dst_sel:DWORD dst_unused:UNUSED_PAD src0_sel:DWORD src1_sel:WORD_1
	v_add_co_u32_e32 v80, vcc, s27, v78
	v_and_b32_sdwa v88, v30, v185 dst_sel:DWORD dst_unused:UNUSED_PAD src0_sel:WORD_1 src1_sel:DWORD
	s_nop 0
	v_addc_co_u32_e32 v81, vcc, 0, v79, vcc
	global_store_dwordx2 v[80:81], v[34:35], off
	v_and_b32_sdwa v35, v84, v185 dst_sel:DWORD dst_unused:UNUSED_PAD src0_sel:WORD_1 src1_sel:DWORD
	v_add3_u32 v41, v84, v35, s46
	v_and_b32_sdwa v35, v31, v185 dst_sel:DWORD dst_unused:UNUSED_PAD src0_sel:WORD_1 src1_sel:DWORD
; __device__ __forceinline__ unsigned pack2(float lo, float hi) { return (unsigned)f2bf(lo) | ((unsigned)f2bf(hi) << 16); }
; __device__ void phase_rows(int flags, const float* xin, bf16_t* XB, const bf16_t* mf, const float* g1, const float* g2, float* xout, bf16_t* U,
;                            const float* pin, bf16_t* Pb) {
;     ...
;                     for (int i = 0; i < 4; ++i) { uint2 o; o.x = pack2(x[k][i].x, x[k][i].y); o.y = pack2(x[k][i].z, x[k][i].w); xo[lane + 64 * i] = o; } }
;             }
;             if (flags & 8) { uint2 o; o.x = pack2(pv[k].x, pv[k].y); o.y = pack2(pv[k].z, pv[k].w); ((uint2*)(Pb + (size_t)r * DPLE))[lane] = o; }
;             if (flags & 2) {
;                 float ss = 0.f;
; #pragma unroll
;                 for (int i = 0; i < 4; ++i) ss += x[k][i].x * x[k][i].x + x[k][i].y * x[k][i].y + x[k][i].z * x[k][i].z + x[k][i].w * x[k][i].w;
;                 ss = wave_sum(ss); const float rs2 = rsqrtf(ss * (1.0f / DM) + 1e-6f);
;                 uint2* uo = (uint2*)(U + (size_t)r * DM);
; #pragma unroll
;                 for (int i = 0; i < 4; ++i) { const float4 g = ((const float4*)g2)[lane + 64 * i];
;                     uint2 o; o.x = pack2(x[k][i].x * rs2 * g.x, x[k][i].y * rs2 * g.y); o.y = pack2(x[k][i].z * rs2 * g.z, x[k][i].w * rs2 * g.w); uo[lane + 64 * i] = o; }
	v_and_b32_sdwa v34, v85, v185 dst_sel:DWORD dst_unused:UNUSED_PAD src0_sel:WORD_1 src1_sel:DWORD
	v_add3_u32 v35, v31, v35, s46
	v_add3_u32 v88, v30, v88, s46
	v_add3_u32 v34, v85, v34, s46
	v_and_b32_e32 v35, 0xffff0000, v35
	v_and_b32_e32 v88, 0xffff0000, v88
	v_or_b32_sdwa v35, v35, v34 dst_sel:DWORD dst_unused:UNUSED_PAD src0_sel:DWORD src1_sel:WORD_1
	v_or_b32_sdwa v34, v88, v41 dst_sel:DWORD dst_unused:UNUSED_PAD src0_sel:DWORD src1_sel:WORD_1
	global_store_dwordx2 v[80:81], v[34:35], off offset:512
	v_and_b32_sdwa v35, v82, v185 dst_sel:DWORD dst_unused:UNUSED_PAD src0_sel:WORD_1 src1_sel:DWORD
	v_add3_u32 v41, v82, v35, s46
	v_and_b32_sdwa v35, v27, v185 dst_sel:DWORD dst_unused:UNUSED_PAD src0_sel:WORD_1 src1_sel:DWORD
	v_and_b32_sdwa v88, v26, v185 dst_sel:DWORD dst_unused:UNUSED_PAD src0_sel:WORD_1 src1_sel:DWORD
	v_and_b32_sdwa v34, v83, v185 dst_sel:DWORD dst_unused:UNUSED_PAD src0_sel:WORD_1 src1_sel:DWORD
	v_add3_u32 v35, v27, v35, s46
	v_add3_u32 v88, v26, v88, s46
	v_add3_u32 v34, v83, v34, s46
	v_and_b32_e32 v35, 0xffff0000, v35
	v_and_b32_e32 v88, 0xffff0000, v88
	v_or_b32_sdwa v35, v35, v34 dst_sel:DWORD dst_unused:UNUSED_PAD src0_sel:DWORD src1_sel:WORD_1
	v_or_b32_sdwa v34, v88, v41 dst_sel:DWORD dst_unused:UNUSED_PAD src0_sel:DWORD src1_sel:WORD_1
	global_store_dwordx2 v[80:81], v[34:35], off offset:1024
	v_and_b32_sdwa v35, v20, v185 dst_sel:DWORD dst_unused:UNUSED_PAD src0_sel:WORD_1 src1_sel:DWORD
	v_add3_u32 v41, v20, v35, s46
	v_and_b32_sdwa v35, v23, v185 dst_sel:DWORD dst_unused:UNUSED_PAD src0_sel:WORD_1 src1_sel:DWORD
	v_and_b32_sdwa v88, v22, v185 dst_sel:DWORD dst_unused:UNUSED_PAD src0_sel:WORD_1 src1_sel:DWORD
	v_and_b32_sdwa v34, v21, v185 dst_sel:DWORD dst_unused:UNUSED_PAD src0_sel:WORD_1 src1_sel:DWORD
	v_add3_u32 v35, v23, v35, s46
	v_add3_u32 v88, v22, v88, s46
	v_add3_u32 v34, v21, v34, s46
	v_and_b32_e32 v35, 0xffff0000, v35
	v_and_b32_e32 v88, 0xffff0000, v88
	v_or_b32_sdwa v35, v35, v34 dst_sel:DWORD dst_unused:UNUSED_PAD src0_sel:DWORD src1_sel:WORD_1
	v_or_b32_sdwa v34, v88, v41 dst_sel:DWORD dst_unused:UNUSED_PAD src0_sel:DWORD src1_sel:WORD_1
	global_store_dwordx2 v[80:81], v[34:35], off offset:1536
	v_add3_u32 v34, v36, v130, s46
	v_add3_u32 v36, v39, v131, s46
	v_add3_u32 v35, v38, v127, s46
	v_and_b32_e32 v36, 0xffff0000, v36
	v_lshl_add_u64 v[124:125], v[62:63], 0, v[0:1]
	v_or_b32_sdwa v35, v36, v35 dst_sel:DWORD dst_unused:UNUSED_PAD src0_sel:DWORD src1_sel:WORD_1
	v_or_b32_sdwa v34, v37, v34 dst_sel:DWORD dst_unused:UNUSED_PAD src0_sel:DWORD src1_sel:WORD_1
	global_store_dwordx2 v[124:125], v[34:35], off
	v_mov_b64_e32 v[34:35], v[136:137]
	v_mov_b64_e32 v[36:37], v[138:139]
	v_mov_b32_e32 v80, v92
	v_mov_b32_e32 v81, v30
	v_mov_b32_e32 v38, v86
	v_mov_b32_e32 v39, v84
	v_pk_mul_f32 v[80:81], v[80:81], v[80:81]
	v_mov_b32_e32 v88, v26
	v_pk_fma_f32 v[38:39], v[38:39], v[38:39], v[80:81]
	v_mov_b32_e32 v80, v87
	v_mov_b32_e32 v81, v85
	v_pk_fma_f32 v[38:39], v[80:81], v[80:81], v[38:39]
	v_mov_b32_e32 v80, v93
	v_mov_b32_e32 v81, v31
	v_mov_b32_e32 v89, v22
	v_pk_fma_f32 v[38:39], v[80:81], v[80:81], v[38:39]
	v_mov_b32_e32 v80, v82
	v_mov_b32_e32 v81, v20
	v_pk_mul_f32 v[88:89], v[88:89], v[88:89]
	v_add_f32_e32 v38, v38, v39
	v_pk_fma_f32 v[80:81], v[80:81], v[80:81], v[88:89]
	v_mov_b32_e32 v88, v83
	v_mov_b32_e32 v89, v21
	v_pk_fma_f32 v[80:81], v[88:89], v[88:89], v[80:81]
	v_mov_b32_e32 v88, v27
	v_mov_b32_e32 v89, v23
	v_pk_fma_f32 v[80:81], v[88:89], v[88:89], v[80:81]
	s_nop 0
	v_add_f32_e32 v38, v80, v38
	v_add_f32_e32 v38, v38, v81
	ds_bpermute_b32 v39, v96, v38
	s_waitcnt lgkmcnt(0)
	v_add_f32_e32 v38, v38, v39
	ds_bpermute_b32 v39, v97, v38
	s_waitcnt lgkmcnt(0)
	v_add_f32_e32 v38, v38, v39
	ds_bpermute_b32 v39, v98, v38
	s_waitcnt lgkmcnt(0)
	v_add_f32_e32 v38, v38, v39
	ds_bpermute_b32 v39, v99, v38
	s_waitcnt lgkmcnt(0)
	v_add_f32_e32 v38, v38, v39
	ds_bpermute_b32 v39, v100, v38
	s_waitcnt lgkmcnt(0)
	v_add_f32_e32 v38, v38, v39
	ds_bpermute_b32 v39, v101, v38
	s_waitcnt lgkmcnt(0)
	v_add_f32_e32 v38, v38, v39
	v_fmamk_f32 v38, v38, 0x3a800000, v184
	v_mul_f32_e32 v39, 0x4b800000, v38
	v_cmp_gt_f32_e32 vcc, s67, v38
	s_nop 1
	v_cndmask_b32_e32 v38, v38, v39, vcc
	v_rsq_f32_e32 v38, v38
	s_nop 0
	v_mul_f32_e32 v39, 0x45800000, v38
	v_cndmask_b32_e32 v38, v38, v39, vcc
	v_pk_mul_f32 v[80:81], v[86:87], v[38:39] op_sel_hi:[1,0]
	v_add_co_u32_e32 v78, vcc, s66, v78
	v_mov_b32_e32 v86, v34
	v_mov_b32_e32 v87, v36
	v_pk_mul_f32 v[80:81], v[86:87], v[80:81]
	v_pk_mul_f32 v[86:87], v[92:93], v[38:39] op_sel_hi:[1,0]
	v_mov_b32_e32 v36, v35
	v_pk_mul_f32 v[34:35], v[36:37], v[86:87]
	v_and_b32_sdwa v36, v81, v185 dst_sel:DWORD dst_unused:UNUSED_PAD src0_sel:WORD_1 src1_sel:DWORD
	v_and_b32_sdwa v39, v35, v185 dst_sel:DWORD dst_unused:UNUSED_PAD src0_sel:WORD_1 src1_sel:DWORD
	v_and_b32_sdwa v41, v34, v185 dst_sel:DWORD dst_unused:UNUSED_PAD src0_sel:WORD_1 src1_sel:DWORD
	v_and_b32_sdwa v37, v80, v185 dst_sel:DWORD dst_unused:UNUSED_PAD src0_sel:WORD_1 src1_sel:DWORD
	v_add3_u32 v35, v35, v39, s46
	v_add3_u32 v34, v34, v41, s46
	v_add3_u32 v37, v80, v37, s46
	v_add3_u32 v36, v81, v36, s46
	v_and_b32_e32 v35, 0xffff0000, v35
	v_and_b32_e32 v34, 0xffff0000, v34
	v_or_b32_sdwa v35, v35, v36 dst_sel:DWORD dst_unused:UNUSED_PAD src0_sel:DWORD src1_sel:WORD_1
	v_or_b32_sdwa v34, v34, v37 dst_sel:DWORD dst_unused:UNUSED_PAD src0_sel:DWORD src1_sel:WORD_1
	v_addc_co_u32_e32 v79, vcc, 0, v79, vcc
	global_store_dwordx2 v[78:79], v[34:35], off
	v_mov_b64_e32 v[34:35], v[140:141]
	v_mov_b64_e32 v[36:37], v[142:143]
	v_pk_mul_f32 v[80:81], v[84:85], v[38:39] op_sel_hi:[1,0]
; __device__ __forceinline__ unsigned pack2(float lo, float hi) { return (unsigned)f2bf(lo) | ((unsigned)f2bf(hi) << 16); }
; __device__ __forceinline__ float bflo(unsigned u) { return __uint_as_float(u << 16); }
; __device__ __forceinline__ float bfhi(unsigned u) { return __uint_as_float(u & 0xffff0000u); }
; __device__ void phase_rows(int flags, const float* xin, bf16_t* XB, const bf16_t* mf, const float* g1, const float* g2, float* xout, bf16_t* U,
;                            const float* pin, bf16_t* Pb) {
;     ...
;         for (int k = 0; k < 2; ++k) { const int r = r0 + k * stride; if (r < TCH) {
;             if (flags & 1) {
;                 float ss = 0.f; float4 m[4];
; #pragma unroll
;                 for (int i = 0; i < 4; ++i) { m[i] = make_float4(bflo(mq[k][i].x), bfhi(mq[k][i].x), bflo(mq[k][i].y), bfhi(mq[k][i].y)); ss += m[i].x * m[i].x + m[i].y * m[i].y + m[i].z * m[i].z + m[i].w * m[i].w; }
;                 ss = wave_sum(ss); const float rs = rsqrtf(ss * (1.0f / DM) + 1e-6f);
; #pragma unroll
;                 for (int i = 0; i < 4; ++i) { const float4 g = ((const float4*)g1)[lane + 64 * i];
;                     x[k][i].x += m[i].x * rs * g.x; x[k][i].y += m[i].y * rs * g.y; x[k][i].z += m[i].z * rs * g.z; x[k][i].w += m[i].w * rs * g.w; }
;     ...
;             if (flags & 2) {
;                 float ss = 0.f;
; #pragma unroll
;                 for (int i = 0; i < 4; ++i) ss += x[k][i].x * x[k][i].x + x[k][i].y * x[k][i].y + x[k][i].z * x[k][i].z + x[k][i].w * x[k][i].w;
;                 ss = wave_sum(ss); const float rs2 = rsqrtf(ss * (1.0f / DM) + 1e-6f);
;                 uint2* uo = (uint2*)(U + (size_t)r * DM);
; #pragma unroll
;                 for (int i = 0; i < 4; ++i) { const float4 g = ((const float4*)g2)[lane + 64 * i];
;                     uint2 o; o.x = pack2(x[k][i].x * rs2 * g.x, x[k][i].y * rs2 * g.y); o.y = pack2(x[k][i].z * rs2 * g.z, x[k][i].w * rs2 * g.w); uo[lane + 64 * i] = o; }
	v_pk_mul_f32 v[30:31], v[30:31], v[38:39] op_sel_hi:[1,0]
	v_mov_b32_e32 v85, v36
	v_mov_b32_e32 v36, v35
	v_mov_b32_e32 v84, v34
	v_pk_mul_f32 v[30:31], v[36:37], v[30:31]
	v_pk_mul_f32 v[34:35], v[84:85], v[80:81]
	v_and_b32_sdwa v39, v31, v185 dst_sel:DWORD dst_unused:UNUSED_PAD src0_sel:WORD_1 src1_sel:DWORD
	v_and_b32_sdwa v41, v30, v185 dst_sel:DWORD dst_unused:UNUSED_PAD src0_sel:WORD_1 src1_sel:DWORD
	v_and_b32_sdwa v36, v35, v185 dst_sel:DWORD dst_unused:UNUSED_PAD src0_sel:WORD_1 src1_sel:DWORD
	v_and_b32_sdwa v37, v34, v185 dst_sel:DWORD dst_unused:UNUSED_PAD src0_sel:WORD_1 src1_sel:DWORD
	v_add3_u32 v31, v31, v39, s46
	v_add3_u32 v30, v30, v41, s46
	v_add3_u32 v34, v34, v37, s46
	v_add3_u32 v35, v35, v36, s46
	v_and_b32_e32 v31, 0xffff0000, v31
	v_and_b32_e32 v30, 0xffff0000, v30
	v_or_b32_sdwa v31, v31, v35 dst_sel:DWORD dst_unused:UNUSED_PAD src0_sel:DWORD src1_sel:WORD_1
	v_or_b32_sdwa v30, v30, v34 dst_sel:DWORD dst_unused:UNUSED_PAD src0_sel:DWORD src1_sel:WORD_1
	global_store_dwordx2 v[78:79], v[30:31], off offset:512
	v_mov_b64_e32 v[34:35], v[144:145]
	v_mov_b64_e32 v[36:37], v[146:147]
	v_pk_mul_f32 v[26:27], v[26:27], v[38:39] op_sel_hi:[1,0]
	v_pk_mul_f32 v[30:31], v[82:83], v[38:39] op_sel_hi:[1,0]
	v_pk_mul_f32 v[22:23], v[22:23], v[38:39] op_sel_hi:[1,0]
	v_pk_mul_f32 v[20:21], v[20:21], v[38:39] op_sel_hi:[1,0]
	v_mov_b32_e32 v81, v36
	v_mov_b32_e32 v36, v35
	v_mov_b32_e32 v80, v34
	v_pk_mul_f32 v[26:27], v[26:27], v[36:37]
	v_pk_mul_f32 v[30:31], v[30:31], v[80:81]
	v_and_b32_sdwa v36, v27, v185 dst_sel:DWORD dst_unused:UNUSED_PAD src0_sel:WORD_1 src1_sel:DWORD
	v_and_b32_sdwa v37, v26, v185 dst_sel:DWORD dst_unused:UNUSED_PAD src0_sel:WORD_1 src1_sel:DWORD
	v_and_b32_sdwa v34, v31, v185 dst_sel:DWORD dst_unused:UNUSED_PAD src0_sel:WORD_1 src1_sel:DWORD
	v_and_b32_sdwa v35, v30, v185 dst_sel:DWORD dst_unused:UNUSED_PAD src0_sel:WORD_1 src1_sel:DWORD
	v_add3_u32 v27, v27, v36, s46
	v_add3_u32 v26, v26, v37, s46
	v_add3_u32 v30, v30, v35, s46
	v_add3_u32 v31, v31, v34, s46
	v_and_b32_e32 v27, 0xffff0000, v27
	v_and_b32_e32 v26, 0xffff0000, v26
	v_or_b32_sdwa v27, v27, v31 dst_sel:DWORD dst_unused:UNUSED_PAD src0_sel:DWORD src1_sel:WORD_1
	v_or_b32_sdwa v26, v26, v30 dst_sel:DWORD dst_unused:UNUSED_PAD src0_sel:DWORD src1_sel:WORD_1
	global_store_dwordx2 v[78:79], v[26:27], off offset:1024
	v_mov_b64_e32 v[34:35], v[148:149]
	v_mov_b64_e32 v[36:37], v[150:151]
	v_mov_b32_e32 v27, v36
	v_mov_b32_e32 v36, v35
	v_mov_b32_e32 v26, v34
	v_pk_mul_f32 v[22:23], v[22:23], v[36:37]
	v_pk_mul_f32 v[20:21], v[20:21], v[26:27]
	v_and_b32_sdwa v30, v23, v185 dst_sel:DWORD dst_unused:UNUSED_PAD src0_sel:WORD_1 src1_sel:DWORD
	v_and_b32_sdwa v31, v22, v185 dst_sel:DWORD dst_unused:UNUSED_PAD src0_sel:WORD_1 src1_sel:DWORD
	v_and_b32_sdwa v26, v21, v185 dst_sel:DWORD dst_unused:UNUSED_PAD src0_sel:WORD_1 src1_sel:DWORD
	v_and_b32_sdwa v27, v20, v185 dst_sel:DWORD dst_unused:UNUSED_PAD src0_sel:WORD_1 src1_sel:DWORD
	v_add3_u32 v23, v23, v30, s46
	v_add3_u32 v22, v22, v31, s46
	v_add3_u32 v20, v20, v27, s46
	v_add3_u32 v21, v21, v26, s46
	v_and_b32_e32 v23, 0xffff0000, v23
	v_and_b32_e32 v22, 0xffff0000, v22
	v_or_b32_sdwa v21, v23, v21 dst_sel:DWORD dst_unused:UNUSED_PAD src0_sel:DWORD src1_sel:WORD_1
	v_or_b32_sdwa v20, v22, v20 dst_sel:DWORD dst_unused:UNUSED_PAD src0_sel:DWORD src1_sel:WORD_1
	global_store_dwordx2 v[78:79], v[20:21], off offset:1536
	s_and_saveexec_b64 s[58:59], s[6:7]
	s_cbranch_execz .LBB0_167
	global_load_dwordx4 v[20:23], v[50:51], off offset:3072
	global_load_dwordx4 v[34:37], v[50:51], off offset:2048
	global_load_dwordx4 v[78:81], v[50:51], off offset:1024
	global_load_dwordx4 v[82:85], v[50:51], off
	v_and_b32_e32 v89, 0xffff0000, v72
	v_and_b32_e32 v93, 0xffff0000, v74
	v_lshlrev_b32_e32 v88, 16, v72
	v_lshlrev_b32_e32 v92, 16, v74
	v_mov_b32_e32 v108, v93
	v_mov_b32_e32 v109, v89
	v_and_b32_e32 v27, 0xffff0000, v68
	v_and_b32_e32 v39, 0xffff0000, v70
	v_lshlrev_b32_e32 v90, 16, v73
	v_lshlrev_b32_e32 v94, 16, v75
	v_mov_b32_e32 v106, v92
	v_mov_b32_e32 v107, v88
	v_pk_mul_f32 v[108:109], v[108:109], v[108:109]
	v_lshlrev_b32_e32 v26, 16, v68
	v_lshlrev_b32_e32 v38, 16, v70
	v_and_b32_e32 v91, 0xffff0000, v73
	v_and_b32_e32 v95, 0xffff0000, v75
	v_mov_b32_e32 v102, v94
	v_mov_b32_e32 v103, v90
	v_pk_fma_f32 v[106:107], v[106:107], v[106:107], v[108:109]
	v_mov_b32_e32 v110, v39
	v_mov_b32_e32 v111, v27
	v_lshlrev_b32_e32 v30, 16, v69
	v_lshlrev_b32_e32 v86, 16, v71
	v_mov_b32_e32 v104, v95
	v_mov_b32_e32 v105, v91
	v_pk_fma_f32 v[102:103], v[102:103], v[102:103], v[106:107]
	v_mov_b32_e32 v108, v38
	v_mov_b32_e32 v109, v26
	v_pk_mul_f32 v[110:111], v[110:111], v[110:111]
	v_and_b32_e32 v31, 0xffff0000, v69
	v_and_b32_e32 v87, 0xffff0000, v71
	v_pk_fma_f32 v[102:103], v[104:105], v[104:105], v[102:103]
	v_mov_b32_e32 v104, v86
	v_mov_b32_e32 v105, v30
	v_pk_fma_f32 v[108:109], v[108:109], v[108:109], v[110:111]
	v_mov_b32_e32 v106, v87
	v_mov_b32_e32 v107, v31
	v_pk_fma_f32 v[104:105], v[104:105], v[104:105], v[108:109]
	s_nop 0
	v_pk_fma_f32 v[104:105], v[106:107], v[106:107], v[104:105]
	s_nop 0
	v_add_f32_e32 v41, v104, v105
	v_add_f32_e32 v41, v103, v41
	v_add_f32_e32 v41, v102, v41
	ds_bpermute_b32 v102, v96, v41
	s_waitcnt lgkmcnt(0)
	v_add_f32_e32 v41, v41, v102
	ds_bpermute_b32 v102, v97, v41
	s_waitcnt lgkmcnt(0)
	v_add_f32_e32 v41, v41, v102
	ds_bpermute_b32 v102, v98, v41
	s_waitcnt lgkmcnt(0)
	v_add_f32_e32 v41, v41, v102
	ds_bpermute_b32 v102, v99, v41
	s_waitcnt lgkmcnt(0)
	v_add_f32_e32 v41, v41, v102
	ds_bpermute_b32 v102, v100, v41
	s_waitcnt lgkmcnt(0)
; __device__ __forceinline__ unsigned pack2(float lo, float hi) { return (unsigned)f2bf(lo) | ((unsigned)f2bf(hi) << 16); }
; __device__ void phase_rows(int flags, const float* xin, bf16_t* XB, const bf16_t* mf, const float* g1, const float* g2, float* xout, bf16_t* U,
;                            const float* pin, bf16_t* Pb) {
;     ...
;                     x[k][i].x += m[i].x * rs * g.x; x[k][i].y += m[i].y * rs * g.y; x[k][i].z += m[i].z * rs * g.z; x[k][i].w += m[i].w * rs * g.w; }
;                 if (flags & 32) { float4* xo = (float4*)(xout + (size_t)r * DM);
; #pragma unroll
;                     for (int i = 0; i < 4; ++i) __builtin_nontemporal_store((f32x4){x[k][i].x, x[k][i].y, x[k][i].z, x[k][i].w}, (f32x4*)(xo + lane + 64 * i)); }
;                 else { uint2* xo = (uint2*)(XB + (size_t)r * DM);
; #pragma unroll
;                     for (int i = 0; i < 4; ++i) { uint2 o; o.x = pack2(x[k][i].x, x[k][i].y); o.y = pack2(x[k][i].z, x[k][i].w); xo[lane + 64 * i] = o; } }
;             }
;             if (flags & 8) { uint2 o; o.x = pack2(pv[k].x, pv[k].y); o.y = pack2(pv[k].z, pv[k].w); ((uint2*)(Pb + (size_t)r * DPLE))[lane] = o; }
;             if (flags & 2) {
;                 float ss = 0.f;
; #pragma unroll
;                 for (int i = 0; i < 4; ++i) ss += x[k][i].x * x[k][i].x + x[k][i].y * x[k][i].y + x[k][i].z * x[k][i].z + x[k][i].w * x[k][i].w;
;                 ss = wave_sum(ss); const float rs2 = rsqrtf(ss * (1.0f / DM) + 1e-6f);
;                 uint2* uo = (uint2*)(U + (size_t)r * DM);
; #pragma unroll
;                 for (int i = 0; i < 4; ++i) { const float4 g = ((const float4*)g2)[lane + 64 * i];
;                     uint2 o; o.x = pack2(x[k][i].x * rs2 * g.x, x[k][i].y * rs2 * g.y); o.y = pack2(x[k][i].z * rs2 * g.z, x[k][i].w * rs2 * g.w); uo[lane + 64 * i] = o; }
	v_add_f32_e32 v41, v41, v102
	ds_bpermute_b32 v102, v101, v41
	s_waitcnt lgkmcnt(0)
	v_add_f32_e32 v41, v41, v102
	v_fmamk_f32 v41, v41, 0x3a800000, v184
	v_mul_f32_e32 v102, 0x4b800000, v41
	v_cmp_gt_f32_e32 vcc, s67, v41
	s_nop 1
	v_cndmask_b32_e32 v41, v41, v102, vcc
	v_rsq_f32_e32 v41, v41
	s_nop 0
	v_mul_f32_e32 v102, 0x45800000, v41
	v_cndmask_b32_e32 v102, v41, v102, vcc
	v_pk_mul_f32 v[26:27], v[102:103], v[26:27] op_sel_hi:[0,1]
	v_pk_mul_f32 v[30:31], v[102:103], v[30:31] op_sel_hi:[0,1]
	v_pk_mul_f32 v[94:95], v[102:103], v[94:95] op_sel_hi:[0,1]
	s_waitcnt vmcnt(0)
	v_pk_fma_f32 v[2:3], v[82:83], v[26:27], v[2:3]
	v_pk_fma_f32 v[4:5], v[84:85], v[30:31], v[4:5]
	v_pk_fma_f32 v[16:17], v[94:95], v[22:23], v[16:17]
	v_and_b32_sdwa v23, v2, v185 dst_sel:DWORD dst_unused:UNUSED_PAD src0_sel:WORD_1 src1_sel:DWORD
	v_add3_u32 v30, v2, v23, s46
	v_and_b32_sdwa v23, v5, v185 dst_sel:DWORD dst_unused:UNUSED_PAD src0_sel:WORD_1 src1_sel:DWORD
	v_and_b32_sdwa v31, v3, v185 dst_sel:DWORD dst_unused:UNUSED_PAD src0_sel:WORD_1 src1_sel:DWORD
	v_and_b32_sdwa v22, v4, v185 dst_sel:DWORD dst_unused:UNUSED_PAD src0_sel:WORD_1 src1_sel:DWORD
	v_add3_u32 v23, v5, v23, s46
	v_add3_u32 v31, v3, v31, s46
	v_pk_mul_f32 v[38:39], v[102:103], v[38:39] op_sel_hi:[0,1]
	v_pk_mul_f32 v[92:93], v[102:103], v[92:93] op_sel_hi:[0,1]
	v_lshlrev_b64 v[26:27], 11, v[24:25]
	v_add3_u32 v22, v4, v22, s46
	v_and_b32_e32 v23, 0xffff0000, v23
	v_and_b32_e32 v31, 0xffff0000, v31
	v_pk_mul_f32 v[86:87], v[102:103], v[86:87] op_sel_hi:[0,1]
	v_pk_fma_f32 v[6:7], v[78:79], v[38:39], v[6:7]
	v_pk_fma_f32 v[14:15], v[92:93], v[20:21], v[14:15]
	v_lshl_add_u64 v[20:21], v[56:57], 0, v[26:27]
	v_or_b32_sdwa v23, v23, v22 dst_sel:DWORD dst_unused:UNUSED_PAD src0_sel:DWORD src1_sel:WORD_1
	v_or_b32_sdwa v22, v31, v30 dst_sel:DWORD dst_unused:UNUSED_PAD src0_sel:DWORD src1_sel:WORD_1
	v_pk_fma_f32 v[8:9], v[80:81], v[86:87], v[8:9]
	global_store_dwordx2 v[20:21], v[22:23], off
	v_and_b32_sdwa v23, v6, v185 dst_sel:DWORD dst_unused:UNUSED_PAD src0_sel:WORD_1 src1_sel:DWORD
	v_add3_u32 v30, v6, v23, s46
	v_and_b32_sdwa v23, v9, v185 dst_sel:DWORD dst_unused:UNUSED_PAD src0_sel:WORD_1 src1_sel:DWORD
	v_and_b32_sdwa v31, v7, v185 dst_sel:DWORD dst_unused:UNUSED_PAD src0_sel:WORD_1 src1_sel:DWORD
	v_and_b32_sdwa v22, v8, v185 dst_sel:DWORD dst_unused:UNUSED_PAD src0_sel:WORD_1 src1_sel:DWORD
	v_add3_u32 v23, v9, v23, s46
	v_add3_u32 v31, v7, v31, s46
	v_pk_mul_f32 v[88:89], v[102:103], v[88:89] op_sel_hi:[0,1]
	v_add3_u32 v22, v8, v22, s46
	v_and_b32_e32 v23, 0xffff0000, v23
	v_and_b32_e32 v31, 0xffff0000, v31
	v_pk_mul_f32 v[90:91], v[102:103], v[90:91] op_sel_hi:[0,1]
	v_pk_fma_f32 v[10:11], v[34:35], v[88:89], v[10:11]
	v_or_b32_sdwa v23, v23, v22 dst_sel:DWORD dst_unused:UNUSED_PAD src0_sel:DWORD src1_sel:WORD_1
	v_or_b32_sdwa v22, v31, v30 dst_sel:DWORD dst_unused:UNUSED_PAD src0_sel:DWORD src1_sel:WORD_1
	v_pk_fma_f32 v[12:13], v[90:91], v[36:37], v[12:13]
	global_store_dwordx2 v[20:21], v[22:23], off offset:512
	v_and_b32_sdwa v23, v10, v185 dst_sel:DWORD dst_unused:UNUSED_PAD src0_sel:WORD_1 src1_sel:DWORD
	v_add3_u32 v30, v10, v23, s46
	v_and_b32_sdwa v23, v13, v185 dst_sel:DWORD dst_unused:UNUSED_PAD src0_sel:WORD_1 src1_sel:DWORD
	v_and_b32_sdwa v31, v11, v185 dst_sel:DWORD dst_unused:UNUSED_PAD src0_sel:WORD_1 src1_sel:DWORD
	v_and_b32_sdwa v22, v12, v185 dst_sel:DWORD dst_unused:UNUSED_PAD src0_sel:WORD_1 src1_sel:DWORD
	v_add3_u32 v23, v13, v23, s46
	v_add3_u32 v31, v11, v31, s46
	v_add3_u32 v22, v12, v22, s46
	v_and_b32_e32 v23, 0xffff0000, v23
	v_and_b32_e32 v31, 0xffff0000, v31
	v_or_b32_sdwa v23, v23, v22 dst_sel:DWORD dst_unused:UNUSED_PAD src0_sel:DWORD src1_sel:WORD_1
	v_or_b32_sdwa v22, v31, v30 dst_sel:DWORD dst_unused:UNUSED_PAD src0_sel:DWORD src1_sel:WORD_1
	global_store_dwordx2 v[20:21], v[22:23], off offset:1024
	v_and_b32_sdwa v23, v14, v185 dst_sel:DWORD dst_unused:UNUSED_PAD src0_sel:WORD_1 src1_sel:DWORD
	v_add3_u32 v30, v14, v23, s46
	v_and_b32_sdwa v23, v17, v185 dst_sel:DWORD dst_unused:UNUSED_PAD src0_sel:WORD_1 src1_sel:DWORD
	v_and_b32_sdwa v31, v15, v185 dst_sel:DWORD dst_unused:UNUSED_PAD src0_sel:WORD_1 src1_sel:DWORD
	v_and_b32_sdwa v22, v16, v185 dst_sel:DWORD dst_unused:UNUSED_PAD src0_sel:WORD_1 src1_sel:DWORD
	v_add3_u32 v23, v17, v23, s46
	v_add3_u32 v31, v15, v31, s46
	v_add3_u32 v22, v16, v22, s46
	v_and_b32_e32 v23, 0xffff0000, v23
	v_and_b32_e32 v31, 0xffff0000, v31
	v_or_b32_sdwa v23, v23, v22 dst_sel:DWORD dst_unused:UNUSED_PAD src0_sel:DWORD src1_sel:WORD_1
	v_or_b32_sdwa v22, v31, v30 dst_sel:DWORD dst_unused:UNUSED_PAD src0_sel:DWORD src1_sel:WORD_1
	global_store_dwordx2 v[20:21], v[22:23], off offset:1536
	v_and_b32_sdwa v23, v32, v185 dst_sel:DWORD dst_unused:UNUSED_PAD src0_sel:WORD_1 src1_sel:DWORD
	v_and_b32_sdwa v30, v29, v185 dst_sel:DWORD dst_unused:UNUSED_PAD src0_sel:WORD_1 src1_sel:DWORD
	v_and_b32_sdwa v31, v28, v185 dst_sel:DWORD dst_unused:UNUSED_PAD src0_sel:WORD_1 src1_sel:DWORD
	v_and_b32_sdwa v22, v33, v185 dst_sel:DWORD dst_unused:UNUSED_PAD src0_sel:WORD_1 src1_sel:DWORD
	v_lshlrev_b64 v[20:21], 9, v[24:25]
	v_add3_u32 v24, v32, v23, s46
	v_add3_u32 v23, v29, v30, s46
	v_add3_u32 v25, v28, v31, s46
	v_add3_u32 v22, v33, v22, s46
	v_and_b32_e32 v23, 0xffff0000, v23
	v_and_b32_e32 v25, 0xffff0000, v25
	v_lshl_add_u64 v[20:21], v[48:49], 0, v[20:21]
	v_or_b32_sdwa v23, v22, v23 dst_sel:DWORD dst_unused:UNUSED_PAD src0_sel:WORD_1 src1_sel:DWORD
	v_or_b32_sdwa v22, v24, v25 dst_sel:DWORD dst_unused:UNUSED_PAD src0_sel:WORD_1 src1_sel:DWORD
	global_store_dwordx2 v[20:21], v[22:23], off
	v_mov_b64_e32 v[20:21], v[136:137]
	v_mov_b64_e32 v[22:23], v[138:139]
	v_mov_b32_e32 v28, v3
	v_mov_b32_e32 v29, v7
	v_mov_b32_e32 v24, v2
	v_mov_b32_e32 v25, v6
	v_pk_mul_f32 v[28:29], v[28:29], v[28:29]
	v_mov_b32_e32 v30, v11
	v_pk_fma_f32 v[24:25], v[24:25], v[24:25], v[28:29]
	v_mov_b32_e32 v28, v4
	v_mov_b32_e32 v29, v8
	v_pk_fma_f32 v[24:25], v[28:29], v[28:29], v[24:25]
	v_mov_b32_e32 v28, v5
	v_mov_b32_e32 v29, v9
	v_mov_b32_e32 v31, v15
	v_pk_fma_f32 v[24:25], v[28:29], v[28:29], v[24:25]
	v_mov_b32_e32 v28, v10
	v_mov_b32_e32 v29, v14
	v_pk_mul_f32 v[30:31], v[30:31], v[30:31]
	v_add_f32_e32 v24, v24, v25
	v_pk_fma_f32 v[28:29], v[28:29], v[28:29], v[30:31]
	v_mov_b32_e32 v30, v12
	v_mov_b32_e32 v31, v16
	v_pk_fma_f32 v[28:29], v[30:31], v[30:31], v[28:29]
	v_mov_b32_e32 v30, v13
	v_mov_b32_e32 v31, v17
	v_pk_fma_f32 v[28:29], v[30:31], v[30:31], v[28:29]
	v_lshl_add_u64 v[26:27], v[58:59], 0, v[26:27]
	v_add_f32_e32 v24, v28, v24
	v_add_f32_e32 v24, v24, v29
	ds_bpermute_b32 v25, v96, v24
	v_mov_b32_e32 v29, v5
	s_waitcnt lgkmcnt(0)
; __device__ __forceinline__ unsigned pack2(float lo, float hi) { return (unsigned)f2bf(lo) | ((unsigned)f2bf(hi) << 16); }
; __device__ void phase_rows(int flags, const float* xin, bf16_t* XB, const bf16_t* mf, const float* g1, const float* g2, float* xout, bf16_t* U,
;                            const float* pin, bf16_t* Pb) {
;     ...
;             if (flags & 2) {
;                 float ss = 0.f;
; #pragma unroll
;                 for (int i = 0; i < 4; ++i) ss += x[k][i].x * x[k][i].x + x[k][i].y * x[k][i].y + x[k][i].z * x[k][i].z + x[k][i].w * x[k][i].w;
;                 ss = wave_sum(ss); const float rs2 = rsqrtf(ss * (1.0f / DM) + 1e-6f);
;                 uint2* uo = (uint2*)(U + (size_t)r * DM);
; #pragma unroll
;                 for (int i = 0; i < 4; ++i) { const float4 g = ((const float4*)g2)[lane + 64 * i];
;                     uint2 o; o.x = pack2(x[k][i].x * rs2 * g.x, x[k][i].y * rs2 * g.y); o.y = pack2(x[k][i].z * rs2 * g.z, x[k][i].w * rs2 * g.w); uo[lane + 64 * i] = o; }
	v_add_f32_e32 v24, v24, v25
	ds_bpermute_b32 v25, v97, v24
	s_waitcnt lgkmcnt(0)
	v_add_f32_e32 v24, v24, v25
	ds_bpermute_b32 v25, v98, v24
	s_waitcnt lgkmcnt(0)
	v_add_f32_e32 v24, v24, v25
	ds_bpermute_b32 v25, v99, v24
	s_waitcnt lgkmcnt(0)
	v_add_f32_e32 v24, v24, v25
	ds_bpermute_b32 v25, v100, v24
	s_waitcnt lgkmcnt(0)
	v_add_f32_e32 v25, v24, v25
	ds_bpermute_b32 v28, v101, v25
	v_mov_b32_e32 v24, v2
	s_waitcnt lgkmcnt(0)
	v_add_f32_e32 v25, v25, v28
	v_fmamk_f32 v25, v25, 0x3a800000, v184
	v_mul_f32_e32 v28, 0x4b800000, v25
	v_cmp_gt_f32_e32 vcc, s67, v25
	v_mov_b32_e32 v32, v20
	v_cndmask_b32_e32 v25, v25, v28, vcc
	v_rsq_f32_e32 v30, v25
	v_mov_b32_e32 v25, v4
	v_mov_b32_e32 v28, v3
	v_mov_b32_e32 v33, v22
	v_mul_f32_e32 v31, 0x45800000, v30
	v_cndmask_b32_e32 v30, v30, v31, vcc
	v_pk_mul_f32 v[24:25], v[24:25], v[30:31] op_sel_hi:[1,0]
	v_pk_mul_f32 v[28:29], v[28:29], v[30:31] op_sel_hi:[1,0]
	v_pk_mul_f32 v[24:25], v[32:33], v[24:25]
	v_mov_b32_e32 v22, v21
	v_pk_mul_f32 v[20:21], v[22:23], v[28:29]
	v_and_b32_sdwa v22, v25, v185 dst_sel:DWORD dst_unused:UNUSED_PAD src0_sel:WORD_1 src1_sel:DWORD
	v_and_b32_sdwa v23, v24, v185 dst_sel:DWORD dst_unused:UNUSED_PAD src0_sel:WORD_1 src1_sel:DWORD
	v_add3_u32 v23, v24, v23, s46
	v_add3_u32 v22, v25, v22, s46
	v_and_b32_sdwa v24, v21, v185 dst_sel:DWORD dst_unused:UNUSED_PAD src0_sel:WORD_1 src1_sel:DWORD
	v_and_b32_sdwa v25, v20, v185 dst_sel:DWORD dst_unused:UNUSED_PAD src0_sel:WORD_1 src1_sel:DWORD
	v_add3_u32 v21, v21, v24, s46
	v_add3_u32 v20, v20, v25, s46
	v_and_b32_e32 v21, 0xffff0000, v21
	v_and_b32_e32 v20, 0xffff0000, v20
	v_or_b32_sdwa v21, v21, v22 dst_sel:DWORD dst_unused:UNUSED_PAD src0_sel:DWORD src1_sel:WORD_1
	v_or_b32_sdwa v20, v20, v23 dst_sel:DWORD dst_unused:UNUSED_PAD src0_sel:DWORD src1_sel:WORD_1
	global_store_dwordx2 v[26:27], v[20:21], off
	v_mov_b64_e32 v[20:21], v[140:141]
	v_mov_b64_e32 v[22:23], v[142:143]
	v_mov_b32_e32 v28, v7
	v_mov_b32_e32 v29, v9
	v_mov_b32_e32 v24, v6
	v_mov_b32_e32 v25, v8
	v_pk_mul_f32 v[28:29], v[28:29], v[30:31] op_sel_hi:[1,0]
	v_pk_mul_f32 v[24:25], v[24:25], v[30:31] op_sel_hi:[1,0]
	v_mov_b32_e32 v33, v22
	v_mov_b32_e32 v22, v21
	v_mov_b32_e32 v32, v20
	v_pk_mul_f32 v[22:23], v[22:23], v[28:29]
	v_pk_mul_f32 v[20:21], v[32:33], v[24:25]
	v_and_b32_sdwa v28, v23, v185 dst_sel:DWORD dst_unused:UNUSED_PAD src0_sel:WORD_1 src1_sel:DWORD
	v_and_b32_sdwa v29, v22, v185 dst_sel:DWORD dst_unused:UNUSED_PAD src0_sel:WORD_1 src1_sel:DWORD
	v_and_b32_sdwa v24, v21, v185 dst_sel:DWORD dst_unused:UNUSED_PAD src0_sel:WORD_1 src1_sel:DWORD
	v_and_b32_sdwa v25, v20, v185 dst_sel:DWORD dst_unused:UNUSED_PAD src0_sel:WORD_1 src1_sel:DWORD
	v_add3_u32 v23, v23, v28, s46
	v_add3_u32 v22, v22, v29, s46
	v_add3_u32 v20, v20, v25, s46
	v_add3_u32 v21, v21, v24, s46
	v_and_b32_e32 v23, 0xffff0000, v23
	v_and_b32_e32 v22, 0xffff0000, v22
	v_or_b32_sdwa v21, v23, v21 dst_sel:DWORD dst_unused:UNUSED_PAD src0_sel:DWORD src1_sel:WORD_1
	v_or_b32_sdwa v20, v22, v20 dst_sel:DWORD dst_unused:UNUSED_PAD src0_sel:DWORD src1_sel:WORD_1
	global_store_dwordx2 v[26:27], v[20:21], off offset:512
	v_mov_b64_e32 v[20:21], v[144:145]
	v_mov_b64_e32 v[22:23], v[146:147]
	v_mov_b32_e32 v28, v11
	v_mov_b32_e32 v29, v13
	v_mov_b32_e32 v24, v10
	v_mov_b32_e32 v25, v12
	v_pk_mul_f32 v[28:29], v[28:29], v[30:31] op_sel_hi:[1,0]
	v_pk_mul_f32 v[24:25], v[24:25], v[30:31] op_sel_hi:[1,0]
	v_mov_b32_e32 v33, v22
	v_mov_b32_e32 v22, v21
	v_mov_b32_e32 v32, v20
	v_pk_mul_f32 v[22:23], v[28:29], v[22:23]
	v_pk_mul_f32 v[20:21], v[24:25], v[32:33]
	v_and_b32_sdwa v28, v23, v185 dst_sel:DWORD dst_unused:UNUSED_PAD src0_sel:WORD_1 src1_sel:DWORD
	v_and_b32_sdwa v29, v22, v185 dst_sel:DWORD dst_unused:UNUSED_PAD src0_sel:WORD_1 src1_sel:DWORD
	v_and_b32_sdwa v24, v21, v185 dst_sel:DWORD dst_unused:UNUSED_PAD src0_sel:WORD_1 src1_sel:DWORD
	v_and_b32_sdwa v25, v20, v185 dst_sel:DWORD dst_unused:UNUSED_PAD src0_sel:WORD_1 src1_sel:DWORD
	v_add3_u32 v23, v23, v28, s46
	v_add3_u32 v22, v22, v29, s46
	v_add3_u32 v20, v20, v25, s46
	v_add3_u32 v21, v21, v24, s46
	v_and_b32_e32 v23, 0xffff0000, v23
	v_and_b32_e32 v22, 0xffff0000, v22
	v_or_b32_sdwa v21, v23, v21 dst_sel:DWORD dst_unused:UNUSED_PAD src0_sel:DWORD src1_sel:WORD_1
	v_or_b32_sdwa v20, v22, v20 dst_sel:DWORD dst_unused:UNUSED_PAD src0_sel:DWORD src1_sel:WORD_1
	global_store_dwordx2 v[26:27], v[20:21], off offset:1024
	v_mov_b64_e32 v[20:21], v[148:149]
	v_mov_b64_e32 v[22:23], v[150:151]
	v_mov_b32_e32 v24, v14
	v_mov_b32_e32 v25, v16
	v_mov_b32_e32 v28, v15
	v_mov_b32_e32 v29, v17
	v_pk_mul_f32 v[24:25], v[24:25], v[30:31] op_sel_hi:[1,0]
	v_pk_mul_f32 v[28:29], v[28:29], v[30:31] op_sel_hi:[1,0]
	v_mov_b32_e32 v31, v22
	v_mov_b32_e32 v22, v21
	v_mov_b32_e32 v30, v20
	v_pk_mul_f32 v[22:23], v[28:29], v[22:23]
	v_pk_mul_f32 v[20:21], v[24:25], v[30:31]
	v_and_b32_sdwa v28, v23, v185 dst_sel:DWORD dst_unused:UNUSED_PAD src0_sel:WORD_1 src1_sel:DWORD
	v_and_b32_sdwa v29, v22, v185 dst_sel:DWORD dst_unused:UNUSED_PAD src0_sel:WORD_1 src1_sel:DWORD
	v_and_b32_sdwa v24, v21, v185 dst_sel:DWORD dst_unused:UNUSED_PAD src0_sel:WORD_1 src1_sel:DWORD
	v_and_b32_sdwa v25, v20, v185 dst_sel:DWORD dst_unused:UNUSED_PAD src0_sel:WORD_1 src1_sel:DWORD
	v_add3_u32 v23, v23, v28, s46
	v_add3_u32 v22, v22, v29, s46
	v_add3_u32 v20, v20, v25, s46
	v_add3_u32 v21, v21, v24, s46
	v_and_b32_e32 v23, 0xffff0000, v23
	v_and_b32_e32 v22, 0xffff0000, v22
	v_or_b32_sdwa v21, v23, v21 dst_sel:DWORD dst_unused:UNUSED_PAD src0_sel:DWORD src1_sel:WORD_1
	v_or_b32_sdwa v20, v22, v20 dst_sel:DWORD dst_unused:UNUSED_PAD src0_sel:DWORD src1_sel:WORD_1
	global_store_dwordx2 v[26:27], v[20:21], off offset:1536
	s_branch .LBB0_167

; __device__ __forceinline__ float bflo(unsigned u) { return __uint_as_float(u << 16); }
; __device__ void phase_rows(int flags, const float* xin, bf16_t* XB, const bf16_t* mf, const float* g1, const float* g2, float* xout, bf16_t* U,
;                            const float* pin, bf16_t* Pb) {
;     const int tid = o_tid(), wave = tid >> 6, lane = tid & 63; const int bid = o_bid(), nblk = o_nblk();
;     const int stride = nblk * 8;
;     for (int r0 = bid * 8 + wave; r0 < TCH; r0 += 2 * stride) {
;         float4 x[2][4]; uint2 mq[2][4]; float4 pv[2];
; #pragma unroll
;         for (int k = 0; k < 2; ++k) { const int r = r0 + k * stride; if (r < TCH) {
;             if (flags & 16) { const uint2* xr = (const uint2*)(XB + (size_t)r * DM);
; #pragma unroll
;                 for (int i = 0; i < 4; ++i) { const uint2 q = xr[lane + 64 * i]; x[k][i] = make_float4(bflo(q.x), bfhi(q.x), bflo(q.y), bfhi(q.y)); } }
;             else { const float4* xr = (const float4*)(xin + (size_t)r * DM);
; #pragma unroll
;                 for (int i = 0; i < 4; ++i) x[k][i] = xr[lane + 64 * i]; }
;             if (flags & 1) { const uint2* mr = (const uint2*)(mf + (size_t)r * DM);
; #pragma unroll
;                 for (int i = 0; i < 4; ++i) { const unsigned long long t64 = __builtin_nontemporal_load((const unsigned long long*)(mr + lane + 64 * i)); mq[k][i] = make_uint2((unsigned)t64, (unsigned)(t64 >> 32)); } }
;             if (flags & 8) pv[k] = ((const float4*)(pin + (size_t)r * DPLE))[lane]; } }
; #pragma unroll
;         for (int k = 0; k < 2; ++k) { const int r = r0 + k * stride; if (r < TCH) {
;             if (flags & 1) {
;                 float ss = 0.f; float4 m[4];
; #pragma unroll
;                 for (int i = 0; i < 4; ++i) { m[i] = make_float4(bflo(mq[k][i].x), bfhi(mq[k][i].x), bflo(mq[k][i].y), bfhi(mq[k][i].y)); ss += m[i].x * m[i].x + m[i].y * m[i].y + m[i].z * m[i].z + m[i].w * m[i].w; }
;                 ss = wave_sum(ss); const float rs = rsqrtf(ss * (1.0f / DM) + 1e-6f);
; #pragma unroll
;                 for (int i = 0; i < 4; ++i) { const float4 g = ((const float4*)g1)[lane + 64 * i];
;                     x[k][i].x += m[i].x * rs * g.x; x[k][i].y += m[i].y * rs * g.y; x[k][i].z += m[i].z * rs * g.z; x[k][i].w += m[i].w * rs * g.w; }
;                 if (flags & 32) { float4* xo = (float4*)(xout + (size_t)r * DM);
; #pragma unroll
.LBB0_183:
	s_load_dwordx2 s[22:23], s[82:83], 0x40
	s_andn2_b64 vcc, exec, s[20:21]
	s_mov_b64 s[6:7], -1
	s_cbranch_vccnz .LBB0_192
	v_mov_b32_e32 v0, v180
	s_mov_b32 s7, s49
	s_mov_b32 s6, s64
	s_waitcnt vmcnt(0)
	v_ashrrev_i32_e32 v2, 6, v0
	v_lshl_add_u32 v26, s7, 3, v2
	s_mov_b32 s7, 0x8000
	v_cmp_gt_i32_e32 vcc, s7, v26
	s_and_saveexec_b64 s[20:21], vcc
	s_cbranch_execz .LBB0_191
	v_and_b32_e32 v5, 64, v191
	v_add_u32_e32 v5, 64, v5
	s_waitcnt vmcnt(0)
	v_xor_b32_e32 v6, 32, v191
	v_cmp_lt_i32_e32 vcc, v6, v5
	s_load_dwordx2 s[24:25], s[82:83], 0x20
	s_lshl_b32 s19, s6, 3
	v_cndmask_b32_e32 v6, v191, v6, vcc
	v_lshlrev_b32_e32 v64, 2, v6
	v_xor_b32_e32 v6, 16, v191
	v_cmp_lt_i32_e32 vcc, v6, v5
	v_and_b32_e32 v4, 63, v0
	s_waitcnt lgkmcnt(0)
	s_add_u32 s6, s24, 0x1000
	v_cndmask_b32_e32 v6, v191, v6, vcc
	v_lshlrev_b32_e32 v65, 2, v6
	v_xor_b32_e32 v6, 8, v191
	v_cmp_lt_i32_e32 vcc, v6, v5
	s_addc_u32 s7, s25, 0
	v_lshlrev_b32_e32 v12, 4, v4
	v_cndmask_b32_e32 v6, v191, v6, vcc
	v_lshlrev_b32_e32 v66, 2, v6
	v_xor_b32_e32 v6, 4, v191
	v_cmp_lt_i32_e32 vcc, v6, v5
	v_mov_b32_e32 v13, v1
	v_lshlrev_b32_e32 v0, 3, v4
	v_cndmask_b32_e32 v6, v191, v6, vcc
	v_lshlrev_b32_e32 v67, 2, v6
	v_xor_b32_e32 v6, 2, v191
	v_cmp_lt_i32_e32 vcc, v6, v5
	v_or_b32_e32 v8, 0x400, v12
	v_mov_b32_e32 v9, v1
	v_cndmask_b32_e32 v6, v191, v6, vcc
	v_lshlrev_b32_e32 v68, 2, v6
	v_xor_b32_e32 v6, 1, v191
	v_cmp_lt_i32_e32 vcc, v6, v5
	v_or_b32_e32 v10, 0x800, v12
	v_mov_b32_e32 v11, v1
	v_cndmask_b32_e32 v5, v191, v6, vcc
	v_lshlrev_b32_e32 v69, 2, v5
	v_lshl_add_u64 v[4:5], s[22:23], 0, v[12:13]
	v_lshl_add_u64 v[6:7], s[6:7], 0, v[12:13]
	v_or_b32_e32 v12, 0xc00, v12
	v_lshl_add_u64 v[2:3], s[14:15], 0, v[0:1]
	v_lshl_add_u64 v[8:9], s[6:7], 0, v[8:9]
	v_lshl_add_u64 v[10:11], s[6:7], 0, v[10:11]
	v_lshl_add_u64 v[12:13], s[6:7], 0, v[12:13]
	v_lshl_add_u64 v[14:15], s[10:11], 0, v[0:1]
	v_lshl_add_u64 v[16:17], s[8:9], 0, v[0:1]
	s_mov_b64 s[24:25], 0
	global_load_dwordx4 v[136:139], v[6:7], off
	global_load_dwordx4 v[140:143], v[8:9], off
	global_load_dwordx4 v[144:147], v[10:11], off
	global_load_dwordx4 v[148:151], v[12:13], off
	s_branch .LBB0_187

; __device__ __forceinline__ unsigned pack2(float lo, float hi) { return (unsigned)f2bf(lo) | ((unsigned)f2bf(hi) << 16); }
; __device__ __forceinline__ float bflo(unsigned u) { return __uint_as_float(u << 16); }
; __device__ __forceinline__ float bfhi(unsigned u) { return __uint_as_float(u & 0xffff0000u); }
; __device__ void phase_rows(int flags, const float* xin, bf16_t* XB, const bf16_t* mf, const float* g1, const float* g2, float* xout, bf16_t* U,
;                            const float* pin, bf16_t* Pb) {
;     ...
;         for (int k = 0; k < 2; ++k) { const int r = r0 + k * stride; if (r < TCH) {
;             if (flags & 1) {
;                 float ss = 0.f; float4 m[4];
; #pragma unroll
;                 for (int i = 0; i < 4; ++i) { m[i] = make_float4(bflo(mq[k][i].x), bfhi(mq[k][i].x), bflo(mq[k][i].y), bfhi(mq[k][i].y)); ss += m[i].x * m[i].x + m[i].y * m[i].y + m[i].z * m[i].z + m[i].w * m[i].w; }
;                 ss = wave_sum(ss); const float rs = rsqrtf(ss * (1.0f / DM) + 1e-6f);
; #pragma unroll
;                 for (int i = 0; i < 4; ++i) { const float4 g = ((const float4*)g1)[lane + 64 * i];
;                     x[k][i].x += m[i].x * rs * g.x; x[k][i].y += m[i].y * rs * g.y; x[k][i].z += m[i].z * rs * g.z; x[k][i].w += m[i].w * rs * g.w; }
;                 if (flags & 32) { float4* xo = (float4*)(xout + (size_t)r * DM);
; #pragma unroll
;                     for (int i = 0; i < 4; ++i) __builtin_nontemporal_store((f32x4){x[k][i].x, x[k][i].y, x[k][i].z, x[k][i].w}, (f32x4*)(xo + lane + 64 * i)); }
;                 else { uint2* xo = (uint2*)(XB + (size_t)r * DM);
; #pragma unroll
;                     for (int i = 0; i < 4; ++i) { uint2 o; o.x = pack2(x[k][i].x, x[k][i].y); o.y = pack2(x[k][i].z, x[k][i].w); xo[lane + 64 * i] = o; } }
.LBB0_189:
	s_or_b64 exec, exec, s[6:7]
	global_load_dwordx4 v[70:73], v[4:5], off
	global_load_dwordx4 v[74:77], v[4:5], off offset:1024
	s_waitcnt vmcnt(4)
	v_lshlrev_b32_e32 v84, 16, v60
	v_and_b32_e32 v86, 0xffff0000, v60
	v_lshlrev_b32_e32 v85, 16, v61
	v_and_b32_e32 v87, 0xffff0000, v61
	s_waitcnt vmcnt(3)
	v_lshlrev_b32_e32 v88, 16, v58
	v_and_b32_e32 v90, 0xffff0000, v58
	v_lshlrev_b32_e32 v89, 16, v59
	v_and_b32_e32 v91, 0xffff0000, v59
	global_load_dwordx4 v[58:61], v[4:5], off offset:2048
	v_lshlrev_b32_e32 v82, 16, v62
	v_and_b32_e32 v62, 0xffff0000, v62
	v_mov_b32_e32 v80, v62
	v_mov_b32_e32 v81, v86
	v_lshlrev_b32_e32 v83, 16, v63
	v_mov_b32_e32 v78, v82
	v_mov_b32_e32 v79, v84
	v_pk_mul_f32 v[80:81], v[80:81], v[80:81]
	v_and_b32_e32 v63, 0xffff0000, v63
	v_pk_fma_f32 v[78:79], v[78:79], v[78:79], v[80:81]
	v_mov_b32_e32 v80, v83
	v_mov_b32_e32 v81, v85
	v_pk_fma_f32 v[78:79], v[80:81], v[80:81], v[78:79]
	v_mov_b32_e32 v80, v63
	v_mov_b32_e32 v81, v87
	v_pk_fma_f32 v[94:95], v[80:81], v[80:81], v[78:79]
	global_load_dwordx4 v[78:81], v[4:5], off offset:3072
	s_waitcnt vmcnt(4)
	v_lshlrev_b32_e32 v92, 16, v56
	v_and_b32_e32 v56, 0xffff0000, v56
	v_mov_b32_e32 v98, v90
	v_mov_b32_e32 v99, v56
	v_lshlrev_b32_e32 v93, 16, v57
	v_mov_b32_e32 v96, v88
	v_mov_b32_e32 v97, v92
	v_pk_mul_f32 v[98:99], v[98:99], v[98:99]
	v_and_b32_e32 v57, 0xffff0000, v57
	v_pk_fma_f32 v[96:97], v[96:97], v[96:97], v[98:99]
	v_mov_b32_e32 v98, v89
	v_mov_b32_e32 v99, v93
	v_pk_fma_f32 v[96:97], v[98:99], v[98:99], v[96:97]
	v_mov_b32_e32 v98, v91
	v_mov_b32_e32 v99, v57
	v_pk_fma_f32 v[96:97], v[98:99], v[98:99], v[96:97]
	v_add_f32_e32 v0, v94, v95
	v_add_f32_e32 v0, v0, v96
	v_add_f32_e32 v0, v0, v97
	ds_bpermute_b32 v94, v64, v0
	v_and_b32_e32 v102, 0xffff0000, v48
	v_lshlrev_b32_e32 v95, 16, v55
	v_lshlrev_b32_e32 v101, 16, v49
	v_and_b32_e32 v103, 0xffff0000, v49
	s_waitcnt lgkmcnt(0)
	v_add_f32_e32 v0, v0, v94
	ds_bpermute_b32 v94, v65, v0
	v_and_b32_e32 v55, 0xffff0000, v55
	v_lshlrev_b32_e32 v97, 16, v53
	v_and_b32_e32 v53, 0xffff0000, v53
	v_lshlrev_b32_e32 v99, 16, v51
	s_waitcnt lgkmcnt(0)
	v_add_f32_e32 v0, v0, v94
	ds_bpermute_b32 v96, v66, v0
	v_lshlrev_b32_e32 v94, 16, v54
	v_and_b32_e32 v54, 0xffff0000, v54
	v_and_b32_e32 v51, 0xffff0000, v51
	s_waitcnt lgkmcnt(0)
	v_add_f32_e32 v0, v0, v96
	ds_bpermute_b32 v98, v67, v0
	v_lshlrev_b32_e32 v96, 16, v52
	v_and_b32_e32 v52, 0xffff0000, v52
	s_waitcnt lgkmcnt(0)
	v_add_f32_e32 v0, v0, v98
	ds_bpermute_b32 v100, v68, v0
	v_lshlrev_b32_e32 v98, 16, v50
	v_and_b32_e32 v50, 0xffff0000, v50
	s_waitcnt lgkmcnt(0)
	v_add_f32_e32 v0, v0, v100
	ds_bpermute_b32 v104, v69, v0
	v_lshlrev_b32_e32 v100, 16, v48
	s_waitcnt vmcnt(3)
	v_mov_b32_e32 v48, v70
	s_waitcnt vmcnt(2)
	v_mov_b32_e32 v70, v74
	s_waitcnt lgkmcnt(0)
	v_add_f32_e32 v0, v0, v104
	v_fmamk_f32 v0, v0, 0x3a800000, v184
	v_mul_f32_e32 v74, 0x4b800000, v0
	v_cmp_gt_f32_e64 s[6:7], s67, v0
	v_mov_b32_e32 v49, v72
	v_mov_b32_e32 v72, v71
	v_cndmask_b32_e64 v0, v0, v74, s[6:7]
	v_rsq_f32_e32 v0, v0
	s_waitcnt vmcnt(1)
	v_mov_b32_e32 v74, v58
	v_mov_b32_e32 v71, v76
	v_mov_b32_e32 v76, v75
	v_mul_f32_e32 v58, 0x45800000, v0
	v_cndmask_b32_e64 v0, v0, v58, s[6:7]
	v_mov_b32_e32 v75, v60
	v_mov_b32_e32 v60, v59
	v_pk_mul_f32 v[58:59], v[0:1], v[82:83] op_sel_hi:[0,1]
	v_pk_fma_f32 v[58:59], v[48:49], v[58:59], v[94:95]
	v_pk_mul_f32 v[48:49], v[0:1], v[62:63] op_sel_hi:[0,1]
	v_pk_fma_f32 v[62:63], v[72:73], v[48:49], v[54:55]
	v_pk_mul_f32 v[48:49], v[0:1], v[84:85] op_sel_hi:[0,1]
	v_pk_fma_f32 v[70:71], v[70:71], v[48:49], v[96:97]
	v_pk_mul_f32 v[48:49], v[0:1], v[86:87] op_sel_hi:[0,1]
	v_pk_fma_f32 v[72:73], v[76:77], v[48:49], v[52:53]
	v_pk_mul_f32 v[48:49], v[0:1], v[88:89] op_sel_hi:[0,1]
	v_pk_fma_f32 v[74:75], v[74:75], v[48:49], v[98:99]
	v_pk_mul_f32 v[48:49], v[0:1], v[90:91] op_sel_hi:[0,1]
	v_pk_fma_f32 v[60:61], v[60:61], v[48:49], v[50:51]
	v_pk_mul_f32 v[48:49], v[0:1], v[92:93] op_sel_hi:[0,1]
	s_waitcnt vmcnt(0)
	v_mov_b32_e32 v50, v78
	v_mov_b32_e32 v51, v80
	v_and_b32_sdwa v53, v63, v185 dst_sel:DWORD dst_unused:UNUSED_PAD src0_sel:WORD_1 src1_sel:DWORD
	v_and_b32_sdwa v54, v62, v185 dst_sel:DWORD dst_unused:UNUSED_PAD src0_sel:WORD_1 src1_sel:DWORD
	v_pk_fma_f32 v[48:49], v[48:49], v[50:51], v[100:101]
	v_pk_mul_f32 v[50:51], v[0:1], v[56:57] op_sel_hi:[0,1]
	v_and_b32_sdwa v0, v59, v185 dst_sel:DWORD dst_unused:UNUSED_PAD src0_sel:WORD_1 src1_sel:DWORD
	v_and_b32_sdwa v52, v58, v185 dst_sel:DWORD dst_unused:UNUSED_PAD src0_sel:WORD_1 src1_sel:DWORD
	v_add3_u32 v53, v63, v53, s46
	v_add3_u32 v54, v62, v54, s46
	v_add3_u32 v52, v58, v52, s46
	v_add3_u32 v0, v59, v0, s46
	v_and_b32_e32 v53, 0xffff0000, v53
	v_and_b32_e32 v54, 0xffff0000, v54
	v_or_b32_sdwa v53, v53, v0 dst_sel:DWORD dst_unused:UNUSED_PAD src0_sel:DWORD src1_sel:WORD_1
	v_or_b32_sdwa v52, v54, v52 dst_sel:DWORD dst_unused:UNUSED_PAD src0_sel:DWORD src1_sel:WORD_1
	global_store_dwordx2 v[46:47], v[52:53], off
	v_and_b32_sdwa v53, v73, v185 dst_sel:DWORD dst_unused:UNUSED_PAD src0_sel:WORD_1 src1_sel:DWORD
	v_and_b32_sdwa v54, v72, v185 dst_sel:DWORD dst_unused:UNUSED_PAD src0_sel:WORD_1 src1_sel:DWORD
	v_and_b32_sdwa v0, v71, v185 dst_sel:DWORD dst_unused:UNUSED_PAD src0_sel:WORD_1 src1_sel:DWORD
	v_and_b32_sdwa v52, v70, v185 dst_sel:DWORD dst_unused:UNUSED_PAD src0_sel:WORD_1 src1_sel:DWORD
	v_add3_u32 v53, v73, v53, s46
	v_add3_u32 v54, v72, v54, s46
	v_add3_u32 v52, v70, v52, s46
	v_add3_u32 v0, v71, v0, s46
	v_and_b32_e32 v53, 0xffff0000, v53
	v_and_b32_e32 v54, 0xffff0000, v54
	v_or_b32_sdwa v53, v53, v0 dst_sel:DWORD dst_unused:UNUSED_PAD src0_sel:DWORD src1_sel:WORD_1
; __device__ __forceinline__ unsigned pack2(float lo, float hi) { return (unsigned)f2bf(lo) | ((unsigned)f2bf(hi) << 16); }
; __device__ void phase_rows(int flags, const float* xin, bf16_t* XB, const bf16_t* mf, const float* g1, const float* g2, float* xout, bf16_t* U,
;                            const float* pin, bf16_t* Pb) {
;     ...
;                 else { uint2* xo = (uint2*)(XB + (size_t)r * DM);
; #pragma unroll
;                     for (int i = 0; i < 4; ++i) { uint2 o; o.x = pack2(x[k][i].x, x[k][i].y); o.y = pack2(x[k][i].z, x[k][i].w); xo[lane + 64 * i] = o; } }
;             }
;             if (flags & 8) { uint2 o; o.x = pack2(pv[k].x, pv[k].y); o.y = pack2(pv[k].z, pv[k].w); ((uint2*)(Pb + (size_t)r * DPLE))[lane] = o; }
;             if (flags & 2) {
;                 float ss = 0.f;
; #pragma unroll
;                 for (int i = 0; i < 4; ++i) ss += x[k][i].x * x[k][i].x + x[k][i].y * x[k][i].y + x[k][i].z * x[k][i].z + x[k][i].w * x[k][i].w;
;                 ss = wave_sum(ss); const float rs2 = rsqrtf(ss * (1.0f / DM) + 1e-6f);
;                 uint2* uo = (uint2*)(U + (size_t)r * DM);
; #pragma unroll
;                 for (int i = 0; i < 4; ++i) { const float4 g = ((const float4*)g2)[lane + 64 * i];
;                     uint2 o; o.x = pack2(x[k][i].x * rs2 * g.x, x[k][i].y * rs2 * g.y); o.y = pack2(x[k][i].z * rs2 * g.z, x[k][i].w * rs2 * g.w); uo[lane + 64 * i] = o; }
	v_or_b32_sdwa v52, v54, v52 dst_sel:DWORD dst_unused:UNUSED_PAD src0_sel:DWORD src1_sel:WORD_1
	global_store_dwordx2 v[46:47], v[52:53], off offset:512
	v_and_b32_sdwa v53, v61, v185 dst_sel:DWORD dst_unused:UNUSED_PAD src0_sel:WORD_1 src1_sel:DWORD
	v_and_b32_sdwa v54, v60, v185 dst_sel:DWORD dst_unused:UNUSED_PAD src0_sel:WORD_1 src1_sel:DWORD
	v_and_b32_sdwa v0, v75, v185 dst_sel:DWORD dst_unused:UNUSED_PAD src0_sel:WORD_1 src1_sel:DWORD
	v_and_b32_sdwa v52, v74, v185 dst_sel:DWORD dst_unused:UNUSED_PAD src0_sel:WORD_1 src1_sel:DWORD
	v_add3_u32 v53, v61, v53, s46
	v_add3_u32 v54, v60, v54, s46
	v_mov_b32_e32 v80, v79
	v_add3_u32 v52, v74, v52, s46
	v_add3_u32 v0, v75, v0, s46
	v_and_b32_e32 v53, 0xffff0000, v53
	v_and_b32_e32 v54, 0xffff0000, v54
	v_pk_fma_f32 v[50:51], v[50:51], v[80:81], v[102:103]
	v_or_b32_sdwa v53, v53, v0 dst_sel:DWORD dst_unused:UNUSED_PAD src0_sel:DWORD src1_sel:WORD_1
	v_or_b32_sdwa v52, v54, v52 dst_sel:DWORD dst_unused:UNUSED_PAD src0_sel:DWORD src1_sel:WORD_1
	global_store_dwordx2 v[46:47], v[52:53], off offset:1024
	v_and_b32_sdwa v53, v51, v185 dst_sel:DWORD dst_unused:UNUSED_PAD src0_sel:WORD_1 src1_sel:DWORD
	v_and_b32_sdwa v54, v50, v185 dst_sel:DWORD dst_unused:UNUSED_PAD src0_sel:WORD_1 src1_sel:DWORD
	v_and_b32_sdwa v0, v49, v185 dst_sel:DWORD dst_unused:UNUSED_PAD src0_sel:WORD_1 src1_sel:DWORD
	v_and_b32_sdwa v52, v48, v185 dst_sel:DWORD dst_unused:UNUSED_PAD src0_sel:WORD_1 src1_sel:DWORD
	v_add3_u32 v53, v51, v53, s46
	v_add3_u32 v54, v50, v54, s46
	v_add3_u32 v52, v48, v52, s46
	v_add3_u32 v0, v49, v0, s46
	v_and_b32_e32 v53, 0xffff0000, v53
	v_and_b32_e32 v54, 0xffff0000, v54
	v_or_b32_sdwa v53, v53, v0 dst_sel:DWORD dst_unused:UNUSED_PAD src0_sel:DWORD src1_sel:WORD_1
	v_or_b32_sdwa v52, v54, v52 dst_sel:DWORD dst_unused:UNUSED_PAD src0_sel:DWORD src1_sel:WORD_1
	global_store_dwordx2 v[46:47], v[52:53], off offset:1536
	v_mov_b64_e32 v[52:53], v[136:137]
	v_mov_b64_e32 v[54:55], v[138:139]
	v_mov_b32_e32 v56, v62
	v_mov_b32_e32 v57, v72
	v_mov_b32_e32 v46, v58
	v_mov_b32_e32 v47, v70
	v_pk_mul_f32 v[56:57], v[56:57], v[56:57]
	v_mov_b32_e32 v76, v60
	v_pk_fma_f32 v[46:47], v[46:47], v[46:47], v[56:57]
	v_mov_b32_e32 v56, v59
	v_mov_b32_e32 v57, v71
	v_pk_fma_f32 v[46:47], v[56:57], v[56:57], v[46:47]
	v_mov_b32_e32 v56, v63
	v_mov_b32_e32 v57, v73
	v_mov_b32_e32 v77, v50
	v_pk_fma_f32 v[46:47], v[56:57], v[56:57], v[46:47]
	v_mov_b32_e32 v56, v74
	v_mov_b32_e32 v57, v48
	v_pk_mul_f32 v[76:77], v[76:77], v[76:77]
	v_add_f32_e32 v0, v46, v47
	v_pk_fma_f32 v[56:57], v[56:57], v[56:57], v[76:77]
	v_mov_b32_e32 v76, v75
	v_mov_b32_e32 v77, v49
	v_pk_fma_f32 v[56:57], v[76:77], v[76:77], v[56:57]
	v_mov_b32_e32 v76, v61
	v_mov_b32_e32 v77, v51
	v_pk_fma_f32 v[56:57], v[76:77], v[76:77], v[56:57]
	v_mov_b32_e32 v47, v54
	v_add_f32_e32 v0, v56, v0
	v_add_f32_e32 v0, v0, v57
	ds_bpermute_b32 v46, v64, v0
	v_lshl_add_u64 v[56:57], v[16:17], 0, v[44:45]
	v_mov_b32_e32 v54, v53
	s_waitcnt lgkmcnt(0)
	v_add_f32_e32 v0, v0, v46
	ds_bpermute_b32 v46, v65, v0
	s_waitcnt lgkmcnt(0)
	v_add_f32_e32 v0, v0, v46
	ds_bpermute_b32 v46, v66, v0
	s_waitcnt lgkmcnt(0)
	v_add_f32_e32 v0, v0, v46
	ds_bpermute_b32 v46, v67, v0
	s_waitcnt lgkmcnt(0)
	v_add_f32_e32 v0, v0, v46
	ds_bpermute_b32 v46, v68, v0
	s_waitcnt lgkmcnt(0)
	v_add_f32_e32 v0, v0, v46
	ds_bpermute_b32 v46, v69, v0
	s_waitcnt lgkmcnt(0)
	v_add_f32_e32 v0, v0, v46
	v_fmamk_f32 v0, v0, 0x3a800000, v184
	v_mul_f32_e32 v46, 0x4b800000, v0
	v_cmp_gt_f32_e64 s[6:7], s67, v0
	s_nop 1
	v_cndmask_b32_e64 v0, v0, v46, s[6:7]
	v_rsq_f32_e32 v0, v0
	v_mov_b32_e32 v46, v52
	v_mul_f32_e32 v44, 0x45800000, v0
	v_cndmask_b32_e64 v0, v0, v44, s[6:7]
	v_pk_mul_f32 v[44:45], v[58:59], v[0:1] op_sel_hi:[1,0]
	v_pk_mul_f32 v[48:49], v[48:49], v[0:1] op_sel_hi:[1,0]
	v_pk_mul_f32 v[44:45], v[46:47], v[44:45]
	v_pk_mul_f32 v[46:47], v[62:63], v[0:1] op_sel_hi:[1,0]
	v_and_b32_sdwa v52, v45, v185 dst_sel:DWORD dst_unused:UNUSED_PAD src0_sel:WORD_1 src1_sel:DWORD
	v_pk_mul_f32 v[46:47], v[54:55], v[46:47]
	v_and_b32_sdwa v53, v44, v185 dst_sel:DWORD dst_unused:UNUSED_PAD src0_sel:WORD_1 src1_sel:DWORD
	v_add3_u32 v44, v44, v53, s46
	v_add3_u32 v45, v45, v52, s46
	v_and_b32_sdwa v52, v47, v185 dst_sel:DWORD dst_unused:UNUSED_PAD src0_sel:WORD_1 src1_sel:DWORD
	v_and_b32_sdwa v53, v46, v185 dst_sel:DWORD dst_unused:UNUSED_PAD src0_sel:WORD_1 src1_sel:DWORD
	v_add3_u32 v47, v47, v52, s46
	v_add3_u32 v46, v46, v53, s46
	v_and_b32_e32 v47, 0xffff0000, v47
	v_and_b32_e32 v46, 0xffff0000, v46
	v_or_b32_sdwa v45, v47, v45 dst_sel:DWORD dst_unused:UNUSED_PAD src0_sel:DWORD src1_sel:WORD_1
	v_or_b32_sdwa v44, v46, v44 dst_sel:DWORD dst_unused:UNUSED_PAD src0_sel:DWORD src1_sel:WORD_1
	global_store_dwordx2 v[56:57], v[44:45], off
	v_mov_b64_e32 v[44:45], v[140:141]
	v_mov_b64_e32 v[46:47], v[142:143]
	v_pk_mul_f32 v[54:55], v[72:73], v[0:1] op_sel_hi:[1,0]
	v_pk_mul_f32 v[52:53], v[70:71], v[0:1] op_sel_hi:[1,0]
	v_pk_mul_f32 v[50:51], v[50:51], v[0:1] op_sel_hi:[1,0]
	v_mov_b32_e32 v59, v46
	v_mov_b32_e32 v46, v45
	v_mov_b32_e32 v58, v44
	v_pk_mul_f32 v[46:47], v[46:47], v[54:55]
	v_pk_mul_f32 v[44:45], v[58:59], v[52:53]
	v_and_b32_sdwa v54, v47, v185 dst_sel:DWORD dst_unused:UNUSED_PAD src0_sel:WORD_1 src1_sel:DWORD
	v_and_b32_sdwa v55, v46, v185 dst_sel:DWORD dst_unused:UNUSED_PAD src0_sel:WORD_1 src1_sel:DWORD
	v_and_b32_sdwa v52, v45, v185 dst_sel:DWORD dst_unused:UNUSED_PAD src0_sel:WORD_1 src1_sel:DWORD
	v_and_b32_sdwa v53, v44, v185 dst_sel:DWORD dst_unused:UNUSED_PAD src0_sel:WORD_1 src1_sel:DWORD
	v_add3_u32 v47, v47, v54, s46
	v_add3_u32 v46, v46, v55, s46
; __device__ __forceinline__ unsigned pack2(float lo, float hi) { return (unsigned)f2bf(lo) | ((unsigned)f2bf(hi) << 16); }
; __device__ __forceinline__ float bflo(unsigned u) { return __uint_as_float(u << 16); }
; __device__ __forceinline__ float bfhi(unsigned u) { return __uint_as_float(u & 0xffff0000u); }
; __device__ void phase_rows(int flags, const float* xin, bf16_t* XB, const bf16_t* mf, const float* g1, const float* g2, float* xout, bf16_t* U,
;                            const float* pin, bf16_t* Pb) {
;     ...
;         for (int k = 0; k < 2; ++k) { const int r = r0 + k * stride; if (r < TCH) {
;             if (flags & 1) {
;                 float ss = 0.f; float4 m[4];
; #pragma unroll
;                 for (int i = 0; i < 4; ++i) { m[i] = make_float4(bflo(mq[k][i].x), bfhi(mq[k][i].x), bflo(mq[k][i].y), bfhi(mq[k][i].y)); ss += m[i].x * m[i].x + m[i].y * m[i].y + m[i].z * m[i].z + m[i].w * m[i].w; }
;                 ss = wave_sum(ss); const float rs = rsqrtf(ss * (1.0f / DM) + 1e-6f);
; #pragma unroll
;                 for (int i = 0; i < 4; ++i) { const float4 g = ((const float4*)g1)[lane + 64 * i];
;                     x[k][i].x += m[i].x * rs * g.x; x[k][i].y += m[i].y * rs * g.y; x[k][i].z += m[i].z * rs * g.z; x[k][i].w += m[i].w * rs * g.w; }
;     ...
;             if (flags & 2) {
;                 float ss = 0.f;
; #pragma unroll
;                 for (int i = 0; i < 4; ++i) ss += x[k][i].x * x[k][i].x + x[k][i].y * x[k][i].y + x[k][i].z * x[k][i].z + x[k][i].w * x[k][i].w;
;                 ss = wave_sum(ss); const float rs2 = rsqrtf(ss * (1.0f / DM) + 1e-6f);
;                 uint2* uo = (uint2*)(U + (size_t)r * DM);
; #pragma unroll
;                 for (int i = 0; i < 4; ++i) { const float4 g = ((const float4*)g2)[lane + 64 * i];
;                     uint2 o; o.x = pack2(x[k][i].x * rs2 * g.x, x[k][i].y * rs2 * g.y); o.y = pack2(x[k][i].z * rs2 * g.z, x[k][i].w * rs2 * g.w); uo[lane + 64 * i] = o; }
	v_add3_u32 v44, v44, v53, s46
	v_add3_u32 v45, v45, v52, s46
	v_and_b32_e32 v47, 0xffff0000, v47
	v_and_b32_e32 v46, 0xffff0000, v46
	v_or_b32_sdwa v45, v47, v45 dst_sel:DWORD dst_unused:UNUSED_PAD src0_sel:DWORD src1_sel:WORD_1
	v_or_b32_sdwa v44, v46, v44 dst_sel:DWORD dst_unused:UNUSED_PAD src0_sel:DWORD src1_sel:WORD_1
	global_store_dwordx2 v[56:57], v[44:45], off offset:512
	v_mov_b64_e32 v[44:45], v[144:145]
	v_mov_b64_e32 v[46:47], v[146:147]
	v_pk_mul_f32 v[54:55], v[60:61], v[0:1] op_sel_hi:[1,0]
	v_pk_mul_f32 v[52:53], v[74:75], v[0:1] op_sel_hi:[1,0]
	v_mov_b32_e32 v59, v46
	v_mov_b32_e32 v46, v45
	v_mov_b32_e32 v58, v44
	v_pk_mul_f32 v[46:47], v[54:55], v[46:47]
	v_pk_mul_f32 v[44:45], v[52:53], v[58:59]
	v_and_b32_sdwa v54, v47, v185 dst_sel:DWORD dst_unused:UNUSED_PAD src0_sel:WORD_1 src1_sel:DWORD
	v_and_b32_sdwa v55, v46, v185 dst_sel:DWORD dst_unused:UNUSED_PAD src0_sel:WORD_1 src1_sel:DWORD
	v_and_b32_sdwa v52, v45, v185 dst_sel:DWORD dst_unused:UNUSED_PAD src0_sel:WORD_1 src1_sel:DWORD
	v_and_b32_sdwa v53, v44, v185 dst_sel:DWORD dst_unused:UNUSED_PAD src0_sel:WORD_1 src1_sel:DWORD
	v_add3_u32 v47, v47, v54, s46
	v_add3_u32 v46, v46, v55, s46
	v_add3_u32 v44, v44, v53, s46
	v_add3_u32 v45, v45, v52, s46
	v_and_b32_e32 v47, 0xffff0000, v47
	v_and_b32_e32 v46, 0xffff0000, v46
	v_or_b32_sdwa v45, v47, v45 dst_sel:DWORD dst_unused:UNUSED_PAD src0_sel:DWORD src1_sel:WORD_1
	v_or_b32_sdwa v44, v46, v44 dst_sel:DWORD dst_unused:UNUSED_PAD src0_sel:DWORD src1_sel:WORD_1
	global_store_dwordx2 v[56:57], v[44:45], off offset:1024
	v_mov_b64_e32 v[44:45], v[148:149]
	v_mov_b64_e32 v[46:47], v[150:151]
	v_mov_b32_e32 v52, v44
	v_mov_b32_e32 v53, v46
	v_mov_b32_e32 v46, v45
	v_pk_mul_f32 v[44:45], v[48:49], v[52:53]
	v_pk_mul_f32 v[46:47], v[50:51], v[46:47]
	v_and_b32_sdwa v0, v45, v185 dst_sel:DWORD dst_unused:UNUSED_PAD src0_sel:WORD_1 src1_sel:DWORD
	v_and_b32_sdwa v49, v47, v185 dst_sel:DWORD dst_unused:UNUSED_PAD src0_sel:WORD_1 src1_sel:DWORD
	v_and_b32_sdwa v50, v46, v185 dst_sel:DWORD dst_unused:UNUSED_PAD src0_sel:WORD_1 src1_sel:DWORD
	v_and_b32_sdwa v48, v44, v185 dst_sel:DWORD dst_unused:UNUSED_PAD src0_sel:WORD_1 src1_sel:DWORD
	v_add3_u32 v0, v45, v0, s46
	v_add3_u32 v45, v47, v49, s46
	v_add3_u32 v46, v46, v50, s46
	v_add3_u32 v44, v44, v48, s46
	v_and_b32_e32 v45, 0xffff0000, v45
	v_and_b32_e32 v46, 0xffff0000, v46
	v_or_b32_sdwa v45, v45, v0 dst_sel:DWORD dst_unused:UNUSED_PAD src0_sel:DWORD src1_sel:WORD_1
	v_or_b32_sdwa v44, v46, v44 dst_sel:DWORD dst_unused:UNUSED_PAD src0_sel:DWORD src1_sel:WORD_1
	global_store_dwordx2 v[56:57], v[44:45], off offset:1536
	s_and_saveexec_b64 s[6:7], vcc
	s_cbranch_execz .LBB0_186
	global_load_dwordx4 v[44:47], v[4:5], off offset:3072
	global_load_dwordx4 v[48:51], v[4:5], off offset:2048
	global_load_dwordx4 v[52:55], v[4:5], off offset:1024
	global_load_dwordx4 v[56:59], v[4:5], off
	v_and_b32_e32 v75, 0xffff0000, v20
	v_and_b32_e32 v79, 0xffff0000, v18
	v_lshlrev_b32_e32 v74, 16, v20
	v_lshlrev_b32_e32 v78, 16, v18
	v_mov_b32_e32 v88, v79
	v_mov_b32_e32 v89, v75
	v_and_b32_e32 v61, 0xffff0000, v24
	v_and_b32_e32 v71, 0xffff0000, v22
	v_lshlrev_b32_e32 v76, 16, v21
	v_lshlrev_b32_e32 v80, 16, v19
	v_mov_b32_e32 v86, v78
	v_mov_b32_e32 v87, v74
	v_pk_mul_f32 v[88:89], v[88:89], v[88:89]
	v_lshlrev_b32_e32 v60, 16, v24
	v_lshlrev_b32_e32 v70, 16, v22
	v_and_b32_e32 v77, 0xffff0000, v21
	v_and_b32_e32 v81, 0xffff0000, v19
	v_mov_b32_e32 v82, v80
	v_mov_b32_e32 v83, v76
	v_pk_fma_f32 v[86:87], v[86:87], v[86:87], v[88:89]
	v_mov_b32_e32 v90, v71
	v_mov_b32_e32 v91, v61
	v_lshlrev_b32_e32 v62, 16, v25
	v_lshlrev_b32_e32 v72, 16, v23
	v_mov_b32_e32 v84, v81
	v_mov_b32_e32 v85, v77
	v_pk_fma_f32 v[82:83], v[82:83], v[82:83], v[86:87]
	v_mov_b32_e32 v88, v70
	v_mov_b32_e32 v89, v60
	v_pk_mul_f32 v[90:91], v[90:91], v[90:91]
	v_and_b32_e32 v63, 0xffff0000, v25
	v_and_b32_e32 v73, 0xffff0000, v23
	v_pk_fma_f32 v[82:83], v[84:85], v[84:85], v[82:83]
	v_mov_b32_e32 v84, v72
	v_mov_b32_e32 v85, v62
	v_pk_fma_f32 v[88:89], v[88:89], v[88:89], v[90:91]
	v_mov_b32_e32 v86, v73
	v_mov_b32_e32 v87, v63
	v_pk_fma_f32 v[84:85], v[84:85], v[84:85], v[88:89]
	s_nop 0
	v_pk_fma_f32 v[84:85], v[86:87], v[86:87], v[84:85]
	s_nop 0
	v_add_f32_e32 v0, v84, v85
	v_add_f32_e32 v0, v83, v0
	v_add_f32_e32 v0, v82, v0
	ds_bpermute_b32 v82, v64, v0
	s_waitcnt lgkmcnt(0)
	v_add_f32_e32 v0, v0, v82
	ds_bpermute_b32 v82, v65, v0
	s_waitcnt lgkmcnt(0)
	v_add_f32_e32 v0, v0, v82
	ds_bpermute_b32 v82, v66, v0
	s_waitcnt lgkmcnt(0)
	v_add_f32_e32 v0, v0, v82
	ds_bpermute_b32 v82, v67, v0
	s_waitcnt lgkmcnt(0)
	v_add_f32_e32 v0, v0, v82
	ds_bpermute_b32 v82, v68, v0
	s_waitcnt lgkmcnt(0)
	v_add_f32_e32 v0, v0, v82
	ds_bpermute_b32 v82, v69, v0
	s_waitcnt lgkmcnt(0)
	v_add_f32_e32 v0, v0, v82
	v_fmamk_f32 v0, v0, 0x3a800000, v184
	v_mul_f32_e32 v82, 0x4b800000, v0
	v_cmp_gt_f32_e32 vcc, s67, v0
	s_nop 1
	v_cndmask_b32_e32 v0, v0, v82, vcc
	v_rsq_f32_e32 v0, v0
	s_nop 0
	v_mul_f32_e32 v82, 0x45800000, v0
	v_cndmask_b32_e32 v0, v0, v82, vcc
	v_pk_mul_f32 v[60:61], v[0:1], v[60:61] op_sel_hi:[0,1]
	v_pk_mul_f32 v[62:63], v[0:1], v[62:63] op_sel_hi:[0,1]
	v_pk_mul_f32 v[80:81], v[0:1], v[80:81] op_sel_hi:[0,1]
	s_waitcnt vmcnt(0)
; __device__ __forceinline__ unsigned pack2(float lo, float hi) { return (unsigned)f2bf(lo) | ((unsigned)f2bf(hi) << 16); }
; __device__ void phase_rows(int flags, const float* xin, bf16_t* XB, const bf16_t* mf, const float* g1, const float* g2, float* xout, bf16_t* U,
;                            const float* pin, bf16_t* Pb) {
;     ...
;                     x[k][i].x += m[i].x * rs * g.x; x[k][i].y += m[i].y * rs * g.y; x[k][i].z += m[i].z * rs * g.z; x[k][i].w += m[i].w * rs * g.w; }
;                 if (flags & 32) { float4* xo = (float4*)(xout + (size_t)r * DM);
; #pragma unroll
;                     for (int i = 0; i < 4; ++i) __builtin_nontemporal_store((f32x4){x[k][i].x, x[k][i].y, x[k][i].z, x[k][i].w}, (f32x4*)(xo + lane + 64 * i)); }
;                 else { uint2* xo = (uint2*)(XB + (size_t)r * DM);
; #pragma unroll
;                     for (int i = 0; i < 4; ++i) { uint2 o; o.x = pack2(x[k][i].x, x[k][i].y); o.y = pack2(x[k][i].z, x[k][i].w); xo[lane + 64 * i] = o; } }
;             }
;             if (flags & 8) { uint2 o; o.x = pack2(pv[k].x, pv[k].y); o.y = pack2(pv[k].z, pv[k].w); ((uint2*)(Pb + (size_t)r * DPLE))[lane] = o; }
;             if (flags & 2) {
;                 float ss = 0.f;
; #pragma unroll
;                 for (int i = 0; i < 4; ++i) ss += x[k][i].x * x[k][i].x + x[k][i].y * x[k][i].y + x[k][i].z * x[k][i].z + x[k][i].w * x[k][i].w;
;                 ss = wave_sum(ss); const float rs2 = rsqrtf(ss * (1.0f / DM) + 1e-6f);
;                 uint2* uo = (uint2*)(U + (size_t)r * DM);
; #pragma unroll
;                 for (int i = 0; i < 4; ++i) { const float4 g = ((const float4*)g2)[lane + 64 * i];
;                     uint2 o; o.x = pack2(x[k][i].x * rs2 * g.x, x[k][i].y * rs2 * g.y); o.y = pack2(x[k][i].z * rs2 * g.z, x[k][i].w * rs2 * g.w); uo[lane + 64 * i] = o; }
	v_pk_fma_f32 v[28:29], v[56:57], v[60:61], v[28:29]
	v_pk_fma_f32 v[30:31], v[58:59], v[62:63], v[30:31]
	v_pk_mul_f32 v[74:75], v[0:1], v[74:75] op_sel_hi:[0,1]
	v_pk_fma_f32 v[42:43], v[80:81], v[46:47], v[42:43]
	v_and_b32_sdwa v46, v31, v185 dst_sel:DWORD dst_unused:UNUSED_PAD src0_sel:WORD_1 src1_sel:DWORD
	v_and_b32_sdwa v47, v29, v185 dst_sel:DWORD dst_unused:UNUSED_PAD src0_sel:WORD_1 src1_sel:DWORD
	v_pk_mul_f32 v[70:71], v[0:1], v[70:71] op_sel_hi:[0,1]
	v_pk_mul_f32 v[72:73], v[0:1], v[72:73] op_sel_hi:[0,1]
	v_pk_mul_f32 v[76:77], v[0:1], v[76:77] op_sel_hi:[0,1]
	v_pk_mul_f32 v[78:79], v[0:1], v[78:79] op_sel_hi:[0,1]
	v_pk_fma_f32 v[36:37], v[48:49], v[74:75], v[36:37]
	v_lshlrev_b64 v[48:49], 11, v[26:27]
	v_and_b32_sdwa v0, v30, v185 dst_sel:DWORD dst_unused:UNUSED_PAD src0_sel:WORD_1 src1_sel:DWORD
	v_and_b32_sdwa v27, v28, v185 dst_sel:DWORD dst_unused:UNUSED_PAD src0_sel:WORD_1 src1_sel:DWORD
	v_add3_u32 v46, v31, v46, s46
	v_add3_u32 v47, v29, v47, s46
	v_pk_fma_f32 v[38:39], v[76:77], v[50:51], v[38:39]
	v_add3_u32 v27, v28, v27, s46
	v_add3_u32 v0, v30, v0, s46
	v_and_b32_e32 v46, 0xffff0000, v46
	v_and_b32_e32 v50, 0xffff0000, v47
	v_pk_fma_f32 v[32:33], v[52:53], v[70:71], v[32:33]
	v_pk_fma_f32 v[34:35], v[54:55], v[72:73], v[34:35]
	v_pk_fma_f32 v[40:41], v[78:79], v[44:45], v[40:41]
	v_lshl_add_u64 v[44:45], v[14:15], 0, v[48:49]
	v_or_b32_sdwa v47, v46, v0 dst_sel:DWORD dst_unused:UNUSED_PAD src0_sel:DWORD src1_sel:WORD_1
	v_or_b32_sdwa v46, v50, v27 dst_sel:DWORD dst_unused:UNUSED_PAD src0_sel:DWORD src1_sel:WORD_1
	global_store_dwordx2 v[44:45], v[46:47], off
	v_and_b32_sdwa v46, v35, v185 dst_sel:DWORD dst_unused:UNUSED_PAD src0_sel:WORD_1 src1_sel:DWORD
	v_and_b32_sdwa v47, v33, v185 dst_sel:DWORD dst_unused:UNUSED_PAD src0_sel:WORD_1 src1_sel:DWORD
	v_and_b32_sdwa v0, v34, v185 dst_sel:DWORD dst_unused:UNUSED_PAD src0_sel:WORD_1 src1_sel:DWORD
	v_and_b32_sdwa v27, v32, v185 dst_sel:DWORD dst_unused:UNUSED_PAD src0_sel:WORD_1 src1_sel:DWORD
	v_add3_u32 v46, v35, v46, s46
	v_add3_u32 v47, v33, v47, s46
	v_add3_u32 v27, v32, v27, s46
	v_add3_u32 v0, v34, v0, s46
	v_and_b32_e32 v46, 0xffff0000, v46
	v_and_b32_e32 v50, 0xffff0000, v47
	v_or_b32_sdwa v47, v46, v0 dst_sel:DWORD dst_unused:UNUSED_PAD src0_sel:DWORD src1_sel:WORD_1
	v_or_b32_sdwa v46, v50, v27 dst_sel:DWORD dst_unused:UNUSED_PAD src0_sel:DWORD src1_sel:WORD_1
	global_store_dwordx2 v[44:45], v[46:47], off offset:512
	v_and_b32_sdwa v46, v39, v185 dst_sel:DWORD dst_unused:UNUSED_PAD src0_sel:WORD_1 src1_sel:DWORD
	v_and_b32_sdwa v47, v37, v185 dst_sel:DWORD dst_unused:UNUSED_PAD src0_sel:WORD_1 src1_sel:DWORD
	v_and_b32_sdwa v0, v38, v185 dst_sel:DWORD dst_unused:UNUSED_PAD src0_sel:WORD_1 src1_sel:DWORD
	v_and_b32_sdwa v27, v36, v185 dst_sel:DWORD dst_unused:UNUSED_PAD src0_sel:WORD_1 src1_sel:DWORD
	v_add3_u32 v46, v39, v46, s46
	v_add3_u32 v47, v37, v47, s46
	v_add3_u32 v27, v36, v27, s46
	v_add3_u32 v0, v38, v0, s46
	v_and_b32_e32 v46, 0xffff0000, v46
	v_and_b32_e32 v50, 0xffff0000, v47
	v_or_b32_sdwa v47, v46, v0 dst_sel:DWORD dst_unused:UNUSED_PAD src0_sel:DWORD src1_sel:WORD_1
	v_or_b32_sdwa v46, v50, v27 dst_sel:DWORD dst_unused:UNUSED_PAD src0_sel:DWORD src1_sel:WORD_1
	global_store_dwordx2 v[44:45], v[46:47], off offset:1024
	v_and_b32_sdwa v46, v43, v185 dst_sel:DWORD dst_unused:UNUSED_PAD src0_sel:WORD_1 src1_sel:DWORD
	v_and_b32_sdwa v47, v41, v185 dst_sel:DWORD dst_unused:UNUSED_PAD src0_sel:WORD_1 src1_sel:DWORD
	v_and_b32_sdwa v0, v42, v185 dst_sel:DWORD dst_unused:UNUSED_PAD src0_sel:WORD_1 src1_sel:DWORD
	v_and_b32_sdwa v27, v40, v185 dst_sel:DWORD dst_unused:UNUSED_PAD src0_sel:WORD_1 src1_sel:DWORD
	v_add3_u32 v46, v43, v46, s46
	v_add3_u32 v47, v41, v47, s46
	v_add3_u32 v27, v40, v27, s46
	v_add3_u32 v0, v42, v0, s46
	v_and_b32_e32 v46, 0xffff0000, v46
	v_and_b32_e32 v50, 0xffff0000, v47
	v_or_b32_sdwa v47, v46, v0 dst_sel:DWORD dst_unused:UNUSED_PAD src0_sel:DWORD src1_sel:WORD_1
	v_or_b32_sdwa v46, v50, v27 dst_sel:DWORD dst_unused:UNUSED_PAD src0_sel:DWORD src1_sel:WORD_1
	global_store_dwordx2 v[44:45], v[46:47], off offset:1536
	v_mov_b64_e32 v[44:45], v[136:137]
	v_mov_b64_e32 v[46:47], v[138:139]
	v_mov_b32_e32 v52, v29
	v_mov_b32_e32 v53, v33
	v_mov_b32_e32 v50, v28
	v_mov_b32_e32 v51, v32
	v_pk_mul_f32 v[52:53], v[52:53], v[52:53]
	v_mov_b32_e32 v54, v37
	v_pk_fma_f32 v[50:51], v[50:51], v[50:51], v[52:53]
	v_mov_b32_e32 v52, v30
	v_mov_b32_e32 v53, v34
	v_pk_fma_f32 v[50:51], v[52:53], v[52:53], v[50:51]
	v_mov_b32_e32 v52, v31
	v_mov_b32_e32 v53, v35
	v_mov_b32_e32 v55, v41
	v_pk_fma_f32 v[50:51], v[52:53], v[52:53], v[50:51]
	v_mov_b32_e32 v52, v36
	v_mov_b32_e32 v53, v40
	v_pk_mul_f32 v[54:55], v[54:55], v[54:55]
	v_add_f32_e32 v0, v50, v51
	v_pk_fma_f32 v[52:53], v[52:53], v[52:53], v[54:55]
	v_mov_b32_e32 v54, v38
	v_mov_b32_e32 v55, v42
	v_pk_fma_f32 v[52:53], v[54:55], v[54:55], v[52:53]
	v_mov_b32_e32 v54, v39
	v_mov_b32_e32 v55, v43
	v_pk_fma_f32 v[52:53], v[54:55], v[54:55], v[52:53]
	v_mov_b32_e32 v50, v28
	v_add_f32_e32 v0, v52, v0
	v_add_f32_e32 v0, v0, v53
	ds_bpermute_b32 v27, v64, v0
	v_mov_b32_e32 v51, v30
	v_mov_b32_e32 v52, v29
	v_mov_b32_e32 v53, v31
	v_lshl_add_u64 v[48:49], v[16:17], 0, v[48:49]
	s_waitcnt lgkmcnt(0)
	v_add_f32_e32 v0, v0, v27
	ds_bpermute_b32 v27, v65, v0
	s_waitcnt lgkmcnt(0)
	v_add_f32_e32 v0, v0, v27
	ds_bpermute_b32 v27, v66, v0
	s_waitcnt lgkmcnt(0)
; __device__ __forceinline__ unsigned pack2(float lo, float hi) { return (unsigned)f2bf(lo) | ((unsigned)f2bf(hi) << 16); }
; __device__ void phase_rows(int flags, const float* xin, bf16_t* XB, const bf16_t* mf, const float* g1, const float* g2, float* xout, bf16_t* U,
;                            const float* pin, bf16_t* Pb) {
;     ...
;                 ss = wave_sum(ss); const float rs2 = rsqrtf(ss * (1.0f / DM) + 1e-6f);
;                 uint2* uo = (uint2*)(U + (size_t)r * DM);
; #pragma unroll
;                 for (int i = 0; i < 4; ++i) { const float4 g = ((const float4*)g2)[lane + 64 * i];
;                     uint2 o; o.x = pack2(x[k][i].x * rs2 * g.x, x[k][i].y * rs2 * g.y); o.y = pack2(x[k][i].z * rs2 * g.z, x[k][i].w * rs2 * g.w); uo[lane + 64 * i] = o; }
	v_add_f32_e32 v0, v0, v27
	ds_bpermute_b32 v27, v67, v0
	s_waitcnt lgkmcnt(0)
	v_add_f32_e32 v0, v0, v27
	ds_bpermute_b32 v27, v68, v0
	s_waitcnt lgkmcnt(0)
	v_add_f32_e32 v0, v0, v27
	ds_bpermute_b32 v27, v69, v0
	s_waitcnt lgkmcnt(0)
	v_add_f32_e32 v0, v0, v27
	v_fmamk_f32 v0, v0, 0x3a800000, v184
	v_mul_f32_e32 v27, 0x4b800000, v0
	v_cmp_gt_f32_e32 vcc, s67, v0
	v_mov_b32_e32 v54, v44
	v_cndmask_b32_e32 v0, v0, v27, vcc
	v_rsq_f32_e32 v0, v0
	v_mov_b32_e32 v55, v46
	v_mov_b32_e32 v46, v45
	v_mul_f32_e32 v27, 0x45800000, v0
	v_cndmask_b32_e32 v0, v0, v27, vcc
	v_pk_mul_f32 v[50:51], v[50:51], v[0:1] op_sel_hi:[1,0]
	v_pk_mul_f32 v[52:53], v[52:53], v[0:1] op_sel_hi:[1,0]
	v_pk_mul_f32 v[50:51], v[54:55], v[50:51]
	v_pk_mul_f32 v[44:45], v[46:47], v[52:53]
	v_and_b32_sdwa v46, v50, v185 dst_sel:DWORD dst_unused:UNUSED_PAD src0_sel:WORD_1 src1_sel:DWORD
	v_add3_u32 v46, v50, v46, s46
	v_and_b32_sdwa v47, v45, v185 dst_sel:DWORD dst_unused:UNUSED_PAD src0_sel:WORD_1 src1_sel:DWORD
	v_and_b32_sdwa v50, v44, v185 dst_sel:DWORD dst_unused:UNUSED_PAD src0_sel:WORD_1 src1_sel:DWORD
	v_and_b32_sdwa v27, v51, v185 dst_sel:DWORD dst_unused:UNUSED_PAD src0_sel:WORD_1 src1_sel:DWORD
	v_add3_u32 v45, v45, v47, s46
	v_add3_u32 v44, v44, v50, s46
	v_add3_u32 v27, v51, v27, s46
	v_and_b32_e32 v45, 0xffff0000, v45
	v_and_b32_e32 v44, 0xffff0000, v44
	v_or_b32_sdwa v45, v45, v27 dst_sel:DWORD dst_unused:UNUSED_PAD src0_sel:DWORD src1_sel:WORD_1
	v_or_b32_sdwa v44, v44, v46 dst_sel:DWORD dst_unused:UNUSED_PAD src0_sel:DWORD src1_sel:WORD_1
	global_store_dwordx2 v[48:49], v[44:45], off
	v_mov_b64_e32 v[44:45], v[140:141]
	v_mov_b64_e32 v[46:47], v[142:143]
	v_mov_b32_e32 v50, v32
	v_mov_b32_e32 v51, v34
	v_mov_b32_e32 v52, v33
	v_mov_b32_e32 v53, v35
	v_pk_mul_f32 v[50:51], v[50:51], v[0:1] op_sel_hi:[1,0]
	v_pk_mul_f32 v[52:53], v[52:53], v[0:1] op_sel_hi:[1,0]
	v_mov_b32_e32 v54, v44
	v_mov_b32_e32 v55, v46
	v_mov_b32_e32 v46, v45
	v_pk_mul_f32 v[44:45], v[54:55], v[50:51]
	v_pk_mul_f32 v[46:47], v[46:47], v[52:53]
	v_and_b32_sdwa v27, v45, v185 dst_sel:DWORD dst_unused:UNUSED_PAD src0_sel:WORD_1 src1_sel:DWORD
	v_and_b32_sdwa v51, v47, v185 dst_sel:DWORD dst_unused:UNUSED_PAD src0_sel:WORD_1 src1_sel:DWORD
	v_and_b32_sdwa v52, v46, v185 dst_sel:DWORD dst_unused:UNUSED_PAD src0_sel:WORD_1 src1_sel:DWORD
	v_and_b32_sdwa v50, v44, v185 dst_sel:DWORD dst_unused:UNUSED_PAD src0_sel:WORD_1 src1_sel:DWORD
	v_add3_u32 v27, v45, v27, s46
	v_add3_u32 v45, v47, v51, s46
	v_add3_u32 v46, v46, v52, s46
	v_add3_u32 v44, v44, v50, s46
	v_and_b32_e32 v45, 0xffff0000, v45
	v_and_b32_e32 v46, 0xffff0000, v46
	v_or_b32_sdwa v45, v45, v27 dst_sel:DWORD dst_unused:UNUSED_PAD src0_sel:DWORD src1_sel:WORD_1
	v_or_b32_sdwa v44, v46, v44 dst_sel:DWORD dst_unused:UNUSED_PAD src0_sel:DWORD src1_sel:WORD_1
	global_store_dwordx2 v[48:49], v[44:45], off offset:512
	v_mov_b64_e32 v[44:45], v[144:145]
	v_mov_b64_e32 v[46:47], v[146:147]
	v_mov_b32_e32 v50, v36
	v_mov_b32_e32 v51, v38
	v_mov_b32_e32 v52, v37
	v_mov_b32_e32 v53, v39
	v_pk_mul_f32 v[50:51], v[50:51], v[0:1] op_sel_hi:[1,0]
	v_pk_mul_f32 v[52:53], v[52:53], v[0:1] op_sel_hi:[1,0]
	v_mov_b32_e32 v54, v44
	v_mov_b32_e32 v55, v46
	v_mov_b32_e32 v46, v45
	v_pk_mul_f32 v[44:45], v[50:51], v[54:55]
	v_pk_mul_f32 v[46:47], v[52:53], v[46:47]
	v_and_b32_sdwa v27, v45, v185 dst_sel:DWORD dst_unused:UNUSED_PAD src0_sel:WORD_1 src1_sel:DWORD
	v_and_b32_sdwa v51, v47, v185 dst_sel:DWORD dst_unused:UNUSED_PAD src0_sel:WORD_1 src1_sel:DWORD
	v_and_b32_sdwa v52, v46, v185 dst_sel:DWORD dst_unused:UNUSED_PAD src0_sel:WORD_1 src1_sel:DWORD
	v_and_b32_sdwa v50, v44, v185 dst_sel:DWORD dst_unused:UNUSED_PAD src0_sel:WORD_1 src1_sel:DWORD
	v_add3_u32 v27, v45, v27, s46
	v_add3_u32 v45, v47, v51, s46
	v_add3_u32 v46, v46, v52, s46
	v_add3_u32 v44, v44, v50, s46
	v_and_b32_e32 v45, 0xffff0000, v45
	v_and_b32_e32 v46, 0xffff0000, v46
	v_or_b32_sdwa v45, v45, v27 dst_sel:DWORD dst_unused:UNUSED_PAD src0_sel:DWORD src1_sel:WORD_1
	v_or_b32_sdwa v44, v46, v44 dst_sel:DWORD dst_unused:UNUSED_PAD src0_sel:DWORD src1_sel:WORD_1
	global_store_dwordx2 v[48:49], v[44:45], off offset:1024
	v_mov_b64_e32 v[44:45], v[148:149]
	v_mov_b64_e32 v[46:47], v[150:151]
	v_mov_b32_e32 v50, v40
	v_mov_b32_e32 v51, v42
	v_mov_b32_e32 v52, v41
	v_mov_b32_e32 v53, v43
	v_pk_mul_f32 v[50:51], v[50:51], v[0:1] op_sel_hi:[1,0]
	v_pk_mul_f32 v[52:53], v[52:53], v[0:1] op_sel_hi:[1,0]
	v_mov_b32_e32 v54, v44
	v_mov_b32_e32 v55, v46
	v_mov_b32_e32 v46, v45
	v_pk_mul_f32 v[44:45], v[50:51], v[54:55]
	v_pk_mul_f32 v[46:47], v[52:53], v[46:47]
	v_and_b32_sdwa v0, v45, v185 dst_sel:DWORD dst_unused:UNUSED_PAD src0_sel:WORD_1 src1_sel:DWORD
	v_and_b32_sdwa v27, v44, v185 dst_sel:DWORD dst_unused:UNUSED_PAD src0_sel:WORD_1 src1_sel:DWORD
	v_and_b32_sdwa v50, v47, v185 dst_sel:DWORD dst_unused:UNUSED_PAD src0_sel:WORD_1 src1_sel:DWORD
	v_and_b32_sdwa v51, v46, v185 dst_sel:DWORD dst_unused:UNUSED_PAD src0_sel:WORD_1 src1_sel:DWORD
	v_add3_u32 v27, v44, v27, s46
	v_add3_u32 v0, v45, v0, s46
	v_add3_u32 v44, v47, v50, s46
	v_add3_u32 v45, v46, v51, s46
	v_and_b32_e32 v44, 0xffff0000, v44
	v_and_b32_e32 v46, 0xffff0000, v45
	v_or_b32_sdwa v45, v44, v0 dst_sel:DWORD dst_unused:UNUSED_PAD src0_sel:DWORD src1_sel:WORD_1
	v_or_b32_sdwa v44, v46, v27 dst_sel:DWORD dst_unused:UNUSED_PAD src0_sel:DWORD src1_sel:WORD_1
	global_store_dwordx2 v[48:49], v[44:45], off offset:1536
	s_branch .LBB0_186

; __device__ __forceinline__ float bflo(unsigned u) { return __uint_as_float(u << 16); }
; __device__ void phase_rows(int flags, const float* xin, bf16_t* XB, const bf16_t* mf, const float* g1, const float* g2, float* xout, bf16_t* U,
;                            const float* pin, bf16_t* Pb) {
;     const int tid = o_tid(), wave = tid >> 6, lane = tid & 63; const int bid = o_bid(), nblk = o_nblk();
;     const int stride = nblk * 8;
;     for (int r0 = bid * 8 + wave; r0 < TCH; r0 += 2 * stride) {
;         float4 x[2][4]; uint2 mq[2][4]; float4 pv[2];
; #pragma unroll
;         for (int k = 0; k < 2; ++k) { const int r = r0 + k * stride; if (r < TCH) {
;             if (flags & 16) { const uint2* xr = (const uint2*)(XB + (size_t)r * DM);
; #pragma unroll
;                 for (int i = 0; i < 4; ++i) { const uint2 q = xr[lane + 64 * i]; x[k][i] = make_float4(bflo(q.x), bfhi(q.x), bflo(q.y), bfhi(q.y)); } }
;             else { const float4* xr = (const float4*)(xin + (size_t)r * DM);
; #pragma unroll
;                 for (int i = 0; i < 4; ++i) x[k][i] = xr[lane + 64 * i]; }
;             if (flags & 1) { const uint2* mr = (const uint2*)(mf + (size_t)r * DM);
; #pragma unroll
;                 for (int i = 0; i < 4; ++i) { const unsigned long long t64 = __builtin_nontemporal_load((const unsigned long long*)(mr + lane + 64 * i)); mq[k][i] = make_uint2((unsigned)t64, (unsigned)(t64 >> 32)); } }
;             if (flags & 8) pv[k] = ((const float4*)(pin + (size_t)r * DPLE))[lane]; } }
; #pragma unroll
;         for (int k = 0; k < 2; ++k) { const int r = r0 + k * stride; if (r < TCH) {
;             if (flags & 1) {
;                 float ss = 0.f; float4 m[4];
; #pragma unroll
;                 for (int i = 0; i < 4; ++i) { m[i] = make_float4(bflo(mq[k][i].x), bfhi(mq[k][i].x), bflo(mq[k][i].y), bfhi(mq[k][i].y)); ss += m[i].x * m[i].x + m[i].y * m[i].y + m[i].z * m[i].z + m[i].w * m[i].w; }
;                 ss = wave_sum(ss); const float rs = rsqrtf(ss * (1.0f / DM) + 1e-6f);
; #pragma unroll
;                 for (int i = 0; i < 4; ++i) { const float4 g = ((const float4*)g1)[lane + 64 * i];
;                     x[k][i].x += m[i].x * rs * g.x; x[k][i].y += m[i].y * rs * g.y; x[k][i].z += m[i].z * rs * g.z; x[k][i].w += m[i].w * rs * g.w; }
;                 if (flags & 32) { float4* xo = (float4*)(xout + (size_t)r * DM);
; #pragma unroll
.LBB0_202:
	v_mov_b32_e32 v0, v180
	s_mov_b32 s7, s49
	s_mov_b32 s6, s64
	s_waitcnt vmcnt(0)
	v_ashrrev_i32_e32 v2, 6, v0
	v_lshl_add_u32 v60, s7, 3, v2
	s_mov_b32 s7, 0x8000
	v_cmp_gt_i32_e32 vcc, s7, v60
	s_and_saveexec_b64 s[10:11], vcc
	s_cbranch_execz .LBB0_209
	v_and_b32_e32 v2, 63, v0
	v_and_b32_e32 v0, 64, v191
	v_add_u32_e32 v0, 64, v0
	v_xor_b32_e32 v3, 32, v191
	v_cmp_lt_i32_e32 vcc, v3, v0
	s_load_dwordx2 s[14:15], s[82:83], 0x20
	s_waitcnt lgkmcnt(0)
	s_lshl_b32 s12, s6, 3
	v_cndmask_b32_e32 v3, v191, v3, vcc
	v_lshlrev_b32_e32 v62, 2, v3
	v_xor_b32_e32 v3, 16, v191
	v_cmp_lt_i32_e32 vcc, v3, v0
	s_and_b64 s[6:7], s[4:5], exec
	s_cselect_b32 s6, 0x1000, 0
	v_cndmask_b32_e32 v3, v191, v3, vcc
	v_lshlrev_b32_e32 v63, 2, v3
	v_xor_b32_e32 v3, 8, v191
	v_cmp_lt_i32_e32 vcc, v3, v0
	s_add_u32 s6, s14, s6
	s_addc_u32 s7, s15, 0
	v_cndmask_b32_e32 v3, v191, v3, vcc
	v_lshlrev_b32_e32 v64, 2, v3
	v_xor_b32_e32 v3, 4, v191
	v_cmp_lt_i32_e32 vcc, v3, v0
	s_nop 1
	v_cndmask_b32_e32 v3, v191, v3, vcc
	v_lshlrev_b32_e32 v65, 2, v3
	v_xor_b32_e32 v3, 2, v191
	v_cmp_lt_i32_e32 vcc, v3, v0
	s_nop 1
	v_cndmask_b32_e32 v3, v191, v3, vcc
	v_lshlrev_b32_e32 v66, 2, v3
	v_xor_b32_e32 v3, 1, v191
	v_cmp_lt_i32_e32 vcc, v3, v0
	s_nop 1
	v_cndmask_b32_e32 v0, v191, v3, vcc
	v_lshlrev_b32_e32 v67, 2, v0
	v_lshlrev_b32_e32 v0, 4, v2
	v_lshl_add_u64 v[34:35], s[6:7], 0, v[0:1]
	v_lshl_add_u64 v[36:37], s[0:1], 0, v[0:1]
	v_lshlrev_b32_e32 v0, 3, v2
	v_lshl_add_u64 v[38:39], s[8:9], 0, v[0:1]
	s_mov_b64 s[0:1], 0
	global_load_dwordx4 v[136:139], v[34:35], off
	global_load_dwordx4 v[140:143], v[34:35], off offset:1024
	global_load_dwordx4 v[144:147], v[34:35], off offset:2048
	global_load_dwordx4 v[148:151], v[34:35], off offset:3072
	s_branch .LBB0_205

; __device__ __forceinline__ unsigned pack2(float lo, float hi) { return (unsigned)f2bf(lo) | ((unsigned)f2bf(hi) << 16); }
; __device__ void phase_rows(int flags, const float* xin, bf16_t* XB, const bf16_t* mf, const float* g1, const float* g2, float* xout, bf16_t* U,
;                            const float* pin, bf16_t* Pb) {
;     ...
;             if (flags & 2) {
;                 float ss = 0.f;
; #pragma unroll
;                 for (int i = 0; i < 4; ++i) ss += x[k][i].x * x[k][i].x + x[k][i].y * x[k][i].y + x[k][i].z * x[k][i].z + x[k][i].w * x[k][i].w;
;                 ss = wave_sum(ss); const float rs2 = rsqrtf(ss * (1.0f / DM) + 1e-6f);
;                 uint2* uo = (uint2*)(U + (size_t)r * DM);
; #pragma unroll
;                 for (int i = 0; i < 4; ++i) { const float4 g = ((const float4*)g2)[lane + 64 * i];
;                     uint2 o; o.x = pack2(x[k][i].x * rs2 * g.x, x[k][i].y * rs2 * g.y); o.y = pack2(x[k][i].z * rs2 * g.z, x[k][i].w * rs2 * g.w); uo[lane + 64 * i] = o; }
.LBB0_207:
	s_or_b64 exec, exec, s[6:7]
	global_load_dwordx4 v[68:71], v[34:35], off
	s_waitcnt vmcnt(4)
	v_mov_b32_e32 v72, v31
	s_waitcnt vmcnt(3)
	v_mov_b32_e32 v73, v27
	v_mov_b32_e32 v16, v30
	v_mov_b32_e32 v17, v26
	s_waitcnt vmcnt(2)
	v_mov_b32_e32 v80, v23
	s_waitcnt vmcnt(1)
	v_mov_b32_e32 v81, v19
	v_pk_mul_f32 v[72:73], v[72:73], v[72:73]
	v_mov_b32_e32 v74, v32
	v_mov_b32_e32 v75, v28
	v_mov_b32_e32 v78, v22
	v_mov_b32_e32 v79, v18
	v_pk_mul_f32 v[80:81], v[80:81], v[80:81]
	v_pk_fma_f32 v[16:17], v[16:17], v[16:17], v[72:73]
	v_mov_b32_e32 v76, v33
	v_mov_b32_e32 v77, v29
	v_mov_b32_e32 v82, v24
	v_mov_b32_e32 v83, v20
	v_pk_fma_f32 v[72:73], v[78:79], v[78:79], v[80:81]
	v_pk_fma_f32 v[16:17], v[74:75], v[74:75], v[16:17]
	v_mov_b32_e32 v84, v25
	v_mov_b32_e32 v85, v21
	v_pk_fma_f32 v[72:73], v[82:83], v[82:83], v[72:73]
	v_pk_fma_f32 v[16:17], v[76:77], v[76:77], v[16:17]
	v_pk_fma_f32 v[72:73], v[84:85], v[84:85], v[72:73]
	v_add_f32_e32 v0, v16, v17
	v_add_f32_e32 v0, v0, v72
	v_add_f32_e32 v0, v0, v73
	ds_bpermute_b32 v16, v62, v0
	s_waitcnt lgkmcnt(0)
	v_add_f32_e32 v0, v0, v16
	ds_bpermute_b32 v16, v63, v0
	s_waitcnt lgkmcnt(0)
	v_add_f32_e32 v0, v0, v16
	ds_bpermute_b32 v16, v64, v0
	s_waitcnt lgkmcnt(0)
	v_add_f32_e32 v0, v0, v16
	ds_bpermute_b32 v16, v65, v0
	s_waitcnt lgkmcnt(0)
	v_add_f32_e32 v0, v0, v16
	ds_bpermute_b32 v16, v66, v0
	s_waitcnt lgkmcnt(0)
	v_add_f32_e32 v0, v0, v16
	ds_bpermute_b32 v72, v67, v0
	v_lshlrev_b64 v[16:17], 11, v[60:61]
	v_mov_b32_e32 v60, v30
	v_mov_b32_e32 v61, v32
	v_mov_b32_e32 v32, v31
	s_waitcnt lgkmcnt(0)
	v_add_f32_e32 v0, v0, v72
	v_fmamk_f32 v0, v0, 0x3a800000, v184
	v_mul_f32_e32 v30, 0x4b800000, v0
	v_cmp_gt_f32_e64 s[6:7], s67, v0
	v_lshl_add_u64 v[16:17], v[38:39], 0, v[16:17]
	s_nop 0
	v_cndmask_b32_e64 v0, v0, v30, s[6:7]
	v_rsq_f32_e32 v0, v0
	s_nop 0
	v_mul_f32_e32 v30, 0x45800000, v0
	v_cndmask_b32_e64 v0, v0, v30, s[6:7]
	v_pk_mul_f32 v[30:31], v[60:61], v[0:1] op_sel_hi:[1,0]
	v_pk_mul_f32 v[32:33], v[32:33], v[0:1] op_sel_hi:[1,0]
	s_waitcnt vmcnt(0)
	v_mov_b32_e32 v61, v70
	v_mov_b32_e32 v70, v69
	v_mov_b32_e32 v60, v68
	v_pk_mul_f32 v[32:33], v[70:71], v[32:33]
	v_pk_mul_f32 v[30:31], v[60:61], v[30:31]
	v_and_b32_sdwa v68, v33, v185 dst_sel:DWORD dst_unused:UNUSED_PAD src0_sel:WORD_1 src1_sel:DWORD
	v_and_b32_sdwa v69, v32, v185 dst_sel:DWORD dst_unused:UNUSED_PAD src0_sel:WORD_1 src1_sel:DWORD
	v_and_b32_sdwa v60, v31, v185 dst_sel:DWORD dst_unused:UNUSED_PAD src0_sel:WORD_1 src1_sel:DWORD
	v_and_b32_sdwa v61, v30, v185 dst_sel:DWORD dst_unused:UNUSED_PAD src0_sel:WORD_1 src1_sel:DWORD
	v_add3_u32 v33, v33, v68, s46
	v_add3_u32 v32, v32, v69, s46
	v_add3_u32 v30, v30, v61, s46
	v_add3_u32 v31, v31, v60, s46
	v_and_b32_e32 v33, 0xffff0000, v33
	v_and_b32_e32 v32, 0xffff0000, v32
	v_or_b32_sdwa v31, v33, v31 dst_sel:DWORD dst_unused:UNUSED_PAD src0_sel:DWORD src1_sel:WORD_1
	v_or_b32_sdwa v30, v32, v30 dst_sel:DWORD dst_unused:UNUSED_PAD src0_sel:DWORD src1_sel:WORD_1
	global_store_dwordx2 v[16:17], v[30:31], off
	v_mov_b64_e32 v[30:31], v[140:141]
	v_mov_b64_e32 v[32:33], v[142:143]
	v_mov_b32_e32 v60, v26
	v_mov_b32_e32 v61, v28
	v_mov_b32_e32 v28, v27
	v_pk_mul_f32 v[26:27], v[60:61], v[0:1] op_sel_hi:[1,0]
	v_pk_mul_f32 v[28:29], v[28:29], v[0:1] op_sel_hi:[1,0]
	v_mov_b32_e32 v61, v32
	v_mov_b32_e32 v32, v31
	v_mov_b32_e32 v60, v30
	v_pk_mul_f32 v[28:29], v[32:33], v[28:29]
	v_pk_mul_f32 v[26:27], v[60:61], v[26:27]
	v_and_b32_sdwa v32, v29, v185 dst_sel:DWORD dst_unused:UNUSED_PAD src0_sel:WORD_1 src1_sel:DWORD
	v_and_b32_sdwa v33, v28, v185 dst_sel:DWORD dst_unused:UNUSED_PAD src0_sel:WORD_1 src1_sel:DWORD
	v_and_b32_sdwa v30, v27, v185 dst_sel:DWORD dst_unused:UNUSED_PAD src0_sel:WORD_1 src1_sel:DWORD
	v_and_b32_sdwa v31, v26, v185 dst_sel:DWORD dst_unused:UNUSED_PAD src0_sel:WORD_1 src1_sel:DWORD
	v_add3_u32 v29, v29, v32, s46
	v_add3_u32 v28, v28, v33, s46
	v_add3_u32 v26, v26, v31, s46
	v_add3_u32 v27, v27, v30, s46
	v_and_b32_e32 v29, 0xffff0000, v29
	v_and_b32_e32 v28, 0xffff0000, v28
	v_or_b32_sdwa v27, v29, v27 dst_sel:DWORD dst_unused:UNUSED_PAD src0_sel:DWORD src1_sel:WORD_1
	v_or_b32_sdwa v26, v28, v26 dst_sel:DWORD dst_unused:UNUSED_PAD src0_sel:DWORD src1_sel:WORD_1
	global_store_dwordx2 v[16:17], v[26:27], off offset:512
	v_mov_b64_e32 v[26:27], v[144:145]
	v_mov_b64_e32 v[28:29], v[146:147]
	v_mov_b32_e32 v30, v22
	v_mov_b32_e32 v31, v24
	v_mov_b32_e32 v24, v23
	v_pk_mul_f32 v[22:23], v[30:31], v[0:1] op_sel_hi:[1,0]
	v_pk_mul_f32 v[24:25], v[24:25], v[0:1] op_sel_hi:[1,0]
	v_mov_b32_e32 v31, v28
	v_mov_b32_e32 v28, v27
	v_mov_b32_e32 v30, v26
	v_pk_mul_f32 v[24:25], v[24:25], v[28:29]
	v_pk_mul_f32 v[22:23], v[22:23], v[30:31]
	v_and_b32_sdwa v28, v25, v185 dst_sel:DWORD dst_unused:UNUSED_PAD src0_sel:WORD_1 src1_sel:DWORD
	v_and_b32_sdwa v29, v24, v185 dst_sel:DWORD dst_unused:UNUSED_PAD src0_sel:WORD_1 src1_sel:DWORD
	v_and_b32_sdwa v26, v23, v185 dst_sel:DWORD dst_unused:UNUSED_PAD src0_sel:WORD_1 src1_sel:DWORD
	v_and_b32_sdwa v27, v22, v185 dst_sel:DWORD dst_unused:UNUSED_PAD src0_sel:WORD_1 src1_sel:DWORD
	v_add3_u32 v25, v25, v28, s46
	v_add3_u32 v24, v24, v29, s46
	v_add3_u32 v22, v22, v27, s46
	v_add3_u32 v23, v23, v26, s46
	v_and_b32_e32 v25, 0xffff0000, v25
	v_and_b32_e32 v24, 0xffff0000, v24
	v_or_b32_sdwa v23, v25, v23 dst_sel:DWORD dst_unused:UNUSED_PAD src0_sel:DWORD src1_sel:WORD_1
	v_or_b32_sdwa v22, v24, v22 dst_sel:DWORD dst_unused:UNUSED_PAD src0_sel:DWORD src1_sel:WORD_1
	global_store_dwordx2 v[16:17], v[22:23], off offset:1024
	v_mov_b64_e32 v[22:23], v[148:149]
	v_mov_b64_e32 v[24:25], v[150:151]
	v_mov_b32_e32 v26, v18
	v_mov_b32_e32 v27, v20
	v_mov_b32_e32 v20, v19
	v_pk_mul_f32 v[18:19], v[26:27], v[0:1] op_sel_hi:[1,0]
	v_pk_mul_f32 v[20:21], v[20:21], v[0:1] op_sel_hi:[1,0]
	v_mov_b32_e32 v26, v22
	v_mov_b32_e32 v27, v24
	v_mov_b32_e32 v24, v23
	v_pk_mul_f32 v[18:19], v[18:19], v[26:27]
	v_pk_mul_f32 v[20:21], v[20:21], v[24:25]
	v_and_b32_sdwa v0, v19, v185 dst_sel:DWORD dst_unused:UNUSED_PAD src0_sel:WORD_1 src1_sel:DWORD
	v_and_b32_sdwa v23, v21, v185 dst_sel:DWORD dst_unused:UNUSED_PAD src0_sel:WORD_1 src1_sel:DWORD
	v_and_b32_sdwa v24, v20, v185 dst_sel:DWORD dst_unused:UNUSED_PAD src0_sel:WORD_1 src1_sel:DWORD
	v_and_b32_sdwa v22, v18, v185 dst_sel:DWORD dst_unused:UNUSED_PAD src0_sel:WORD_1 src1_sel:DWORD
	v_add3_u32 v0, v19, v0, s46
	v_add3_u32 v19, v21, v23, s46
	v_add3_u32 v20, v20, v24, s46
	v_add3_u32 v18, v18, v22, s46
	v_and_b32_e32 v19, 0xffff0000, v19
	v_and_b32_e32 v20, 0xffff0000, v20
	v_or_b32_sdwa v19, v19, v0 dst_sel:DWORD dst_unused:UNUSED_PAD src0_sel:DWORD src1_sel:WORD_1
	v_or_b32_sdwa v18, v20, v18 dst_sel:DWORD dst_unused:UNUSED_PAD src0_sel:DWORD src1_sel:WORD_1
	global_store_dwordx2 v[16:17], v[18:19], off offset:1536
	s_and_saveexec_b64 s[6:7], vcc
	s_cbranch_execz .LBB0_204
; __device__ __forceinline__ unsigned pack2(float lo, float hi) { return (unsigned)f2bf(lo) | ((unsigned)f2bf(hi) << 16); }
; __device__ void phase_rows(int flags, const float* xin, bf16_t* XB, const bf16_t* mf, const float* g1, const float* g2, float* xout, bf16_t* U,
;                            const float* pin, bf16_t* Pb) {
;     ...
;             if (flags & 2) {
;                 float ss = 0.f;
; #pragma unroll
;                 for (int i = 0; i < 4; ++i) ss += x[k][i].x * x[k][i].x + x[k][i].y * x[k][i].y + x[k][i].z * x[k][i].z + x[k][i].w * x[k][i].w;
;                 ss = wave_sum(ss); const float rs2 = rsqrtf(ss * (1.0f / DM) + 1e-6f);
;                 uint2* uo = (uint2*)(U + (size_t)r * DM);
; #pragma unroll
;                 for (int i = 0; i < 4; ++i) { const float4 g = ((const float4*)g2)[lane + 64 * i];
;                     uint2 o; o.x = pack2(x[k][i].x * rs2 * g.x, x[k][i].y * rs2 * g.y); o.y = pack2(x[k][i].z * rs2 * g.z, x[k][i].w * rs2 * g.w); uo[lane + 64 * i] = o; }
	v_mov_b64_e32 v[18:19], v[136:137]
	v_mov_b64_e32 v[20:21], v[138:139]
	v_mov_b32_e32 v16, v54
	v_mov_b32_e32 v17, v58
	v_mov_b32_e32 v22, v52
	v_mov_b32_e32 v23, v56
	v_mov_b32_e32 v28, v46
	v_mov_b32_e32 v29, v50
	v_pk_mul_f32 v[16:17], v[16:17], v[16:17]
	v_mov_b32_e32 v24, v55
	v_mov_b32_e32 v25, v59
	v_mov_b32_e32 v30, v44
	v_mov_b32_e32 v31, v48
	v_pk_mul_f32 v[28:29], v[28:29], v[28:29]
	v_pk_fma_f32 v[16:17], v[22:23], v[22:23], v[16:17]
	v_mov_b32_e32 v26, v53
	v_mov_b32_e32 v27, v57
	v_mov_b32_e32 v32, v47
	v_mov_b32_e32 v33, v51
	v_pk_fma_f32 v[22:23], v[30:31], v[30:31], v[28:29]
	v_pk_fma_f32 v[16:17], v[24:25], v[24:25], v[16:17]
	v_mov_b32_e32 v60, v45
	v_mov_b32_e32 v61, v49
	v_pk_fma_f32 v[22:23], v[32:33], v[32:33], v[22:23]
	v_pk_fma_f32 v[16:17], v[26:27], v[26:27], v[16:17]
	v_pk_fma_f32 v[22:23], v[60:61], v[60:61], v[22:23]
	v_add_f32_e32 v0, v16, v17
	v_add_f32_e32 v0, v23, v0
	v_add_f32_e32 v0, v22, v0
	ds_bpermute_b32 v16, v62, v0
	s_waitcnt lgkmcnt(0)
	v_add_f32_e32 v0, v0, v16
	ds_bpermute_b32 v16, v63, v0
	s_waitcnt lgkmcnt(0)
	v_add_f32_e32 v0, v0, v16
	ds_bpermute_b32 v16, v64, v0
	s_waitcnt lgkmcnt(0)
	v_add_f32_e32 v0, v0, v16
	ds_bpermute_b32 v16, v65, v0
	s_waitcnt lgkmcnt(0)
	v_add_f32_e32 v0, v0, v16
	ds_bpermute_b32 v16, v66, v0
	s_waitcnt lgkmcnt(0)
	v_add_f32_e32 v0, v0, v16
	ds_bpermute_b32 v16, v67, v0
	s_waitcnt lgkmcnt(0)
	v_add_f32_e32 v0, v0, v16
	v_fmamk_f32 v0, v0, 0x3a800000, v184
	v_mul_f32_e32 v16, 0x4b800000, v0
	v_cmp_gt_f32_e32 vcc, s67, v0
	v_mov_b32_e32 v27, v20
	v_cndmask_b32_e32 v0, v0, v16, vcc
	v_rsq_f32_e32 v0, v0
	v_mov_b32_e32 v20, v19
	v_mov_b32_e32 v26, v18
	v_lshlrev_b64 v[16:17], 11, v[42:43]
	v_mul_f32_e32 v22, 0x45800000, v0
	v_cndmask_b32_e32 v0, v0, v22, vcc
	v_pk_mul_f32 v[24:25], v[56:57], v[0:1] op_sel_hi:[1,0]
	v_pk_mul_f32 v[22:23], v[58:59], v[0:1] op_sel_hi:[1,0]
	v_pk_mul_f32 v[20:21], v[20:21], v[24:25]
	v_pk_mul_f32 v[18:19], v[26:27], v[22:23]
	v_and_b32_sdwa v24, v21, v185 dst_sel:DWORD dst_unused:UNUSED_PAD src0_sel:WORD_1 src1_sel:DWORD
	v_and_b32_sdwa v25, v20, v185 dst_sel:DWORD dst_unused:UNUSED_PAD src0_sel:WORD_1 src1_sel:DWORD
	v_and_b32_sdwa v22, v19, v185 dst_sel:DWORD dst_unused:UNUSED_PAD src0_sel:WORD_1 src1_sel:DWORD
	v_and_b32_sdwa v23, v18, v185 dst_sel:DWORD dst_unused:UNUSED_PAD src0_sel:WORD_1 src1_sel:DWORD
	v_add3_u32 v21, v21, v24, s46
	v_add3_u32 v20, v20, v25, s46
	v_add3_u32 v18, v18, v23, s46
	v_add3_u32 v19, v19, v22, s46
	v_and_b32_e32 v21, 0xffff0000, v21
	v_and_b32_e32 v20, 0xffff0000, v20
	v_lshl_add_u64 v[16:17], v[38:39], 0, v[16:17]
	v_or_b32_sdwa v19, v21, v19 dst_sel:DWORD dst_unused:UNUSED_PAD src0_sel:DWORD src1_sel:WORD_1
	v_or_b32_sdwa v18, v20, v18 dst_sel:DWORD dst_unused:UNUSED_PAD src0_sel:DWORD src1_sel:WORD_1
	global_store_dwordx2 v[16:17], v[18:19], off
	v_mov_b64_e32 v[18:19], v[140:141]
	v_mov_b64_e32 v[20:21], v[142:143]
	v_pk_mul_f32 v[24:25], v[52:53], v[0:1] op_sel_hi:[1,0]
	v_pk_mul_f32 v[22:23], v[54:55], v[0:1] op_sel_hi:[1,0]
	v_mov_b32_e32 v27, v20
	v_mov_b32_e32 v20, v19
	v_mov_b32_e32 v26, v18
	v_pk_mul_f32 v[20:21], v[20:21], v[24:25]
	v_pk_mul_f32 v[18:19], v[26:27], v[22:23]
	v_and_b32_sdwa v24, v21, v185 dst_sel:DWORD dst_unused:UNUSED_PAD src0_sel:WORD_1 src1_sel:DWORD
	v_and_b32_sdwa v25, v20, v185 dst_sel:DWORD dst_unused:UNUSED_PAD src0_sel:WORD_1 src1_sel:DWORD
	v_and_b32_sdwa v22, v19, v185 dst_sel:DWORD dst_unused:UNUSED_PAD src0_sel:WORD_1 src1_sel:DWORD
	v_and_b32_sdwa v23, v18, v185 dst_sel:DWORD dst_unused:UNUSED_PAD src0_sel:WORD_1 src1_sel:DWORD
	v_add3_u32 v21, v21, v24, s46
	v_add3_u32 v20, v20, v25, s46
	v_add3_u32 v18, v18, v23, s46
	v_add3_u32 v19, v19, v22, s46
	v_and_b32_e32 v21, 0xffff0000, v21
	v_and_b32_e32 v20, 0xffff0000, v20
	v_or_b32_sdwa v19, v21, v19 dst_sel:DWORD dst_unused:UNUSED_PAD src0_sel:DWORD src1_sel:WORD_1
	v_or_b32_sdwa v18, v20, v18 dst_sel:DWORD dst_unused:UNUSED_PAD src0_sel:DWORD src1_sel:WORD_1
	global_store_dwordx2 v[16:17], v[18:19], off offset:512
	v_mov_b64_e32 v[18:19], v[144:145]
	v_mov_b64_e32 v[20:21], v[146:147]
	v_pk_mul_f32 v[24:25], v[48:49], v[0:1] op_sel_hi:[1,0]
	v_pk_mul_f32 v[22:23], v[50:51], v[0:1] op_sel_hi:[1,0]
	v_mov_b32_e32 v27, v20
	v_mov_b32_e32 v20, v19
	v_mov_b32_e32 v26, v18
	v_pk_mul_f32 v[20:21], v[24:25], v[20:21]
	v_pk_mul_f32 v[18:19], v[22:23], v[26:27]
	v_and_b32_sdwa v24, v21, v185 dst_sel:DWORD dst_unused:UNUSED_PAD src0_sel:WORD_1 src1_sel:DWORD
	v_and_b32_sdwa v25, v20, v185 dst_sel:DWORD dst_unused:UNUSED_PAD src0_sel:WORD_1 src1_sel:DWORD
	v_and_b32_sdwa v22, v19, v185 dst_sel:DWORD dst_unused:UNUSED_PAD src0_sel:WORD_1 src1_sel:DWORD
	v_and_b32_sdwa v23, v18, v185 dst_sel:DWORD dst_unused:UNUSED_PAD src0_sel:WORD_1 src1_sel:DWORD
	v_add3_u32 v21, v21, v24, s46
	v_add3_u32 v20, v20, v25, s46
	v_add3_u32 v18, v18, v23, s46
	v_add3_u32 v19, v19, v22, s46
	v_and_b32_e32 v21, 0xffff0000, v21
	v_and_b32_e32 v20, 0xffff0000, v20
	v_or_b32_sdwa v19, v21, v19 dst_sel:DWORD dst_unused:UNUSED_PAD src0_sel:DWORD src1_sel:WORD_1
	v_or_b32_sdwa v18, v20, v18 dst_sel:DWORD dst_unused:UNUSED_PAD src0_sel:DWORD src1_sel:WORD_1
	global_store_dwordx2 v[16:17], v[18:19], off offset:1024
	v_mov_b64_e32 v[18:19], v[148:149]
	v_mov_b64_e32 v[20:21], v[150:151]
	v_pk_mul_f32 v[22:23], v[46:47], v[0:1] op_sel_hi:[1,0]
	v_pk_mul_f32 v[24:25], v[44:45], v[0:1] op_sel_hi:[1,0]
	v_mov_b32_e32 v26, v18
	v_mov_b32_e32 v27, v20
	v_mov_b32_e32 v20, v19
	v_pk_mul_f32 v[18:19], v[22:23], v[26:27]
	v_pk_mul_f32 v[20:21], v[24:25], v[20:21]
	v_and_b32_sdwa v0, v19, v185 dst_sel:DWORD dst_unused:UNUSED_PAD src0_sel:WORD_1 src1_sel:DWORD
	v_and_b32_sdwa v23, v21, v185 dst_sel:DWORD dst_unused:UNUSED_PAD src0_sel:WORD_1 src1_sel:DWORD
	v_and_b32_sdwa v24, v20, v185 dst_sel:DWORD dst_unused:UNUSED_PAD src0_sel:WORD_1 src1_sel:DWORD
	v_and_b32_sdwa v22, v18, v185 dst_sel:DWORD dst_unused:UNUSED_PAD src0_sel:WORD_1 src1_sel:DWORD
	v_add3_u32 v0, v19, v0, s46
	v_add3_u32 v19, v21, v23, s46
	v_add3_u32 v20, v20, v24, s46
	v_add3_u32 v18, v18, v22, s46
	v_and_b32_e32 v19, 0xffff0000, v19
	v_and_b32_e32 v20, 0xffff0000, v20
	v_or_b32_sdwa v19, v19, v0 dst_sel:DWORD dst_unused:UNUSED_PAD src0_sel:DWORD src1_sel:WORD_1
	v_or_b32_sdwa v18, v20, v18 dst_sel:DWORD dst_unused:UNUSED_PAD src0_sel:DWORD src1_sel:WORD_1
	global_store_dwordx2 v[16:17], v[18:19], off offset:1536
	s_branch .LBB0_204

; __device__ __forceinline__ float sigmoidf_(float x) { return __builtin_amdgcn_rcpf(1.0f + __expf(-x)); }
; __device__ __forceinline__ void unpack8(const uint4 u, float (&f)[8]) { f[0] = bflo(u.x); f[1] = bfhi(u.x); f[2] = bflo(u.y); f[3] = bfhi(u.y); f[4] = bflo(u.z); f[5] = bfhi(u.z); f[6] = bflo(u.w); f[7] = bfhi(u.w); }
; __device__ __forceinline__ uint4 pack8(const float (&f)[8]) { uint4 u; u.x = pack2(f[0], f[1]); u.y = pack2(f[2], f[3]); u.z = pack2(f[4], f[5]); u.w = pack2(f[6], f[7]); return u; }
;     __device__ __forceinline__ void operator()(const f32x4 (&acc)[2][2][4][2], const Unit& u, int wr, int wc, int fr, int fq) const {
;         EPIP_ROWS( float gr[8]; unpack8(*(const uint4*)(gate + row * LDP + C_GR + col8 + co), gr); float o[8];
;             _Pragma("unroll") for (int e = 0; e < 4; ++e) { o[e] = sigmoidf_(fminf(fmaxf(gr[e], -30.f), 30.f)) * v0[e]; o[4 + e] = sigmoidf_(fminf(fmaxf(gr[4 + e], -30.f), 30.f)) * v1[e]; }
;             *(uint4*)(O + row * DM + col8 + co) = pack8(o); )
;     }
.LBB0_330:
	s_and_b64 vcc, exec, s[0:1]
	s_cbranch_vccz .LBB0_346
	s_cmp_gt_i32 s53, 2
	s_mov_b64 s[0:1], -1
	s_cbranch_scc0 .LBB0_344
	s_cmp_gt_i32 s53, 5
	s_cbranch_scc0 .LBB0_336
	s_cmp_eq_u32 s53, 6
	s_mov_b64 s[12:13], -1
	s_cbranch_scc0 .LBB0_335
	v_lshl_or_b32 v2, s44, 8, v204
	v_ashrrev_i32_e32 v3, 31, v2
	v_lshl_add_u32 v0, s61, 8, v196
	s_waitcnt vmcnt(0)
	v_readlane_b32 s0, v249, 14
	v_readlane_b32 s1, v249, 15
	v_lshlrev_b64 v[132:133], 1, v[2:3]
	v_mov_b32_e32 v134, v0
	v_ashrrev_i32_e32 v135, 31, v0
	v_lshlrev_b64 v[134:135], 11, v[134:135]
	s_nop 1
	v_lshl_add_u64 v[206:207], s[0:1], 0, v[132:133]
	v_lshl_add_u64 v[206:207], v[206:207], 0, v[134:135]
	v_mov_b64_e32 v[136:137], s[82:83]
	v_mad_i64_i32 v[208:209], vcc, v0, s47, v[136:137]
	v_lshl_add_u64 v[208:209], v[208:209], 0, v[132:133]
	s_mov_b64 s[0:1], 0x2300
	v_lshl_add_u64 v[2:3], v[208:209], 0, s[0:1]
	global_load_dwordx4 v[132:135], v[2:3], off
	global_load_dwordx4 v[136:139], v[2:3], off offset:256
	s_mov_b64 s[0:1], 0x2e300
	v_lshl_add_u64 v[2:3], v[208:209], 0, s[0:1]
	global_load_dwordx4 v[140:143], v[2:3], off
	global_load_dwordx4 v[144:147], v[2:3], off offset:256
	s_mov_b64 s[0:1], 0x5a300
	v_lshl_add_u64 v[2:3], v[208:209], 0, s[0:1]
	global_load_dwordx4 v[148:151], v[2:3], off
	global_load_dwordx4 v[152:155], v[2:3], off offset:256
	s_mov_b64 s[0:1], 0x86300
	v_lshl_add_u64 v[2:3], v[208:209], 0, s[0:1]
	global_load_dwordx4 v[228:231], v[2:3], off
	global_load_dwordx4 v[232:235], v[2:3], off offset:256
	s_mov_b64 s[0:1], 0x162300
	v_lshl_add_u64 v[2:3], v[208:209], 0, s[0:1]
	global_load_dwordx4 v[236:239], v[2:3], off
	global_load_dwordx4 v[240:243], v[2:3], off offset:256
	v_mov_b64_e32 v[210:211], v[206:207]
	s_waitcnt vmcnt(8)
	v_lshlrev_b32_e32 v156, 16, v132
	v_and_b32_e32 v157, 0xffff0000, v132
	v_lshlrev_b32_e32 v158, 16, v133
	v_and_b32_e32 v159, 0xffff0000, v133
	v_lshlrev_b32_e32 v160, 16, v134
	v_and_b32_e32 v161, 0xffff0000, v134
	v_lshlrev_b32_e32 v162, 16, v135
	v_and_b32_e32 v163, 0xffff0000, v135
	v_max_f32_e32 v156, v156, v156
	v_max_f32_e32 v157, v157, v157
	v_max_f32_e32 v158, v158, v158
	v_max_f32_e32 v159, v159, v159
	v_max_f32_e32 v160, v160, v160
	v_max_f32_e32 v161, v161, v161
	v_max_f32_e32 v162, v162, v162
	v_max_f32_e32 v163, v163, v163
	v_med3_f32 v156, v156, s48, v192
	v_med3_f32 v157, v157, s48, v192
	v_med3_f32 v158, v158, s48, v192
	v_med3_f32 v159, v159, s48, v192
	v_med3_f32 v160, v160, s48, v192
	v_med3_f32 v161, v161, s48, v192
	v_med3_f32 v162, v162, s48, v192
	v_med3_f32 v163, v163, s48, v192
	v_mul_f32_e32 v156, 0xbfb8aa3b, v156
	v_mul_f32_e32 v157, 0xbfb8aa3b, v157
	v_mul_f32_e32 v158, 0xbfb8aa3b, v158
	v_mul_f32_e32 v159, 0xbfb8aa3b, v159
	v_mul_f32_e32 v160, 0xbfb8aa3b, v160
	v_mul_f32_e32 v161, 0xbfb8aa3b, v161
	v_mul_f32_e32 v162, 0xbfb8aa3b, v162
	v_mul_f32_e32 v163, 0xbfb8aa3b, v163
	v_exp_f32_e32 v156, v156
	v_exp_f32_e32 v157, v157
	v_exp_f32_e32 v158, v158
	v_exp_f32_e32 v159, v159
	v_exp_f32_e32 v160, v160
	v_exp_f32_e32 v161, v161
	v_exp_f32_e32 v162, v162
	v_exp_f32_e32 v163, v163
	v_add_f32_e32 v156, 1.0, v156
	v_add_f32_e32 v157, 1.0, v157
	v_add_f32_e32 v158, 1.0, v158
	v_add_f32_e32 v159, 1.0, v159
	v_add_f32_e32 v160, 1.0, v160
	v_add_f32_e32 v161, 1.0, v161
	v_add_f32_e32 v162, 1.0, v162
	v_add_f32_e32 v163, 1.0, v163
	v_rcp_f32_e32 v156, v156
	v_rcp_f32_e32 v157, v157
	v_rcp_f32_e32 v158, v158
	v_rcp_f32_e32 v159, v159
	v_rcp_f32_e32 v160, v160
	v_rcp_f32_e32 v161, v161
	v_rcp_f32_e32 v162, v162
	v_rcp_f32_e32 v163, v163
	v_mul_f32_e32 v156, v156, v48
	v_mul_f32_e32 v157, v157, v49
	v_mul_f32_e32 v158, v158, v50
	v_mul_f32_e32 v159, v159, v51
	v_mul_f32_e32 v160, v160, v52
	v_mul_f32_e32 v161, v161, v53
	v_mul_f32_e32 v162, v162, v54
	v_mul_f32_e32 v163, v163, v55
	v_and_b32_sdwa v216, v156, v185 dst_sel:DWORD dst_unused:UNUSED_PAD src0_sel:WORD_1 src1_sel:DWORD
	v_and_b32_sdwa v217, v157, v185 dst_sel:DWORD dst_unused:UNUSED_PAD src0_sel:WORD_1 src1_sel:DWORD
	v_and_b32_sdwa v218, v158, v185 dst_sel:DWORD dst_unused:UNUSED_PAD src0_sel:WORD_1 src1_sel:DWORD
	v_and_b32_sdwa v219, v159, v185 dst_sel:DWORD dst_unused:UNUSED_PAD src0_sel:WORD_1 src1_sel:DWORD
	v_and_b32_sdwa v220, v160, v185 dst_sel:DWORD dst_unused:UNUSED_PAD src0_sel:WORD_1 src1_sel:DWORD
	v_and_b32_sdwa v221, v161, v185 dst_sel:DWORD dst_unused:UNUSED_PAD src0_sel:WORD_1 src1_sel:DWORD
	v_and_b32_sdwa v222, v162, v185 dst_sel:DWORD dst_unused:UNUSED_PAD src0_sel:WORD_1 src1_sel:DWORD
	v_and_b32_sdwa v223, v163, v185 dst_sel:DWORD dst_unused:UNUSED_PAD src0_sel:WORD_1 src1_sel:DWORD
	v_add3_u32 v156, v156, v216, s46
	v_add3_u32 v157, v157, v217, s46
	v_add3_u32 v158, v158, v218, s46
	v_add3_u32 v159, v159, v219, s46
	v_add3_u32 v160, v160, v220, s46
	v_add3_u32 v161, v161, v221, s46
	v_add3_u32 v162, v162, v222, s46
	v_add3_u32 v163, v163, v223, s46
	v_and_b32_e32 v157, 0xffff0000, v157
	v_and_b32_e32 v159, 0xffff0000, v159
	v_and_b32_e32 v161, 0xffff0000, v161
	v_and_b32_e32 v163, 0xffff0000, v163
	v_or_b32_sdwa v176, v157, v156 dst_sel:DWORD dst_unused:UNUSED_PAD src0_sel:DWORD src1_sel:WORD_1
	v_or_b32_sdwa v177, v159, v158 dst_sel:DWORD dst_unused:UNUSED_PAD src0_sel:DWORD src1_sel:WORD_1
	v_or_b32_sdwa v178, v161, v160 dst_sel:DWORD dst_unused:UNUSED_PAD src0_sel:DWORD src1_sel:WORD_1
	v_or_b32_sdwa v179, v163, v162 dst_sel:DWORD dst_unused:UNUSED_PAD src0_sel:DWORD src1_sel:WORD_1
	global_store_dwordx4 v[210:211], v[176:179], off
	v_lshlrev_b32_e32 v156, 16, v136
	v_and_b32_e32 v157, 0xffff0000, v136
	v_lshlrev_b32_e32 v158, 16, v137
	v_and_b32_e32 v159, 0xffff0000, v137
	v_lshlrev_b32_e32 v160, 16, v138
; __device__ __forceinline__ float sigmoidf_(float x) { return __builtin_amdgcn_rcpf(1.0f + __expf(-x)); }
; __device__ __forceinline__ void unpack8(const uint4 u, float (&f)[8]) { f[0] = bflo(u.x); f[1] = bfhi(u.x); f[2] = bflo(u.y); f[3] = bfhi(u.y); f[4] = bflo(u.z); f[5] = bfhi(u.z); f[6] = bflo(u.w); f[7] = bfhi(u.w); }
; __device__ __forceinline__ uint4 pack8(const float (&f)[8]) { uint4 u; u.x = pack2(f[0], f[1]); u.y = pack2(f[2], f[3]); u.z = pack2(f[4], f[5]); u.w = pack2(f[6], f[7]); return u; }
;     __device__ __forceinline__ void operator()(const f32x4 (&acc)[2][2][4][2], const Unit& u, int wr, int wc, int fr, int fq) const {
;         EPIP_ROWS( float gr[8]; unpack8(*(const uint4*)(gate + row * LDP + C_GR + col8 + co), gr); float o[8];
;             _Pragma("unroll") for (int e = 0; e < 4; ++e) { o[e] = sigmoidf_(fminf(fmaxf(gr[e], -30.f), 30.f)) * v0[e]; o[4 + e] = sigmoidf_(fminf(fmaxf(gr[4 + e], -30.f), 30.f)) * v1[e]; }
;             *(uint4*)(O + row * DM + col8 + co) = pack8(o); )
;     }
	v_and_b32_e32 v161, 0xffff0000, v138
	v_lshlrev_b32_e32 v162, 16, v139
	v_and_b32_e32 v163, 0xffff0000, v139
	v_max_f32_e32 v156, v156, v156
	v_max_f32_e32 v157, v157, v157
	v_max_f32_e32 v158, v158, v158
	v_max_f32_e32 v159, v159, v159
	v_max_f32_e32 v160, v160, v160
	v_max_f32_e32 v161, v161, v161
	v_max_f32_e32 v162, v162, v162
	v_max_f32_e32 v163, v163, v163
	v_med3_f32 v156, v156, s48, v192
	v_med3_f32 v157, v157, s48, v192
	v_med3_f32 v158, v158, s48, v192
	v_med3_f32 v159, v159, s48, v192
	v_med3_f32 v160, v160, s48, v192
	v_med3_f32 v161, v161, s48, v192
	v_med3_f32 v162, v162, s48, v192
	v_med3_f32 v163, v163, s48, v192
	v_mul_f32_e32 v156, 0xbfb8aa3b, v156
	v_mul_f32_e32 v157, 0xbfb8aa3b, v157
	v_mul_f32_e32 v158, 0xbfb8aa3b, v158
	v_mul_f32_e32 v159, 0xbfb8aa3b, v159
	v_mul_f32_e32 v160, 0xbfb8aa3b, v160
	v_mul_f32_e32 v161, 0xbfb8aa3b, v161
	v_mul_f32_e32 v162, 0xbfb8aa3b, v162
	v_mul_f32_e32 v163, 0xbfb8aa3b, v163
	v_exp_f32_e32 v156, v156
	v_exp_f32_e32 v157, v157
	v_exp_f32_e32 v158, v158
	v_exp_f32_e32 v159, v159
	v_exp_f32_e32 v160, v160
	v_exp_f32_e32 v161, v161
	v_exp_f32_e32 v162, v162
	v_exp_f32_e32 v163, v163
	v_add_f32_e32 v156, 1.0, v156
	v_add_f32_e32 v157, 1.0, v157
	v_add_f32_e32 v158, 1.0, v158
	v_add_f32_e32 v159, 1.0, v159
	v_add_f32_e32 v160, 1.0, v160
	v_add_f32_e32 v161, 1.0, v161
	v_add_f32_e32 v162, 1.0, v162
	v_add_f32_e32 v163, 1.0, v163
	v_rcp_f32_e32 v156, v156
	v_rcp_f32_e32 v157, v157
	v_rcp_f32_e32 v158, v158
	v_rcp_f32_e32 v159, v159
	v_rcp_f32_e32 v160, v160
	v_rcp_f32_e32 v161, v161
	v_rcp_f32_e32 v162, v162
	v_rcp_f32_e32 v163, v163
	v_mul_f32_e32 v156, v156, v80
	v_mul_f32_e32 v157, v157, v81
	v_mul_f32_e32 v158, v158, v82
	v_mul_f32_e32 v159, v159, v83
	v_mul_f32_e32 v160, v160, v84
	v_mul_f32_e32 v161, v161, v85
	v_mul_f32_e32 v162, v162, v86
	v_mul_f32_e32 v163, v163, v87
	v_and_b32_sdwa v216, v156, v185 dst_sel:DWORD dst_unused:UNUSED_PAD src0_sel:WORD_1 src1_sel:DWORD
	v_and_b32_sdwa v217, v157, v185 dst_sel:DWORD dst_unused:UNUSED_PAD src0_sel:WORD_1 src1_sel:DWORD
	v_and_b32_sdwa v218, v158, v185 dst_sel:DWORD dst_unused:UNUSED_PAD src0_sel:WORD_1 src1_sel:DWORD
	v_and_b32_sdwa v219, v159, v185 dst_sel:DWORD dst_unused:UNUSED_PAD src0_sel:WORD_1 src1_sel:DWORD
	v_and_b32_sdwa v220, v160, v185 dst_sel:DWORD dst_unused:UNUSED_PAD src0_sel:WORD_1 src1_sel:DWORD
	v_and_b32_sdwa v221, v161, v185 dst_sel:DWORD dst_unused:UNUSED_PAD src0_sel:WORD_1 src1_sel:DWORD
	v_and_b32_sdwa v222, v162, v185 dst_sel:DWORD dst_unused:UNUSED_PAD src0_sel:WORD_1 src1_sel:DWORD
	v_and_b32_sdwa v223, v163, v185 dst_sel:DWORD dst_unused:UNUSED_PAD src0_sel:WORD_1 src1_sel:DWORD
	v_add3_u32 v156, v156, v216, s46
	v_add3_u32 v157, v157, v217, s46
	v_add3_u32 v158, v158, v218, s46
	v_add3_u32 v159, v159, v219, s46
	v_add3_u32 v160, v160, v220, s46
	v_add3_u32 v161, v161, v221, s46
	v_add3_u32 v162, v162, v222, s46
	v_add3_u32 v163, v163, v223, s46
	v_and_b32_e32 v157, 0xffff0000, v157
	v_and_b32_e32 v159, 0xffff0000, v159
	v_and_b32_e32 v161, 0xffff0000, v161
	v_and_b32_e32 v163, 0xffff0000, v163
	v_or_b32_sdwa v224, v157, v156 dst_sel:DWORD dst_unused:UNUSED_PAD src0_sel:DWORD src1_sel:WORD_1
	v_or_b32_sdwa v225, v159, v158 dst_sel:DWORD dst_unused:UNUSED_PAD src0_sel:DWORD src1_sel:WORD_1
	v_or_b32_sdwa v226, v161, v160 dst_sel:DWORD dst_unused:UNUSED_PAD src0_sel:DWORD src1_sel:WORD_1
	v_or_b32_sdwa v227, v163, v162 dst_sel:DWORD dst_unused:UNUSED_PAD src0_sel:DWORD src1_sel:WORD_1
	global_store_dwordx4 v[210:211], v[224:227], off offset:256
	s_mov_b64 s[0:1], 0x18e300
	v_lshl_add_u64 v[2:3], v[208:209], 0, s[0:1]
	global_load_dwordx4 v[132:135], v[2:3], off
	global_load_dwordx4 v[136:139], v[2:3], off offset:256
	s_mov_b64 s[0:1], 0x8000
	v_lshl_add_u64 v[212:213], v[206:207], 0, s[0:1]
	s_waitcnt vmcnt(10)
	v_lshlrev_b32_e32 v156, 16, v140
	v_and_b32_e32 v157, 0xffff0000, v140
	v_lshlrev_b32_e32 v158, 16, v141
	v_and_b32_e32 v159, 0xffff0000, v141
	v_lshlrev_b32_e32 v160, 16, v142
	v_and_b32_e32 v161, 0xffff0000, v142
	v_lshlrev_b32_e32 v162, 16, v143
	v_and_b32_e32 v163, 0xffff0000, v143
	v_max_f32_e32 v156, v156, v156
	v_max_f32_e32 v157, v157, v157
	v_max_f32_e32 v158, v158, v158
	v_max_f32_e32 v159, v159, v159
	v_max_f32_e32 v160, v160, v160
	v_max_f32_e32 v161, v161, v161
	v_max_f32_e32 v162, v162, v162
	v_max_f32_e32 v163, v163, v163
	v_med3_f32 v156, v156, s48, v192
	v_med3_f32 v157, v157, s48, v192
	v_med3_f32 v158, v158, s48, v192
	v_med3_f32 v159, v159, s48, v192
	v_med3_f32 v160, v160, s48, v192
	v_med3_f32 v161, v161, s48, v192
	v_med3_f32 v162, v162, s48, v192
	v_med3_f32 v163, v163, s48, v192
	v_mul_f32_e32 v156, 0xbfb8aa3b, v156
	v_mul_f32_e32 v157, 0xbfb8aa3b, v157
	v_mul_f32_e32 v158, 0xbfb8aa3b, v158
	v_mul_f32_e32 v159, 0xbfb8aa3b, v159
	v_mul_f32_e32 v160, 0xbfb8aa3b, v160
	v_mul_f32_e32 v161, 0xbfb8aa3b, v161
	v_mul_f32_e32 v162, 0xbfb8aa3b, v162
	v_mul_f32_e32 v163, 0xbfb8aa3b, v163
	v_exp_f32_e32 v156, v156
	v_exp_f32_e32 v157, v157
	v_exp_f32_e32 v158, v158
	v_exp_f32_e32 v159, v159
	v_exp_f32_e32 v160, v160
	v_exp_f32_e32 v161, v161
	v_exp_f32_e32 v162, v162
	v_exp_f32_e32 v163, v163
	v_add_f32_e32 v156, 1.0, v156
	v_add_f32_e32 v157, 1.0, v157
	v_add_f32_e32 v158, 1.0, v158
	v_add_f32_e32 v159, 1.0, v159
	v_add_f32_e32 v160, 1.0, v160
	v_add_f32_e32 v161, 1.0, v161
	v_add_f32_e32 v162, 1.0, v162
	v_add_f32_e32 v163, 1.0, v163
	v_rcp_f32_e32 v156, v156
	v_rcp_f32_e32 v157, v157
	v_rcp_f32_e32 v158, v158
	v_rcp_f32_e32 v159, v159
	v_rcp_f32_e32 v160, v160
	v_rcp_f32_e32 v161, v161
	v_rcp_f32_e32 v162, v162
	v_rcp_f32_e32 v163, v163
	v_mul_f32_e32 v156, v156, v56
	v_mul_f32_e32 v157, v157, v57
; __device__ __forceinline__ float sigmoidf_(float x) { return __builtin_amdgcn_rcpf(1.0f + __expf(-x)); }
; __device__ __forceinline__ void unpack8(const uint4 u, float (&f)[8]) { f[0] = bflo(u.x); f[1] = bfhi(u.x); f[2] = bflo(u.y); f[3] = bfhi(u.y); f[4] = bflo(u.z); f[5] = bfhi(u.z); f[6] = bflo(u.w); f[7] = bfhi(u.w); }
; __device__ __forceinline__ uint4 pack8(const float (&f)[8]) { uint4 u; u.x = pack2(f[0], f[1]); u.y = pack2(f[2], f[3]); u.z = pack2(f[4], f[5]); u.w = pack2(f[6], f[7]); return u; }
;     __device__ __forceinline__ void operator()(const f32x4 (&acc)[2][2][4][2], const Unit& u, int wr, int wc, int fr, int fq) const {
;         EPIP_ROWS( float gr[8]; unpack8(*(const uint4*)(gate + row * LDP + C_GR + col8 + co), gr); float o[8];
;             _Pragma("unroll") for (int e = 0; e < 4; ++e) { o[e] = sigmoidf_(fminf(fmaxf(gr[e], -30.f), 30.f)) * v0[e]; o[4 + e] = sigmoidf_(fminf(fmaxf(gr[4 + e], -30.f), 30.f)) * v1[e]; }
;             *(uint4*)(O + row * DM + col8 + co) = pack8(o); )
;     }
	v_mul_f32_e32 v158, v158, v58
	v_mul_f32_e32 v159, v159, v59
	v_mul_f32_e32 v160, v160, v60
	v_mul_f32_e32 v161, v161, v61
	v_mul_f32_e32 v162, v162, v62
	v_mul_f32_e32 v163, v163, v63
	v_and_b32_sdwa v216, v156, v185 dst_sel:DWORD dst_unused:UNUSED_PAD src0_sel:WORD_1 src1_sel:DWORD
	v_and_b32_sdwa v217, v157, v185 dst_sel:DWORD dst_unused:UNUSED_PAD src0_sel:WORD_1 src1_sel:DWORD
	v_and_b32_sdwa v218, v158, v185 dst_sel:DWORD dst_unused:UNUSED_PAD src0_sel:WORD_1 src1_sel:DWORD
	v_and_b32_sdwa v219, v159, v185 dst_sel:DWORD dst_unused:UNUSED_PAD src0_sel:WORD_1 src1_sel:DWORD
	v_and_b32_sdwa v220, v160, v185 dst_sel:DWORD dst_unused:UNUSED_PAD src0_sel:WORD_1 src1_sel:DWORD
	v_and_b32_sdwa v221, v161, v185 dst_sel:DWORD dst_unused:UNUSED_PAD src0_sel:WORD_1 src1_sel:DWORD
	v_and_b32_sdwa v222, v162, v185 dst_sel:DWORD dst_unused:UNUSED_PAD src0_sel:WORD_1 src1_sel:DWORD
	v_and_b32_sdwa v223, v163, v185 dst_sel:DWORD dst_unused:UNUSED_PAD src0_sel:WORD_1 src1_sel:DWORD
	v_add3_u32 v156, v156, v216, s46
	v_add3_u32 v157, v157, v217, s46
	v_add3_u32 v158, v158, v218, s46
	v_add3_u32 v159, v159, v219, s46
	v_add3_u32 v160, v160, v220, s46
	v_add3_u32 v161, v161, v221, s46
	v_add3_u32 v162, v162, v222, s46
	v_add3_u32 v163, v163, v223, s46
	v_and_b32_e32 v157, 0xffff0000, v157
	v_and_b32_e32 v159, 0xffff0000, v159
	v_and_b32_e32 v161, 0xffff0000, v161
	v_and_b32_e32 v163, 0xffff0000, v163
	v_or_b32_sdwa v176, v157, v156 dst_sel:DWORD dst_unused:UNUSED_PAD src0_sel:DWORD src1_sel:WORD_1
	v_or_b32_sdwa v177, v159, v158 dst_sel:DWORD dst_unused:UNUSED_PAD src0_sel:DWORD src1_sel:WORD_1
	v_or_b32_sdwa v178, v161, v160 dst_sel:DWORD dst_unused:UNUSED_PAD src0_sel:DWORD src1_sel:WORD_1
	v_or_b32_sdwa v179, v163, v162 dst_sel:DWORD dst_unused:UNUSED_PAD src0_sel:DWORD src1_sel:WORD_1
	global_store_dwordx4 v[212:213], v[176:179], off
	v_lshlrev_b32_e32 v156, 16, v144
	v_and_b32_e32 v157, 0xffff0000, v144
	v_lshlrev_b32_e32 v158, 16, v145
	v_and_b32_e32 v159, 0xffff0000, v145
	v_lshlrev_b32_e32 v160, 16, v146
	v_and_b32_e32 v161, 0xffff0000, v146
	v_lshlrev_b32_e32 v162, 16, v147
	v_and_b32_e32 v163, 0xffff0000, v147
	v_max_f32_e32 v156, v156, v156
	v_max_f32_e32 v157, v157, v157
	v_max_f32_e32 v158, v158, v158
	v_max_f32_e32 v159, v159, v159
	v_max_f32_e32 v160, v160, v160
	v_max_f32_e32 v161, v161, v161
	v_max_f32_e32 v162, v162, v162
	v_max_f32_e32 v163, v163, v163
	v_med3_f32 v156, v156, s48, v192
	v_med3_f32 v157, v157, s48, v192
	v_med3_f32 v158, v158, s48, v192
	v_med3_f32 v159, v159, s48, v192
	v_med3_f32 v160, v160, s48, v192
	v_med3_f32 v161, v161, s48, v192
	v_med3_f32 v162, v162, s48, v192
	v_med3_f32 v163, v163, s48, v192
	v_mul_f32_e32 v156, 0xbfb8aa3b, v156
	v_mul_f32_e32 v157, 0xbfb8aa3b, v157
	v_mul_f32_e32 v158, 0xbfb8aa3b, v158
	v_mul_f32_e32 v159, 0xbfb8aa3b, v159
	v_mul_f32_e32 v160, 0xbfb8aa3b, v160
	v_mul_f32_e32 v161, 0xbfb8aa3b, v161
	v_mul_f32_e32 v162, 0xbfb8aa3b, v162
	v_mul_f32_e32 v163, 0xbfb8aa3b, v163
	v_exp_f32_e32 v156, v156
	v_exp_f32_e32 v157, v157
	v_exp_f32_e32 v158, v158
	v_exp_f32_e32 v159, v159
	v_exp_f32_e32 v160, v160
	v_exp_f32_e32 v161, v161
	v_exp_f32_e32 v162, v162
	v_exp_f32_e32 v163, v163
	v_add_f32_e32 v156, 1.0, v156
	v_add_f32_e32 v157, 1.0, v157
	v_add_f32_e32 v158, 1.0, v158
	v_add_f32_e32 v159, 1.0, v159
	v_add_f32_e32 v160, 1.0, v160
	v_add_f32_e32 v161, 1.0, v161
	v_add_f32_e32 v162, 1.0, v162
	v_add_f32_e32 v163, 1.0, v163
	v_rcp_f32_e32 v156, v156
	v_rcp_f32_e32 v157, v157
	v_rcp_f32_e32 v158, v158
	v_rcp_f32_e32 v159, v159
	v_rcp_f32_e32 v160, v160
	v_rcp_f32_e32 v161, v161
	v_rcp_f32_e32 v162, v162
	v_rcp_f32_e32 v163, v163
	v_mul_f32_e32 v156, v156, v88
	v_mul_f32_e32 v157, v157, v89
	v_mul_f32_e32 v158, v158, v90
	v_mul_f32_e32 v159, v159, v91
	v_mul_f32_e32 v160, v160, v92
	v_mul_f32_e32 v161, v161, v93
	v_mul_f32_e32 v162, v162, v94
	v_mul_f32_e32 v163, v163, v95
	v_and_b32_sdwa v216, v156, v185 dst_sel:DWORD dst_unused:UNUSED_PAD src0_sel:WORD_1 src1_sel:DWORD
	v_and_b32_sdwa v217, v157, v185 dst_sel:DWORD dst_unused:UNUSED_PAD src0_sel:WORD_1 src1_sel:DWORD
	v_and_b32_sdwa v218, v158, v185 dst_sel:DWORD dst_unused:UNUSED_PAD src0_sel:WORD_1 src1_sel:DWORD
	v_and_b32_sdwa v219, v159, v185 dst_sel:DWORD dst_unused:UNUSED_PAD src0_sel:WORD_1 src1_sel:DWORD
	v_and_b32_sdwa v220, v160, v185 dst_sel:DWORD dst_unused:UNUSED_PAD src0_sel:WORD_1 src1_sel:DWORD
	v_and_b32_sdwa v221, v161, v185 dst_sel:DWORD dst_unused:UNUSED_PAD src0_sel:WORD_1 src1_sel:DWORD
	v_and_b32_sdwa v222, v162, v185 dst_sel:DWORD dst_unused:UNUSED_PAD src0_sel:WORD_1 src1_sel:DWORD
	v_and_b32_sdwa v223, v163, v185 dst_sel:DWORD dst_unused:UNUSED_PAD src0_sel:WORD_1 src1_sel:DWORD
	v_add3_u32 v156, v156, v216, s46
	v_add3_u32 v157, v157, v217, s46
	v_add3_u32 v158, v158, v218, s46
	v_add3_u32 v159, v159, v219, s46
	v_add3_u32 v160, v160, v220, s46
	v_add3_u32 v161, v161, v221, s46
	v_add3_u32 v162, v162, v222, s46
	v_add3_u32 v163, v163, v223, s46
	v_and_b32_e32 v157, 0xffff0000, v157
	v_and_b32_e32 v159, 0xffff0000, v159
	v_and_b32_e32 v161, 0xffff0000, v161
	v_and_b32_e32 v163, 0xffff0000, v163
	v_or_b32_sdwa v224, v157, v156 dst_sel:DWORD dst_unused:UNUSED_PAD src0_sel:DWORD src1_sel:WORD_1
	v_or_b32_sdwa v225, v159, v158 dst_sel:DWORD dst_unused:UNUSED_PAD src0_sel:DWORD src1_sel:WORD_1
	v_or_b32_sdwa v226, v161, v160 dst_sel:DWORD dst_unused:UNUSED_PAD src0_sel:DWORD src1_sel:WORD_1
	v_or_b32_sdwa v227, v163, v162 dst_sel:DWORD dst_unused:UNUSED_PAD src0_sel:DWORD src1_sel:WORD_1
	global_store_dwordx4 v[212:213], v[224:227], off offset:256
	s_mov_b64 s[0:1], 0x1ba300
	v_lshl_add_u64 v[2:3], v[208:209], 0, s[0:1]
	global_load_dwordx4 v[140:143], v[2:3], off
	global_load_dwordx4 v[144:147], v[2:3], off offset:256
	s_mov_b64 s[0:1], 0x10000
	v_lshl_add_u64 v[210:211], v[206:207], 0, s[0:1]
	s_waitcnt vmcnt(12)
; __device__ __forceinline__ float sigmoidf_(float x) { return __builtin_amdgcn_rcpf(1.0f + __expf(-x)); }
; __device__ __forceinline__ void unpack8(const uint4 u, float (&f)[8]) { f[0] = bflo(u.x); f[1] = bfhi(u.x); f[2] = bflo(u.y); f[3] = bfhi(u.y); f[4] = bflo(u.z); f[5] = bfhi(u.z); f[6] = bflo(u.w); f[7] = bfhi(u.w); }
; __device__ __forceinline__ uint4 pack8(const float (&f)[8]) { uint4 u; u.x = pack2(f[0], f[1]); u.y = pack2(f[2], f[3]); u.z = pack2(f[4], f[5]); u.w = pack2(f[6], f[7]); return u; }
;     __device__ __forceinline__ void operator()(const f32x4 (&acc)[2][2][4][2], const Unit& u, int wr, int wc, int fr, int fq) const {
;         EPIP_ROWS( float gr[8]; unpack8(*(const uint4*)(gate + row * LDP + C_GR + col8 + co), gr); float o[8];
;             _Pragma("unroll") for (int e = 0; e < 4; ++e) { o[e] = sigmoidf_(fminf(fmaxf(gr[e], -30.f), 30.f)) * v0[e]; o[4 + e] = sigmoidf_(fminf(fmaxf(gr[4 + e], -30.f), 30.f)) * v1[e]; }
;             *(uint4*)(O + row * DM + col8 + co) = pack8(o); )
;     }
	v_lshlrev_b32_e32 v156, 16, v148
	v_and_b32_e32 v157, 0xffff0000, v148
	v_lshlrev_b32_e32 v158, 16, v149
	v_and_b32_e32 v159, 0xffff0000, v149
	v_lshlrev_b32_e32 v160, 16, v150
	v_and_b32_e32 v161, 0xffff0000, v150
	v_lshlrev_b32_e32 v162, 16, v151
	v_and_b32_e32 v163, 0xffff0000, v151
	v_max_f32_e32 v156, v156, v156
	v_max_f32_e32 v157, v157, v157
	v_max_f32_e32 v158, v158, v158
	v_max_f32_e32 v159, v159, v159
	v_max_f32_e32 v160, v160, v160
	v_max_f32_e32 v161, v161, v161
	v_max_f32_e32 v162, v162, v162
	v_max_f32_e32 v163, v163, v163
	v_med3_f32 v156, v156, s48, v192
	v_med3_f32 v157, v157, s48, v192
	v_med3_f32 v158, v158, s48, v192
	v_med3_f32 v159, v159, s48, v192
	v_med3_f32 v160, v160, s48, v192
	v_med3_f32 v161, v161, s48, v192
	v_med3_f32 v162, v162, s48, v192
	v_med3_f32 v163, v163, s48, v192
	v_mul_f32_e32 v156, 0xbfb8aa3b, v156
	v_mul_f32_e32 v157, 0xbfb8aa3b, v157
	v_mul_f32_e32 v158, 0xbfb8aa3b, v158
	v_mul_f32_e32 v159, 0xbfb8aa3b, v159
	v_mul_f32_e32 v160, 0xbfb8aa3b, v160
	v_mul_f32_e32 v161, 0xbfb8aa3b, v161
	v_mul_f32_e32 v162, 0xbfb8aa3b, v162
	v_mul_f32_e32 v163, 0xbfb8aa3b, v163
	v_exp_f32_e32 v156, v156
	v_exp_f32_e32 v157, v157
	v_exp_f32_e32 v158, v158
	v_exp_f32_e32 v159, v159
	v_exp_f32_e32 v160, v160
	v_exp_f32_e32 v161, v161
	v_exp_f32_e32 v162, v162
	v_exp_f32_e32 v163, v163
	v_add_f32_e32 v156, 1.0, v156
	v_add_f32_e32 v157, 1.0, v157
	v_add_f32_e32 v158, 1.0, v158
	v_add_f32_e32 v159, 1.0, v159
	v_add_f32_e32 v160, 1.0, v160
	v_add_f32_e32 v161, 1.0, v161
	v_add_f32_e32 v162, 1.0, v162
	v_add_f32_e32 v163, 1.0, v163
	v_rcp_f32_e32 v156, v156
	v_rcp_f32_e32 v157, v157
	v_rcp_f32_e32 v158, v158
	v_rcp_f32_e32 v159, v159
	v_rcp_f32_e32 v160, v160
	v_rcp_f32_e32 v161, v161
	v_rcp_f32_e32 v162, v162
	v_rcp_f32_e32 v163, v163
	v_mul_f32_e32 v156, v156, v64
	v_mul_f32_e32 v157, v157, v65
	v_mul_f32_e32 v158, v158, v66
	v_mul_f32_e32 v159, v159, v67
	v_mul_f32_e32 v160, v160, v68
	v_mul_f32_e32 v161, v161, v69
	v_mul_f32_e32 v162, v162, v70
	v_mul_f32_e32 v163, v163, v71
	v_and_b32_sdwa v216, v156, v185 dst_sel:DWORD dst_unused:UNUSED_PAD src0_sel:WORD_1 src1_sel:DWORD
	v_and_b32_sdwa v217, v157, v185 dst_sel:DWORD dst_unused:UNUSED_PAD src0_sel:WORD_1 src1_sel:DWORD
	v_and_b32_sdwa v218, v158, v185 dst_sel:DWORD dst_unused:UNUSED_PAD src0_sel:WORD_1 src1_sel:DWORD
	v_and_b32_sdwa v219, v159, v185 dst_sel:DWORD dst_unused:UNUSED_PAD src0_sel:WORD_1 src1_sel:DWORD
	v_and_b32_sdwa v220, v160, v185 dst_sel:DWORD dst_unused:UNUSED_PAD src0_sel:WORD_1 src1_sel:DWORD
	v_and_b32_sdwa v221, v161, v185 dst_sel:DWORD dst_unused:UNUSED_PAD src0_sel:WORD_1 src1_sel:DWORD
	v_and_b32_sdwa v222, v162, v185 dst_sel:DWORD dst_unused:UNUSED_PAD src0_sel:WORD_1 src1_sel:DWORD
	v_and_b32_sdwa v223, v163, v185 dst_sel:DWORD dst_unused:UNUSED_PAD src0_sel:WORD_1 src1_sel:DWORD
	v_add3_u32 v156, v156, v216, s46
	v_add3_u32 v157, v157, v217, s46
	v_add3_u32 v158, v158, v218, s46
	v_add3_u32 v159, v159, v219, s46
	v_add3_u32 v160, v160, v220, s46
	v_add3_u32 v161, v161, v221, s46
	v_add3_u32 v162, v162, v222, s46
	v_add3_u32 v163, v163, v223, s46
	v_and_b32_e32 v157, 0xffff0000, v157
	v_and_b32_e32 v159, 0xffff0000, v159
	v_and_b32_e32 v161, 0xffff0000, v161
	v_and_b32_e32 v163, 0xffff0000, v163
	v_or_b32_sdwa v176, v157, v156 dst_sel:DWORD dst_unused:UNUSED_PAD src0_sel:DWORD src1_sel:WORD_1
	v_or_b32_sdwa v177, v159, v158 dst_sel:DWORD dst_unused:UNUSED_PAD src0_sel:DWORD src1_sel:WORD_1
	v_or_b32_sdwa v178, v161, v160 dst_sel:DWORD dst_unused:UNUSED_PAD src0_sel:DWORD src1_sel:WORD_1
	v_or_b32_sdwa v179, v163, v162 dst_sel:DWORD dst_unused:UNUSED_PAD src0_sel:DWORD src1_sel:WORD_1
	global_store_dwordx4 v[210:211], v[176:179], off
	v_lshlrev_b32_e32 v156, 16, v152
	v_and_b32_e32 v157, 0xffff0000, v152
	v_lshlrev_b32_e32 v158, 16, v153
	v_and_b32_e32 v159, 0xffff0000, v153
	v_lshlrev_b32_e32 v160, 16, v154
	v_and_b32_e32 v161, 0xffff0000, v154
	v_lshlrev_b32_e32 v162, 16, v155
	v_and_b32_e32 v163, 0xffff0000, v155
	v_max_f32_e32 v156, v156, v156
	v_max_f32_e32 v157, v157, v157
	v_max_f32_e32 v158, v158, v158
	v_max_f32_e32 v159, v159, v159
	v_max_f32_e32 v160, v160, v160
	v_max_f32_e32 v161, v161, v161
	v_max_f32_e32 v162, v162, v162
	v_max_f32_e32 v163, v163, v163
	v_med3_f32 v156, v156, s48, v192
	v_med3_f32 v157, v157, s48, v192
	v_med3_f32 v158, v158, s48, v192
	v_med3_f32 v159, v159, s48, v192
	v_med3_f32 v160, v160, s48, v192
	v_med3_f32 v161, v161, s48, v192
	v_med3_f32 v162, v162, s48, v192
	v_med3_f32 v163, v163, s48, v192
	v_mul_f32_e32 v156, 0xbfb8aa3b, v156
	v_mul_f32_e32 v157, 0xbfb8aa3b, v157
	v_mul_f32_e32 v158, 0xbfb8aa3b, v158
	v_mul_f32_e32 v159, 0xbfb8aa3b, v159
	v_mul_f32_e32 v160, 0xbfb8aa3b, v160
	v_mul_f32_e32 v161, 0xbfb8aa3b, v161
	v_mul_f32_e32 v162, 0xbfb8aa3b, v162
	v_mul_f32_e32 v163, 0xbfb8aa3b, v163
	v_exp_f32_e32 v156, v156
	v_exp_f32_e32 v157, v157
	v_exp_f32_e32 v158, v158
	v_exp_f32_e32 v159, v159
	v_exp_f32_e32 v160, v160
	v_exp_f32_e32 v161, v161
	v_exp_f32_e32 v162, v162
	v_exp_f32_e32 v163, v163
	v_add_f32_e32 v156, 1.0, v156
	v_add_f32_e32 v157, 1.0, v157
	v_add_f32_e32 v158, 1.0, v158
	v_add_f32_e32 v159, 1.0, v159
	v_add_f32_e32 v160, 1.0, v160
	v_add_f32_e32 v161, 1.0, v161
	v_add_f32_e32 v162, 1.0, v162
	v_add_f32_e32 v163, 1.0, v163
	v_rcp_f32_e32 v156, v156
	v_rcp_f32_e32 v157, v157
	v_rcp_f32_e32 v158, v158
	v_rcp_f32_e32 v159, v159
	v_rcp_f32_e32 v160, v160
	v_rcp_f32_e32 v161, v161
	v_rcp_f32_e32 v162, v162
	v_rcp_f32_e32 v163, v163
	v_mul_f32_e32 v156, v156, v96
	v_mul_f32_e32 v157, v157, v97
	v_mul_f32_e32 v158, v158, v98
	v_mul_f32_e32 v159, v159, v99
	v_mul_f32_e32 v160, v160, v100
; __device__ __forceinline__ float sigmoidf_(float x) { return __builtin_amdgcn_rcpf(1.0f + __expf(-x)); }
; __device__ __forceinline__ void unpack8(const uint4 u, float (&f)[8]) { f[0] = bflo(u.x); f[1] = bfhi(u.x); f[2] = bflo(u.y); f[3] = bfhi(u.y); f[4] = bflo(u.z); f[5] = bfhi(u.z); f[6] = bflo(u.w); f[7] = bfhi(u.w); }
; __device__ __forceinline__ uint4 pack8(const float (&f)[8]) { uint4 u; u.x = pack2(f[0], f[1]); u.y = pack2(f[2], f[3]); u.z = pack2(f[4], f[5]); u.w = pack2(f[6], f[7]); return u; }
;     __device__ __forceinline__ void operator()(const f32x4 (&acc)[2][2][4][2], const Unit& u, int wr, int wc, int fr, int fq) const {
;         EPIP_ROWS( float gr[8]; unpack8(*(const uint4*)(gate + row * LDP + C_GR + col8 + co), gr); float o[8];
;             _Pragma("unroll") for (int e = 0; e < 4; ++e) { o[e] = sigmoidf_(fminf(fmaxf(gr[e], -30.f), 30.f)) * v0[e]; o[4 + e] = sigmoidf_(fminf(fmaxf(gr[4 + e], -30.f), 30.f)) * v1[e]; }
;             *(uint4*)(O + row * DM + col8 + co) = pack8(o); )
;     }
	v_mul_f32_e32 v161, v161, v101
	v_mul_f32_e32 v162, v162, v102
	v_mul_f32_e32 v163, v163, v103
	v_and_b32_sdwa v216, v156, v185 dst_sel:DWORD dst_unused:UNUSED_PAD src0_sel:WORD_1 src1_sel:DWORD
	v_and_b32_sdwa v217, v157, v185 dst_sel:DWORD dst_unused:UNUSED_PAD src0_sel:WORD_1 src1_sel:DWORD
	v_and_b32_sdwa v218, v158, v185 dst_sel:DWORD dst_unused:UNUSED_PAD src0_sel:WORD_1 src1_sel:DWORD
	v_and_b32_sdwa v219, v159, v185 dst_sel:DWORD dst_unused:UNUSED_PAD src0_sel:WORD_1 src1_sel:DWORD
	v_and_b32_sdwa v220, v160, v185 dst_sel:DWORD dst_unused:UNUSED_PAD src0_sel:WORD_1 src1_sel:DWORD
	v_and_b32_sdwa v221, v161, v185 dst_sel:DWORD dst_unused:UNUSED_PAD src0_sel:WORD_1 src1_sel:DWORD
	v_and_b32_sdwa v222, v162, v185 dst_sel:DWORD dst_unused:UNUSED_PAD src0_sel:WORD_1 src1_sel:DWORD
	v_and_b32_sdwa v223, v163, v185 dst_sel:DWORD dst_unused:UNUSED_PAD src0_sel:WORD_1 src1_sel:DWORD
	v_add3_u32 v156, v156, v216, s46
	v_add3_u32 v157, v157, v217, s46
	v_add3_u32 v158, v158, v218, s46
	v_add3_u32 v159, v159, v219, s46
	v_add3_u32 v160, v160, v220, s46
	v_add3_u32 v161, v161, v221, s46
	v_add3_u32 v162, v162, v222, s46
	v_add3_u32 v163, v163, v223, s46
	v_and_b32_e32 v157, 0xffff0000, v157
	v_and_b32_e32 v159, 0xffff0000, v159
	v_and_b32_e32 v161, 0xffff0000, v161
	v_and_b32_e32 v163, 0xffff0000, v163
	v_or_b32_sdwa v224, v157, v156 dst_sel:DWORD dst_unused:UNUSED_PAD src0_sel:DWORD src1_sel:WORD_1
	v_or_b32_sdwa v225, v159, v158 dst_sel:DWORD dst_unused:UNUSED_PAD src0_sel:DWORD src1_sel:WORD_1
	v_or_b32_sdwa v226, v161, v160 dst_sel:DWORD dst_unused:UNUSED_PAD src0_sel:DWORD src1_sel:WORD_1
	v_or_b32_sdwa v227, v163, v162 dst_sel:DWORD dst_unused:UNUSED_PAD src0_sel:DWORD src1_sel:WORD_1
	global_store_dwordx4 v[210:211], v[224:227], off offset:256
	s_mov_b64 s[0:1], 0x1e6300
	v_lshl_add_u64 v[2:3], v[208:209], 0, s[0:1]
	global_load_dwordx4 v[148:151], v[2:3], off
	global_load_dwordx4 v[152:155], v[2:3], off offset:256
	s_mov_b64 s[0:1], 0x18000
	v_lshl_add_u64 v[212:213], v[206:207], 0, s[0:1]
	s_waitcnt vmcnt(14)
	v_lshlrev_b32_e32 v156, 16, v228
	v_and_b32_e32 v157, 0xffff0000, v228
	v_lshlrev_b32_e32 v158, 16, v229
	v_and_b32_e32 v159, 0xffff0000, v229
	v_lshlrev_b32_e32 v160, 16, v230
	v_and_b32_e32 v161, 0xffff0000, v230
	v_lshlrev_b32_e32 v162, 16, v231
	v_and_b32_e32 v163, 0xffff0000, v231
	v_max_f32_e32 v156, v156, v156
	v_max_f32_e32 v157, v157, v157
	v_max_f32_e32 v158, v158, v158
	v_max_f32_e32 v159, v159, v159
	v_max_f32_e32 v160, v160, v160
	v_max_f32_e32 v161, v161, v161
	v_max_f32_e32 v162, v162, v162
	v_max_f32_e32 v163, v163, v163
	v_med3_f32 v156, v156, s48, v192
	v_med3_f32 v157, v157, s48, v192
	v_med3_f32 v158, v158, s48, v192
	v_med3_f32 v159, v159, s48, v192
	v_med3_f32 v160, v160, s48, v192
	v_med3_f32 v161, v161, s48, v192
	v_med3_f32 v162, v162, s48, v192
	v_med3_f32 v163, v163, s48, v192
	v_mul_f32_e32 v156, 0xbfb8aa3b, v156
	v_mul_f32_e32 v157, 0xbfb8aa3b, v157
	v_mul_f32_e32 v158, 0xbfb8aa3b, v158
	v_mul_f32_e32 v159, 0xbfb8aa3b, v159
	v_mul_f32_e32 v160, 0xbfb8aa3b, v160
	v_mul_f32_e32 v161, 0xbfb8aa3b, v161
	v_mul_f32_e32 v162, 0xbfb8aa3b, v162
	v_mul_f32_e32 v163, 0xbfb8aa3b, v163
	v_exp_f32_e32 v156, v156
	v_exp_f32_e32 v157, v157
	v_exp_f32_e32 v158, v158
	v_exp_f32_e32 v159, v159
	v_exp_f32_e32 v160, v160
	v_exp_f32_e32 v161, v161
	v_exp_f32_e32 v162, v162
	v_exp_f32_e32 v163, v163
	v_add_f32_e32 v156, 1.0, v156
	v_add_f32_e32 v157, 1.0, v157
	v_add_f32_e32 v158, 1.0, v158
	v_add_f32_e32 v159, 1.0, v159
	v_add_f32_e32 v160, 1.0, v160
	v_add_f32_e32 v161, 1.0, v161
	v_add_f32_e32 v162, 1.0, v162
	v_add_f32_e32 v163, 1.0, v163
	v_rcp_f32_e32 v156, v156
	v_rcp_f32_e32 v157, v157
	v_rcp_f32_e32 v158, v158
	v_rcp_f32_e32 v159, v159
	v_rcp_f32_e32 v160, v160
	v_rcp_f32_e32 v161, v161
	v_rcp_f32_e32 v162, v162
	v_rcp_f32_e32 v163, v163
	v_mul_f32_e32 v156, v156, v72
	v_mul_f32_e32 v157, v157, v73
	v_mul_f32_e32 v158, v158, v74
	v_mul_f32_e32 v159, v159, v75
	v_mul_f32_e32 v160, v160, v76
	v_mul_f32_e32 v161, v161, v77
	v_mul_f32_e32 v162, v162, v78
	v_mul_f32_e32 v163, v163, v79
	v_and_b32_sdwa v216, v156, v185 dst_sel:DWORD dst_unused:UNUSED_PAD src0_sel:WORD_1 src1_sel:DWORD
	v_and_b32_sdwa v217, v157, v185 dst_sel:DWORD dst_unused:UNUSED_PAD src0_sel:WORD_1 src1_sel:DWORD
	v_and_b32_sdwa v218, v158, v185 dst_sel:DWORD dst_unused:UNUSED_PAD src0_sel:WORD_1 src1_sel:DWORD
	v_and_b32_sdwa v219, v159, v185 dst_sel:DWORD dst_unused:UNUSED_PAD src0_sel:WORD_1 src1_sel:DWORD
	v_and_b32_sdwa v220, v160, v185 dst_sel:DWORD dst_unused:UNUSED_PAD src0_sel:WORD_1 src1_sel:DWORD
	v_and_b32_sdwa v221, v161, v185 dst_sel:DWORD dst_unused:UNUSED_PAD src0_sel:WORD_1 src1_sel:DWORD
	v_and_b32_sdwa v222, v162, v185 dst_sel:DWORD dst_unused:UNUSED_PAD src0_sel:WORD_1 src1_sel:DWORD
	v_and_b32_sdwa v223, v163, v185 dst_sel:DWORD dst_unused:UNUSED_PAD src0_sel:WORD_1 src1_sel:DWORD
	v_add3_u32 v156, v156, v216, s46
	v_add3_u32 v157, v157, v217, s46
	v_add3_u32 v158, v158, v218, s46
	v_add3_u32 v159, v159, v219, s46
	v_add3_u32 v160, v160, v220, s46
	v_add3_u32 v161, v161, v221, s46
	v_add3_u32 v162, v162, v222, s46
	v_add3_u32 v163, v163, v223, s46
	v_and_b32_e32 v157, 0xffff0000, v157
	v_and_b32_e32 v159, 0xffff0000, v159
	v_and_b32_e32 v161, 0xffff0000, v161
	v_and_b32_e32 v163, 0xffff0000, v163
	v_or_b32_sdwa v176, v157, v156 dst_sel:DWORD dst_unused:UNUSED_PAD src0_sel:DWORD src1_sel:WORD_1
	v_or_b32_sdwa v177, v159, v158 dst_sel:DWORD dst_unused:UNUSED_PAD src0_sel:DWORD src1_sel:WORD_1
	v_or_b32_sdwa v178, v161, v160 dst_sel:DWORD dst_unused:UNUSED_PAD src0_sel:DWORD src1_sel:WORD_1
; __device__ __forceinline__ float sigmoidf_(float x) { return __builtin_amdgcn_rcpf(1.0f + __expf(-x)); }
; __device__ __forceinline__ void unpack8(const uint4 u, float (&f)[8]) { f[0] = bflo(u.x); f[1] = bfhi(u.x); f[2] = bflo(u.y); f[3] = bfhi(u.y); f[4] = bflo(u.z); f[5] = bfhi(u.z); f[6] = bflo(u.w); f[7] = bfhi(u.w); }
; __device__ __forceinline__ uint4 pack8(const float (&f)[8]) { uint4 u; u.x = pack2(f[0], f[1]); u.y = pack2(f[2], f[3]); u.z = pack2(f[4], f[5]); u.w = pack2(f[6], f[7]); return u; }
;     __device__ __forceinline__ void operator()(const f32x4 (&acc)[2][2][4][2], const Unit& u, int wr, int wc, int fr, int fq) const {
;         EPIP_ROWS( float gr[8]; unpack8(*(const uint4*)(gate + row * LDP + C_GR + col8 + co), gr); float o[8];
;             _Pragma("unroll") for (int e = 0; e < 4; ++e) { o[e] = sigmoidf_(fminf(fmaxf(gr[e], -30.f), 30.f)) * v0[e]; o[4 + e] = sigmoidf_(fminf(fmaxf(gr[4 + e], -30.f), 30.f)) * v1[e]; }
;             *(uint4*)(O + row * DM + col8 + co) = pack8(o); )
;     }
	v_or_b32_sdwa v179, v163, v162 dst_sel:DWORD dst_unused:UNUSED_PAD src0_sel:DWORD src1_sel:WORD_1
	global_store_dwordx4 v[212:213], v[176:179], off
	v_lshlrev_b32_e32 v156, 16, v232
	v_and_b32_e32 v157, 0xffff0000, v232
	v_lshlrev_b32_e32 v158, 16, v233
	v_and_b32_e32 v159, 0xffff0000, v233
	v_lshlrev_b32_e32 v160, 16, v234
	v_and_b32_e32 v161, 0xffff0000, v234
	v_lshlrev_b32_e32 v162, 16, v235
	v_and_b32_e32 v163, 0xffff0000, v235
	v_max_f32_e32 v156, v156, v156
	v_max_f32_e32 v157, v157, v157
	v_max_f32_e32 v158, v158, v158
	v_max_f32_e32 v159, v159, v159
	v_max_f32_e32 v160, v160, v160
	v_max_f32_e32 v161, v161, v161
	v_max_f32_e32 v162, v162, v162
	v_max_f32_e32 v163, v163, v163
	v_med3_f32 v156, v156, s48, v192
	v_med3_f32 v157, v157, s48, v192
	v_med3_f32 v158, v158, s48, v192
	v_med3_f32 v159, v159, s48, v192
	v_med3_f32 v160, v160, s48, v192
	v_med3_f32 v161, v161, s48, v192
	v_med3_f32 v162, v162, s48, v192
	v_med3_f32 v163, v163, s48, v192
	v_mul_f32_e32 v156, 0xbfb8aa3b, v156
	v_mul_f32_e32 v157, 0xbfb8aa3b, v157
	v_mul_f32_e32 v158, 0xbfb8aa3b, v158
	v_mul_f32_e32 v159, 0xbfb8aa3b, v159
	v_mul_f32_e32 v160, 0xbfb8aa3b, v160
	v_mul_f32_e32 v161, 0xbfb8aa3b, v161
	v_mul_f32_e32 v162, 0xbfb8aa3b, v162
	v_mul_f32_e32 v163, 0xbfb8aa3b, v163
	v_exp_f32_e32 v156, v156
	v_exp_f32_e32 v157, v157
	v_exp_f32_e32 v158, v158
	v_exp_f32_e32 v159, v159
	v_exp_f32_e32 v160, v160
	v_exp_f32_e32 v161, v161
	v_exp_f32_e32 v162, v162
	v_exp_f32_e32 v163, v163
	v_add_f32_e32 v156, 1.0, v156
	v_add_f32_e32 v157, 1.0, v157
	v_add_f32_e32 v158, 1.0, v158
	v_add_f32_e32 v159, 1.0, v159
	v_add_f32_e32 v160, 1.0, v160
	v_add_f32_e32 v161, 1.0, v161
	v_add_f32_e32 v162, 1.0, v162
	v_add_f32_e32 v163, 1.0, v163
	v_rcp_f32_e32 v156, v156
	v_rcp_f32_e32 v157, v157
	v_rcp_f32_e32 v158, v158
	v_rcp_f32_e32 v159, v159
	v_rcp_f32_e32 v160, v160
	v_rcp_f32_e32 v161, v161
	v_rcp_f32_e32 v162, v162
	v_rcp_f32_e32 v163, v163
	v_mul_f32_e32 v156, v156, v104
	v_mul_f32_e32 v157, v157, v105
	v_mul_f32_e32 v158, v158, v106
	v_mul_f32_e32 v159, v159, v107
	v_mul_f32_e32 v160, v160, v108
	v_mul_f32_e32 v161, v161, v109
	v_mul_f32_e32 v162, v162, v110
	v_mul_f32_e32 v163, v163, v111
	v_and_b32_sdwa v216, v156, v185 dst_sel:DWORD dst_unused:UNUSED_PAD src0_sel:WORD_1 src1_sel:DWORD
	v_and_b32_sdwa v217, v157, v185 dst_sel:DWORD dst_unused:UNUSED_PAD src0_sel:WORD_1 src1_sel:DWORD
	v_and_b32_sdwa v218, v158, v185 dst_sel:DWORD dst_unused:UNUSED_PAD src0_sel:WORD_1 src1_sel:DWORD
	v_and_b32_sdwa v219, v159, v185 dst_sel:DWORD dst_unused:UNUSED_PAD src0_sel:WORD_1 src1_sel:DWORD
	v_and_b32_sdwa v220, v160, v185 dst_sel:DWORD dst_unused:UNUSED_PAD src0_sel:WORD_1 src1_sel:DWORD
	v_and_b32_sdwa v221, v161, v185 dst_sel:DWORD dst_unused:UNUSED_PAD src0_sel:WORD_1 src1_sel:DWORD
	v_and_b32_sdwa v222, v162, v185 dst_sel:DWORD dst_unused:UNUSED_PAD src0_sel:WORD_1 src1_sel:DWORD
	v_and_b32_sdwa v223, v163, v185 dst_sel:DWORD dst_unused:UNUSED_PAD src0_sel:WORD_1 src1_sel:DWORD
	v_add3_u32 v156, v156, v216, s46
	v_add3_u32 v157, v157, v217, s46
	v_add3_u32 v158, v158, v218, s46
	v_add3_u32 v159, v159, v219, s46
	v_add3_u32 v160, v160, v220, s46
	v_add3_u32 v161, v161, v221, s46
	v_add3_u32 v162, v162, v222, s46
	v_add3_u32 v163, v163, v223, s46
	v_and_b32_e32 v157, 0xffff0000, v157
	v_and_b32_e32 v159, 0xffff0000, v159
	v_and_b32_e32 v161, 0xffff0000, v161
	v_and_b32_e32 v163, 0xffff0000, v163
	v_or_b32_sdwa v224, v157, v156 dst_sel:DWORD dst_unused:UNUSED_PAD src0_sel:DWORD src1_sel:WORD_1
	v_or_b32_sdwa v225, v159, v158 dst_sel:DWORD dst_unused:UNUSED_PAD src0_sel:DWORD src1_sel:WORD_1
	v_or_b32_sdwa v226, v161, v160 dst_sel:DWORD dst_unused:UNUSED_PAD src0_sel:DWORD src1_sel:WORD_1
	v_or_b32_sdwa v227, v163, v162 dst_sel:DWORD dst_unused:UNUSED_PAD src0_sel:DWORD src1_sel:WORD_1
	global_store_dwordx4 v[212:213], v[224:227], off offset:256
	s_mov_b64 s[0:1], 0x40000
	v_lshl_add_u64 v[210:211], v[206:207], 0, s[0:1]
	s_waitcnt vmcnt(14)
	v_lshlrev_b32_e32 v156, 16, v236
	v_and_b32_e32 v157, 0xffff0000, v236
	v_lshlrev_b32_e32 v158, 16, v237
	v_and_b32_e32 v159, 0xffff0000, v237
	v_lshlrev_b32_e32 v160, 16, v238
	v_and_b32_e32 v161, 0xffff0000, v238
	v_lshlrev_b32_e32 v162, 16, v239
	v_and_b32_e32 v163, 0xffff0000, v239
	v_max_f32_e32 v156, v156, v156
	v_max_f32_e32 v157, v157, v157
	v_max_f32_e32 v158, v158, v158
	v_max_f32_e32 v159, v159, v159
	v_max_f32_e32 v160, v160, v160
	v_max_f32_e32 v161, v161, v161
	v_max_f32_e32 v162, v162, v162
	v_max_f32_e32 v163, v163, v163
	v_med3_f32 v156, v156, s48, v192
	v_med3_f32 v157, v157, s48, v192
	v_med3_f32 v158, v158, s48, v192
	v_med3_f32 v159, v159, s48, v192
	v_med3_f32 v160, v160, s48, v192
	v_med3_f32 v161, v161, s48, v192
	v_med3_f32 v162, v162, s48, v192
	v_med3_f32 v163, v163, s48, v192
	v_mul_f32_e32 v156, 0xbfb8aa3b, v156
	v_mul_f32_e32 v157, 0xbfb8aa3b, v157
	v_mul_f32_e32 v158, 0xbfb8aa3b, v158
	v_mul_f32_e32 v159, 0xbfb8aa3b, v159
	v_mul_f32_e32 v160, 0xbfb8aa3b, v160
	v_mul_f32_e32 v161, 0xbfb8aa3b, v161
	v_mul_f32_e32 v162, 0xbfb8aa3b, v162
	v_mul_f32_e32 v163, 0xbfb8aa3b, v163
	v_exp_f32_e32 v156, v156
	v_exp_f32_e32 v157, v157
	v_exp_f32_e32 v158, v158
	v_exp_f32_e32 v159, v159
	v_exp_f32_e32 v160, v160
	v_exp_f32_e32 v161, v161
	v_exp_f32_e32 v162, v162
	v_exp_f32_e32 v163, v163
	v_add_f32_e32 v156, 1.0, v156
	v_add_f32_e32 v157, 1.0, v157
	v_add_f32_e32 v158, 1.0, v158
	v_add_f32_e32 v159, 1.0, v159
	v_add_f32_e32 v160, 1.0, v160
	v_add_f32_e32 v161, 1.0, v161
	v_add_f32_e32 v162, 1.0, v162
	v_add_f32_e32 v163, 1.0, v163
	v_rcp_f32_e32 v156, v156
	v_rcp_f32_e32 v157, v157
	v_rcp_f32_e32 v158, v158
	v_rcp_f32_e32 v159, v159
; __device__ __forceinline__ float sigmoidf_(float x) { return __builtin_amdgcn_rcpf(1.0f + __expf(-x)); }
; __device__ __forceinline__ void unpack8(const uint4 u, float (&f)[8]) { f[0] = bflo(u.x); f[1] = bfhi(u.x); f[2] = bflo(u.y); f[3] = bfhi(u.y); f[4] = bflo(u.z); f[5] = bfhi(u.z); f[6] = bflo(u.w); f[7] = bfhi(u.w); }
; __device__ __forceinline__ uint4 pack8(const float (&f)[8]) { uint4 u; u.x = pack2(f[0], f[1]); u.y = pack2(f[2], f[3]); u.z = pack2(f[4], f[5]); u.w = pack2(f[6], f[7]); return u; }
;     __device__ __forceinline__ void operator()(const f32x4 (&acc)[2][2][4][2], const Unit& u, int wr, int wc, int fr, int fq) const {
;         EPIP_ROWS( float gr[8]; unpack8(*(const uint4*)(gate + row * LDP + C_GR + col8 + co), gr); float o[8];
;             _Pragma("unroll") for (int e = 0; e < 4; ++e) { o[e] = sigmoidf_(fminf(fmaxf(gr[e], -30.f), 30.f)) * v0[e]; o[4 + e] = sigmoidf_(fminf(fmaxf(gr[4 + e], -30.f), 30.f)) * v1[e]; }
;             *(uint4*)(O + row * DM + col8 + co) = pack8(o); )
;     }
	v_rcp_f32_e32 v160, v160
	v_rcp_f32_e32 v161, v161
	v_rcp_f32_e32 v162, v162
	v_rcp_f32_e32 v163, v163
	v_mul_f32_e32 v156, v156, v112
	v_mul_f32_e32 v157, v157, v113
	v_mul_f32_e32 v158, v158, v114
	v_mul_f32_e32 v159, v159, v115
	v_mul_f32_e32 v160, v160, v116
	v_mul_f32_e32 v161, v161, v117
	v_mul_f32_e32 v162, v162, v118
	v_mul_f32_e32 v163, v163, v119
	v_and_b32_sdwa v216, v156, v185 dst_sel:DWORD dst_unused:UNUSED_PAD src0_sel:WORD_1 src1_sel:DWORD
	v_and_b32_sdwa v217, v157, v185 dst_sel:DWORD dst_unused:UNUSED_PAD src0_sel:WORD_1 src1_sel:DWORD
	v_and_b32_sdwa v218, v158, v185 dst_sel:DWORD dst_unused:UNUSED_PAD src0_sel:WORD_1 src1_sel:DWORD
	v_and_b32_sdwa v219, v159, v185 dst_sel:DWORD dst_unused:UNUSED_PAD src0_sel:WORD_1 src1_sel:DWORD
	v_and_b32_sdwa v220, v160, v185 dst_sel:DWORD dst_unused:UNUSED_PAD src0_sel:WORD_1 src1_sel:DWORD
	v_and_b32_sdwa v221, v161, v185 dst_sel:DWORD dst_unused:UNUSED_PAD src0_sel:WORD_1 src1_sel:DWORD
	v_and_b32_sdwa v222, v162, v185 dst_sel:DWORD dst_unused:UNUSED_PAD src0_sel:WORD_1 src1_sel:DWORD
	v_and_b32_sdwa v223, v163, v185 dst_sel:DWORD dst_unused:UNUSED_PAD src0_sel:WORD_1 src1_sel:DWORD
	v_add3_u32 v156, v156, v216, s46
	v_add3_u32 v157, v157, v217, s46
	v_add3_u32 v158, v158, v218, s46
	v_add3_u32 v159, v159, v219, s46
	v_add3_u32 v160, v160, v220, s46
	v_add3_u32 v161, v161, v221, s46
	v_add3_u32 v162, v162, v222, s46
	v_add3_u32 v163, v163, v223, s46
	v_and_b32_e32 v157, 0xffff0000, v157
	v_and_b32_e32 v159, 0xffff0000, v159
	v_and_b32_e32 v161, 0xffff0000, v161
	v_and_b32_e32 v163, 0xffff0000, v163
	v_or_b32_sdwa v176, v157, v156 dst_sel:DWORD dst_unused:UNUSED_PAD src0_sel:DWORD src1_sel:WORD_1
	v_or_b32_sdwa v177, v159, v158 dst_sel:DWORD dst_unused:UNUSED_PAD src0_sel:DWORD src1_sel:WORD_1
	v_or_b32_sdwa v178, v161, v160 dst_sel:DWORD dst_unused:UNUSED_PAD src0_sel:DWORD src1_sel:WORD_1
	v_or_b32_sdwa v179, v163, v162 dst_sel:DWORD dst_unused:UNUSED_PAD src0_sel:DWORD src1_sel:WORD_1
	global_store_dwordx4 v[210:211], v[176:179], off
	v_lshlrev_b32_e32 v156, 16, v240
	v_and_b32_e32 v157, 0xffff0000, v240
	v_lshlrev_b32_e32 v158, 16, v241
	v_and_b32_e32 v159, 0xffff0000, v241
	v_lshlrev_b32_e32 v160, 16, v242
	v_and_b32_e32 v161, 0xffff0000, v242
	v_lshlrev_b32_e32 v162, 16, v243
	v_and_b32_e32 v163, 0xffff0000, v243
	v_max_f32_e32 v156, v156, v156
	v_max_f32_e32 v157, v157, v157
	v_max_f32_e32 v158, v158, v158
	v_max_f32_e32 v159, v159, v159
	v_max_f32_e32 v160, v160, v160
	v_max_f32_e32 v161, v161, v161
	v_max_f32_e32 v162, v162, v162
	v_max_f32_e32 v163, v163, v163
	v_med3_f32 v156, v156, s48, v192
	v_med3_f32 v157, v157, s48, v192
	v_med3_f32 v158, v158, s48, v192
	v_med3_f32 v159, v159, s48, v192
	v_med3_f32 v160, v160, s48, v192
	v_med3_f32 v161, v161, s48, v192
	v_med3_f32 v162, v162, s48, v192
	v_med3_f32 v163, v163, s48, v192
	v_mul_f32_e32 v156, 0xbfb8aa3b, v156
	v_mul_f32_e32 v157, 0xbfb8aa3b, v157
	v_mul_f32_e32 v158, 0xbfb8aa3b, v158
	v_mul_f32_e32 v159, 0xbfb8aa3b, v159
	v_mul_f32_e32 v160, 0xbfb8aa3b, v160
	v_mul_f32_e32 v161, 0xbfb8aa3b, v161
	v_mul_f32_e32 v162, 0xbfb8aa3b, v162
	v_mul_f32_e32 v163, 0xbfb8aa3b, v163
	v_exp_f32_e32 v156, v156
	v_exp_f32_e32 v157, v157
	v_exp_f32_e32 v158, v158
	v_exp_f32_e32 v159, v159
	v_exp_f32_e32 v160, v160
	v_exp_f32_e32 v161, v161
	v_exp_f32_e32 v162, v162
	v_exp_f32_e32 v163, v163
	v_add_f32_e32 v156, 1.0, v156
	v_add_f32_e32 v157, 1.0, v157
	v_add_f32_e32 v158, 1.0, v158
	v_add_f32_e32 v159, 1.0, v159
	v_add_f32_e32 v160, 1.0, v160
	v_add_f32_e32 v161, 1.0, v161
	v_add_f32_e32 v162, 1.0, v162
	v_add_f32_e32 v163, 1.0, v163
	v_rcp_f32_e32 v156, v156
	v_rcp_f32_e32 v157, v157
	v_rcp_f32_e32 v158, v158
	v_rcp_f32_e32 v159, v159
	v_rcp_f32_e32 v160, v160
	v_rcp_f32_e32 v161, v161
	v_rcp_f32_e32 v162, v162
	v_rcp_f32_e32 v163, v163
	v_mul_f32_e32 v156, v156, v4
	v_mul_f32_e32 v157, v157, v5
	v_mul_f32_e32 v158, v158, v6
	v_mul_f32_e32 v159, v159, v7
	v_mul_f32_e32 v160, v160, v8
	v_mul_f32_e32 v161, v161, v9
	v_mul_f32_e32 v162, v162, v10
	v_mul_f32_e32 v163, v163, v11
	v_and_b32_sdwa v216, v156, v185 dst_sel:DWORD dst_unused:UNUSED_PAD src0_sel:WORD_1 src1_sel:DWORD
	v_and_b32_sdwa v217, v157, v185 dst_sel:DWORD dst_unused:UNUSED_PAD src0_sel:WORD_1 src1_sel:DWORD
	v_and_b32_sdwa v218, v158, v185 dst_sel:DWORD dst_unused:UNUSED_PAD src0_sel:WORD_1 src1_sel:DWORD
	v_and_b32_sdwa v219, v159, v185 dst_sel:DWORD dst_unused:UNUSED_PAD src0_sel:WORD_1 src1_sel:DWORD
	v_and_b32_sdwa v220, v160, v185 dst_sel:DWORD dst_unused:UNUSED_PAD src0_sel:WORD_1 src1_sel:DWORD
	v_and_b32_sdwa v221, v161, v185 dst_sel:DWORD dst_unused:UNUSED_PAD src0_sel:WORD_1 src1_sel:DWORD
	v_and_b32_sdwa v222, v162, v185 dst_sel:DWORD dst_unused:UNUSED_PAD src0_sel:WORD_1 src1_sel:DWORD
	v_and_b32_sdwa v223, v163, v185 dst_sel:DWORD dst_unused:UNUSED_PAD src0_sel:WORD_1 src1_sel:DWORD
	v_add3_u32 v156, v156, v216, s46
	v_add3_u32 v157, v157, v217, s46
	v_add3_u32 v158, v158, v218, s46
	v_add3_u32 v159, v159, v219, s46
	v_add3_u32 v160, v160, v220, s46
	v_add3_u32 v161, v161, v221, s46
	v_add3_u32 v162, v162, v222, s46
	v_add3_u32 v163, v163, v223, s46
	v_and_b32_e32 v157, 0xffff0000, v157
	v_and_b32_e32 v159, 0xffff0000, v159
	v_and_b32_e32 v161, 0xffff0000, v161
	v_and_b32_e32 v163, 0xffff0000, v163
	v_or_b32_sdwa v224, v157, v156 dst_sel:DWORD dst_unused:UNUSED_PAD src0_sel:DWORD src1_sel:WORD_1
	v_or_b32_sdwa v225, v159, v158 dst_sel:DWORD dst_unused:UNUSED_PAD src0_sel:DWORD src1_sel:WORD_1
	v_or_b32_sdwa v226, v161, v160 dst_sel:DWORD dst_unused:UNUSED_PAD src0_sel:DWORD src1_sel:WORD_1
	v_or_b32_sdwa v227, v163, v162 dst_sel:DWORD dst_unused:UNUSED_PAD src0_sel:DWORD src1_sel:WORD_1
	global_store_dwordx4 v[210:211], v[224:227], off offset:256
	s_mov_b64 s[0:1], 0x48000
	v_lshl_add_u64 v[212:213], v[206:207], 0, s[0:1]
	s_waitcnt vmcnt(12)
; __device__ __forceinline__ float sigmoidf_(float x) { return __builtin_amdgcn_rcpf(1.0f + __expf(-x)); }
; __device__ __forceinline__ void unpack8(const uint4 u, float (&f)[8]) { f[0] = bflo(u.x); f[1] = bfhi(u.x); f[2] = bflo(u.y); f[3] = bfhi(u.y); f[4] = bflo(u.z); f[5] = bfhi(u.z); f[6] = bflo(u.w); f[7] = bfhi(u.w); }
; __device__ __forceinline__ uint4 pack8(const float (&f)[8]) { uint4 u; u.x = pack2(f[0], f[1]); u.y = pack2(f[2], f[3]); u.z = pack2(f[4], f[5]); u.w = pack2(f[6], f[7]); return u; }
;     __device__ __forceinline__ void operator()(const f32x4 (&acc)[2][2][4][2], const Unit& u, int wr, int wc, int fr, int fq) const {
;         EPIP_ROWS( float gr[8]; unpack8(*(const uint4*)(gate + row * LDP + C_GR + col8 + co), gr); float o[8];
;             _Pragma("unroll") for (int e = 0; e < 4; ++e) { o[e] = sigmoidf_(fminf(fmaxf(gr[e], -30.f), 30.f)) * v0[e]; o[4 + e] = sigmoidf_(fminf(fmaxf(gr[4 + e], -30.f), 30.f)) * v1[e]; }
;             *(uint4*)(O + row * DM + col8 + co) = pack8(o); )
;     }
	v_lshlrev_b32_e32 v156, 16, v132
	v_and_b32_e32 v157, 0xffff0000, v132
	v_lshlrev_b32_e32 v158, 16, v133
	v_and_b32_e32 v159, 0xffff0000, v133
	v_lshlrev_b32_e32 v160, 16, v134
	v_and_b32_e32 v161, 0xffff0000, v134
	v_lshlrev_b32_e32 v162, 16, v135
	v_and_b32_e32 v163, 0xffff0000, v135
	v_max_f32_e32 v156, v156, v156
	v_max_f32_e32 v157, v157, v157
	v_max_f32_e32 v158, v158, v158
	v_max_f32_e32 v159, v159, v159
	v_max_f32_e32 v160, v160, v160
	v_max_f32_e32 v161, v161, v161
	v_max_f32_e32 v162, v162, v162
	v_max_f32_e32 v163, v163, v163
	v_med3_f32 v156, v156, s48, v192
	v_med3_f32 v157, v157, s48, v192
	v_med3_f32 v158, v158, s48, v192
	v_med3_f32 v159, v159, s48, v192
	v_med3_f32 v160, v160, s48, v192
	v_med3_f32 v161, v161, s48, v192
	v_med3_f32 v162, v162, s48, v192
	v_med3_f32 v163, v163, s48, v192
	v_mul_f32_e32 v156, 0xbfb8aa3b, v156
	v_mul_f32_e32 v157, 0xbfb8aa3b, v157
	v_mul_f32_e32 v158, 0xbfb8aa3b, v158
	v_mul_f32_e32 v159, 0xbfb8aa3b, v159
	v_mul_f32_e32 v160, 0xbfb8aa3b, v160
	v_mul_f32_e32 v161, 0xbfb8aa3b, v161
	v_mul_f32_e32 v162, 0xbfb8aa3b, v162
	v_mul_f32_e32 v163, 0xbfb8aa3b, v163
	v_exp_f32_e32 v156, v156
	v_exp_f32_e32 v157, v157
	v_exp_f32_e32 v158, v158
	v_exp_f32_e32 v159, v159
	v_exp_f32_e32 v160, v160
	v_exp_f32_e32 v161, v161
	v_exp_f32_e32 v162, v162
	v_exp_f32_e32 v163, v163
	v_add_f32_e32 v156, 1.0, v156
	v_add_f32_e32 v157, 1.0, v157
	v_add_f32_e32 v158, 1.0, v158
	v_add_f32_e32 v159, 1.0, v159
	v_add_f32_e32 v160, 1.0, v160
	v_add_f32_e32 v161, 1.0, v161
	v_add_f32_e32 v162, 1.0, v162
	v_add_f32_e32 v163, 1.0, v163
	v_rcp_f32_e32 v156, v156
	v_rcp_f32_e32 v157, v157
	v_rcp_f32_e32 v158, v158
	v_rcp_f32_e32 v159, v159
	v_rcp_f32_e32 v160, v160
	v_rcp_f32_e32 v161, v161
	v_rcp_f32_e32 v162, v162
	v_rcp_f32_e32 v163, v163
	v_mul_f32_e32 v156, v156, v120
	v_mul_f32_e32 v157, v157, v121
	v_mul_f32_e32 v158, v158, v122
	v_mul_f32_e32 v159, v159, v123
	v_mul_f32_e32 v160, v160, v124
	v_mul_f32_e32 v161, v161, v125
	v_mul_f32_e32 v162, v162, v126
	v_mul_f32_e32 v163, v163, v127
	v_and_b32_sdwa v216, v156, v185 dst_sel:DWORD dst_unused:UNUSED_PAD src0_sel:WORD_1 src1_sel:DWORD
	v_and_b32_sdwa v217, v157, v185 dst_sel:DWORD dst_unused:UNUSED_PAD src0_sel:WORD_1 src1_sel:DWORD
	v_and_b32_sdwa v218, v158, v185 dst_sel:DWORD dst_unused:UNUSED_PAD src0_sel:WORD_1 src1_sel:DWORD
	v_and_b32_sdwa v219, v159, v185 dst_sel:DWORD dst_unused:UNUSED_PAD src0_sel:WORD_1 src1_sel:DWORD
	v_and_b32_sdwa v220, v160, v185 dst_sel:DWORD dst_unused:UNUSED_PAD src0_sel:WORD_1 src1_sel:DWORD
	v_and_b32_sdwa v221, v161, v185 dst_sel:DWORD dst_unused:UNUSED_PAD src0_sel:WORD_1 src1_sel:DWORD
	v_and_b32_sdwa v222, v162, v185 dst_sel:DWORD dst_unused:UNUSED_PAD src0_sel:WORD_1 src1_sel:DWORD
	v_and_b32_sdwa v223, v163, v185 dst_sel:DWORD dst_unused:UNUSED_PAD src0_sel:WORD_1 src1_sel:DWORD
	v_add3_u32 v156, v156, v216, s46
	v_add3_u32 v157, v157, v217, s46
	v_add3_u32 v158, v158, v218, s46
	v_add3_u32 v159, v159, v219, s46
	v_add3_u32 v160, v160, v220, s46
	v_add3_u32 v161, v161, v221, s46
	v_add3_u32 v162, v162, v222, s46
	v_add3_u32 v163, v163, v223, s46
	v_and_b32_e32 v157, 0xffff0000, v157
	v_and_b32_e32 v159, 0xffff0000, v159
	v_and_b32_e32 v161, 0xffff0000, v161
	v_and_b32_e32 v163, 0xffff0000, v163
	v_or_b32_sdwa v176, v157, v156 dst_sel:DWORD dst_unused:UNUSED_PAD src0_sel:DWORD src1_sel:WORD_1
	v_or_b32_sdwa v177, v159, v158 dst_sel:DWORD dst_unused:UNUSED_PAD src0_sel:DWORD src1_sel:WORD_1
	v_or_b32_sdwa v178, v161, v160 dst_sel:DWORD dst_unused:UNUSED_PAD src0_sel:DWORD src1_sel:WORD_1
	v_or_b32_sdwa v179, v163, v162 dst_sel:DWORD dst_unused:UNUSED_PAD src0_sel:DWORD src1_sel:WORD_1
	global_store_dwordx4 v[212:213], v[176:179], off
	v_lshlrev_b32_e32 v156, 16, v136
	v_and_b32_e32 v157, 0xffff0000, v136
	v_lshlrev_b32_e32 v158, 16, v137
	v_and_b32_e32 v159, 0xffff0000, v137
	v_lshlrev_b32_e32 v160, 16, v138
	v_and_b32_e32 v161, 0xffff0000, v138
	v_lshlrev_b32_e32 v162, 16, v139
	v_and_b32_e32 v163, 0xffff0000, v139
	v_max_f32_e32 v156, v156, v156
	v_max_f32_e32 v157, v157, v157
	v_max_f32_e32 v158, v158, v158
	v_max_f32_e32 v159, v159, v159
	v_max_f32_e32 v160, v160, v160
	v_max_f32_e32 v161, v161, v161
	v_max_f32_e32 v162, v162, v162
	v_max_f32_e32 v163, v163, v163
	v_med3_f32 v156, v156, s48, v192
	v_med3_f32 v157, v157, s48, v192
	v_med3_f32 v158, v158, s48, v192
	v_med3_f32 v159, v159, s48, v192
	v_med3_f32 v160, v160, s48, v192
	v_med3_f32 v161, v161, s48, v192
	v_med3_f32 v162, v162, s48, v192
	v_med3_f32 v163, v163, s48, v192
	v_mul_f32_e32 v156, 0xbfb8aa3b, v156
	v_mul_f32_e32 v157, 0xbfb8aa3b, v157
	v_mul_f32_e32 v158, 0xbfb8aa3b, v158
	v_mul_f32_e32 v159, 0xbfb8aa3b, v159
	v_mul_f32_e32 v160, 0xbfb8aa3b, v160
	v_mul_f32_e32 v161, 0xbfb8aa3b, v161
	v_mul_f32_e32 v162, 0xbfb8aa3b, v162
	v_mul_f32_e32 v163, 0xbfb8aa3b, v163
	v_exp_f32_e32 v156, v156
	v_exp_f32_e32 v157, v157
	v_exp_f32_e32 v158, v158
	v_exp_f32_e32 v159, v159
	v_exp_f32_e32 v160, v160
	v_exp_f32_e32 v161, v161
	v_exp_f32_e32 v162, v162
	v_exp_f32_e32 v163, v163
	v_add_f32_e32 v156, 1.0, v156
	v_add_f32_e32 v157, 1.0, v157
	v_add_f32_e32 v158, 1.0, v158
	v_add_f32_e32 v159, 1.0, v159
	v_add_f32_e32 v160, 1.0, v160
	v_add_f32_e32 v161, 1.0, v161
	v_add_f32_e32 v162, 1.0, v162
	v_add_f32_e32 v163, 1.0, v163
	v_rcp_f32_e32 v156, v156
	v_rcp_f32_e32 v157, v157
	v_rcp_f32_e32 v158, v158
	v_rcp_f32_e32 v159, v159
	v_rcp_f32_e32 v160, v160
	v_rcp_f32_e32 v161, v161
	v_rcp_f32_e32 v162, v162
	v_rcp_f32_e32 v163, v163
	v_mul_f32_e32 v156, v156, v12
	v_mul_f32_e32 v157, v157, v13
	v_mul_f32_e32 v158, v158, v14
	v_mul_f32_e32 v159, v159, v15
	v_mul_f32_e32 v160, v160, v16
; __device__ __forceinline__ float sigmoidf_(float x) { return __builtin_amdgcn_rcpf(1.0f + __expf(-x)); }
; __device__ __forceinline__ void unpack8(const uint4 u, float (&f)[8]) { f[0] = bflo(u.x); f[1] = bfhi(u.x); f[2] = bflo(u.y); f[3] = bfhi(u.y); f[4] = bflo(u.z); f[5] = bfhi(u.z); f[6] = bflo(u.w); f[7] = bfhi(u.w); }
; __device__ __forceinline__ uint4 pack8(const float (&f)[8]) { uint4 u; u.x = pack2(f[0], f[1]); u.y = pack2(f[2], f[3]); u.z = pack2(f[4], f[5]); u.w = pack2(f[6], f[7]); return u; }
;     __device__ __forceinline__ void operator()(const f32x4 (&acc)[2][2][4][2], const Unit& u, int wr, int wc, int fr, int fq) const {
;         EPIP_ROWS( float gr[8]; unpack8(*(const uint4*)(gate + row * LDP + C_GR + col8 + co), gr); float o[8];
;             _Pragma("unroll") for (int e = 0; e < 4; ++e) { o[e] = sigmoidf_(fminf(fmaxf(gr[e], -30.f), 30.f)) * v0[e]; o[4 + e] = sigmoidf_(fminf(fmaxf(gr[4 + e], -30.f), 30.f)) * v1[e]; }
;             *(uint4*)(O + row * DM + col8 + co) = pack8(o); )
;     }
	v_mul_f32_e32 v161, v161, v17
	v_mul_f32_e32 v162, v162, v18
	v_mul_f32_e32 v163, v163, v19
	v_and_b32_sdwa v216, v156, v185 dst_sel:DWORD dst_unused:UNUSED_PAD src0_sel:WORD_1 src1_sel:DWORD
	v_and_b32_sdwa v217, v157, v185 dst_sel:DWORD dst_unused:UNUSED_PAD src0_sel:WORD_1 src1_sel:DWORD
	v_and_b32_sdwa v218, v158, v185 dst_sel:DWORD dst_unused:UNUSED_PAD src0_sel:WORD_1 src1_sel:DWORD
	v_and_b32_sdwa v219, v159, v185 dst_sel:DWORD dst_unused:UNUSED_PAD src0_sel:WORD_1 src1_sel:DWORD
	v_and_b32_sdwa v220, v160, v185 dst_sel:DWORD dst_unused:UNUSED_PAD src0_sel:WORD_1 src1_sel:DWORD
	v_and_b32_sdwa v221, v161, v185 dst_sel:DWORD dst_unused:UNUSED_PAD src0_sel:WORD_1 src1_sel:DWORD
	v_and_b32_sdwa v222, v162, v185 dst_sel:DWORD dst_unused:UNUSED_PAD src0_sel:WORD_1 src1_sel:DWORD
	v_and_b32_sdwa v223, v163, v185 dst_sel:DWORD dst_unused:UNUSED_PAD src0_sel:WORD_1 src1_sel:DWORD
	v_add3_u32 v156, v156, v216, s46
	v_add3_u32 v157, v157, v217, s46
	v_add3_u32 v158, v158, v218, s46
	v_add3_u32 v159, v159, v219, s46
	v_add3_u32 v160, v160, v220, s46
	v_add3_u32 v161, v161, v221, s46
	v_add3_u32 v162, v162, v222, s46
	v_add3_u32 v163, v163, v223, s46
	v_and_b32_e32 v157, 0xffff0000, v157
	v_and_b32_e32 v159, 0xffff0000, v159
	v_and_b32_e32 v161, 0xffff0000, v161
	v_and_b32_e32 v163, 0xffff0000, v163
	v_or_b32_sdwa v224, v157, v156 dst_sel:DWORD dst_unused:UNUSED_PAD src0_sel:DWORD src1_sel:WORD_1
	v_or_b32_sdwa v225, v159, v158 dst_sel:DWORD dst_unused:UNUSED_PAD src0_sel:DWORD src1_sel:WORD_1
	v_or_b32_sdwa v226, v161, v160 dst_sel:DWORD dst_unused:UNUSED_PAD src0_sel:DWORD src1_sel:WORD_1
	v_or_b32_sdwa v227, v163, v162 dst_sel:DWORD dst_unused:UNUSED_PAD src0_sel:DWORD src1_sel:WORD_1
	global_store_dwordx4 v[212:213], v[224:227], off offset:256
	s_mov_b64 s[0:1], 0x50000
	v_lshl_add_u64 v[210:211], v[206:207], 0, s[0:1]
	s_waitcnt vmcnt(10)
	v_lshlrev_b32_e32 v156, 16, v140
	v_and_b32_e32 v157, 0xffff0000, v140
	v_lshlrev_b32_e32 v158, 16, v141
	v_and_b32_e32 v159, 0xffff0000, v141
	v_lshlrev_b32_e32 v160, 16, v142
	v_and_b32_e32 v161, 0xffff0000, v142
	v_lshlrev_b32_e32 v162, 16, v143
	v_and_b32_e32 v163, 0xffff0000, v143
	v_max_f32_e32 v156, v156, v156
	v_max_f32_e32 v157, v157, v157
	v_max_f32_e32 v158, v158, v158
	v_max_f32_e32 v159, v159, v159
	v_max_f32_e32 v160, v160, v160
	v_max_f32_e32 v161, v161, v161
	v_max_f32_e32 v162, v162, v162
	v_max_f32_e32 v163, v163, v163
	v_med3_f32 v156, v156, s48, v192
	v_med3_f32 v157, v157, s48, v192
	v_med3_f32 v158, v158, s48, v192
	v_med3_f32 v159, v159, s48, v192
	v_med3_f32 v160, v160, s48, v192
	v_med3_f32 v161, v161, s48, v192
	v_med3_f32 v162, v162, s48, v192
	v_med3_f32 v163, v163, s48, v192
	v_mul_f32_e32 v156, 0xbfb8aa3b, v156
	v_mul_f32_e32 v157, 0xbfb8aa3b, v157
	v_mul_f32_e32 v158, 0xbfb8aa3b, v158
	v_mul_f32_e32 v159, 0xbfb8aa3b, v159
	v_mul_f32_e32 v160, 0xbfb8aa3b, v160
	v_mul_f32_e32 v161, 0xbfb8aa3b, v161
	v_mul_f32_e32 v162, 0xbfb8aa3b, v162
	v_mul_f32_e32 v163, 0xbfb8aa3b, v163
	v_exp_f32_e32 v156, v156
	v_exp_f32_e32 v157, v157
	v_exp_f32_e32 v158, v158
	v_exp_f32_e32 v159, v159
	v_exp_f32_e32 v160, v160
	v_exp_f32_e32 v161, v161
	v_exp_f32_e32 v162, v162
	v_exp_f32_e32 v163, v163
	v_add_f32_e32 v156, 1.0, v156
	v_add_f32_e32 v157, 1.0, v157
	v_add_f32_e32 v158, 1.0, v158
	v_add_f32_e32 v159, 1.0, v159
	v_add_f32_e32 v160, 1.0, v160
	v_add_f32_e32 v161, 1.0, v161
	v_add_f32_e32 v162, 1.0, v162
	v_add_f32_e32 v163, 1.0, v163
	v_rcp_f32_e32 v156, v156
	v_rcp_f32_e32 v157, v157
	v_rcp_f32_e32 v158, v158
	v_rcp_f32_e32 v159, v159
	v_rcp_f32_e32 v160, v160
	v_rcp_f32_e32 v161, v161
	v_rcp_f32_e32 v162, v162
	v_rcp_f32_e32 v163, v163
	v_mul_f32_e32 v156, v156, v128
	v_mul_f32_e32 v157, v157, v129
	v_mul_f32_e32 v158, v158, v130
	v_mul_f32_e32 v159, v159, v131
	v_mul_f32_e32 v160, v160, v36
	v_mul_f32_e32 v161, v161, v37
	v_mul_f32_e32 v162, v162, v38
	v_mul_f32_e32 v163, v163, v39
	v_and_b32_sdwa v216, v156, v185 dst_sel:DWORD dst_unused:UNUSED_PAD src0_sel:WORD_1 src1_sel:DWORD
	v_and_b32_sdwa v217, v157, v185 dst_sel:DWORD dst_unused:UNUSED_PAD src0_sel:WORD_1 src1_sel:DWORD
	v_and_b32_sdwa v218, v158, v185 dst_sel:DWORD dst_unused:UNUSED_PAD src0_sel:WORD_1 src1_sel:DWORD
	v_and_b32_sdwa v219, v159, v185 dst_sel:DWORD dst_unused:UNUSED_PAD src0_sel:WORD_1 src1_sel:DWORD
	v_and_b32_sdwa v220, v160, v185 dst_sel:DWORD dst_unused:UNUSED_PAD src0_sel:WORD_1 src1_sel:DWORD
	v_and_b32_sdwa v221, v161, v185 dst_sel:DWORD dst_unused:UNUSED_PAD src0_sel:WORD_1 src1_sel:DWORD
	v_and_b32_sdwa v222, v162, v185 dst_sel:DWORD dst_unused:UNUSED_PAD src0_sel:WORD_1 src1_sel:DWORD
	v_and_b32_sdwa v223, v163, v185 dst_sel:DWORD dst_unused:UNUSED_PAD src0_sel:WORD_1 src1_sel:DWORD
	v_add3_u32 v156, v156, v216, s46
	v_add3_u32 v157, v157, v217, s46
	v_add3_u32 v158, v158, v218, s46
	v_add3_u32 v159, v159, v219, s46
	v_add3_u32 v160, v160, v220, s46
	v_add3_u32 v161, v161, v221, s46
	v_add3_u32 v162, v162, v222, s46
	v_add3_u32 v163, v163, v223, s46
	v_and_b32_e32 v157, 0xffff0000, v157
	v_and_b32_e32 v159, 0xffff0000, v159
	v_and_b32_e32 v161, 0xffff0000, v161
	v_and_b32_e32 v163, 0xffff0000, v163
	v_or_b32_sdwa v176, v157, v156 dst_sel:DWORD dst_unused:UNUSED_PAD src0_sel:DWORD src1_sel:WORD_1
	v_or_b32_sdwa v177, v159, v158 dst_sel:DWORD dst_unused:UNUSED_PAD src0_sel:DWORD src1_sel:WORD_1
	v_or_b32_sdwa v178, v161, v160 dst_sel:DWORD dst_unused:UNUSED_PAD src0_sel:DWORD src1_sel:WORD_1
	v_or_b32_sdwa v179, v163, v162 dst_sel:DWORD dst_unused:UNUSED_PAD src0_sel:DWORD src1_sel:WORD_1
	global_store_dwordx4 v[210:211], v[176:179], off
	v_lshlrev_b32_e32 v156, 16, v144
	v_and_b32_e32 v157, 0xffff0000, v144
; __device__ __forceinline__ float sigmoidf_(float x) { return __builtin_amdgcn_rcpf(1.0f + __expf(-x)); }
; __device__ __forceinline__ void unpack8(const uint4 u, float (&f)[8]) { f[0] = bflo(u.x); f[1] = bfhi(u.x); f[2] = bflo(u.y); f[3] = bfhi(u.y); f[4] = bflo(u.z); f[5] = bfhi(u.z); f[6] = bflo(u.w); f[7] = bfhi(u.w); }
; __device__ __forceinline__ uint4 pack8(const float (&f)[8]) { uint4 u; u.x = pack2(f[0], f[1]); u.y = pack2(f[2], f[3]); u.z = pack2(f[4], f[5]); u.w = pack2(f[6], f[7]); return u; }
;     __device__ __forceinline__ void operator()(const f32x4 (&acc)[2][2][4][2], const Unit& u, int wr, int wc, int fr, int fq) const {
;         EPIP_ROWS( float gr[8]; unpack8(*(const uint4*)(gate + row * LDP + C_GR + col8 + co), gr); float o[8];
;             _Pragma("unroll") for (int e = 0; e < 4; ++e) { o[e] = sigmoidf_(fminf(fmaxf(gr[e], -30.f), 30.f)) * v0[e]; o[4 + e] = sigmoidf_(fminf(fmaxf(gr[4 + e], -30.f), 30.f)) * v1[e]; }
;             *(uint4*)(O + row * DM + col8 + co) = pack8(o); )
;     }
	v_lshlrev_b32_e32 v158, 16, v145
	v_and_b32_e32 v159, 0xffff0000, v145
	v_lshlrev_b32_e32 v160, 16, v146
	v_and_b32_e32 v161, 0xffff0000, v146
	v_lshlrev_b32_e32 v162, 16, v147
	v_and_b32_e32 v163, 0xffff0000, v147
	v_max_f32_e32 v156, v156, v156
	v_max_f32_e32 v157, v157, v157
	v_max_f32_e32 v158, v158, v158
	v_max_f32_e32 v159, v159, v159
	v_max_f32_e32 v160, v160, v160
	v_max_f32_e32 v161, v161, v161
	v_max_f32_e32 v162, v162, v162
	v_max_f32_e32 v163, v163, v163
	v_med3_f32 v156, v156, s48, v192
	v_med3_f32 v157, v157, s48, v192
	v_med3_f32 v158, v158, s48, v192
	v_med3_f32 v159, v159, s48, v192
	v_med3_f32 v160, v160, s48, v192
	v_med3_f32 v161, v161, s48, v192
	v_med3_f32 v162, v162, s48, v192
	v_med3_f32 v163, v163, s48, v192
	v_mul_f32_e32 v156, 0xbfb8aa3b, v156
	v_mul_f32_e32 v157, 0xbfb8aa3b, v157
	v_mul_f32_e32 v158, 0xbfb8aa3b, v158
	v_mul_f32_e32 v159, 0xbfb8aa3b, v159
	v_mul_f32_e32 v160, 0xbfb8aa3b, v160
	v_mul_f32_e32 v161, 0xbfb8aa3b, v161
	v_mul_f32_e32 v162, 0xbfb8aa3b, v162
	v_mul_f32_e32 v163, 0xbfb8aa3b, v163
	v_exp_f32_e32 v156, v156
	v_exp_f32_e32 v157, v157
	v_exp_f32_e32 v158, v158
	v_exp_f32_e32 v159, v159
	v_exp_f32_e32 v160, v160
	v_exp_f32_e32 v161, v161
	v_exp_f32_e32 v162, v162
	v_exp_f32_e32 v163, v163
	v_add_f32_e32 v156, 1.0, v156
	v_add_f32_e32 v157, 1.0, v157
	v_add_f32_e32 v158, 1.0, v158
	v_add_f32_e32 v159, 1.0, v159
	v_add_f32_e32 v160, 1.0, v160
	v_add_f32_e32 v161, 1.0, v161
	v_add_f32_e32 v162, 1.0, v162
	v_add_f32_e32 v163, 1.0, v163
	v_rcp_f32_e32 v156, v156
	v_rcp_f32_e32 v157, v157
	v_rcp_f32_e32 v158, v158
	v_rcp_f32_e32 v159, v159
	v_rcp_f32_e32 v160, v160
	v_rcp_f32_e32 v161, v161
	v_rcp_f32_e32 v162, v162
	v_rcp_f32_e32 v163, v163
	v_mul_f32_e32 v156, v156, v20
	v_mul_f32_e32 v157, v157, v21
	v_mul_f32_e32 v158, v158, v22
	v_mul_f32_e32 v159, v159, v23
	v_mul_f32_e32 v160, v160, v24
	v_mul_f32_e32 v161, v161, v25
	v_mul_f32_e32 v162, v162, v26
	v_mul_f32_e32 v163, v163, v27
	v_and_b32_sdwa v216, v156, v185 dst_sel:DWORD dst_unused:UNUSED_PAD src0_sel:WORD_1 src1_sel:DWORD
	v_and_b32_sdwa v217, v157, v185 dst_sel:DWORD dst_unused:UNUSED_PAD src0_sel:WORD_1 src1_sel:DWORD
	v_and_b32_sdwa v218, v158, v185 dst_sel:DWORD dst_unused:UNUSED_PAD src0_sel:WORD_1 src1_sel:DWORD
	v_and_b32_sdwa v219, v159, v185 dst_sel:DWORD dst_unused:UNUSED_PAD src0_sel:WORD_1 src1_sel:DWORD
	v_and_b32_sdwa v220, v160, v185 dst_sel:DWORD dst_unused:UNUSED_PAD src0_sel:WORD_1 src1_sel:DWORD
	v_and_b32_sdwa v221, v161, v185 dst_sel:DWORD dst_unused:UNUSED_PAD src0_sel:WORD_1 src1_sel:DWORD
	v_and_b32_sdwa v222, v162, v185 dst_sel:DWORD dst_unused:UNUSED_PAD src0_sel:WORD_1 src1_sel:DWORD
	v_and_b32_sdwa v223, v163, v185 dst_sel:DWORD dst_unused:UNUSED_PAD src0_sel:WORD_1 src1_sel:DWORD
	v_add3_u32 v156, v156, v216, s46
	v_add3_u32 v157, v157, v217, s46
	v_add3_u32 v158, v158, v218, s46
	v_add3_u32 v159, v159, v219, s46
	v_add3_u32 v160, v160, v220, s46
	v_add3_u32 v161, v161, v221, s46
	v_add3_u32 v162, v162, v222, s46
	v_add3_u32 v163, v163, v223, s46
	v_and_b32_e32 v157, 0xffff0000, v157
	v_and_b32_e32 v159, 0xffff0000, v159
	v_and_b32_e32 v161, 0xffff0000, v161
	v_and_b32_e32 v163, 0xffff0000, v163
	v_or_b32_sdwa v224, v157, v156 dst_sel:DWORD dst_unused:UNUSED_PAD src0_sel:DWORD src1_sel:WORD_1
	v_or_b32_sdwa v225, v159, v158 dst_sel:DWORD dst_unused:UNUSED_PAD src0_sel:DWORD src1_sel:WORD_1
	v_or_b32_sdwa v226, v161, v160 dst_sel:DWORD dst_unused:UNUSED_PAD src0_sel:DWORD src1_sel:WORD_1
	v_or_b32_sdwa v227, v163, v162 dst_sel:DWORD dst_unused:UNUSED_PAD src0_sel:DWORD src1_sel:WORD_1
	global_store_dwordx4 v[210:211], v[224:227], off offset:256
	s_mov_b64 s[0:1], 0x58000
	v_lshl_add_u64 v[212:213], v[206:207], 0, s[0:1]
	s_waitcnt vmcnt(8)
	v_lshlrev_b32_e32 v156, 16, v148
	v_and_b32_e32 v157, 0xffff0000, v148
	v_lshlrev_b32_e32 v158, 16, v149
	v_and_b32_e32 v159, 0xffff0000, v149
	v_lshlrev_b32_e32 v160, 16, v150
	v_and_b32_e32 v161, 0xffff0000, v150
	v_lshlrev_b32_e32 v162, 16, v151
	v_and_b32_e32 v163, 0xffff0000, v151
	v_max_f32_e32 v156, v156, v156
	v_max_f32_e32 v157, v157, v157
	v_max_f32_e32 v158, v158, v158
	v_max_f32_e32 v159, v159, v159
	v_max_f32_e32 v160, v160, v160
	v_max_f32_e32 v161, v161, v161
	v_max_f32_e32 v162, v162, v162
	v_max_f32_e32 v163, v163, v163
	v_med3_f32 v156, v156, s48, v192
	v_med3_f32 v157, v157, s48, v192
	v_med3_f32 v158, v158, s48, v192
	v_med3_f32 v159, v159, s48, v192
	v_med3_f32 v160, v160, s48, v192
	v_med3_f32 v161, v161, s48, v192
	v_med3_f32 v162, v162, s48, v192
	v_med3_f32 v163, v163, s48, v192
	v_mul_f32_e32 v156, 0xbfb8aa3b, v156
	v_mul_f32_e32 v157, 0xbfb8aa3b, v157
	v_mul_f32_e32 v158, 0xbfb8aa3b, v158
	v_mul_f32_e32 v159, 0xbfb8aa3b, v159
	v_mul_f32_e32 v160, 0xbfb8aa3b, v160
	v_mul_f32_e32 v161, 0xbfb8aa3b, v161
	v_mul_f32_e32 v162, 0xbfb8aa3b, v162
	v_mul_f32_e32 v163, 0xbfb8aa3b, v163
	v_exp_f32_e32 v156, v156
	v_exp_f32_e32 v157, v157
	v_exp_f32_e32 v158, v158
	v_exp_f32_e32 v159, v159
	v_exp_f32_e32 v160, v160
	v_exp_f32_e32 v161, v161
	v_exp_f32_e32 v162, v162
	v_exp_f32_e32 v163, v163
	v_add_f32_e32 v156, 1.0, v156
	v_add_f32_e32 v157, 1.0, v157
	v_add_f32_e32 v158, 1.0, v158
	v_add_f32_e32 v159, 1.0, v159
	v_add_f32_e32 v160, 1.0, v160
	v_add_f32_e32 v161, 1.0, v161
	v_add_f32_e32 v162, 1.0, v162
	v_add_f32_e32 v163, 1.0, v163
	v_rcp_f32_e32 v156, v156
	v_rcp_f32_e32 v157, v157
	v_rcp_f32_e32 v158, v158
	v_rcp_f32_e32 v159, v159
	v_rcp_f32_e32 v160, v160
	v_rcp_f32_e32 v161, v161
	v_rcp_f32_e32 v162, v162
	v_rcp_f32_e32 v163, v163
	v_mul_f32_e32 v156, v156, v40
	v_mul_f32_e32 v157, v157, v41
; __device__ __forceinline__ float sigmoidf_(float x) { return __builtin_amdgcn_rcpf(1.0f + __expf(-x)); }
; __device__ __forceinline__ void unpack8(const uint4 u, float (&f)[8]) { f[0] = bflo(u.x); f[1] = bfhi(u.x); f[2] = bflo(u.y); f[3] = bfhi(u.y); f[4] = bflo(u.z); f[5] = bfhi(u.z); f[6] = bflo(u.w); f[7] = bfhi(u.w); }
; __device__ __forceinline__ uint4 pack8(const float (&f)[8]) { uint4 u; u.x = pack2(f[0], f[1]); u.y = pack2(f[2], f[3]); u.z = pack2(f[4], f[5]); u.w = pack2(f[6], f[7]); return u; }
;     __device__ __forceinline__ void operator()(const f32x4 (&acc)[2][2][4][2], const Unit& u, int wr, int wc, int fr, int fq) const {
;         EPIP_ROWS( float gr[8]; unpack8(*(const uint4*)(gate + row * LDP + C_GR + col8 + co), gr); float o[8];
;             _Pragma("unroll") for (int e = 0; e < 4; ++e) { o[e] = sigmoidf_(fminf(fmaxf(gr[e], -30.f), 30.f)) * v0[e]; o[4 + e] = sigmoidf_(fminf(fmaxf(gr[4 + e], -30.f), 30.f)) * v1[e]; }
;             *(uint4*)(O + row * DM + col8 + co) = pack8(o); )
;     }
	v_mul_f32_e32 v158, v158, v42
	v_mul_f32_e32 v159, v159, v43
	v_mul_f32_e32 v160, v160, v44
	v_mul_f32_e32 v161, v161, v45
	v_mul_f32_e32 v162, v162, v46
	v_mul_f32_e32 v163, v163, v47
	v_and_b32_sdwa v216, v156, v185 dst_sel:DWORD dst_unused:UNUSED_PAD src0_sel:WORD_1 src1_sel:DWORD
	v_and_b32_sdwa v217, v157, v185 dst_sel:DWORD dst_unused:UNUSED_PAD src0_sel:WORD_1 src1_sel:DWORD
	v_and_b32_sdwa v218, v158, v185 dst_sel:DWORD dst_unused:UNUSED_PAD src0_sel:WORD_1 src1_sel:DWORD
	v_and_b32_sdwa v219, v159, v185 dst_sel:DWORD dst_unused:UNUSED_PAD src0_sel:WORD_1 src1_sel:DWORD
	v_and_b32_sdwa v220, v160, v185 dst_sel:DWORD dst_unused:UNUSED_PAD src0_sel:WORD_1 src1_sel:DWORD
	v_and_b32_sdwa v221, v161, v185 dst_sel:DWORD dst_unused:UNUSED_PAD src0_sel:WORD_1 src1_sel:DWORD
	v_and_b32_sdwa v222, v162, v185 dst_sel:DWORD dst_unused:UNUSED_PAD src0_sel:WORD_1 src1_sel:DWORD
	v_and_b32_sdwa v223, v163, v185 dst_sel:DWORD dst_unused:UNUSED_PAD src0_sel:WORD_1 src1_sel:DWORD
	v_add3_u32 v156, v156, v216, s46
	v_add3_u32 v157, v157, v217, s46
	v_add3_u32 v158, v158, v218, s46
	v_add3_u32 v159, v159, v219, s46
	v_add3_u32 v160, v160, v220, s46
	v_add3_u32 v161, v161, v221, s46
	v_add3_u32 v162, v162, v222, s46
	v_add3_u32 v163, v163, v223, s46
	v_and_b32_e32 v157, 0xffff0000, v157
	v_and_b32_e32 v159, 0xffff0000, v159
	v_and_b32_e32 v161, 0xffff0000, v161
	v_and_b32_e32 v163, 0xffff0000, v163
	v_or_b32_sdwa v176, v157, v156 dst_sel:DWORD dst_unused:UNUSED_PAD src0_sel:DWORD src1_sel:WORD_1
	v_or_b32_sdwa v177, v159, v158 dst_sel:DWORD dst_unused:UNUSED_PAD src0_sel:DWORD src1_sel:WORD_1
	v_or_b32_sdwa v178, v161, v160 dst_sel:DWORD dst_unused:UNUSED_PAD src0_sel:DWORD src1_sel:WORD_1
	v_or_b32_sdwa v179, v163, v162 dst_sel:DWORD dst_unused:UNUSED_PAD src0_sel:DWORD src1_sel:WORD_1
	global_store_dwordx4 v[212:213], v[176:179], off
	v_lshlrev_b32_e32 v156, 16, v152
	v_and_b32_e32 v157, 0xffff0000, v152
	v_lshlrev_b32_e32 v158, 16, v153
	v_and_b32_e32 v159, 0xffff0000, v153
	v_lshlrev_b32_e32 v160, 16, v154
	v_and_b32_e32 v161, 0xffff0000, v154
	v_lshlrev_b32_e32 v162, 16, v155
	v_and_b32_e32 v163, 0xffff0000, v155
	v_max_f32_e32 v156, v156, v156
	v_max_f32_e32 v157, v157, v157
	v_max_f32_e32 v158, v158, v158
	v_max_f32_e32 v159, v159, v159
	v_max_f32_e32 v160, v160, v160
	v_max_f32_e32 v161, v161, v161
	v_max_f32_e32 v162, v162, v162
	v_max_f32_e32 v163, v163, v163
	v_med3_f32 v156, v156, s48, v192
	v_med3_f32 v157, v157, s48, v192
	v_med3_f32 v158, v158, s48, v192
	v_med3_f32 v159, v159, s48, v192
	v_med3_f32 v160, v160, s48, v192
	v_med3_f32 v161, v161, s48, v192
	v_med3_f32 v162, v162, s48, v192
	v_med3_f32 v163, v163, s48, v192
	v_mul_f32_e32 v156, 0xbfb8aa3b, v156
	v_mul_f32_e32 v157, 0xbfb8aa3b, v157
	v_mul_f32_e32 v158, 0xbfb8aa3b, v158
	v_mul_f32_e32 v159, 0xbfb8aa3b, v159
	v_mul_f32_e32 v160, 0xbfb8aa3b, v160
	v_mul_f32_e32 v161, 0xbfb8aa3b, v161
	v_mul_f32_e32 v162, 0xbfb8aa3b, v162
	v_mul_f32_e32 v163, 0xbfb8aa3b, v163
	v_exp_f32_e32 v156, v156
	v_exp_f32_e32 v157, v157
	v_exp_f32_e32 v158, v158
	v_exp_f32_e32 v159, v159
	v_exp_f32_e32 v160, v160
	v_exp_f32_e32 v161, v161
	v_exp_f32_e32 v162, v162
	v_exp_f32_e32 v163, v163
	v_add_f32_e32 v156, 1.0, v156
	v_add_f32_e32 v157, 1.0, v157
	v_add_f32_e32 v158, 1.0, v158
	v_add_f32_e32 v159, 1.0, v159
	v_add_f32_e32 v160, 1.0, v160
	v_add_f32_e32 v161, 1.0, v161
	v_add_f32_e32 v162, 1.0, v162
	v_add_f32_e32 v163, 1.0, v163
	v_rcp_f32_e32 v156, v156
	v_rcp_f32_e32 v157, v157
	v_rcp_f32_e32 v158, v158
	v_rcp_f32_e32 v159, v159
	v_rcp_f32_e32 v160, v160
	v_rcp_f32_e32 v161, v161
	v_rcp_f32_e32 v162, v162
	v_rcp_f32_e32 v163, v163
	v_mul_f32_e32 v156, v156, v28
	v_mul_f32_e32 v157, v157, v29
	v_mul_f32_e32 v158, v158, v30
	v_mul_f32_e32 v159, v159, v31
	v_mul_f32_e32 v160, v160, v32
	v_mul_f32_e32 v161, v161, v33
	v_mul_f32_e32 v162, v162, v34
	v_mul_f32_e32 v163, v163, v35
	v_and_b32_sdwa v216, v156, v185 dst_sel:DWORD dst_unused:UNUSED_PAD src0_sel:WORD_1 src1_sel:DWORD
	v_and_b32_sdwa v217, v157, v185 dst_sel:DWORD dst_unused:UNUSED_PAD src0_sel:WORD_1 src1_sel:DWORD
	v_and_b32_sdwa v218, v158, v185 dst_sel:DWORD dst_unused:UNUSED_PAD src0_sel:WORD_1 src1_sel:DWORD
	v_and_b32_sdwa v219, v159, v185 dst_sel:DWORD dst_unused:UNUSED_PAD src0_sel:WORD_1 src1_sel:DWORD
	v_and_b32_sdwa v220, v160, v185 dst_sel:DWORD dst_unused:UNUSED_PAD src0_sel:WORD_1 src1_sel:DWORD
	v_and_b32_sdwa v221, v161, v185 dst_sel:DWORD dst_unused:UNUSED_PAD src0_sel:WORD_1 src1_sel:DWORD
	v_and_b32_sdwa v222, v162, v185 dst_sel:DWORD dst_unused:UNUSED_PAD src0_sel:WORD_1 src1_sel:DWORD
	v_and_b32_sdwa v223, v163, v185 dst_sel:DWORD dst_unused:UNUSED_PAD src0_sel:WORD_1 src1_sel:DWORD
	v_add3_u32 v156, v156, v216, s46
	v_add3_u32 v157, v157, v217, s46
	v_add3_u32 v158, v158, v218, s46
	v_add3_u32 v159, v159, v219, s46
	v_add3_u32 v160, v160, v220, s46
	v_add3_u32 v161, v161, v221, s46
	v_add3_u32 v162, v162, v222, s46
	v_add3_u32 v163, v163, v223, s46
	v_and_b32_e32 v157, 0xffff0000, v157
	v_and_b32_e32 v159, 0xffff0000, v159
	v_and_b32_e32 v161, 0xffff0000, v161
	v_and_b32_e32 v163, 0xffff0000, v163
	v_or_b32_sdwa v224, v157, v156 dst_sel:DWORD dst_unused:UNUSED_PAD src0_sel:DWORD src1_sel:WORD_1
	v_or_b32_sdwa v225, v159, v158 dst_sel:DWORD dst_unused:UNUSED_PAD src0_sel:DWORD src1_sel:WORD_1
	v_or_b32_sdwa v226, v161, v160 dst_sel:DWORD dst_unused:UNUSED_PAD src0_sel:DWORD src1_sel:WORD_1
	v_or_b32_sdwa v227, v163, v162 dst_sel:DWORD dst_unused:UNUSED_PAD src0_sel:DWORD src1_sel:WORD_1
	global_store_dwordx4 v[212:213], v[224:227], off offset:256
	s_mov_b64 s[12:13], 0

; __device__ __forceinline__ float sigmoidf_(float x) { return __builtin_amdgcn_rcpf(1.0f + __expf(-x)); }
; __device__ __forceinline__ void unpack8(const uint4 u, float (&f)[8]) { f[0] = bflo(u.x); f[1] = bfhi(u.x); f[2] = bflo(u.y); f[3] = bfhi(u.y); f[4] = bflo(u.z); f[5] = bfhi(u.z); f[6] = bflo(u.w); f[7] = bfhi(u.w); }
; __device__ __forceinline__ uint4 pack8(const float (&f)[8]) { uint4 u; u.x = pack2(f[0], f[1]); u.y = pack2(f[2], f[3]); u.z = pack2(f[4], f[5]); u.w = pack2(f[6], f[7]); return u; }
;     __device__ __forceinline__ void operator()(const f32x4 (&acc)[2][2][4][2], const Unit& u, int wr, int wc, int fr, int fq) const {
;         EPIP_ROWS( float pq[8]; unpack8(*(const uint4*)(pp + row * DM + col8 + co), pq); float o[8];
;             _Pragma("unroll") for (int e = 0; e < 4; ++e) { o[e] = sigmoidf_(v0[e]) * pq[e]; o[4 + e] = sigmoidf_(v1[e]) * pq[4 + e]; }
;             *(uint4*)(O + row * DM + col8 + co) = pack8(o); )
;     }
.LBB0_346:
	s_and_b64 vcc, exec, s[12:13]
	s_cbranch_vccz .LBB0_348
	v_lshl_or_b32 v2, s44, 8, v204
	v_ashrrev_i32_e32 v3, 31, v2
	v_lshl_add_u32 v0, s61, 8, v196
	s_waitcnt vmcnt(0)
	v_readlane_b32 s0, v249, 42
	v_readlane_b32 s1, v249, 43
	v_lshlrev_b64 v[132:133], 1, v[2:3]
	v_mov_b32_e32 v134, v0
	v_ashrrev_i32_e32 v135, 31, v0
	v_lshlrev_b64 v[134:135], 11, v[134:135]
	s_nop 1
	v_lshl_add_u64 v[208:209], s[0:1], 0, v[132:133]
	v_lshl_add_u64 v[208:209], v[208:209], 0, v[134:135]
	v_lshl_add_u64 v[206:207], s[70:71], 0, v[132:133]
	v_lshl_add_u64 v[206:207], v[206:207], 0, v[134:135]
	v_mov_b64_e32 v[2:3], v[208:209]
	global_load_dwordx4 v[132:135], v[2:3], off
	global_load_dwordx4 v[136:139], v[2:3], off offset:256
	s_mov_b64 s[0:1], 0x8000
	v_lshl_add_u64 v[2:3], v[208:209], 0, s[0:1]
	global_load_dwordx4 v[140:143], v[2:3], off
	global_load_dwordx4 v[144:147], v[2:3], off offset:256
	s_mov_b64 s[0:1], 0x10000
	v_lshl_add_u64 v[2:3], v[208:209], 0, s[0:1]
	global_load_dwordx4 v[148:151], v[2:3], off
	global_load_dwordx4 v[152:155], v[2:3], off offset:256
	s_mov_b64 s[0:1], 0x18000
	v_lshl_add_u64 v[2:3], v[208:209], 0, s[0:1]
	global_load_dwordx4 v[228:231], v[2:3], off
	global_load_dwordx4 v[232:235], v[2:3], off offset:256
	s_mov_b64 s[0:1], 0x40000
	v_lshl_add_u64 v[2:3], v[208:209], 0, s[0:1]
	global_load_dwordx4 v[236:239], v[2:3], off
	global_load_dwordx4 v[240:243], v[2:3], off offset:256
	v_mov_b64_e32 v[210:211], v[206:207]
	v_mul_f32_e32 v156, 0xbfb8aa3b, v48
	v_mul_f32_e32 v157, 0xbfb8aa3b, v49
	v_mul_f32_e32 v158, 0xbfb8aa3b, v50
	v_mul_f32_e32 v159, 0xbfb8aa3b, v51
	v_mul_f32_e32 v160, 0xbfb8aa3b, v52
	v_mul_f32_e32 v161, 0xbfb8aa3b, v53
	v_mul_f32_e32 v162, 0xbfb8aa3b, v54
	v_mul_f32_e32 v163, 0xbfb8aa3b, v55
	v_exp_f32_e32 v156, v156
	v_exp_f32_e32 v157, v157
	v_exp_f32_e32 v158, v158
	v_exp_f32_e32 v159, v159
	v_exp_f32_e32 v160, v160
	v_exp_f32_e32 v161, v161
	v_exp_f32_e32 v162, v162
	v_exp_f32_e32 v163, v163
	v_add_f32_e32 v156, 1.0, v156
	v_add_f32_e32 v157, 1.0, v157
	v_add_f32_e32 v158, 1.0, v158
	v_add_f32_e32 v159, 1.0, v159
	v_add_f32_e32 v160, 1.0, v160
	v_add_f32_e32 v161, 1.0, v161
	v_add_f32_e32 v162, 1.0, v162
	v_add_f32_e32 v163, 1.0, v163
	v_rcp_f32_e32 v156, v156
	v_rcp_f32_e32 v157, v157
	v_rcp_f32_e32 v158, v158
	v_rcp_f32_e32 v159, v159
	v_rcp_f32_e32 v160, v160
	v_rcp_f32_e32 v161, v161
	v_rcp_f32_e32 v162, v162
	v_rcp_f32_e32 v163, v163
	s_waitcnt vmcnt(8)
	v_lshlrev_b32_e32 v216, 16, v132
	v_and_b32_e32 v217, 0xffff0000, v132
	v_lshlrev_b32_e32 v218, 16, v133
	v_and_b32_e32 v219, 0xffff0000, v133
	v_lshlrev_b32_e32 v220, 16, v134
	v_and_b32_e32 v221, 0xffff0000, v134
	v_lshlrev_b32_e32 v222, 16, v135
	v_and_b32_e32 v223, 0xffff0000, v135
	v_mul_f32_e32 v156, v156, v216
	v_mul_f32_e32 v157, v157, v217
	v_mul_f32_e32 v158, v158, v218
	v_mul_f32_e32 v159, v159, v219
	v_mul_f32_e32 v160, v160, v220
	v_mul_f32_e32 v161, v161, v221
	v_mul_f32_e32 v162, v162, v222
	v_mul_f32_e32 v163, v163, v223
	v_and_b32_sdwa v216, v156, v185 dst_sel:DWORD dst_unused:UNUSED_PAD src0_sel:WORD_1 src1_sel:DWORD
	v_and_b32_sdwa v217, v157, v185 dst_sel:DWORD dst_unused:UNUSED_PAD src0_sel:WORD_1 src1_sel:DWORD
	v_and_b32_sdwa v218, v158, v185 dst_sel:DWORD dst_unused:UNUSED_PAD src0_sel:WORD_1 src1_sel:DWORD
	v_and_b32_sdwa v219, v159, v185 dst_sel:DWORD dst_unused:UNUSED_PAD src0_sel:WORD_1 src1_sel:DWORD
	v_and_b32_sdwa v220, v160, v185 dst_sel:DWORD dst_unused:UNUSED_PAD src0_sel:WORD_1 src1_sel:DWORD
	v_and_b32_sdwa v221, v161, v185 dst_sel:DWORD dst_unused:UNUSED_PAD src0_sel:WORD_1 src1_sel:DWORD
	v_and_b32_sdwa v222, v162, v185 dst_sel:DWORD dst_unused:UNUSED_PAD src0_sel:WORD_1 src1_sel:DWORD
	v_and_b32_sdwa v223, v163, v185 dst_sel:DWORD dst_unused:UNUSED_PAD src0_sel:WORD_1 src1_sel:DWORD
	v_add3_u32 v156, v156, v216, s46
	v_add3_u32 v157, v157, v217, s46
	v_add3_u32 v158, v158, v218, s46
	v_add3_u32 v159, v159, v219, s46
	v_add3_u32 v160, v160, v220, s46
	v_add3_u32 v161, v161, v221, s46
	v_add3_u32 v162, v162, v222, s46
	v_add3_u32 v163, v163, v223, s46
	v_and_b32_e32 v157, 0xffff0000, v157
	v_and_b32_e32 v159, 0xffff0000, v159
	v_and_b32_e32 v161, 0xffff0000, v161
	v_and_b32_e32 v163, 0xffff0000, v163
	v_or_b32_sdwa v176, v157, v156 dst_sel:DWORD dst_unused:UNUSED_PAD src0_sel:DWORD src1_sel:WORD_1
	v_or_b32_sdwa v177, v159, v158 dst_sel:DWORD dst_unused:UNUSED_PAD src0_sel:DWORD src1_sel:WORD_1
	v_or_b32_sdwa v178, v161, v160 dst_sel:DWORD dst_unused:UNUSED_PAD src0_sel:DWORD src1_sel:WORD_1
	v_or_b32_sdwa v179, v163, v162 dst_sel:DWORD dst_unused:UNUSED_PAD src0_sel:DWORD src1_sel:WORD_1
	global_store_dwordx4 v[210:211], v[176:179], off
	v_mul_f32_e32 v156, 0xbfb8aa3b, v80
	v_mul_f32_e32 v157, 0xbfb8aa3b, v81
	v_mul_f32_e32 v158, 0xbfb8aa3b, v82
	v_mul_f32_e32 v159, 0xbfb8aa3b, v83
	v_mul_f32_e32 v160, 0xbfb8aa3b, v84
	v_mul_f32_e32 v161, 0xbfb8aa3b, v85
	v_mul_f32_e32 v162, 0xbfb8aa3b, v86
	v_mul_f32_e32 v163, 0xbfb8aa3b, v87
	v_exp_f32_e32 v156, v156
	v_exp_f32_e32 v157, v157
	v_exp_f32_e32 v158, v158
	v_exp_f32_e32 v159, v159
	v_exp_f32_e32 v160, v160
	v_exp_f32_e32 v161, v161
	v_exp_f32_e32 v162, v162
	v_exp_f32_e32 v163, v163
	v_add_f32_e32 v156, 1.0, v156
	v_add_f32_e32 v157, 1.0, v157
	v_add_f32_e32 v158, 1.0, v158
	v_add_f32_e32 v159, 1.0, v159
	v_add_f32_e32 v160, 1.0, v160
	v_add_f32_e32 v161, 1.0, v161
	v_add_f32_e32 v162, 1.0, v162
	v_add_f32_e32 v163, 1.0, v163
	v_rcp_f32_e32 v156, v156
	v_rcp_f32_e32 v157, v157
	v_rcp_f32_e32 v158, v158
	v_rcp_f32_e32 v159, v159
	v_rcp_f32_e32 v160, v160
	v_rcp_f32_e32 v161, v161
	v_rcp_f32_e32 v162, v162
	v_rcp_f32_e32 v163, v163
	v_lshlrev_b32_e32 v216, 16, v136
; __device__ __forceinline__ float sigmoidf_(float x) { return __builtin_amdgcn_rcpf(1.0f + __expf(-x)); }
; __device__ __forceinline__ void unpack8(const uint4 u, float (&f)[8]) { f[0] = bflo(u.x); f[1] = bfhi(u.x); f[2] = bflo(u.y); f[3] = bfhi(u.y); f[4] = bflo(u.z); f[5] = bfhi(u.z); f[6] = bflo(u.w); f[7] = bfhi(u.w); }
; __device__ __forceinline__ uint4 pack8(const float (&f)[8]) { uint4 u; u.x = pack2(f[0], f[1]); u.y = pack2(f[2], f[3]); u.z = pack2(f[4], f[5]); u.w = pack2(f[6], f[7]); return u; }
;     __device__ __forceinline__ void operator()(const f32x4 (&acc)[2][2][4][2], const Unit& u, int wr, int wc, int fr, int fq) const {
;         EPIP_ROWS( float pq[8]; unpack8(*(const uint4*)(pp + row * DM + col8 + co), pq); float o[8];
;             _Pragma("unroll") for (int e = 0; e < 4; ++e) { o[e] = sigmoidf_(v0[e]) * pq[e]; o[4 + e] = sigmoidf_(v1[e]) * pq[4 + e]; }
;             *(uint4*)(O + row * DM + col8 + co) = pack8(o); )
;     }
	v_and_b32_e32 v217, 0xffff0000, v136
	v_lshlrev_b32_e32 v218, 16, v137
	v_and_b32_e32 v219, 0xffff0000, v137
	v_lshlrev_b32_e32 v220, 16, v138
	v_and_b32_e32 v221, 0xffff0000, v138
	v_lshlrev_b32_e32 v222, 16, v139
	v_and_b32_e32 v223, 0xffff0000, v139
	v_mul_f32_e32 v156, v156, v216
	v_mul_f32_e32 v157, v157, v217
	v_mul_f32_e32 v158, v158, v218
	v_mul_f32_e32 v159, v159, v219
	v_mul_f32_e32 v160, v160, v220
	v_mul_f32_e32 v161, v161, v221
	v_mul_f32_e32 v162, v162, v222
	v_mul_f32_e32 v163, v163, v223
	v_and_b32_sdwa v216, v156, v185 dst_sel:DWORD dst_unused:UNUSED_PAD src0_sel:WORD_1 src1_sel:DWORD
	v_and_b32_sdwa v217, v157, v185 dst_sel:DWORD dst_unused:UNUSED_PAD src0_sel:WORD_1 src1_sel:DWORD
	v_and_b32_sdwa v218, v158, v185 dst_sel:DWORD dst_unused:UNUSED_PAD src0_sel:WORD_1 src1_sel:DWORD
	v_and_b32_sdwa v219, v159, v185 dst_sel:DWORD dst_unused:UNUSED_PAD src0_sel:WORD_1 src1_sel:DWORD
	v_and_b32_sdwa v220, v160, v185 dst_sel:DWORD dst_unused:UNUSED_PAD src0_sel:WORD_1 src1_sel:DWORD
	v_and_b32_sdwa v221, v161, v185 dst_sel:DWORD dst_unused:UNUSED_PAD src0_sel:WORD_1 src1_sel:DWORD
	v_and_b32_sdwa v222, v162, v185 dst_sel:DWORD dst_unused:UNUSED_PAD src0_sel:WORD_1 src1_sel:DWORD
	v_and_b32_sdwa v223, v163, v185 dst_sel:DWORD dst_unused:UNUSED_PAD src0_sel:WORD_1 src1_sel:DWORD
	v_add3_u32 v156, v156, v216, s46
	v_add3_u32 v157, v157, v217, s46
	v_add3_u32 v158, v158, v218, s46
	v_add3_u32 v159, v159, v219, s46
	v_add3_u32 v160, v160, v220, s46
	v_add3_u32 v161, v161, v221, s46
	v_add3_u32 v162, v162, v222, s46
	v_add3_u32 v163, v163, v223, s46
	v_and_b32_e32 v157, 0xffff0000, v157
	v_and_b32_e32 v159, 0xffff0000, v159
	v_and_b32_e32 v161, 0xffff0000, v161
	v_and_b32_e32 v163, 0xffff0000, v163
	v_or_b32_sdwa v224, v157, v156 dst_sel:DWORD dst_unused:UNUSED_PAD src0_sel:DWORD src1_sel:WORD_1
	v_or_b32_sdwa v225, v159, v158 dst_sel:DWORD dst_unused:UNUSED_PAD src0_sel:DWORD src1_sel:WORD_1
	v_or_b32_sdwa v226, v161, v160 dst_sel:DWORD dst_unused:UNUSED_PAD src0_sel:DWORD src1_sel:WORD_1
	v_or_b32_sdwa v227, v163, v162 dst_sel:DWORD dst_unused:UNUSED_PAD src0_sel:DWORD src1_sel:WORD_1
	global_store_dwordx4 v[210:211], v[224:227], off offset:256
	s_mov_b64 s[0:1], 0x48000
	v_lshl_add_u64 v[2:3], v[208:209], 0, s[0:1]
	global_load_dwordx4 v[132:135], v[2:3], off
	global_load_dwordx4 v[136:139], v[2:3], off offset:256
	s_mov_b64 s[0:1], 0x8000
	v_lshl_add_u64 v[212:213], v[206:207], 0, s[0:1]
	v_mul_f32_e32 v156, 0xbfb8aa3b, v56
	v_mul_f32_e32 v157, 0xbfb8aa3b, v57
	v_mul_f32_e32 v158, 0xbfb8aa3b, v58
	v_mul_f32_e32 v159, 0xbfb8aa3b, v59
	v_mul_f32_e32 v160, 0xbfb8aa3b, v60
	v_mul_f32_e32 v161, 0xbfb8aa3b, v61
	v_mul_f32_e32 v162, 0xbfb8aa3b, v62
	v_mul_f32_e32 v163, 0xbfb8aa3b, v63
	v_exp_f32_e32 v156, v156
	v_exp_f32_e32 v157, v157
	v_exp_f32_e32 v158, v158
	v_exp_f32_e32 v159, v159
	v_exp_f32_e32 v160, v160
	v_exp_f32_e32 v161, v161
	v_exp_f32_e32 v162, v162
	v_exp_f32_e32 v163, v163
	v_add_f32_e32 v156, 1.0, v156
	v_add_f32_e32 v157, 1.0, v157
	v_add_f32_e32 v158, 1.0, v158
	v_add_f32_e32 v159, 1.0, v159
	v_add_f32_e32 v160, 1.0, v160
	v_add_f32_e32 v161, 1.0, v161
	v_add_f32_e32 v162, 1.0, v162
	v_add_f32_e32 v163, 1.0, v163
	v_rcp_f32_e32 v156, v156
	v_rcp_f32_e32 v157, v157
	v_rcp_f32_e32 v158, v158
	v_rcp_f32_e32 v159, v159
	v_rcp_f32_e32 v160, v160
	v_rcp_f32_e32 v161, v161
	v_rcp_f32_e32 v162, v162
	v_rcp_f32_e32 v163, v163
	s_waitcnt vmcnt(10)
	v_lshlrev_b32_e32 v216, 16, v140
	v_and_b32_e32 v217, 0xffff0000, v140
	v_lshlrev_b32_e32 v218, 16, v141
	v_and_b32_e32 v219, 0xffff0000, v141
	v_lshlrev_b32_e32 v220, 16, v142
	v_and_b32_e32 v221, 0xffff0000, v142
	v_lshlrev_b32_e32 v222, 16, v143
	v_and_b32_e32 v223, 0xffff0000, v143
	v_mul_f32_e32 v156, v156, v216
	v_mul_f32_e32 v157, v157, v217
	v_mul_f32_e32 v158, v158, v218
	v_mul_f32_e32 v159, v159, v219
	v_mul_f32_e32 v160, v160, v220
	v_mul_f32_e32 v161, v161, v221
	v_mul_f32_e32 v162, v162, v222
	v_mul_f32_e32 v163, v163, v223
	v_and_b32_sdwa v216, v156, v185 dst_sel:DWORD dst_unused:UNUSED_PAD src0_sel:WORD_1 src1_sel:DWORD
	v_and_b32_sdwa v217, v157, v185 dst_sel:DWORD dst_unused:UNUSED_PAD src0_sel:WORD_1 src1_sel:DWORD
	v_and_b32_sdwa v218, v158, v185 dst_sel:DWORD dst_unused:UNUSED_PAD src0_sel:WORD_1 src1_sel:DWORD
	v_and_b32_sdwa v219, v159, v185 dst_sel:DWORD dst_unused:UNUSED_PAD src0_sel:WORD_1 src1_sel:DWORD
	v_and_b32_sdwa v220, v160, v185 dst_sel:DWORD dst_unused:UNUSED_PAD src0_sel:WORD_1 src1_sel:DWORD
	v_and_b32_sdwa v221, v161, v185 dst_sel:DWORD dst_unused:UNUSED_PAD src0_sel:WORD_1 src1_sel:DWORD
	v_and_b32_sdwa v222, v162, v185 dst_sel:DWORD dst_unused:UNUSED_PAD src0_sel:WORD_1 src1_sel:DWORD
	v_and_b32_sdwa v223, v163, v185 dst_sel:DWORD dst_unused:UNUSED_PAD src0_sel:WORD_1 src1_sel:DWORD
	v_add3_u32 v156, v156, v216, s46
	v_add3_u32 v157, v157, v217, s46
	v_add3_u32 v158, v158, v218, s46
	v_add3_u32 v159, v159, v219, s46
	v_add3_u32 v160, v160, v220, s46
	v_add3_u32 v161, v161, v221, s46
	v_add3_u32 v162, v162, v222, s46
	v_add3_u32 v163, v163, v223, s46
	v_and_b32_e32 v157, 0xffff0000, v157
	v_and_b32_e32 v159, 0xffff0000, v159
	v_and_b32_e32 v161, 0xffff0000, v161
	v_and_b32_e32 v163, 0xffff0000, v163
	v_or_b32_sdwa v176, v157, v156 dst_sel:DWORD dst_unused:UNUSED_PAD src0_sel:DWORD src1_sel:WORD_1
	v_or_b32_sdwa v177, v159, v158 dst_sel:DWORD dst_unused:UNUSED_PAD src0_sel:DWORD src1_sel:WORD_1
	v_or_b32_sdwa v178, v161, v160 dst_sel:DWORD dst_unused:UNUSED_PAD src0_sel:DWORD src1_sel:WORD_1
	v_or_b32_sdwa v179, v163, v162 dst_sel:DWORD dst_unused:UNUSED_PAD src0_sel:DWORD src1_sel:WORD_1
	global_store_dwordx4 v[212:213], v[176:179], off
; __device__ __forceinline__ float sigmoidf_(float x) { return __builtin_amdgcn_rcpf(1.0f + __expf(-x)); }
; __device__ __forceinline__ void unpack8(const uint4 u, float (&f)[8]) { f[0] = bflo(u.x); f[1] = bfhi(u.x); f[2] = bflo(u.y); f[3] = bfhi(u.y); f[4] = bflo(u.z); f[5] = bfhi(u.z); f[6] = bflo(u.w); f[7] = bfhi(u.w); }
; __device__ __forceinline__ uint4 pack8(const float (&f)[8]) { uint4 u; u.x = pack2(f[0], f[1]); u.y = pack2(f[2], f[3]); u.z = pack2(f[4], f[5]); u.w = pack2(f[6], f[7]); return u; }
;     __device__ __forceinline__ void operator()(const f32x4 (&acc)[2][2][4][2], const Unit& u, int wr, int wc, int fr, int fq) const {
;         EPIP_ROWS( float pq[8]; unpack8(*(const uint4*)(pp + row * DM + col8 + co), pq); float o[8];
;             _Pragma("unroll") for (int e = 0; e < 4; ++e) { o[e] = sigmoidf_(v0[e]) * pq[e]; o[4 + e] = sigmoidf_(v1[e]) * pq[4 + e]; }
;             *(uint4*)(O + row * DM + col8 + co) = pack8(o); )
;     }
	v_mul_f32_e32 v156, 0xbfb8aa3b, v88
	v_mul_f32_e32 v157, 0xbfb8aa3b, v89
	v_mul_f32_e32 v158, 0xbfb8aa3b, v90
	v_mul_f32_e32 v159, 0xbfb8aa3b, v91
	v_mul_f32_e32 v160, 0xbfb8aa3b, v92
	v_mul_f32_e32 v161, 0xbfb8aa3b, v93
	v_mul_f32_e32 v162, 0xbfb8aa3b, v94
	v_mul_f32_e32 v163, 0xbfb8aa3b, v95
	v_exp_f32_e32 v156, v156
	v_exp_f32_e32 v157, v157
	v_exp_f32_e32 v158, v158
	v_exp_f32_e32 v159, v159
	v_exp_f32_e32 v160, v160
	v_exp_f32_e32 v161, v161
	v_exp_f32_e32 v162, v162
	v_exp_f32_e32 v163, v163
	v_add_f32_e32 v156, 1.0, v156
	v_add_f32_e32 v157, 1.0, v157
	v_add_f32_e32 v158, 1.0, v158
	v_add_f32_e32 v159, 1.0, v159
	v_add_f32_e32 v160, 1.0, v160
	v_add_f32_e32 v161, 1.0, v161
	v_add_f32_e32 v162, 1.0, v162
	v_add_f32_e32 v163, 1.0, v163
	v_rcp_f32_e32 v156, v156
	v_rcp_f32_e32 v157, v157
	v_rcp_f32_e32 v158, v158
	v_rcp_f32_e32 v159, v159
	v_rcp_f32_e32 v160, v160
	v_rcp_f32_e32 v161, v161
	v_rcp_f32_e32 v162, v162
	v_rcp_f32_e32 v163, v163
	v_lshlrev_b32_e32 v216, 16, v144
	v_and_b32_e32 v217, 0xffff0000, v144
	v_lshlrev_b32_e32 v218, 16, v145
	v_and_b32_e32 v219, 0xffff0000, v145
	v_lshlrev_b32_e32 v220, 16, v146
	v_and_b32_e32 v221, 0xffff0000, v146
	v_lshlrev_b32_e32 v222, 16, v147
	v_and_b32_e32 v223, 0xffff0000, v147
	v_mul_f32_e32 v156, v156, v216
	v_mul_f32_e32 v157, v157, v217
	v_mul_f32_e32 v158, v158, v218
	v_mul_f32_e32 v159, v159, v219
	v_mul_f32_e32 v160, v160, v220
	v_mul_f32_e32 v161, v161, v221
	v_mul_f32_e32 v162, v162, v222
	v_mul_f32_e32 v163, v163, v223
	v_and_b32_sdwa v216, v156, v185 dst_sel:DWORD dst_unused:UNUSED_PAD src0_sel:WORD_1 src1_sel:DWORD
	v_and_b32_sdwa v217, v157, v185 dst_sel:DWORD dst_unused:UNUSED_PAD src0_sel:WORD_1 src1_sel:DWORD
	v_and_b32_sdwa v218, v158, v185 dst_sel:DWORD dst_unused:UNUSED_PAD src0_sel:WORD_1 src1_sel:DWORD
	v_and_b32_sdwa v219, v159, v185 dst_sel:DWORD dst_unused:UNUSED_PAD src0_sel:WORD_1 src1_sel:DWORD
	v_and_b32_sdwa v220, v160, v185 dst_sel:DWORD dst_unused:UNUSED_PAD src0_sel:WORD_1 src1_sel:DWORD
	v_and_b32_sdwa v221, v161, v185 dst_sel:DWORD dst_unused:UNUSED_PAD src0_sel:WORD_1 src1_sel:DWORD
	v_and_b32_sdwa v222, v162, v185 dst_sel:DWORD dst_unused:UNUSED_PAD src0_sel:WORD_1 src1_sel:DWORD
	v_and_b32_sdwa v223, v163, v185 dst_sel:DWORD dst_unused:UNUSED_PAD src0_sel:WORD_1 src1_sel:DWORD
	v_add3_u32 v156, v156, v216, s46
	v_add3_u32 v157, v157, v217, s46
	v_add3_u32 v158, v158, v218, s46
	v_add3_u32 v159, v159, v219, s46
	v_add3_u32 v160, v160, v220, s46
	v_add3_u32 v161, v161, v221, s46
	v_add3_u32 v162, v162, v222, s46
	v_add3_u32 v163, v163, v223, s46
	v_and_b32_e32 v157, 0xffff0000, v157
	v_and_b32_e32 v159, 0xffff0000, v159
	v_and_b32_e32 v161, 0xffff0000, v161
	v_and_b32_e32 v163, 0xffff0000, v163
	v_or_b32_sdwa v224, v157, v156 dst_sel:DWORD dst_unused:UNUSED_PAD src0_sel:DWORD src1_sel:WORD_1
	v_or_b32_sdwa v225, v159, v158 dst_sel:DWORD dst_unused:UNUSED_PAD src0_sel:DWORD src1_sel:WORD_1
	v_or_b32_sdwa v226, v161, v160 dst_sel:DWORD dst_unused:UNUSED_PAD src0_sel:DWORD src1_sel:WORD_1
	v_or_b32_sdwa v227, v163, v162 dst_sel:DWORD dst_unused:UNUSED_PAD src0_sel:DWORD src1_sel:WORD_1
	global_store_dwordx4 v[212:213], v[224:227], off offset:256
	s_mov_b64 s[0:1], 0x50000
	v_lshl_add_u64 v[2:3], v[208:209], 0, s[0:1]
	global_load_dwordx4 v[140:143], v[2:3], off
	global_load_dwordx4 v[144:147], v[2:3], off offset:256
	s_mov_b64 s[0:1], 0x10000
	v_lshl_add_u64 v[210:211], v[206:207], 0, s[0:1]
	v_mul_f32_e32 v156, 0xbfb8aa3b, v64
	v_mul_f32_e32 v157, 0xbfb8aa3b, v65
	v_mul_f32_e32 v158, 0xbfb8aa3b, v66
	v_mul_f32_e32 v159, 0xbfb8aa3b, v67
	v_mul_f32_e32 v160, 0xbfb8aa3b, v68
	v_mul_f32_e32 v161, 0xbfb8aa3b, v69
	v_mul_f32_e32 v162, 0xbfb8aa3b, v70
	v_mul_f32_e32 v163, 0xbfb8aa3b, v71
	v_exp_f32_e32 v156, v156
	v_exp_f32_e32 v157, v157
	v_exp_f32_e32 v158, v158
	v_exp_f32_e32 v159, v159
	v_exp_f32_e32 v160, v160
	v_exp_f32_e32 v161, v161
	v_exp_f32_e32 v162, v162
	v_exp_f32_e32 v163, v163
	v_add_f32_e32 v156, 1.0, v156
	v_add_f32_e32 v157, 1.0, v157
	v_add_f32_e32 v158, 1.0, v158
	v_add_f32_e32 v159, 1.0, v159
	v_add_f32_e32 v160, 1.0, v160
	v_add_f32_e32 v161, 1.0, v161
	v_add_f32_e32 v162, 1.0, v162
	v_add_f32_e32 v163, 1.0, v163
	v_rcp_f32_e32 v156, v156
	v_rcp_f32_e32 v157, v157
	v_rcp_f32_e32 v158, v158
	v_rcp_f32_e32 v159, v159
	v_rcp_f32_e32 v160, v160
	v_rcp_f32_e32 v161, v161
	v_rcp_f32_e32 v162, v162
	v_rcp_f32_e32 v163, v163
	s_waitcnt vmcnt(12)
; __device__ __forceinline__ float sigmoidf_(float x) { return __builtin_amdgcn_rcpf(1.0f + __expf(-x)); }
; __device__ __forceinline__ void unpack8(const uint4 u, float (&f)[8]) { f[0] = bflo(u.x); f[1] = bfhi(u.x); f[2] = bflo(u.y); f[3] = bfhi(u.y); f[4] = bflo(u.z); f[5] = bfhi(u.z); f[6] = bflo(u.w); f[7] = bfhi(u.w); }
; __device__ __forceinline__ uint4 pack8(const float (&f)[8]) { uint4 u; u.x = pack2(f[0], f[1]); u.y = pack2(f[2], f[3]); u.z = pack2(f[4], f[5]); u.w = pack2(f[6], f[7]); return u; }
;     __device__ __forceinline__ void operator()(const f32x4 (&acc)[2][2][4][2], const Unit& u, int wr, int wc, int fr, int fq) const {
;         EPIP_ROWS( float pq[8]; unpack8(*(const uint4*)(pp + row * DM + col8 + co), pq); float o[8];
;             _Pragma("unroll") for (int e = 0; e < 4; ++e) { o[e] = sigmoidf_(v0[e]) * pq[e]; o[4 + e] = sigmoidf_(v1[e]) * pq[4 + e]; }
;             *(uint4*)(O + row * DM + col8 + co) = pack8(o); )
;     }
	v_lshlrev_b32_e32 v216, 16, v148
	v_and_b32_e32 v217, 0xffff0000, v148
	v_lshlrev_b32_e32 v218, 16, v149
	v_and_b32_e32 v219, 0xffff0000, v149
	v_lshlrev_b32_e32 v220, 16, v150
	v_and_b32_e32 v221, 0xffff0000, v150
	v_lshlrev_b32_e32 v222, 16, v151
	v_and_b32_e32 v223, 0xffff0000, v151
	v_mul_f32_e32 v156, v156, v216
	v_mul_f32_e32 v157, v157, v217
	v_mul_f32_e32 v158, v158, v218
	v_mul_f32_e32 v159, v159, v219
	v_mul_f32_e32 v160, v160, v220
	v_mul_f32_e32 v161, v161, v221
	v_mul_f32_e32 v162, v162, v222
	v_mul_f32_e32 v163, v163, v223
	v_and_b32_sdwa v216, v156, v185 dst_sel:DWORD dst_unused:UNUSED_PAD src0_sel:WORD_1 src1_sel:DWORD
	v_and_b32_sdwa v217, v157, v185 dst_sel:DWORD dst_unused:UNUSED_PAD src0_sel:WORD_1 src1_sel:DWORD
	v_and_b32_sdwa v218, v158, v185 dst_sel:DWORD dst_unused:UNUSED_PAD src0_sel:WORD_1 src1_sel:DWORD
	v_and_b32_sdwa v219, v159, v185 dst_sel:DWORD dst_unused:UNUSED_PAD src0_sel:WORD_1 src1_sel:DWORD
	v_and_b32_sdwa v220, v160, v185 dst_sel:DWORD dst_unused:UNUSED_PAD src0_sel:WORD_1 src1_sel:DWORD
	v_and_b32_sdwa v221, v161, v185 dst_sel:DWORD dst_unused:UNUSED_PAD src0_sel:WORD_1 src1_sel:DWORD
	v_and_b32_sdwa v222, v162, v185 dst_sel:DWORD dst_unused:UNUSED_PAD src0_sel:WORD_1 src1_sel:DWORD
	v_and_b32_sdwa v223, v163, v185 dst_sel:DWORD dst_unused:UNUSED_PAD src0_sel:WORD_1 src1_sel:DWORD
	v_add3_u32 v156, v156, v216, s46
	v_add3_u32 v157, v157, v217, s46
	v_add3_u32 v158, v158, v218, s46
	v_add3_u32 v159, v159, v219, s46
	v_add3_u32 v160, v160, v220, s46
	v_add3_u32 v161, v161, v221, s46
	v_add3_u32 v162, v162, v222, s46
	v_add3_u32 v163, v163, v223, s46
	v_and_b32_e32 v157, 0xffff0000, v157
	v_and_b32_e32 v159, 0xffff0000, v159
	v_and_b32_e32 v161, 0xffff0000, v161
	v_and_b32_e32 v163, 0xffff0000, v163
	v_or_b32_sdwa v176, v157, v156 dst_sel:DWORD dst_unused:UNUSED_PAD src0_sel:DWORD src1_sel:WORD_1
	v_or_b32_sdwa v177, v159, v158 dst_sel:DWORD dst_unused:UNUSED_PAD src0_sel:DWORD src1_sel:WORD_1
	v_or_b32_sdwa v178, v161, v160 dst_sel:DWORD dst_unused:UNUSED_PAD src0_sel:DWORD src1_sel:WORD_1
	v_or_b32_sdwa v179, v163, v162 dst_sel:DWORD dst_unused:UNUSED_PAD src0_sel:DWORD src1_sel:WORD_1
	global_store_dwordx4 v[210:211], v[176:179], off
	v_mul_f32_e32 v156, 0xbfb8aa3b, v96
	v_mul_f32_e32 v157, 0xbfb8aa3b, v97
	v_mul_f32_e32 v158, 0xbfb8aa3b, v98
	v_mul_f32_e32 v159, 0xbfb8aa3b, v99
	v_mul_f32_e32 v160, 0xbfb8aa3b, v100
	v_mul_f32_e32 v161, 0xbfb8aa3b, v101
	v_mul_f32_e32 v162, 0xbfb8aa3b, v102
	v_mul_f32_e32 v163, 0xbfb8aa3b, v103
	v_exp_f32_e32 v156, v156
	v_exp_f32_e32 v157, v157
	v_exp_f32_e32 v158, v158
	v_exp_f32_e32 v159, v159
	v_exp_f32_e32 v160, v160
	v_exp_f32_e32 v161, v161
	v_exp_f32_e32 v162, v162
	v_exp_f32_e32 v163, v163
	v_add_f32_e32 v156, 1.0, v156
	v_add_f32_e32 v157, 1.0, v157
	v_add_f32_e32 v158, 1.0, v158
	v_add_f32_e32 v159, 1.0, v159
	v_add_f32_e32 v160, 1.0, v160
	v_add_f32_e32 v161, 1.0, v161
	v_add_f32_e32 v162, 1.0, v162
	v_add_f32_e32 v163, 1.0, v163
	v_rcp_f32_e32 v156, v156
	v_rcp_f32_e32 v157, v157
	v_rcp_f32_e32 v158, v158
	v_rcp_f32_e32 v159, v159
	v_rcp_f32_e32 v160, v160
	v_rcp_f32_e32 v161, v161
	v_rcp_f32_e32 v162, v162
	v_rcp_f32_e32 v163, v163
	v_lshlrev_b32_e32 v216, 16, v152
	v_and_b32_e32 v217, 0xffff0000, v152
	v_lshlrev_b32_e32 v218, 16, v153
	v_and_b32_e32 v219, 0xffff0000, v153
	v_lshlrev_b32_e32 v220, 16, v154
	v_and_b32_e32 v221, 0xffff0000, v154
	v_lshlrev_b32_e32 v222, 16, v155
	v_and_b32_e32 v223, 0xffff0000, v155
	v_mul_f32_e32 v156, v156, v216
	v_mul_f32_e32 v157, v157, v217
	v_mul_f32_e32 v158, v158, v218
	v_mul_f32_e32 v159, v159, v219
	v_mul_f32_e32 v160, v160, v220
	v_mul_f32_e32 v161, v161, v221
	v_mul_f32_e32 v162, v162, v222
	v_mul_f32_e32 v163, v163, v223
	v_and_b32_sdwa v216, v156, v185 dst_sel:DWORD dst_unused:UNUSED_PAD src0_sel:WORD_1 src1_sel:DWORD
	v_and_b32_sdwa v217, v157, v185 dst_sel:DWORD dst_unused:UNUSED_PAD src0_sel:WORD_1 src1_sel:DWORD
	v_and_b32_sdwa v218, v158, v185 dst_sel:DWORD dst_unused:UNUSED_PAD src0_sel:WORD_1 src1_sel:DWORD
	v_and_b32_sdwa v219, v159, v185 dst_sel:DWORD dst_unused:UNUSED_PAD src0_sel:WORD_1 src1_sel:DWORD
	v_and_b32_sdwa v220, v160, v185 dst_sel:DWORD dst_unused:UNUSED_PAD src0_sel:WORD_1 src1_sel:DWORD
	v_and_b32_sdwa v221, v161, v185 dst_sel:DWORD dst_unused:UNUSED_PAD src0_sel:WORD_1 src1_sel:DWORD
	v_and_b32_sdwa v222, v162, v185 dst_sel:DWORD dst_unused:UNUSED_PAD src0_sel:WORD_1 src1_sel:DWORD
	v_and_b32_sdwa v223, v163, v185 dst_sel:DWORD dst_unused:UNUSED_PAD src0_sel:WORD_1 src1_sel:DWORD
	v_add3_u32 v156, v156, v216, s46
	v_add3_u32 v157, v157, v217, s46
	v_add3_u32 v158, v158, v218, s46
	v_add3_u32 v159, v159, v219, s46
	v_add3_u32 v160, v160, v220, s46
	v_add3_u32 v161, v161, v221, s46
	v_add3_u32 v162, v162, v222, s46
	v_add3_u32 v163, v163, v223, s46
	v_and_b32_e32 v157, 0xffff0000, v157
	v_and_b32_e32 v159, 0xffff0000, v159
	v_and_b32_e32 v161, 0xffff0000, v161
	v_and_b32_e32 v163, 0xffff0000, v163
	v_or_b32_sdwa v224, v157, v156 dst_sel:DWORD dst_unused:UNUSED_PAD src0_sel:DWORD src1_sel:WORD_1
	v_or_b32_sdwa v225, v159, v158 dst_sel:DWORD dst_unused:UNUSED_PAD src0_sel:DWORD src1_sel:WORD_1
	v_or_b32_sdwa v226, v161, v160 dst_sel:DWORD dst_unused:UNUSED_PAD src0_sel:DWORD src1_sel:WORD_1
	v_or_b32_sdwa v227, v163, v162 dst_sel:DWORD dst_unused:UNUSED_PAD src0_sel:DWORD src1_sel:WORD_1
	global_store_dwordx4 v[210:211], v[224:227], off offset:256
	s_mov_b64 s[0:1], 0x58000
	v_lshl_add_u64 v[2:3], v[208:209], 0, s[0:1]
	global_load_dwordx4 v[148:151], v[2:3], off
	global_load_dwordx4 v[152:155], v[2:3], off offset:256
	s_mov_b64 s[0:1], 0x18000
	v_lshl_add_u64 v[212:213], v[206:207], 0, s[0:1]
	v_mul_f32_e32 v156, 0xbfb8aa3b, v72
	v_mul_f32_e32 v157, 0xbfb8aa3b, v73
	v_mul_f32_e32 v158, 0xbfb8aa3b, v74
	v_mul_f32_e32 v159, 0xbfb8aa3b, v75
	v_mul_f32_e32 v160, 0xbfb8aa3b, v76
	v_mul_f32_e32 v161, 0xbfb8aa3b, v77
	v_mul_f32_e32 v162, 0xbfb8aa3b, v78
	v_mul_f32_e32 v163, 0xbfb8aa3b, v79
	v_exp_f32_e32 v156, v156
	v_exp_f32_e32 v157, v157
	v_exp_f32_e32 v158, v158
	v_exp_f32_e32 v159, v159
	v_exp_f32_e32 v160, v160
	v_exp_f32_e32 v161, v161
	v_exp_f32_e32 v162, v162
	v_exp_f32_e32 v163, v163
	v_add_f32_e32 v156, 1.0, v156
	v_add_f32_e32 v157, 1.0, v157
	v_add_f32_e32 v158, 1.0, v158
	v_add_f32_e32 v159, 1.0, v159
	v_add_f32_e32 v160, 1.0, v160
	v_add_f32_e32 v161, 1.0, v161
	v_add_f32_e32 v162, 1.0, v162
	v_add_f32_e32 v163, 1.0, v163
	v_rcp_f32_e32 v156, v156
	v_rcp_f32_e32 v157, v157
	v_rcp_f32_e32 v158, v158
	v_rcp_f32_e32 v159, v159
	v_rcp_f32_e32 v160, v160
	v_rcp_f32_e32 v161, v161
	v_rcp_f32_e32 v162, v162
	v_rcp_f32_e32 v163, v163
	s_waitcnt vmcnt(14)
; __device__ __forceinline__ float sigmoidf_(float x) { return __builtin_amdgcn_rcpf(1.0f + __expf(-x)); }
; __device__ __forceinline__ void unpack8(const uint4 u, float (&f)[8]) { f[0] = bflo(u.x); f[1] = bfhi(u.x); f[2] = bflo(u.y); f[3] = bfhi(u.y); f[4] = bflo(u.z); f[5] = bfhi(u.z); f[6] = bflo(u.w); f[7] = bfhi(u.w); }
; __device__ __forceinline__ uint4 pack8(const float (&f)[8]) { uint4 u; u.x = pack2(f[0], f[1]); u.y = pack2(f[2], f[3]); u.z = pack2(f[4], f[5]); u.w = pack2(f[6], f[7]); return u; }
;     __device__ __forceinline__ void operator()(const f32x4 (&acc)[2][2][4][2], const Unit& u, int wr, int wc, int fr, int fq) const {
;         EPIP_ROWS( float pq[8]; unpack8(*(const uint4*)(pp + row * DM + col8 + co), pq); float o[8];
;             _Pragma("unroll") for (int e = 0; e < 4; ++e) { o[e] = sigmoidf_(v0[e]) * pq[e]; o[4 + e] = sigmoidf_(v1[e]) * pq[4 + e]; }
;             *(uint4*)(O + row * DM + col8 + co) = pack8(o); )
;     }
	v_lshlrev_b32_e32 v216, 16, v228
	v_and_b32_e32 v217, 0xffff0000, v228
	v_lshlrev_b32_e32 v218, 16, v229
	v_and_b32_e32 v219, 0xffff0000, v229
	v_lshlrev_b32_e32 v220, 16, v230
	v_and_b32_e32 v221, 0xffff0000, v230
	v_lshlrev_b32_e32 v222, 16, v231
	v_and_b32_e32 v223, 0xffff0000, v231
	v_mul_f32_e32 v156, v156, v216
	v_mul_f32_e32 v157, v157, v217
	v_mul_f32_e32 v158, v158, v218
	v_mul_f32_e32 v159, v159, v219
	v_mul_f32_e32 v160, v160, v220
	v_mul_f32_e32 v161, v161, v221
	v_mul_f32_e32 v162, v162, v222
	v_mul_f32_e32 v163, v163, v223
	v_and_b32_sdwa v216, v156, v185 dst_sel:DWORD dst_unused:UNUSED_PAD src0_sel:WORD_1 src1_sel:DWORD
	v_and_b32_sdwa v217, v157, v185 dst_sel:DWORD dst_unused:UNUSED_PAD src0_sel:WORD_1 src1_sel:DWORD
	v_and_b32_sdwa v218, v158, v185 dst_sel:DWORD dst_unused:UNUSED_PAD src0_sel:WORD_1 src1_sel:DWORD
	v_and_b32_sdwa v219, v159, v185 dst_sel:DWORD dst_unused:UNUSED_PAD src0_sel:WORD_1 src1_sel:DWORD
	v_and_b32_sdwa v220, v160, v185 dst_sel:DWORD dst_unused:UNUSED_PAD src0_sel:WORD_1 src1_sel:DWORD
	v_and_b32_sdwa v221, v161, v185 dst_sel:DWORD dst_unused:UNUSED_PAD src0_sel:WORD_1 src1_sel:DWORD
	v_and_b32_sdwa v222, v162, v185 dst_sel:DWORD dst_unused:UNUSED_PAD src0_sel:WORD_1 src1_sel:DWORD
	v_and_b32_sdwa v223, v163, v185 dst_sel:DWORD dst_unused:UNUSED_PAD src0_sel:WORD_1 src1_sel:DWORD
	v_add3_u32 v156, v156, v216, s46
	v_add3_u32 v157, v157, v217, s46
	v_add3_u32 v158, v158, v218, s46
	v_add3_u32 v159, v159, v219, s46
	v_add3_u32 v160, v160, v220, s46
	v_add3_u32 v161, v161, v221, s46
	v_add3_u32 v162, v162, v222, s46
	v_add3_u32 v163, v163, v223, s46
	v_and_b32_e32 v157, 0xffff0000, v157
	v_and_b32_e32 v159, 0xffff0000, v159
	v_and_b32_e32 v161, 0xffff0000, v161
	v_and_b32_e32 v163, 0xffff0000, v163
	v_or_b32_sdwa v176, v157, v156 dst_sel:DWORD dst_unused:UNUSED_PAD src0_sel:DWORD src1_sel:WORD_1
	v_or_b32_sdwa v177, v159, v158 dst_sel:DWORD dst_unused:UNUSED_PAD src0_sel:DWORD src1_sel:WORD_1
	v_or_b32_sdwa v178, v161, v160 dst_sel:DWORD dst_unused:UNUSED_PAD src0_sel:DWORD src1_sel:WORD_1
	v_or_b32_sdwa v179, v163, v162 dst_sel:DWORD dst_unused:UNUSED_PAD src0_sel:DWORD src1_sel:WORD_1
	global_store_dwordx4 v[212:213], v[176:179], off
	v_mul_f32_e32 v156, 0xbfb8aa3b, v104
	v_mul_f32_e32 v157, 0xbfb8aa3b, v105
	v_mul_f32_e32 v158, 0xbfb8aa3b, v106
	v_mul_f32_e32 v159, 0xbfb8aa3b, v107
	v_mul_f32_e32 v160, 0xbfb8aa3b, v108
	v_mul_f32_e32 v161, 0xbfb8aa3b, v109
	v_mul_f32_e32 v162, 0xbfb8aa3b, v110
	v_mul_f32_e32 v163, 0xbfb8aa3b, v111
	v_exp_f32_e32 v156, v156
	v_exp_f32_e32 v157, v157
	v_exp_f32_e32 v158, v158
	v_exp_f32_e32 v159, v159
	v_exp_f32_e32 v160, v160
	v_exp_f32_e32 v161, v161
	v_exp_f32_e32 v162, v162
	v_exp_f32_e32 v163, v163
	v_add_f32_e32 v156, 1.0, v156
	v_add_f32_e32 v157, 1.0, v157
	v_add_f32_e32 v158, 1.0, v158
	v_add_f32_e32 v159, 1.0, v159
	v_add_f32_e32 v160, 1.0, v160
	v_add_f32_e32 v161, 1.0, v161
	v_add_f32_e32 v162, 1.0, v162
	v_add_f32_e32 v163, 1.0, v163
	v_rcp_f32_e32 v156, v156
	v_rcp_f32_e32 v157, v157
	v_rcp_f32_e32 v158, v158
	v_rcp_f32_e32 v159, v159
	v_rcp_f32_e32 v160, v160
	v_rcp_f32_e32 v161, v161
	v_rcp_f32_e32 v162, v162
	v_rcp_f32_e32 v163, v163
	v_lshlrev_b32_e32 v216, 16, v232
	v_and_b32_e32 v217, 0xffff0000, v232
	v_lshlrev_b32_e32 v218, 16, v233
	v_and_b32_e32 v219, 0xffff0000, v233
	v_lshlrev_b32_e32 v220, 16, v234
	v_and_b32_e32 v221, 0xffff0000, v234
	v_lshlrev_b32_e32 v222, 16, v235
	v_and_b32_e32 v223, 0xffff0000, v235
	v_mul_f32_e32 v156, v156, v216
	v_mul_f32_e32 v157, v157, v217
	v_mul_f32_e32 v158, v158, v218
	v_mul_f32_e32 v159, v159, v219
	v_mul_f32_e32 v160, v160, v220
	v_mul_f32_e32 v161, v161, v221
	v_mul_f32_e32 v162, v162, v222
	v_mul_f32_e32 v163, v163, v223
	v_and_b32_sdwa v216, v156, v185 dst_sel:DWORD dst_unused:UNUSED_PAD src0_sel:WORD_1 src1_sel:DWORD
	v_and_b32_sdwa v217, v157, v185 dst_sel:DWORD dst_unused:UNUSED_PAD src0_sel:WORD_1 src1_sel:DWORD
	v_and_b32_sdwa v218, v158, v185 dst_sel:DWORD dst_unused:UNUSED_PAD src0_sel:WORD_1 src1_sel:DWORD
	v_and_b32_sdwa v219, v159, v185 dst_sel:DWORD dst_unused:UNUSED_PAD src0_sel:WORD_1 src1_sel:DWORD
	v_and_b32_sdwa v220, v160, v185 dst_sel:DWORD dst_unused:UNUSED_PAD src0_sel:WORD_1 src1_sel:DWORD
	v_and_b32_sdwa v221, v161, v185 dst_sel:DWORD dst_unused:UNUSED_PAD src0_sel:WORD_1 src1_sel:DWORD
	v_and_b32_sdwa v222, v162, v185 dst_sel:DWORD dst_unused:UNUSED_PAD src0_sel:WORD_1 src1_sel:DWORD
	v_and_b32_sdwa v223, v163, v185 dst_sel:DWORD dst_unused:UNUSED_PAD src0_sel:WORD_1 src1_sel:DWORD
	v_add3_u32 v156, v156, v216, s46
	v_add3_u32 v157, v157, v217, s46
	v_add3_u32 v158, v158, v218, s46
	v_add3_u32 v159, v159, v219, s46
	v_add3_u32 v160, v160, v220, s46
	v_add3_u32 v161, v161, v221, s46
	v_add3_u32 v162, v162, v222, s46
	v_add3_u32 v163, v163, v223, s46
	v_and_b32_e32 v157, 0xffff0000, v157
	v_and_b32_e32 v159, 0xffff0000, v159
	v_and_b32_e32 v161, 0xffff0000, v161
	v_and_b32_e32 v163, 0xffff0000, v163
	v_or_b32_sdwa v224, v157, v156 dst_sel:DWORD dst_unused:UNUSED_PAD src0_sel:DWORD src1_sel:WORD_1
	v_or_b32_sdwa v225, v159, v158 dst_sel:DWORD dst_unused:UNUSED_PAD src0_sel:DWORD src1_sel:WORD_1
	v_or_b32_sdwa v226, v161, v160 dst_sel:DWORD dst_unused:UNUSED_PAD src0_sel:DWORD src1_sel:WORD_1
	v_or_b32_sdwa v227, v163, v162 dst_sel:DWORD dst_unused:UNUSED_PAD src0_sel:DWORD src1_sel:WORD_1
	global_store_dwordx4 v[212:213], v[224:227], off offset:256
	s_mov_b64 s[0:1], 0x40000
	v_lshl_add_u64 v[210:211], v[206:207], 0, s[0:1]
	v_mul_f32_e32 v156, 0xbfb8aa3b, v112
	v_mul_f32_e32 v157, 0xbfb8aa3b, v113
	v_mul_f32_e32 v158, 0xbfb8aa3b, v114
	v_mul_f32_e32 v159, 0xbfb8aa3b, v115
	v_mul_f32_e32 v160, 0xbfb8aa3b, v116
	v_mul_f32_e32 v161, 0xbfb8aa3b, v117
	v_mul_f32_e32 v162, 0xbfb8aa3b, v118
	v_mul_f32_e32 v163, 0xbfb8aa3b, v119
	v_exp_f32_e32 v156, v156
	v_exp_f32_e32 v157, v157
	v_exp_f32_e32 v158, v158
	v_exp_f32_e32 v159, v159
	v_exp_f32_e32 v160, v160
	v_exp_f32_e32 v161, v161
	v_exp_f32_e32 v162, v162
	v_exp_f32_e32 v163, v163
	v_add_f32_e32 v156, 1.0, v156
	v_add_f32_e32 v157, 1.0, v157
	v_add_f32_e32 v158, 1.0, v158
	v_add_f32_e32 v159, 1.0, v159
	v_add_f32_e32 v160, 1.0, v160
	v_add_f32_e32 v161, 1.0, v161
	v_add_f32_e32 v162, 1.0, v162
	v_add_f32_e32 v163, 1.0, v163
	v_rcp_f32_e32 v156, v156
	v_rcp_f32_e32 v157, v157
	v_rcp_f32_e32 v158, v158
	v_rcp_f32_e32 v159, v159
	v_rcp_f32_e32 v160, v160
	v_rcp_f32_e32 v161, v161
	v_rcp_f32_e32 v162, v162
	v_rcp_f32_e32 v163, v163
	s_waitcnt vmcnt(14)
; __device__ __forceinline__ float sigmoidf_(float x) { return __builtin_amdgcn_rcpf(1.0f + __expf(-x)); }
; __device__ __forceinline__ void unpack8(const uint4 u, float (&f)[8]) { f[0] = bflo(u.x); f[1] = bfhi(u.x); f[2] = bflo(u.y); f[3] = bfhi(u.y); f[4] = bflo(u.z); f[5] = bfhi(u.z); f[6] = bflo(u.w); f[7] = bfhi(u.w); }
; __device__ __forceinline__ uint4 pack8(const float (&f)[8]) { uint4 u; u.x = pack2(f[0], f[1]); u.y = pack2(f[2], f[3]); u.z = pack2(f[4], f[5]); u.w = pack2(f[6], f[7]); return u; }
;     __device__ __forceinline__ void operator()(const f32x4 (&acc)[2][2][4][2], const Unit& u, int wr, int wc, int fr, int fq) const {
;         EPIP_ROWS( float pq[8]; unpack8(*(const uint4*)(pp + row * DM + col8 + co), pq); float o[8];
;             _Pragma("unroll") for (int e = 0; e < 4; ++e) { o[e] = sigmoidf_(v0[e]) * pq[e]; o[4 + e] = sigmoidf_(v1[e]) * pq[4 + e]; }
;             *(uint4*)(O + row * DM + col8 + co) = pack8(o); )
;     }
	v_lshlrev_b32_e32 v216, 16, v236
	v_and_b32_e32 v217, 0xffff0000, v236
	v_lshlrev_b32_e32 v218, 16, v237
	v_and_b32_e32 v219, 0xffff0000, v237
	v_lshlrev_b32_e32 v220, 16, v238
	v_and_b32_e32 v221, 0xffff0000, v238
	v_lshlrev_b32_e32 v222, 16, v239
	v_and_b32_e32 v223, 0xffff0000, v239
	v_mul_f32_e32 v156, v156, v216
	v_mul_f32_e32 v157, v157, v217
	v_mul_f32_e32 v158, v158, v218
	v_mul_f32_e32 v159, v159, v219
	v_mul_f32_e32 v160, v160, v220
	v_mul_f32_e32 v161, v161, v221
	v_mul_f32_e32 v162, v162, v222
	v_mul_f32_e32 v163, v163, v223
	v_and_b32_sdwa v216, v156, v185 dst_sel:DWORD dst_unused:UNUSED_PAD src0_sel:WORD_1 src1_sel:DWORD
	v_and_b32_sdwa v217, v157, v185 dst_sel:DWORD dst_unused:UNUSED_PAD src0_sel:WORD_1 src1_sel:DWORD
	v_and_b32_sdwa v218, v158, v185 dst_sel:DWORD dst_unused:UNUSED_PAD src0_sel:WORD_1 src1_sel:DWORD
	v_and_b32_sdwa v219, v159, v185 dst_sel:DWORD dst_unused:UNUSED_PAD src0_sel:WORD_1 src1_sel:DWORD
	v_and_b32_sdwa v220, v160, v185 dst_sel:DWORD dst_unused:UNUSED_PAD src0_sel:WORD_1 src1_sel:DWORD
	v_and_b32_sdwa v221, v161, v185 dst_sel:DWORD dst_unused:UNUSED_PAD src0_sel:WORD_1 src1_sel:DWORD
	v_and_b32_sdwa v222, v162, v185 dst_sel:DWORD dst_unused:UNUSED_PAD src0_sel:WORD_1 src1_sel:DWORD
	v_and_b32_sdwa v223, v163, v185 dst_sel:DWORD dst_unused:UNUSED_PAD src0_sel:WORD_1 src1_sel:DWORD
	v_add3_u32 v156, v156, v216, s46
	v_add3_u32 v157, v157, v217, s46
	v_add3_u32 v158, v158, v218, s46
	v_add3_u32 v159, v159, v219, s46
	v_add3_u32 v160, v160, v220, s46
	v_add3_u32 v161, v161, v221, s46
	v_add3_u32 v162, v162, v222, s46
	v_add3_u32 v163, v163, v223, s46
	v_and_b32_e32 v157, 0xffff0000, v157
	v_and_b32_e32 v159, 0xffff0000, v159
	v_and_b32_e32 v161, 0xffff0000, v161
	v_and_b32_e32 v163, 0xffff0000, v163
	v_or_b32_sdwa v176, v157, v156 dst_sel:DWORD dst_unused:UNUSED_PAD src0_sel:DWORD src1_sel:WORD_1
	v_or_b32_sdwa v177, v159, v158 dst_sel:DWORD dst_unused:UNUSED_PAD src0_sel:DWORD src1_sel:WORD_1
	v_or_b32_sdwa v178, v161, v160 dst_sel:DWORD dst_unused:UNUSED_PAD src0_sel:DWORD src1_sel:WORD_1
	v_or_b32_sdwa v179, v163, v162 dst_sel:DWORD dst_unused:UNUSED_PAD src0_sel:DWORD src1_sel:WORD_1
	global_store_dwordx4 v[210:211], v[176:179], off
	v_mul_f32_e32 v156, 0xbfb8aa3b, v4
	v_mul_f32_e32 v157, 0xbfb8aa3b, v5
	v_mul_f32_e32 v158, 0xbfb8aa3b, v6
	v_mul_f32_e32 v159, 0xbfb8aa3b, v7
	v_mul_f32_e32 v160, 0xbfb8aa3b, v8
	v_mul_f32_e32 v161, 0xbfb8aa3b, v9
	v_mul_f32_e32 v162, 0xbfb8aa3b, v10
	v_mul_f32_e32 v163, 0xbfb8aa3b, v11
	v_exp_f32_e32 v156, v156
	v_exp_f32_e32 v157, v157
	v_exp_f32_e32 v158, v158
	v_exp_f32_e32 v159, v159
	v_exp_f32_e32 v160, v160
	v_exp_f32_e32 v161, v161
	v_exp_f32_e32 v162, v162
	v_exp_f32_e32 v163, v163
	v_add_f32_e32 v156, 1.0, v156
	v_add_f32_e32 v157, 1.0, v157
	v_add_f32_e32 v158, 1.0, v158
	v_add_f32_e32 v159, 1.0, v159
	v_add_f32_e32 v160, 1.0, v160
	v_add_f32_e32 v161, 1.0, v161
	v_add_f32_e32 v162, 1.0, v162
	v_add_f32_e32 v163, 1.0, v163
	v_rcp_f32_e32 v156, v156
	v_rcp_f32_e32 v157, v157
	v_rcp_f32_e32 v158, v158
	v_rcp_f32_e32 v159, v159
	v_rcp_f32_e32 v160, v160
	v_rcp_f32_e32 v161, v161
	v_rcp_f32_e32 v162, v162
	v_rcp_f32_e32 v163, v163
	v_lshlrev_b32_e32 v216, 16, v240
	v_and_b32_e32 v217, 0xffff0000, v240
	v_lshlrev_b32_e32 v218, 16, v241
	v_and_b32_e32 v219, 0xffff0000, v241
	v_lshlrev_b32_e32 v220, 16, v242
	v_and_b32_e32 v221, 0xffff0000, v242
	v_lshlrev_b32_e32 v222, 16, v243
	v_and_b32_e32 v223, 0xffff0000, v243
	v_mul_f32_e32 v156, v156, v216
	v_mul_f32_e32 v157, v157, v217
	v_mul_f32_e32 v158, v158, v218
	v_mul_f32_e32 v159, v159, v219
	v_mul_f32_e32 v160, v160, v220
	v_mul_f32_e32 v161, v161, v221
	v_mul_f32_e32 v162, v162, v222
	v_mul_f32_e32 v163, v163, v223
	v_and_b32_sdwa v216, v156, v185 dst_sel:DWORD dst_unused:UNUSED_PAD src0_sel:WORD_1 src1_sel:DWORD
	v_and_b32_sdwa v217, v157, v185 dst_sel:DWORD dst_unused:UNUSED_PAD src0_sel:WORD_1 src1_sel:DWORD
	v_and_b32_sdwa v218, v158, v185 dst_sel:DWORD dst_unused:UNUSED_PAD src0_sel:WORD_1 src1_sel:DWORD
	v_and_b32_sdwa v219, v159, v185 dst_sel:DWORD dst_unused:UNUSED_PAD src0_sel:WORD_1 src1_sel:DWORD
	v_and_b32_sdwa v220, v160, v185 dst_sel:DWORD dst_unused:UNUSED_PAD src0_sel:WORD_1 src1_sel:DWORD
	v_and_b32_sdwa v221, v161, v185 dst_sel:DWORD dst_unused:UNUSED_PAD src0_sel:WORD_1 src1_sel:DWORD
	v_and_b32_sdwa v222, v162, v185 dst_sel:DWORD dst_unused:UNUSED_PAD src0_sel:WORD_1 src1_sel:DWORD
	v_and_b32_sdwa v223, v163, v185 dst_sel:DWORD dst_unused:UNUSED_PAD src0_sel:WORD_1 src1_sel:DWORD
	v_add3_u32 v156, v156, v216, s46
	v_add3_u32 v157, v157, v217, s46
	v_add3_u32 v158, v158, v218, s46
	v_add3_u32 v159, v159, v219, s46
	v_add3_u32 v160, v160, v220, s46
	v_add3_u32 v161, v161, v221, s46
	v_add3_u32 v162, v162, v222, s46
	v_add3_u32 v163, v163, v223, s46
	v_and_b32_e32 v157, 0xffff0000, v157
	v_and_b32_e32 v159, 0xffff0000, v159
	v_and_b32_e32 v161, 0xffff0000, v161
	v_and_b32_e32 v163, 0xffff0000, v163
	v_or_b32_sdwa v224, v157, v156 dst_sel:DWORD dst_unused:UNUSED_PAD src0_sel:DWORD src1_sel:WORD_1
	v_or_b32_sdwa v225, v159, v158 dst_sel:DWORD dst_unused:UNUSED_PAD src0_sel:DWORD src1_sel:WORD_1
	v_or_b32_sdwa v226, v161, v160 dst_sel:DWORD dst_unused:UNUSED_PAD src0_sel:DWORD src1_sel:WORD_1
	v_or_b32_sdwa v227, v163, v162 dst_sel:DWORD dst_unused:UNUSED_PAD src0_sel:DWORD src1_sel:WORD_1
	global_store_dwordx4 v[210:211], v[224:227], off offset:256
	s_mov_b64 s[0:1], 0x48000
	v_lshl_add_u64 v[212:213], v[206:207], 0, s[0:1]
	v_mul_f32_e32 v156, 0xbfb8aa3b, v120
	v_mul_f32_e32 v157, 0xbfb8aa3b, v121
	v_mul_f32_e32 v158, 0xbfb8aa3b, v122
	v_mul_f32_e32 v159, 0xbfb8aa3b, v123
	v_mul_f32_e32 v160, 0xbfb8aa3b, v124
	v_mul_f32_e32 v161, 0xbfb8aa3b, v125
	v_mul_f32_e32 v162, 0xbfb8aa3b, v126
	v_mul_f32_e32 v163, 0xbfb8aa3b, v127
	v_exp_f32_e32 v156, v156
	v_exp_f32_e32 v157, v157
	v_exp_f32_e32 v158, v158
	v_exp_f32_e32 v159, v159
	v_exp_f32_e32 v160, v160
	v_exp_f32_e32 v161, v161
	v_exp_f32_e32 v162, v162
	v_exp_f32_e32 v163, v163
	v_add_f32_e32 v156, 1.0, v156
	v_add_f32_e32 v157, 1.0, v157
	v_add_f32_e32 v158, 1.0, v158
	v_add_f32_e32 v159, 1.0, v159
	v_add_f32_e32 v160, 1.0, v160
	v_add_f32_e32 v161, 1.0, v161
	v_add_f32_e32 v162, 1.0, v162
	v_add_f32_e32 v163, 1.0, v163
	v_rcp_f32_e32 v156, v156
	v_rcp_f32_e32 v157, v157
	v_rcp_f32_e32 v158, v158
	v_rcp_f32_e32 v159, v159
	v_rcp_f32_e32 v160, v160
	v_rcp_f32_e32 v161, v161
	v_rcp_f32_e32 v162, v162
	v_rcp_f32_e32 v163, v163
	s_waitcnt vmcnt(12)
; __device__ __forceinline__ float sigmoidf_(float x) { return __builtin_amdgcn_rcpf(1.0f + __expf(-x)); }
; __device__ __forceinline__ void unpack8(const uint4 u, float (&f)[8]) { f[0] = bflo(u.x); f[1] = bfhi(u.x); f[2] = bflo(u.y); f[3] = bfhi(u.y); f[4] = bflo(u.z); f[5] = bfhi(u.z); f[6] = bflo(u.w); f[7] = bfhi(u.w); }
; __device__ __forceinline__ uint4 pack8(const float (&f)[8]) { uint4 u; u.x = pack2(f[0], f[1]); u.y = pack2(f[2], f[3]); u.z = pack2(f[4], f[5]); u.w = pack2(f[6], f[7]); return u; }
;     __device__ __forceinline__ void operator()(const f32x4 (&acc)[2][2][4][2], const Unit& u, int wr, int wc, int fr, int fq) const {
;         EPIP_ROWS( float pq[8]; unpack8(*(const uint4*)(pp + row * DM + col8 + co), pq); float o[8];
;             _Pragma("unroll") for (int e = 0; e < 4; ++e) { o[e] = sigmoidf_(v0[e]) * pq[e]; o[4 + e] = sigmoidf_(v1[e]) * pq[4 + e]; }
;             *(uint4*)(O + row * DM + col8 + co) = pack8(o); )
;     }
	v_lshlrev_b32_e32 v216, 16, v132
	v_and_b32_e32 v217, 0xffff0000, v132
	v_lshlrev_b32_e32 v218, 16, v133
	v_and_b32_e32 v219, 0xffff0000, v133
	v_lshlrev_b32_e32 v220, 16, v134
	v_and_b32_e32 v221, 0xffff0000, v134
	v_lshlrev_b32_e32 v222, 16, v135
	v_and_b32_e32 v223, 0xffff0000, v135
	v_mul_f32_e32 v156, v156, v216
	v_mul_f32_e32 v157, v157, v217
	v_mul_f32_e32 v158, v158, v218
	v_mul_f32_e32 v159, v159, v219
	v_mul_f32_e32 v160, v160, v220
	v_mul_f32_e32 v161, v161, v221
	v_mul_f32_e32 v162, v162, v222
	v_mul_f32_e32 v163, v163, v223
	v_and_b32_sdwa v216, v156, v185 dst_sel:DWORD dst_unused:UNUSED_PAD src0_sel:WORD_1 src1_sel:DWORD
	v_and_b32_sdwa v217, v157, v185 dst_sel:DWORD dst_unused:UNUSED_PAD src0_sel:WORD_1 src1_sel:DWORD
	v_and_b32_sdwa v218, v158, v185 dst_sel:DWORD dst_unused:UNUSED_PAD src0_sel:WORD_1 src1_sel:DWORD
	v_and_b32_sdwa v219, v159, v185 dst_sel:DWORD dst_unused:UNUSED_PAD src0_sel:WORD_1 src1_sel:DWORD
	v_and_b32_sdwa v220, v160, v185 dst_sel:DWORD dst_unused:UNUSED_PAD src0_sel:WORD_1 src1_sel:DWORD
	v_and_b32_sdwa v221, v161, v185 dst_sel:DWORD dst_unused:UNUSED_PAD src0_sel:WORD_1 src1_sel:DWORD
	v_and_b32_sdwa v222, v162, v185 dst_sel:DWORD dst_unused:UNUSED_PAD src0_sel:WORD_1 src1_sel:DWORD
	v_and_b32_sdwa v223, v163, v185 dst_sel:DWORD dst_unused:UNUSED_PAD src0_sel:WORD_1 src1_sel:DWORD
	v_add3_u32 v156, v156, v216, s46
	v_add3_u32 v157, v157, v217, s46
	v_add3_u32 v158, v158, v218, s46
	v_add3_u32 v159, v159, v219, s46
	v_add3_u32 v160, v160, v220, s46
	v_add3_u32 v161, v161, v221, s46
	v_add3_u32 v162, v162, v222, s46
	v_add3_u32 v163, v163, v223, s46
	v_and_b32_e32 v157, 0xffff0000, v157
	v_and_b32_e32 v159, 0xffff0000, v159
	v_and_b32_e32 v161, 0xffff0000, v161
	v_and_b32_e32 v163, 0xffff0000, v163
	v_or_b32_sdwa v176, v157, v156 dst_sel:DWORD dst_unused:UNUSED_PAD src0_sel:DWORD src1_sel:WORD_1
	v_or_b32_sdwa v177, v159, v158 dst_sel:DWORD dst_unused:UNUSED_PAD src0_sel:DWORD src1_sel:WORD_1
	v_or_b32_sdwa v178, v161, v160 dst_sel:DWORD dst_unused:UNUSED_PAD src0_sel:DWORD src1_sel:WORD_1
	v_or_b32_sdwa v179, v163, v162 dst_sel:DWORD dst_unused:UNUSED_PAD src0_sel:DWORD src1_sel:WORD_1
	global_store_dwordx4 v[212:213], v[176:179], off
	v_mul_f32_e32 v156, 0xbfb8aa3b, v12
	v_mul_f32_e32 v157, 0xbfb8aa3b, v13
	v_mul_f32_e32 v158, 0xbfb8aa3b, v14
	v_mul_f32_e32 v159, 0xbfb8aa3b, v15
	v_mul_f32_e32 v160, 0xbfb8aa3b, v16
	v_mul_f32_e32 v161, 0xbfb8aa3b, v17
	v_mul_f32_e32 v162, 0xbfb8aa3b, v18
	v_mul_f32_e32 v163, 0xbfb8aa3b, v19
	v_exp_f32_e32 v156, v156
	v_exp_f32_e32 v157, v157
	v_exp_f32_e32 v158, v158
	v_exp_f32_e32 v159, v159
	v_exp_f32_e32 v160, v160
	v_exp_f32_e32 v161, v161
	v_exp_f32_e32 v162, v162
	v_exp_f32_e32 v163, v163
	v_add_f32_e32 v156, 1.0, v156
	v_add_f32_e32 v157, 1.0, v157
	v_add_f32_e32 v158, 1.0, v158
	v_add_f32_e32 v159, 1.0, v159
	v_add_f32_e32 v160, 1.0, v160
	v_add_f32_e32 v161, 1.0, v161
	v_add_f32_e32 v162, 1.0, v162
	v_add_f32_e32 v163, 1.0, v163
	v_rcp_f32_e32 v156, v156
	v_rcp_f32_e32 v157, v157
	v_rcp_f32_e32 v158, v158
	v_rcp_f32_e32 v159, v159
	v_rcp_f32_e32 v160, v160
	v_rcp_f32_e32 v161, v161
	v_rcp_f32_e32 v162, v162
	v_rcp_f32_e32 v163, v163
	v_lshlrev_b32_e32 v216, 16, v136
	v_and_b32_e32 v217, 0xffff0000, v136
	v_lshlrev_b32_e32 v218, 16, v137
	v_and_b32_e32 v219, 0xffff0000, v137
	v_lshlrev_b32_e32 v220, 16, v138
	v_and_b32_e32 v221, 0xffff0000, v138
	v_lshlrev_b32_e32 v222, 16, v139
	v_and_b32_e32 v223, 0xffff0000, v139
	v_mul_f32_e32 v156, v156, v216
	v_mul_f32_e32 v157, v157, v217
	v_mul_f32_e32 v158, v158, v218
	v_mul_f32_e32 v159, v159, v219
	v_mul_f32_e32 v160, v160, v220
	v_mul_f32_e32 v161, v161, v221
	v_mul_f32_e32 v162, v162, v222
	v_mul_f32_e32 v163, v163, v223
	v_and_b32_sdwa v216, v156, v185 dst_sel:DWORD dst_unused:UNUSED_PAD src0_sel:WORD_1 src1_sel:DWORD
	v_and_b32_sdwa v217, v157, v185 dst_sel:DWORD dst_unused:UNUSED_PAD src0_sel:WORD_1 src1_sel:DWORD
	v_and_b32_sdwa v218, v158, v185 dst_sel:DWORD dst_unused:UNUSED_PAD src0_sel:WORD_1 src1_sel:DWORD
	v_and_b32_sdwa v219, v159, v185 dst_sel:DWORD dst_unused:UNUSED_PAD src0_sel:WORD_1 src1_sel:DWORD
	v_and_b32_sdwa v220, v160, v185 dst_sel:DWORD dst_unused:UNUSED_PAD src0_sel:WORD_1 src1_sel:DWORD
	v_and_b32_sdwa v221, v161, v185 dst_sel:DWORD dst_unused:UNUSED_PAD src0_sel:WORD_1 src1_sel:DWORD
	v_and_b32_sdwa v222, v162, v185 dst_sel:DWORD dst_unused:UNUSED_PAD src0_sel:WORD_1 src1_sel:DWORD
	v_and_b32_sdwa v223, v163, v185 dst_sel:DWORD dst_unused:UNUSED_PAD src0_sel:WORD_1 src1_sel:DWORD
	v_add3_u32 v156, v156, v216, s46
	v_add3_u32 v157, v157, v217, s46
	v_add3_u32 v158, v158, v218, s46
	v_add3_u32 v159, v159, v219, s46
	v_add3_u32 v160, v160, v220, s46
	v_add3_u32 v161, v161, v221, s46
	v_add3_u32 v162, v162, v222, s46
	v_add3_u32 v163, v163, v223, s46
	v_and_b32_e32 v157, 0xffff0000, v157
	v_and_b32_e32 v159, 0xffff0000, v159
	v_and_b32_e32 v161, 0xffff0000, v161
	v_and_b32_e32 v163, 0xffff0000, v163
	v_or_b32_sdwa v224, v157, v156 dst_sel:DWORD dst_unused:UNUSED_PAD src0_sel:DWORD src1_sel:WORD_1
	v_or_b32_sdwa v225, v159, v158 dst_sel:DWORD dst_unused:UNUSED_PAD src0_sel:DWORD src1_sel:WORD_1
	v_or_b32_sdwa v226, v161, v160 dst_sel:DWORD dst_unused:UNUSED_PAD src0_sel:DWORD src1_sel:WORD_1
	v_or_b32_sdwa v227, v163, v162 dst_sel:DWORD dst_unused:UNUSED_PAD src0_sel:DWORD src1_sel:WORD_1
	global_store_dwordx4 v[212:213], v[224:227], off offset:256
	s_mov_b64 s[0:1], 0x50000
	v_lshl_add_u64 v[210:211], v[206:207], 0, s[0:1]
	v_mul_f32_e32 v156, 0xbfb8aa3b, v128
	v_mul_f32_e32 v157, 0xbfb8aa3b, v129
	v_mul_f32_e32 v158, 0xbfb8aa3b, v130
	v_mul_f32_e32 v159, 0xbfb8aa3b, v131
	v_mul_f32_e32 v160, 0xbfb8aa3b, v36
	v_mul_f32_e32 v161, 0xbfb8aa3b, v37
	v_mul_f32_e32 v162, 0xbfb8aa3b, v38
	v_mul_f32_e32 v163, 0xbfb8aa3b, v39
	v_exp_f32_e32 v156, v156
	v_exp_f32_e32 v157, v157
	v_exp_f32_e32 v158, v158
	v_exp_f32_e32 v159, v159
	v_exp_f32_e32 v160, v160
	v_exp_f32_e32 v161, v161
	v_exp_f32_e32 v162, v162
	v_exp_f32_e32 v163, v163
	v_add_f32_e32 v156, 1.0, v156
	v_add_f32_e32 v157, 1.0, v157
	v_add_f32_e32 v158, 1.0, v158
	v_add_f32_e32 v159, 1.0, v159
	v_add_f32_e32 v160, 1.0, v160
	v_add_f32_e32 v161, 1.0, v161
	v_add_f32_e32 v162, 1.0, v162
	v_add_f32_e32 v163, 1.0, v163
	v_rcp_f32_e32 v156, v156
	v_rcp_f32_e32 v157, v157
	v_rcp_f32_e32 v158, v158
	v_rcp_f32_e32 v159, v159
	v_rcp_f32_e32 v160, v160
	v_rcp_f32_e32 v161, v161
	v_rcp_f32_e32 v162, v162
	v_rcp_f32_e32 v163, v163
	s_waitcnt vmcnt(10)
; __device__ __forceinline__ float sigmoidf_(float x) { return __builtin_amdgcn_rcpf(1.0f + __expf(-x)); }
; __device__ __forceinline__ void unpack8(const uint4 u, float (&f)[8]) { f[0] = bflo(u.x); f[1] = bfhi(u.x); f[2] = bflo(u.y); f[3] = bfhi(u.y); f[4] = bflo(u.z); f[5] = bfhi(u.z); f[6] = bflo(u.w); f[7] = bfhi(u.w); }
; __device__ __forceinline__ uint4 pack8(const float (&f)[8]) { uint4 u; u.x = pack2(f[0], f[1]); u.y = pack2(f[2], f[3]); u.z = pack2(f[4], f[5]); u.w = pack2(f[6], f[7]); return u; }
;     __device__ __forceinline__ void operator()(const f32x4 (&acc)[2][2][4][2], const Unit& u, int wr, int wc, int fr, int fq) const {
;         EPIP_ROWS( float pq[8]; unpack8(*(const uint4*)(pp + row * DM + col8 + co), pq); float o[8];
;             _Pragma("unroll") for (int e = 0; e < 4; ++e) { o[e] = sigmoidf_(v0[e]) * pq[e]; o[4 + e] = sigmoidf_(v1[e]) * pq[4 + e]; }
;             *(uint4*)(O + row * DM + col8 + co) = pack8(o); )
;     }
	v_lshlrev_b32_e32 v216, 16, v140
	v_and_b32_e32 v217, 0xffff0000, v140
	v_lshlrev_b32_e32 v218, 16, v141
	v_and_b32_e32 v219, 0xffff0000, v141
	v_lshlrev_b32_e32 v220, 16, v142
	v_and_b32_e32 v221, 0xffff0000, v142
	v_lshlrev_b32_e32 v222, 16, v143
	v_and_b32_e32 v223, 0xffff0000, v143
	v_mul_f32_e32 v156, v156, v216
	v_mul_f32_e32 v157, v157, v217
	v_mul_f32_e32 v158, v158, v218
	v_mul_f32_e32 v159, v159, v219
	v_mul_f32_e32 v160, v160, v220
	v_mul_f32_e32 v161, v161, v221
	v_mul_f32_e32 v162, v162, v222
	v_mul_f32_e32 v163, v163, v223
	v_and_b32_sdwa v216, v156, v185 dst_sel:DWORD dst_unused:UNUSED_PAD src0_sel:WORD_1 src1_sel:DWORD
	v_and_b32_sdwa v217, v157, v185 dst_sel:DWORD dst_unused:UNUSED_PAD src0_sel:WORD_1 src1_sel:DWORD
	v_and_b32_sdwa v218, v158, v185 dst_sel:DWORD dst_unused:UNUSED_PAD src0_sel:WORD_1 src1_sel:DWORD
	v_and_b32_sdwa v219, v159, v185 dst_sel:DWORD dst_unused:UNUSED_PAD src0_sel:WORD_1 src1_sel:DWORD
	v_and_b32_sdwa v220, v160, v185 dst_sel:DWORD dst_unused:UNUSED_PAD src0_sel:WORD_1 src1_sel:DWORD
	v_and_b32_sdwa v221, v161, v185 dst_sel:DWORD dst_unused:UNUSED_PAD src0_sel:WORD_1 src1_sel:DWORD
	v_and_b32_sdwa v222, v162, v185 dst_sel:DWORD dst_unused:UNUSED_PAD src0_sel:WORD_1 src1_sel:DWORD
	v_and_b32_sdwa v223, v163, v185 dst_sel:DWORD dst_unused:UNUSED_PAD src0_sel:WORD_1 src1_sel:DWORD
	v_add3_u32 v156, v156, v216, s46
	v_add3_u32 v157, v157, v217, s46
	v_add3_u32 v158, v158, v218, s46
	v_add3_u32 v159, v159, v219, s46
	v_add3_u32 v160, v160, v220, s46
	v_add3_u32 v161, v161, v221, s46
	v_add3_u32 v162, v162, v222, s46
	v_add3_u32 v163, v163, v223, s46
	v_and_b32_e32 v157, 0xffff0000, v157
	v_and_b32_e32 v159, 0xffff0000, v159
	v_and_b32_e32 v161, 0xffff0000, v161
	v_and_b32_e32 v163, 0xffff0000, v163
	v_or_b32_sdwa v176, v157, v156 dst_sel:DWORD dst_unused:UNUSED_PAD src0_sel:DWORD src1_sel:WORD_1
	v_or_b32_sdwa v177, v159, v158 dst_sel:DWORD dst_unused:UNUSED_PAD src0_sel:DWORD src1_sel:WORD_1
	v_or_b32_sdwa v178, v161, v160 dst_sel:DWORD dst_unused:UNUSED_PAD src0_sel:DWORD src1_sel:WORD_1
	v_or_b32_sdwa v179, v163, v162 dst_sel:DWORD dst_unused:UNUSED_PAD src0_sel:DWORD src1_sel:WORD_1
	global_store_dwordx4 v[210:211], v[176:179], off
	v_mul_f32_e32 v156, 0xbfb8aa3b, v20
	v_mul_f32_e32 v157, 0xbfb8aa3b, v21
	v_mul_f32_e32 v158, 0xbfb8aa3b, v22
	v_mul_f32_e32 v159, 0xbfb8aa3b, v23
	v_mul_f32_e32 v160, 0xbfb8aa3b, v24
	v_mul_f32_e32 v161, 0xbfb8aa3b, v25
	v_mul_f32_e32 v162, 0xbfb8aa3b, v26
	v_mul_f32_e32 v163, 0xbfb8aa3b, v27
	v_exp_f32_e32 v156, v156
	v_exp_f32_e32 v157, v157
	v_exp_f32_e32 v158, v158
	v_exp_f32_e32 v159, v159
	v_exp_f32_e32 v160, v160
	v_exp_f32_e32 v161, v161
	v_exp_f32_e32 v162, v162
	v_exp_f32_e32 v163, v163
	v_add_f32_e32 v156, 1.0, v156
	v_add_f32_e32 v157, 1.0, v157
	v_add_f32_e32 v158, 1.0, v158
	v_add_f32_e32 v159, 1.0, v159
	v_add_f32_e32 v160, 1.0, v160
	v_add_f32_e32 v161, 1.0, v161
	v_add_f32_e32 v162, 1.0, v162
	v_add_f32_e32 v163, 1.0, v163
	v_rcp_f32_e32 v156, v156
	v_rcp_f32_e32 v157, v157
	v_rcp_f32_e32 v158, v158
	v_rcp_f32_e32 v159, v159
	v_rcp_f32_e32 v160, v160
	v_rcp_f32_e32 v161, v161
	v_rcp_f32_e32 v162, v162
	v_rcp_f32_e32 v163, v163
	v_lshlrev_b32_e32 v216, 16, v144
	v_and_b32_e32 v217, 0xffff0000, v144
	v_lshlrev_b32_e32 v218, 16, v145
	v_and_b32_e32 v219, 0xffff0000, v145
	v_lshlrev_b32_e32 v220, 16, v146
	v_and_b32_e32 v221, 0xffff0000, v146
	v_lshlrev_b32_e32 v222, 16, v147
	v_and_b32_e32 v223, 0xffff0000, v147
	v_mul_f32_e32 v156, v156, v216
	v_mul_f32_e32 v157, v157, v217
	v_mul_f32_e32 v158, v158, v218
	v_mul_f32_e32 v159, v159, v219
	v_mul_f32_e32 v160, v160, v220
	v_mul_f32_e32 v161, v161, v221
	v_mul_f32_e32 v162, v162, v222
	v_mul_f32_e32 v163, v163, v223
	v_and_b32_sdwa v216, v156, v185 dst_sel:DWORD dst_unused:UNUSED_PAD src0_sel:WORD_1 src1_sel:DWORD
	v_and_b32_sdwa v217, v157, v185 dst_sel:DWORD dst_unused:UNUSED_PAD src0_sel:WORD_1 src1_sel:DWORD
	v_and_b32_sdwa v218, v158, v185 dst_sel:DWORD dst_unused:UNUSED_PAD src0_sel:WORD_1 src1_sel:DWORD
	v_and_b32_sdwa v219, v159, v185 dst_sel:DWORD dst_unused:UNUSED_PAD src0_sel:WORD_1 src1_sel:DWORD
	v_and_b32_sdwa v220, v160, v185 dst_sel:DWORD dst_unused:UNUSED_PAD src0_sel:WORD_1 src1_sel:DWORD
	v_and_b32_sdwa v221, v161, v185 dst_sel:DWORD dst_unused:UNUSED_PAD src0_sel:WORD_1 src1_sel:DWORD
	v_and_b32_sdwa v222, v162, v185 dst_sel:DWORD dst_unused:UNUSED_PAD src0_sel:WORD_1 src1_sel:DWORD
	v_and_b32_sdwa v223, v163, v185 dst_sel:DWORD dst_unused:UNUSED_PAD src0_sel:WORD_1 src1_sel:DWORD
	v_add3_u32 v156, v156, v216, s46
	v_add3_u32 v157, v157, v217, s46
	v_add3_u32 v158, v158, v218, s46
	v_add3_u32 v159, v159, v219, s46
	v_add3_u32 v160, v160, v220, s46
	v_add3_u32 v161, v161, v221, s46
	v_add3_u32 v162, v162, v222, s46
	v_add3_u32 v163, v163, v223, s46
	v_and_b32_e32 v157, 0xffff0000, v157
	v_and_b32_e32 v159, 0xffff0000, v159
	v_and_b32_e32 v161, 0xffff0000, v161
	v_and_b32_e32 v163, 0xffff0000, v163
	v_or_b32_sdwa v224, v157, v156 dst_sel:DWORD dst_unused:UNUSED_PAD src0_sel:DWORD src1_sel:WORD_1
	v_or_b32_sdwa v225, v159, v158 dst_sel:DWORD dst_unused:UNUSED_PAD src0_sel:DWORD src1_sel:WORD_1
	v_or_b32_sdwa v226, v161, v160 dst_sel:DWORD dst_unused:UNUSED_PAD src0_sel:DWORD src1_sel:WORD_1
	v_or_b32_sdwa v227, v163, v162 dst_sel:DWORD dst_unused:UNUSED_PAD src0_sel:DWORD src1_sel:WORD_1
	global_store_dwordx4 v[210:211], v[224:227], off offset:256
	s_mov_b64 s[0:1], 0x58000
	v_lshl_add_u64 v[212:213], v[206:207], 0, s[0:1]
	v_mul_f32_e32 v156, 0xbfb8aa3b, v40
	v_mul_f32_e32 v157, 0xbfb8aa3b, v41
	v_mul_f32_e32 v158, 0xbfb8aa3b, v42
	v_mul_f32_e32 v159, 0xbfb8aa3b, v43
	v_mul_f32_e32 v160, 0xbfb8aa3b, v44
	v_mul_f32_e32 v161, 0xbfb8aa3b, v45
	v_mul_f32_e32 v162, 0xbfb8aa3b, v46
	v_mul_f32_e32 v163, 0xbfb8aa3b, v47
	v_exp_f32_e32 v156, v156
	v_exp_f32_e32 v157, v157
	v_exp_f32_e32 v158, v158
	v_exp_f32_e32 v159, v159
	v_exp_f32_e32 v160, v160
	v_exp_f32_e32 v161, v161
	v_exp_f32_e32 v162, v162
	v_exp_f32_e32 v163, v163
	v_add_f32_e32 v156, 1.0, v156
	v_add_f32_e32 v157, 1.0, v157
	v_add_f32_e32 v158, 1.0, v158
	v_add_f32_e32 v159, 1.0, v159
	v_add_f32_e32 v160, 1.0, v160
	v_add_f32_e32 v161, 1.0, v161
	v_add_f32_e32 v162, 1.0, v162
	v_add_f32_e32 v163, 1.0, v163
	v_rcp_f32_e32 v156, v156
	v_rcp_f32_e32 v157, v157
	v_rcp_f32_e32 v158, v158
	v_rcp_f32_e32 v159, v159
	v_rcp_f32_e32 v160, v160
	v_rcp_f32_e32 v161, v161
	v_rcp_f32_e32 v162, v162
	v_rcp_f32_e32 v163, v163
	s_waitcnt vmcnt(8)
; __device__ __forceinline__ float sigmoidf_(float x) { return __builtin_amdgcn_rcpf(1.0f + __expf(-x)); }
; __device__ __forceinline__ void unpack8(const uint4 u, float (&f)[8]) { f[0] = bflo(u.x); f[1] = bfhi(u.x); f[2] = bflo(u.y); f[3] = bfhi(u.y); f[4] = bflo(u.z); f[5] = bfhi(u.z); f[6] = bflo(u.w); f[7] = bfhi(u.w); }
; __device__ __forceinline__ uint4 pack8(const float (&f)[8]) { uint4 u; u.x = pack2(f[0], f[1]); u.y = pack2(f[2], f[3]); u.z = pack2(f[4], f[5]); u.w = pack2(f[6], f[7]); return u; }
;     __device__ __forceinline__ void operator()(const f32x4 (&acc)[2][2][4][2], const Unit& u, int wr, int wc, int fr, int fq) const {
;         EPIP_ROWS( float pq[8]; unpack8(*(const uint4*)(pp + row * DM + col8 + co), pq); float o[8];
;             _Pragma("unroll") for (int e = 0; e < 4; ++e) { o[e] = sigmoidf_(v0[e]) * pq[e]; o[4 + e] = sigmoidf_(v1[e]) * pq[4 + e]; }
;             *(uint4*)(O + row * DM + col8 + co) = pack8(o); )
;     }
	v_lshlrev_b32_e32 v216, 16, v148
	v_and_b32_e32 v217, 0xffff0000, v148
	v_lshlrev_b32_e32 v218, 16, v149
	v_and_b32_e32 v219, 0xffff0000, v149
	v_lshlrev_b32_e32 v220, 16, v150
	v_and_b32_e32 v221, 0xffff0000, v150
	v_lshlrev_b32_e32 v222, 16, v151
	v_and_b32_e32 v223, 0xffff0000, v151
	v_mul_f32_e32 v156, v156, v216
	v_mul_f32_e32 v157, v157, v217
	v_mul_f32_e32 v158, v158, v218
	v_mul_f32_e32 v159, v159, v219
	v_mul_f32_e32 v160, v160, v220
	v_mul_f32_e32 v161, v161, v221
	v_mul_f32_e32 v162, v162, v222
	v_mul_f32_e32 v163, v163, v223
	v_and_b32_sdwa v216, v156, v185 dst_sel:DWORD dst_unused:UNUSED_PAD src0_sel:WORD_1 src1_sel:DWORD
	v_and_b32_sdwa v217, v157, v185 dst_sel:DWORD dst_unused:UNUSED_PAD src0_sel:WORD_1 src1_sel:DWORD
	v_and_b32_sdwa v218, v158, v185 dst_sel:DWORD dst_unused:UNUSED_PAD src0_sel:WORD_1 src1_sel:DWORD
	v_and_b32_sdwa v219, v159, v185 dst_sel:DWORD dst_unused:UNUSED_PAD src0_sel:WORD_1 src1_sel:DWORD
	v_and_b32_sdwa v220, v160, v185 dst_sel:DWORD dst_unused:UNUSED_PAD src0_sel:WORD_1 src1_sel:DWORD
	v_and_b32_sdwa v221, v161, v185 dst_sel:DWORD dst_unused:UNUSED_PAD src0_sel:WORD_1 src1_sel:DWORD
	v_and_b32_sdwa v222, v162, v185 dst_sel:DWORD dst_unused:UNUSED_PAD src0_sel:WORD_1 src1_sel:DWORD
	v_and_b32_sdwa v223, v163, v185 dst_sel:DWORD dst_unused:UNUSED_PAD src0_sel:WORD_1 src1_sel:DWORD
	v_add3_u32 v156, v156, v216, s46
	v_add3_u32 v157, v157, v217, s46
	v_add3_u32 v158, v158, v218, s46
	v_add3_u32 v159, v159, v219, s46
	v_add3_u32 v160, v160, v220, s46
	v_add3_u32 v161, v161, v221, s46
	v_add3_u32 v162, v162, v222, s46
	v_add3_u32 v163, v163, v223, s46
	v_and_b32_e32 v157, 0xffff0000, v157
	v_and_b32_e32 v159, 0xffff0000, v159
	v_and_b32_e32 v161, 0xffff0000, v161
	v_and_b32_e32 v163, 0xffff0000, v163
	v_or_b32_sdwa v176, v157, v156 dst_sel:DWORD dst_unused:UNUSED_PAD src0_sel:DWORD src1_sel:WORD_1
	v_or_b32_sdwa v177, v159, v158 dst_sel:DWORD dst_unused:UNUSED_PAD src0_sel:DWORD src1_sel:WORD_1
	v_or_b32_sdwa v178, v161, v160 dst_sel:DWORD dst_unused:UNUSED_PAD src0_sel:DWORD src1_sel:WORD_1
	v_or_b32_sdwa v179, v163, v162 dst_sel:DWORD dst_unused:UNUSED_PAD src0_sel:DWORD src1_sel:WORD_1
	global_store_dwordx4 v[212:213], v[176:179], off
	v_mul_f32_e32 v156, 0xbfb8aa3b, v28
	v_mul_f32_e32 v157, 0xbfb8aa3b, v29
	v_mul_f32_e32 v158, 0xbfb8aa3b, v30
	v_mul_f32_e32 v159, 0xbfb8aa3b, v31
	v_mul_f32_e32 v160, 0xbfb8aa3b, v32
	v_mul_f32_e32 v161, 0xbfb8aa3b, v33
	v_mul_f32_e32 v162, 0xbfb8aa3b, v34
	v_mul_f32_e32 v163, 0xbfb8aa3b, v35
	v_exp_f32_e32 v156, v156
	v_exp_f32_e32 v157, v157
	v_exp_f32_e32 v158, v158
	v_exp_f32_e32 v159, v159
	v_exp_f32_e32 v160, v160
	v_exp_f32_e32 v161, v161
	v_exp_f32_e32 v162, v162
	v_exp_f32_e32 v163, v163
	v_add_f32_e32 v156, 1.0, v156
	v_add_f32_e32 v157, 1.0, v157
	v_add_f32_e32 v158, 1.0, v158
	v_add_f32_e32 v159, 1.0, v159
	v_add_f32_e32 v160, 1.0, v160
	v_add_f32_e32 v161, 1.0, v161
	v_add_f32_e32 v162, 1.0, v162
	v_add_f32_e32 v163, 1.0, v163
	v_rcp_f32_e32 v156, v156
	v_rcp_f32_e32 v157, v157
	v_rcp_f32_e32 v158, v158
	v_rcp_f32_e32 v159, v159
	v_rcp_f32_e32 v160, v160
	v_rcp_f32_e32 v161, v161
	v_rcp_f32_e32 v162, v162
	v_rcp_f32_e32 v163, v163
	v_lshlrev_b32_e32 v216, 16, v152
	v_and_b32_e32 v217, 0xffff0000, v152
	v_lshlrev_b32_e32 v218, 16, v153
	v_and_b32_e32 v219, 0xffff0000, v153
	v_lshlrev_b32_e32 v220, 16, v154
	v_and_b32_e32 v221, 0xffff0000, v154
	v_lshlrev_b32_e32 v222, 16, v155
	v_and_b32_e32 v223, 0xffff0000, v155
	v_mul_f32_e32 v156, v156, v216
	v_mul_f32_e32 v157, v157, v217
	v_mul_f32_e32 v158, v158, v218
	v_mul_f32_e32 v159, v159, v219
	v_mul_f32_e32 v160, v160, v220
	v_mul_f32_e32 v161, v161, v221
	v_mul_f32_e32 v162, v162, v222
	v_mul_f32_e32 v163, v163, v223
	v_and_b32_sdwa v216, v156, v185 dst_sel:DWORD dst_unused:UNUSED_PAD src0_sel:WORD_1 src1_sel:DWORD
	v_and_b32_sdwa v217, v157, v185 dst_sel:DWORD dst_unused:UNUSED_PAD src0_sel:WORD_1 src1_sel:DWORD
	v_and_b32_sdwa v218, v158, v185 dst_sel:DWORD dst_unused:UNUSED_PAD src0_sel:WORD_1 src1_sel:DWORD
	v_and_b32_sdwa v219, v159, v185 dst_sel:DWORD dst_unused:UNUSED_PAD src0_sel:WORD_1 src1_sel:DWORD
	v_and_b32_sdwa v220, v160, v185 dst_sel:DWORD dst_unused:UNUSED_PAD src0_sel:WORD_1 src1_sel:DWORD
	v_and_b32_sdwa v221, v161, v185 dst_sel:DWORD dst_unused:UNUSED_PAD src0_sel:WORD_1 src1_sel:DWORD
	v_and_b32_sdwa v222, v162, v185 dst_sel:DWORD dst_unused:UNUSED_PAD src0_sel:WORD_1 src1_sel:DWORD
	v_and_b32_sdwa v223, v163, v185 dst_sel:DWORD dst_unused:UNUSED_PAD src0_sel:WORD_1 src1_sel:DWORD
	v_add3_u32 v156, v156, v216, s46
	v_add3_u32 v157, v157, v217, s46
	v_add3_u32 v158, v158, v218, s46
	v_add3_u32 v159, v159, v219, s46
	v_add3_u32 v160, v160, v220, s46
	v_add3_u32 v161, v161, v221, s46
	v_add3_u32 v162, v162, v222, s46
	v_add3_u32 v163, v163, v223, s46
	v_and_b32_e32 v157, 0xffff0000, v157
	v_and_b32_e32 v159, 0xffff0000, v159
	v_and_b32_e32 v161, 0xffff0000, v161
	v_and_b32_e32 v163, 0xffff0000, v163
	v_or_b32_sdwa v224, v157, v156 dst_sel:DWORD dst_unused:UNUSED_PAD src0_sel:DWORD src1_sel:WORD_1
	v_or_b32_sdwa v225, v159, v158 dst_sel:DWORD dst_unused:UNUSED_PAD src0_sel:DWORD src1_sel:WORD_1
	v_or_b32_sdwa v226, v161, v160 dst_sel:DWORD dst_unused:UNUSED_PAD src0_sel:DWORD src1_sel:WORD_1
	v_or_b32_sdwa v227, v163, v162 dst_sel:DWORD dst_unused:UNUSED_PAD src0_sel:DWORD src1_sel:WORD_1
	global_store_dwordx4 v[212:213], v[224:227], off offset:256
	s_mov_b64 s[62:63], 0

; __device__ __forceinline__ float sigmoidf_(float x) { return __builtin_amdgcn_rcpf(1.0f + __expf(-x)); }
; __device__ __forceinline__ void unpack8(const uint4 u, float (&f)[8]) { f[0] = bflo(u.x); f[1] = bfhi(u.x); f[2] = bflo(u.y); f[3] = bfhi(u.y); f[4] = bflo(u.z); f[5] = bfhi(u.z); f[6] = bflo(u.w); f[7] = bfhi(u.w); }
;     __device__ __forceinline__ void mid(f32x4 (&acc)[2][2][4][2], const Unit& u, int wr, int wc, int fr, int fq) const {
;         const int row0 = u.pm * BM + wr * 64 + fr, col8 = u.pn * BM + wc * 32 + 8 * fq;
; #pragma unroll
;         for (int ai = 0; ai < 2; ++ai)
; #pragma unroll
;             for (int m = 0; m < 4; ++m) { const bf16_t* gp = gate + (size_t)(row0 + ai * HALF + m * 16) * LDP + col8;
; #pragma unroll
;                 for (int bj = 0; bj < 2; ++bj) { float gc[8], gr[8]; unpack8(*(const uint4*)(gp + C_GC + bj * HALF), gc); unpack8(*(const uint4*)(gp + C_GR + bj * HALF), gr);
; #pragma unroll
;                     for (int e = 0; e < 4; ++e) { acc[ai][bj][m][0][e] *= sigmoidf_(gc[e]) * (1.0f + __expf(-fminf(fmaxf(gr[e], -30.f), 30.f)));
;                         acc[ai][bj][m][1][e] *= sigmoidf_(gc[4 + e]) * (1.0f + __expf(-fminf(fmaxf(gr[4 + e], -30.f), 30.f))); } } }
;     }
.LBB0_352:
	s_and_b64 vcc, exec, s[0:1]
	s_cbranch_vccz .LBB0_351
	v_lshl_or_b32 v2, s44, 8, v204
	v_ashrrev_i32_e32 v3, 31, v2
	v_lshl_add_u32 v0, s61, 8, v196
	v_lshl_add_u64 v[2:3], v[2:3], 1, s[82:83]
	s_waitcnt vmcnt(0)
	v_mad_i64_i32 v[206:207], vcc, v0, s47, v[2:3]
	s_mov_b64 s[0:1], 0x1b00
	v_lshl_add_u64 v[2:3], v[206:207], 0, s[0:1]
	global_load_dwordx4 v[132:135], v[2:3], off
	global_load_dwordx4 v[136:139], v[2:3], off offset:2048
	s_mov_b64 s[0:1], 0x1c00
	v_lshl_add_u64 v[2:3], v[206:207], 0, s[0:1]
	global_load_dwordx4 v[140:143], v[2:3], off
	global_load_dwordx4 v[144:147], v[2:3], off offset:2048
	s_mov_b64 s[0:1], 0x2db00
	v_lshl_add_u64 v[2:3], v[206:207], 0, s[0:1]
	global_load_dwordx4 v[148:151], v[2:3], off
	global_load_dwordx4 v[152:155], v[2:3], off offset:2048
	s_mov_b64 s[0:1], 0x2dc00
	v_lshl_add_u64 v[2:3], v[206:207], 0, s[0:1]
	global_load_dwordx4 v[156:159], v[2:3], off
	global_load_dwordx4 v[160:163], v[2:3], off offset:2048
	s_mov_b64 s[0:1], 0x59b00
	v_lshl_add_u64 v[2:3], v[206:207], 0, s[0:1]
	global_load_dwordx4 v[208:211], v[2:3], off
	global_load_dwordx4 v[212:215], v[2:3], off offset:2048
	s_mov_b64 s[0:1], 0x59c00
	v_lshl_add_u64 v[2:3], v[206:207], 0, s[0:1]
	global_load_dwordx4 v[216:219], v[2:3], off
	global_load_dwordx4 v[220:223], v[2:3], off offset:2048
	s_mov_b64 s[0:1], 0x85b00
	v_lshl_add_u64 v[2:3], v[206:207], 0, s[0:1]
	global_load_dwordx4 v[240:243], v[2:3], off
	global_load_dwordx4 v[244:247], v[2:3], off offset:2048
	s_waitcnt vmcnt(12)
	v_lshlrev_b32_e32 v224, 16, v132
	v_and_b32_e32 v225, 0xffff0000, v132
	v_lshlrev_b32_e32 v226, 16, v133
	v_and_b32_e32 v227, 0xffff0000, v133
	v_lshlrev_b32_e32 v228, 16, v134
	v_and_b32_e32 v229, 0xffff0000, v134
	v_lshlrev_b32_e32 v230, 16, v135
	v_and_b32_e32 v231, 0xffff0000, v135
	v_lshlrev_b32_e32 v232, 16, v136
	v_and_b32_e32 v233, 0xffff0000, v136
	v_lshlrev_b32_e32 v234, 16, v137
	v_and_b32_e32 v235, 0xffff0000, v137
	v_lshlrev_b32_e32 v236, 16, v138
	v_and_b32_e32 v237, 0xffff0000, v138
	v_lshlrev_b32_e32 v238, 16, v139
	v_and_b32_e32 v239, 0xffff0000, v139
	v_mul_f32_e32 v224, 0xbfb8aa3b, v224
	v_mul_f32_e32 v225, 0xbfb8aa3b, v225
	v_mul_f32_e32 v226, 0xbfb8aa3b, v226
	v_mul_f32_e32 v227, 0xbfb8aa3b, v227
	v_mul_f32_e32 v228, 0xbfb8aa3b, v228
	v_mul_f32_e32 v229, 0xbfb8aa3b, v229
	v_mul_f32_e32 v230, 0xbfb8aa3b, v230
	v_mul_f32_e32 v231, 0xbfb8aa3b, v231
	v_max_f32_e32 v232, v232, v232
	v_max_f32_e32 v233, v233, v233
	v_max_f32_e32 v234, v234, v234
	v_max_f32_e32 v235, v235, v235
	v_max_f32_e32 v236, v236, v236
	v_max_f32_e32 v237, v237, v237
	v_max_f32_e32 v238, v238, v238
	v_max_f32_e32 v239, v239, v239
	v_exp_f32_e32 v224, v224
	v_exp_f32_e32 v225, v225
	v_exp_f32_e32 v226, v226
	v_exp_f32_e32 v227, v227
	v_exp_f32_e32 v228, v228
	v_exp_f32_e32 v229, v229
	v_exp_f32_e32 v230, v230
	v_exp_f32_e32 v231, v231
	v_med3_f32 v232, v232, s48, v192
	v_med3_f32 v233, v233, s48, v192
	v_med3_f32 v234, v234, s48, v192
	v_med3_f32 v235, v235, s48, v192
	v_med3_f32 v236, v236, s48, v192
	v_med3_f32 v237, v237, s48, v192
	v_med3_f32 v238, v238, s48, v192
	v_med3_f32 v239, v239, s48, v192
	v_add_f32_e32 v224, 1.0, v224
	v_add_f32_e32 v225, 1.0, v225
	v_add_f32_e32 v226, 1.0, v226
	v_add_f32_e32 v227, 1.0, v227
	v_add_f32_e32 v228, 1.0, v228
	v_add_f32_e32 v229, 1.0, v229
	v_add_f32_e32 v230, 1.0, v230
	v_add_f32_e32 v231, 1.0, v231
	v_mul_f32_e32 v232, 0xbfb8aa3b, v232
	v_mul_f32_e32 v233, 0xbfb8aa3b, v233
	v_mul_f32_e32 v234, 0xbfb8aa3b, v234
	v_mul_f32_e32 v235, 0xbfb8aa3b, v235
	v_mul_f32_e32 v236, 0xbfb8aa3b, v236
	v_mul_f32_e32 v237, 0xbfb8aa3b, v237
	v_mul_f32_e32 v238, 0xbfb8aa3b, v238
	v_mul_f32_e32 v239, 0xbfb8aa3b, v239
	v_rcp_f32_e32 v224, v224
	v_rcp_f32_e32 v225, v225
	v_rcp_f32_e32 v226, v226
	v_rcp_f32_e32 v227, v227
	v_rcp_f32_e32 v228, v228
	v_rcp_f32_e32 v229, v229
	v_rcp_f32_e32 v230, v230
	v_rcp_f32_e32 v231, v231
	v_exp_f32_e32 v232, v232
	v_exp_f32_e32 v233, v233
	v_exp_f32_e32 v234, v234
	v_exp_f32_e32 v235, v235
	v_exp_f32_e32 v236, v236
	v_exp_f32_e32 v237, v237
	v_exp_f32_e32 v238, v238
	v_exp_f32_e32 v239, v239
	v_mul_f32_e32 v48, v48, v224
	v_mul_f32_e32 v49, v49, v225
	v_mul_f32_e32 v50, v50, v226
	v_mul_f32_e32 v51, v51, v227
	v_mul_f32_e32 v52, v52, v228
	v_mul_f32_e32 v53, v53, v229
	v_mul_f32_e32 v54, v54, v230
	v_mul_f32_e32 v55, v55, v231
	v_add_f32_e32 v232, 1.0, v232
	v_add_f32_e32 v233, 1.0, v233
	v_add_f32_e32 v234, 1.0, v234
	v_add_f32_e32 v235, 1.0, v235
	v_add_f32_e32 v236, 1.0, v236
	v_add_f32_e32 v237, 1.0, v237
	v_add_f32_e32 v238, 1.0, v238
	v_add_f32_e32 v239, 1.0, v239
	v_mul_f32_e32 v48, v48, v232
	v_mul_f32_e32 v49, v49, v233
	v_mul_f32_e32 v50, v50, v234
	v_mul_f32_e32 v51, v51, v235
	v_mul_f32_e32 v52, v52, v236
	v_mul_f32_e32 v53, v53, v237
	v_mul_f32_e32 v54, v54, v238
	v_mul_f32_e32 v55, v55, v239
	s_mov_b64 s[0:1], 0x85c00
	v_lshl_add_u64 v[2:3], v[206:207], 0, s[0:1]
	global_load_dwordx4 v[132:135], v[2:3], off
	global_load_dwordx4 v[136:139], v[2:3], off offset:2048
	s_waitcnt vmcnt(12)
; __device__ __forceinline__ float sigmoidf_(float x) { return __builtin_amdgcn_rcpf(1.0f + __expf(-x)); }
; __device__ __forceinline__ void unpack8(const uint4 u, float (&f)[8]) { f[0] = bflo(u.x); f[1] = bfhi(u.x); f[2] = bflo(u.y); f[3] = bfhi(u.y); f[4] = bflo(u.z); f[5] = bfhi(u.z); f[6] = bflo(u.w); f[7] = bfhi(u.w); }
;     __device__ __forceinline__ void mid(f32x4 (&acc)[2][2][4][2], const Unit& u, int wr, int wc, int fr, int fq) const {
;     ...
;             for (int m = 0; m < 4; ++m) { const bf16_t* gp = gate + (size_t)(row0 + ai * HALF + m * 16) * LDP + col8;
; #pragma unroll
;                 for (int bj = 0; bj < 2; ++bj) { float gc[8], gr[8]; unpack8(*(const uint4*)(gp + C_GC + bj * HALF), gc); unpack8(*(const uint4*)(gp + C_GR + bj * HALF), gr);
; #pragma unroll
;                     for (int e = 0; e < 4; ++e) { acc[ai][bj][m][0][e] *= sigmoidf_(gc[e]) * (1.0f + __expf(-fminf(fmaxf(gr[e], -30.f), 30.f)));
;                         acc[ai][bj][m][1][e] *= sigmoidf_(gc[4 + e]) * (1.0f + __expf(-fminf(fmaxf(gr[4 + e], -30.f), 30.f))); } } }
	v_lshlrev_b32_e32 v224, 16, v140
	v_and_b32_e32 v225, 0xffff0000, v140
	v_lshlrev_b32_e32 v226, 16, v141
	v_and_b32_e32 v227, 0xffff0000, v141
	v_lshlrev_b32_e32 v228, 16, v142
	v_and_b32_e32 v229, 0xffff0000, v142
	v_lshlrev_b32_e32 v230, 16, v143
	v_and_b32_e32 v231, 0xffff0000, v143
	v_lshlrev_b32_e32 v232, 16, v144
	v_and_b32_e32 v233, 0xffff0000, v144
	v_lshlrev_b32_e32 v234, 16, v145
	v_and_b32_e32 v235, 0xffff0000, v145
	v_lshlrev_b32_e32 v236, 16, v146
	v_and_b32_e32 v237, 0xffff0000, v146
	v_lshlrev_b32_e32 v238, 16, v147
	v_and_b32_e32 v239, 0xffff0000, v147
	v_mul_f32_e32 v224, 0xbfb8aa3b, v224
	v_mul_f32_e32 v225, 0xbfb8aa3b, v225
	v_mul_f32_e32 v226, 0xbfb8aa3b, v226
	v_mul_f32_e32 v227, 0xbfb8aa3b, v227
	v_mul_f32_e32 v228, 0xbfb8aa3b, v228
	v_mul_f32_e32 v229, 0xbfb8aa3b, v229
	v_mul_f32_e32 v230, 0xbfb8aa3b, v230
	v_mul_f32_e32 v231, 0xbfb8aa3b, v231
	v_max_f32_e32 v232, v232, v232
	v_max_f32_e32 v233, v233, v233
	v_max_f32_e32 v234, v234, v234
	v_max_f32_e32 v235, v235, v235
	v_max_f32_e32 v236, v236, v236
	v_max_f32_e32 v237, v237, v237
	v_max_f32_e32 v238, v238, v238
	v_max_f32_e32 v239, v239, v239
	v_exp_f32_e32 v224, v224
	v_exp_f32_e32 v225, v225
	v_exp_f32_e32 v226, v226
	v_exp_f32_e32 v227, v227
	v_exp_f32_e32 v228, v228
	v_exp_f32_e32 v229, v229
	v_exp_f32_e32 v230, v230
	v_exp_f32_e32 v231, v231
	v_med3_f32 v232, v232, s48, v192
	v_med3_f32 v233, v233, s48, v192
	v_med3_f32 v234, v234, s48, v192
	v_med3_f32 v235, v235, s48, v192
	v_med3_f32 v236, v236, s48, v192
	v_med3_f32 v237, v237, s48, v192
	v_med3_f32 v238, v238, s48, v192
	v_med3_f32 v239, v239, s48, v192
	v_add_f32_e32 v224, 1.0, v224
	v_add_f32_e32 v225, 1.0, v225
	v_add_f32_e32 v226, 1.0, v226
	v_add_f32_e32 v227, 1.0, v227
	v_add_f32_e32 v228, 1.0, v228
	v_add_f32_e32 v229, 1.0, v229
	v_add_f32_e32 v230, 1.0, v230
	v_add_f32_e32 v231, 1.0, v231
	v_mul_f32_e32 v232, 0xbfb8aa3b, v232
	v_mul_f32_e32 v233, 0xbfb8aa3b, v233
	v_mul_f32_e32 v234, 0xbfb8aa3b, v234
	v_mul_f32_e32 v235, 0xbfb8aa3b, v235
	v_mul_f32_e32 v236, 0xbfb8aa3b, v236
	v_mul_f32_e32 v237, 0xbfb8aa3b, v237
	v_mul_f32_e32 v238, 0xbfb8aa3b, v238
	v_mul_f32_e32 v239, 0xbfb8aa3b, v239
	v_rcp_f32_e32 v224, v224
	v_rcp_f32_e32 v225, v225
	v_rcp_f32_e32 v226, v226
	v_rcp_f32_e32 v227, v227
	v_rcp_f32_e32 v228, v228
	v_rcp_f32_e32 v229, v229
	v_rcp_f32_e32 v230, v230
	v_rcp_f32_e32 v231, v231
	v_exp_f32_e32 v232, v232
	v_exp_f32_e32 v233, v233
	v_exp_f32_e32 v234, v234
	v_exp_f32_e32 v235, v235
	v_exp_f32_e32 v236, v236
	v_exp_f32_e32 v237, v237
	v_exp_f32_e32 v238, v238
	v_exp_f32_e32 v239, v239
	v_mul_f32_e32 v80, v80, v224
	v_mul_f32_e32 v81, v81, v225
	v_mul_f32_e32 v82, v82, v226
	v_mul_f32_e32 v83, v83, v227
	v_mul_f32_e32 v84, v84, v228
	v_mul_f32_e32 v85, v85, v229
	v_mul_f32_e32 v86, v86, v230
	v_mul_f32_e32 v87, v87, v231
	v_add_f32_e32 v232, 1.0, v232
	v_add_f32_e32 v233, 1.0, v233
	v_add_f32_e32 v234, 1.0, v234
	v_add_f32_e32 v235, 1.0, v235
	v_add_f32_e32 v236, 1.0, v236
	v_add_f32_e32 v237, 1.0, v237
	v_add_f32_e32 v238, 1.0, v238
	v_add_f32_e32 v239, 1.0, v239
	v_mul_f32_e32 v80, v80, v232
	v_mul_f32_e32 v81, v81, v233
	v_mul_f32_e32 v82, v82, v234
	v_mul_f32_e32 v83, v83, v235
	v_mul_f32_e32 v84, v84, v236
	v_mul_f32_e32 v85, v85, v237
	v_mul_f32_e32 v86, v86, v238
	v_mul_f32_e32 v87, v87, v239
	s_mov_b64 s[0:1], 0x161b00
	v_lshl_add_u64 v[2:3], v[206:207], 0, s[0:1]
	global_load_dwordx4 v[140:143], v[2:3], off
	global_load_dwordx4 v[144:147], v[2:3], off offset:2048
	s_waitcnt vmcnt(12)
	v_lshlrev_b32_e32 v224, 16, v148
	v_and_b32_e32 v225, 0xffff0000, v148
	v_lshlrev_b32_e32 v226, 16, v149
	v_and_b32_e32 v227, 0xffff0000, v149
	v_lshlrev_b32_e32 v228, 16, v150
	v_and_b32_e32 v229, 0xffff0000, v150
	v_lshlrev_b32_e32 v230, 16, v151
	v_and_b32_e32 v231, 0xffff0000, v151
	v_lshlrev_b32_e32 v232, 16, v152
	v_and_b32_e32 v233, 0xffff0000, v152
	v_lshlrev_b32_e32 v234, 16, v153
	v_and_b32_e32 v235, 0xffff0000, v153
	v_lshlrev_b32_e32 v236, 16, v154
	v_and_b32_e32 v237, 0xffff0000, v154
	v_lshlrev_b32_e32 v238, 16, v155
	v_and_b32_e32 v239, 0xffff0000, v155
	v_mul_f32_e32 v224, 0xbfb8aa3b, v224
	v_mul_f32_e32 v225, 0xbfb8aa3b, v225
	v_mul_f32_e32 v226, 0xbfb8aa3b, v226
	v_mul_f32_e32 v227, 0xbfb8aa3b, v227
	v_mul_f32_e32 v228, 0xbfb8aa3b, v228
	v_mul_f32_e32 v229, 0xbfb8aa3b, v229
	v_mul_f32_e32 v230, 0xbfb8aa3b, v230
	v_mul_f32_e32 v231, 0xbfb8aa3b, v231
	v_max_f32_e32 v232, v232, v232
	v_max_f32_e32 v233, v233, v233
	v_max_f32_e32 v234, v234, v234
	v_max_f32_e32 v235, v235, v235
	v_max_f32_e32 v236, v236, v236
	v_max_f32_e32 v237, v237, v237
	v_max_f32_e32 v238, v238, v238
	v_max_f32_e32 v239, v239, v239
	v_exp_f32_e32 v224, v224
	v_exp_f32_e32 v225, v225
	v_exp_f32_e32 v226, v226
	v_exp_f32_e32 v227, v227
	v_exp_f32_e32 v228, v228
	v_exp_f32_e32 v229, v229
	v_exp_f32_e32 v230, v230
	v_exp_f32_e32 v231, v231
	v_med3_f32 v232, v232, s48, v192
	v_med3_f32 v233, v233, s48, v192
	v_med3_f32 v234, v234, s48, v192
	v_med3_f32 v235, v235, s48, v192
	v_med3_f32 v236, v236, s48, v192
	v_med3_f32 v237, v237, s48, v192
	v_med3_f32 v238, v238, s48, v192
	v_med3_f32 v239, v239, s48, v192
	v_add_f32_e32 v224, 1.0, v224
	v_add_f32_e32 v225, 1.0, v225
	v_add_f32_e32 v226, 1.0, v226
	v_add_f32_e32 v227, 1.0, v227
	v_add_f32_e32 v228, 1.0, v228
	v_add_f32_e32 v229, 1.0, v229
	v_add_f32_e32 v230, 1.0, v230
	v_add_f32_e32 v231, 1.0, v231
	v_mul_f32_e32 v232, 0xbfb8aa3b, v232
	v_mul_f32_e32 v233, 0xbfb8aa3b, v233
	v_mul_f32_e32 v234, 0xbfb8aa3b, v234
	v_mul_f32_e32 v235, 0xbfb8aa3b, v235
	v_mul_f32_e32 v236, 0xbfb8aa3b, v236
	v_mul_f32_e32 v237, 0xbfb8aa3b, v237
	v_mul_f32_e32 v238, 0xbfb8aa3b, v238
	v_mul_f32_e32 v239, 0xbfb8aa3b, v239
	v_rcp_f32_e32 v224, v224
	v_rcp_f32_e32 v225, v225
	v_rcp_f32_e32 v226, v226
	v_rcp_f32_e32 v227, v227
	v_rcp_f32_e32 v228, v228
	v_rcp_f32_e32 v229, v229
	v_rcp_f32_e32 v230, v230
	v_rcp_f32_e32 v231, v231
	v_exp_f32_e32 v232, v232
	v_exp_f32_e32 v233, v233
	v_exp_f32_e32 v234, v234
	v_exp_f32_e32 v235, v235
	v_exp_f32_e32 v236, v236
	v_exp_f32_e32 v237, v237
	v_exp_f32_e32 v238, v238
	v_exp_f32_e32 v239, v239
	v_mul_f32_e32 v56, v56, v224
	v_mul_f32_e32 v57, v57, v225
	v_mul_f32_e32 v58, v58, v226
	v_mul_f32_e32 v59, v59, v227
	v_mul_f32_e32 v60, v60, v228
	v_mul_f32_e32 v61, v61, v229
	v_mul_f32_e32 v62, v62, v230
	v_mul_f32_e32 v63, v63, v231
	v_add_f32_e32 v232, 1.0, v232
	v_add_f32_e32 v233, 1.0, v233
	v_add_f32_e32 v234, 1.0, v234
	v_add_f32_e32 v235, 1.0, v235
	v_add_f32_e32 v236, 1.0, v236
	v_add_f32_e32 v237, 1.0, v237
	v_add_f32_e32 v238, 1.0, v238
	v_add_f32_e32 v239, 1.0, v239
	v_mul_f32_e32 v56, v56, v232
	v_mul_f32_e32 v57, v57, v233
	v_mul_f32_e32 v58, v58, v234
	v_mul_f32_e32 v59, v59, v235
	v_mul_f32_e32 v60, v60, v236
	v_mul_f32_e32 v61, v61, v237
	v_mul_f32_e32 v62, v62, v238
	v_mul_f32_e32 v63, v63, v239
	s_mov_b64 s[0:1], 0x161c00
	v_lshl_add_u64 v[2:3], v[206:207], 0, s[0:1]
	global_load_dwordx4 v[148:151], v[2:3], off
	global_load_dwordx4 v[152:155], v[2:3], off offset:2048
	s_waitcnt vmcnt(12)
; __device__ __forceinline__ float sigmoidf_(float x) { return __builtin_amdgcn_rcpf(1.0f + __expf(-x)); }
; __device__ __forceinline__ void unpack8(const uint4 u, float (&f)[8]) { f[0] = bflo(u.x); f[1] = bfhi(u.x); f[2] = bflo(u.y); f[3] = bfhi(u.y); f[4] = bflo(u.z); f[5] = bfhi(u.z); f[6] = bflo(u.w); f[7] = bfhi(u.w); }
;     __device__ __forceinline__ void mid(f32x4 (&acc)[2][2][4][2], const Unit& u, int wr, int wc, int fr, int fq) const {
;     ...
;             for (int m = 0; m < 4; ++m) { const bf16_t* gp = gate + (size_t)(row0 + ai * HALF + m * 16) * LDP + col8;
; #pragma unroll
;                 for (int bj = 0; bj < 2; ++bj) { float gc[8], gr[8]; unpack8(*(const uint4*)(gp + C_GC + bj * HALF), gc); unpack8(*(const uint4*)(gp + C_GR + bj * HALF), gr);
; #pragma unroll
;                     for (int e = 0; e < 4; ++e) { acc[ai][bj][m][0][e] *= sigmoidf_(gc[e]) * (1.0f + __expf(-fminf(fmaxf(gr[e], -30.f), 30.f)));
;                         acc[ai][bj][m][1][e] *= sigmoidf_(gc[4 + e]) * (1.0f + __expf(-fminf(fmaxf(gr[4 + e], -30.f), 30.f))); } } }
	v_lshlrev_b32_e32 v224, 16, v156
	v_and_b32_e32 v225, 0xffff0000, v156
	v_lshlrev_b32_e32 v226, 16, v157
	v_and_b32_e32 v227, 0xffff0000, v157
	v_lshlrev_b32_e32 v228, 16, v158
	v_and_b32_e32 v229, 0xffff0000, v158
	v_lshlrev_b32_e32 v230, 16, v159
	v_and_b32_e32 v231, 0xffff0000, v159
	v_lshlrev_b32_e32 v232, 16, v160
	v_and_b32_e32 v233, 0xffff0000, v160
	v_lshlrev_b32_e32 v234, 16, v161
	v_and_b32_e32 v235, 0xffff0000, v161
	v_lshlrev_b32_e32 v236, 16, v162
	v_and_b32_e32 v237, 0xffff0000, v162
	v_lshlrev_b32_e32 v238, 16, v163
	v_and_b32_e32 v239, 0xffff0000, v163
	v_mul_f32_e32 v224, 0xbfb8aa3b, v224
	v_mul_f32_e32 v225, 0xbfb8aa3b, v225
	v_mul_f32_e32 v226, 0xbfb8aa3b, v226
	v_mul_f32_e32 v227, 0xbfb8aa3b, v227
	v_mul_f32_e32 v228, 0xbfb8aa3b, v228
	v_mul_f32_e32 v229, 0xbfb8aa3b, v229
	v_mul_f32_e32 v230, 0xbfb8aa3b, v230
	v_mul_f32_e32 v231, 0xbfb8aa3b, v231
	v_max_f32_e32 v232, v232, v232
	v_max_f32_e32 v233, v233, v233
	v_max_f32_e32 v234, v234, v234
	v_max_f32_e32 v235, v235, v235
	v_max_f32_e32 v236, v236, v236
	v_max_f32_e32 v237, v237, v237
	v_max_f32_e32 v238, v238, v238
	v_max_f32_e32 v239, v239, v239
	v_exp_f32_e32 v224, v224
	v_exp_f32_e32 v225, v225
	v_exp_f32_e32 v226, v226
	v_exp_f32_e32 v227, v227
	v_exp_f32_e32 v228, v228
	v_exp_f32_e32 v229, v229
	v_exp_f32_e32 v230, v230
	v_exp_f32_e32 v231, v231
	v_med3_f32 v232, v232, s48, v192
	v_med3_f32 v233, v233, s48, v192
	v_med3_f32 v234, v234, s48, v192
	v_med3_f32 v235, v235, s48, v192
	v_med3_f32 v236, v236, s48, v192
	v_med3_f32 v237, v237, s48, v192
	v_med3_f32 v238, v238, s48, v192
	v_med3_f32 v239, v239, s48, v192
	v_add_f32_e32 v224, 1.0, v224
	v_add_f32_e32 v225, 1.0, v225
	v_add_f32_e32 v226, 1.0, v226
	v_add_f32_e32 v227, 1.0, v227
	v_add_f32_e32 v228, 1.0, v228
	v_add_f32_e32 v229, 1.0, v229
	v_add_f32_e32 v230, 1.0, v230
	v_add_f32_e32 v231, 1.0, v231
	v_mul_f32_e32 v232, 0xbfb8aa3b, v232
	v_mul_f32_e32 v233, 0xbfb8aa3b, v233
	v_mul_f32_e32 v234, 0xbfb8aa3b, v234
	v_mul_f32_e32 v235, 0xbfb8aa3b, v235
	v_mul_f32_e32 v236, 0xbfb8aa3b, v236
	v_mul_f32_e32 v237, 0xbfb8aa3b, v237
	v_mul_f32_e32 v238, 0xbfb8aa3b, v238
	v_mul_f32_e32 v239, 0xbfb8aa3b, v239
	v_rcp_f32_e32 v224, v224
	v_rcp_f32_e32 v225, v225
	v_rcp_f32_e32 v226, v226
	v_rcp_f32_e32 v227, v227
	v_rcp_f32_e32 v228, v228
	v_rcp_f32_e32 v229, v229
	v_rcp_f32_e32 v230, v230
	v_rcp_f32_e32 v231, v231
	v_exp_f32_e32 v232, v232
	v_exp_f32_e32 v233, v233
	v_exp_f32_e32 v234, v234
	v_exp_f32_e32 v235, v235
	v_exp_f32_e32 v236, v236
	v_exp_f32_e32 v237, v237
	v_exp_f32_e32 v238, v238
	v_exp_f32_e32 v239, v239
	v_mul_f32_e32 v88, v88, v224
	v_mul_f32_e32 v89, v89, v225
	v_mul_f32_e32 v90, v90, v226
	v_mul_f32_e32 v91, v91, v227
	v_mul_f32_e32 v92, v92, v228
	v_mul_f32_e32 v93, v93, v229
	v_mul_f32_e32 v94, v94, v230
	v_mul_f32_e32 v95, v95, v231
	v_add_f32_e32 v232, 1.0, v232
	v_add_f32_e32 v233, 1.0, v233
	v_add_f32_e32 v234, 1.0, v234
	v_add_f32_e32 v235, 1.0, v235
	v_add_f32_e32 v236, 1.0, v236
	v_add_f32_e32 v237, 1.0, v237
	v_add_f32_e32 v238, 1.0, v238
	v_add_f32_e32 v239, 1.0, v239
	v_mul_f32_e32 v88, v88, v232
	v_mul_f32_e32 v89, v89, v233
	v_mul_f32_e32 v90, v90, v234
	v_mul_f32_e32 v91, v91, v235
	v_mul_f32_e32 v92, v92, v236
	v_mul_f32_e32 v93, v93, v237
	v_mul_f32_e32 v94, v94, v238
	v_mul_f32_e32 v95, v95, v239
	s_mov_b64 s[0:1], 0x18db00
	v_lshl_add_u64 v[2:3], v[206:207], 0, s[0:1]
	global_load_dwordx4 v[156:159], v[2:3], off
	global_load_dwordx4 v[160:163], v[2:3], off offset:2048
	s_waitcnt vmcnt(12)
	v_lshlrev_b32_e32 v224, 16, v208
	v_and_b32_e32 v225, 0xffff0000, v208
	v_lshlrev_b32_e32 v226, 16, v209
	v_and_b32_e32 v227, 0xffff0000, v209
	v_lshlrev_b32_e32 v228, 16, v210
	v_and_b32_e32 v229, 0xffff0000, v210
	v_lshlrev_b32_e32 v230, 16, v211
	v_and_b32_e32 v231, 0xffff0000, v211
	v_lshlrev_b32_e32 v232, 16, v212
	v_and_b32_e32 v233, 0xffff0000, v212
	v_lshlrev_b32_e32 v234, 16, v213
	v_and_b32_e32 v235, 0xffff0000, v213
	v_lshlrev_b32_e32 v236, 16, v214
	v_and_b32_e32 v237, 0xffff0000, v214
	v_lshlrev_b32_e32 v238, 16, v215
	v_and_b32_e32 v239, 0xffff0000, v215
	v_mul_f32_e32 v224, 0xbfb8aa3b, v224
	v_mul_f32_e32 v225, 0xbfb8aa3b, v225
	v_mul_f32_e32 v226, 0xbfb8aa3b, v226
	v_mul_f32_e32 v227, 0xbfb8aa3b, v227
	v_mul_f32_e32 v228, 0xbfb8aa3b, v228
	v_mul_f32_e32 v229, 0xbfb8aa3b, v229
	v_mul_f32_e32 v230, 0xbfb8aa3b, v230
	v_mul_f32_e32 v231, 0xbfb8aa3b, v231
	v_max_f32_e32 v232, v232, v232
	v_max_f32_e32 v233, v233, v233
	v_max_f32_e32 v234, v234, v234
	v_max_f32_e32 v235, v235, v235
	v_max_f32_e32 v236, v236, v236
	v_max_f32_e32 v237, v237, v237
	v_max_f32_e32 v238, v238, v238
	v_max_f32_e32 v239, v239, v239
	v_exp_f32_e32 v224, v224
	v_exp_f32_e32 v225, v225
	v_exp_f32_e32 v226, v226
	v_exp_f32_e32 v227, v227
	v_exp_f32_e32 v228, v228
	v_exp_f32_e32 v229, v229
	v_exp_f32_e32 v230, v230
	v_exp_f32_e32 v231, v231
	v_med3_f32 v232, v232, s48, v192
	v_med3_f32 v233, v233, s48, v192
	v_med3_f32 v234, v234, s48, v192
	v_med3_f32 v235, v235, s48, v192
	v_med3_f32 v236, v236, s48, v192
	v_med3_f32 v237, v237, s48, v192
	v_med3_f32 v238, v238, s48, v192
	v_med3_f32 v239, v239, s48, v192
	v_add_f32_e32 v224, 1.0, v224
	v_add_f32_e32 v225, 1.0, v225
	v_add_f32_e32 v226, 1.0, v226
	v_add_f32_e32 v227, 1.0, v227
	v_add_f32_e32 v228, 1.0, v228
	v_add_f32_e32 v229, 1.0, v229
	v_add_f32_e32 v230, 1.0, v230
	v_add_f32_e32 v231, 1.0, v231
	v_mul_f32_e32 v232, 0xbfb8aa3b, v232
	v_mul_f32_e32 v233, 0xbfb8aa3b, v233
	v_mul_f32_e32 v234, 0xbfb8aa3b, v234
	v_mul_f32_e32 v235, 0xbfb8aa3b, v235
	v_mul_f32_e32 v236, 0xbfb8aa3b, v236
	v_mul_f32_e32 v237, 0xbfb8aa3b, v237
	v_mul_f32_e32 v238, 0xbfb8aa3b, v238
	v_mul_f32_e32 v239, 0xbfb8aa3b, v239
	v_rcp_f32_e32 v224, v224
	v_rcp_f32_e32 v225, v225
	v_rcp_f32_e32 v226, v226
	v_rcp_f32_e32 v227, v227
	v_rcp_f32_e32 v228, v228
	v_rcp_f32_e32 v229, v229
	v_rcp_f32_e32 v230, v230
	v_rcp_f32_e32 v231, v231
	v_exp_f32_e32 v232, v232
	v_exp_f32_e32 v233, v233
	v_exp_f32_e32 v234, v234
	v_exp_f32_e32 v235, v235
	v_exp_f32_e32 v236, v236
	v_exp_f32_e32 v237, v237
	v_exp_f32_e32 v238, v238
	v_exp_f32_e32 v239, v239
	v_mul_f32_e32 v64, v64, v224
	v_mul_f32_e32 v65, v65, v225
	v_mul_f32_e32 v66, v66, v226
	v_mul_f32_e32 v67, v67, v227
	v_mul_f32_e32 v68, v68, v228
	v_mul_f32_e32 v69, v69, v229
	v_mul_f32_e32 v70, v70, v230
	v_mul_f32_e32 v71, v71, v231
	v_add_f32_e32 v232, 1.0, v232
	v_add_f32_e32 v233, 1.0, v233
	v_add_f32_e32 v234, 1.0, v234
	v_add_f32_e32 v235, 1.0, v235
	v_add_f32_e32 v236, 1.0, v236
	v_add_f32_e32 v237, 1.0, v237
	v_add_f32_e32 v238, 1.0, v238
	v_add_f32_e32 v239, 1.0, v239
	v_mul_f32_e32 v64, v64, v232
	v_mul_f32_e32 v65, v65, v233
	v_mul_f32_e32 v66, v66, v234
	v_mul_f32_e32 v67, v67, v235
	v_mul_f32_e32 v68, v68, v236
	v_mul_f32_e32 v69, v69, v237
	v_mul_f32_e32 v70, v70, v238
	v_mul_f32_e32 v71, v71, v239
	s_mov_b64 s[0:1], 0x18dc00
	v_lshl_add_u64 v[2:3], v[206:207], 0, s[0:1]
	global_load_dwordx4 v[208:211], v[2:3], off
	global_load_dwordx4 v[212:215], v[2:3], off offset:2048
	s_waitcnt vmcnt(12)
; __device__ __forceinline__ float sigmoidf_(float x) { return __builtin_amdgcn_rcpf(1.0f + __expf(-x)); }
; __device__ __forceinline__ void unpack8(const uint4 u, float (&f)[8]) { f[0] = bflo(u.x); f[1] = bfhi(u.x); f[2] = bflo(u.y); f[3] = bfhi(u.y); f[4] = bflo(u.z); f[5] = bfhi(u.z); f[6] = bflo(u.w); f[7] = bfhi(u.w); }
;     __device__ __forceinline__ void mid(f32x4 (&acc)[2][2][4][2], const Unit& u, int wr, int wc, int fr, int fq) const {
;     ...
;             for (int m = 0; m < 4; ++m) { const bf16_t* gp = gate + (size_t)(row0 + ai * HALF + m * 16) * LDP + col8;
; #pragma unroll
;                 for (int bj = 0; bj < 2; ++bj) { float gc[8], gr[8]; unpack8(*(const uint4*)(gp + C_GC + bj * HALF), gc); unpack8(*(const uint4*)(gp + C_GR + bj * HALF), gr);
; #pragma unroll
;                     for (int e = 0; e < 4; ++e) { acc[ai][bj][m][0][e] *= sigmoidf_(gc[e]) * (1.0f + __expf(-fminf(fmaxf(gr[e], -30.f), 30.f)));
;                         acc[ai][bj][m][1][e] *= sigmoidf_(gc[4 + e]) * (1.0f + __expf(-fminf(fmaxf(gr[4 + e], -30.f), 30.f))); } } }
	v_lshlrev_b32_e32 v224, 16, v216
	v_and_b32_e32 v225, 0xffff0000, v216
	v_lshlrev_b32_e32 v226, 16, v217
	v_and_b32_e32 v227, 0xffff0000, v217
	v_lshlrev_b32_e32 v228, 16, v218
	v_and_b32_e32 v229, 0xffff0000, v218
	v_lshlrev_b32_e32 v230, 16, v219
	v_and_b32_e32 v231, 0xffff0000, v219
	v_lshlrev_b32_e32 v232, 16, v220
	v_and_b32_e32 v233, 0xffff0000, v220
	v_lshlrev_b32_e32 v234, 16, v221
	v_and_b32_e32 v235, 0xffff0000, v221
	v_lshlrev_b32_e32 v236, 16, v222
	v_and_b32_e32 v237, 0xffff0000, v222
	v_lshlrev_b32_e32 v238, 16, v223
	v_and_b32_e32 v239, 0xffff0000, v223
	v_mul_f32_e32 v224, 0xbfb8aa3b, v224
	v_mul_f32_e32 v225, 0xbfb8aa3b, v225
	v_mul_f32_e32 v226, 0xbfb8aa3b, v226
	v_mul_f32_e32 v227, 0xbfb8aa3b, v227
	v_mul_f32_e32 v228, 0xbfb8aa3b, v228
	v_mul_f32_e32 v229, 0xbfb8aa3b, v229
	v_mul_f32_e32 v230, 0xbfb8aa3b, v230
	v_mul_f32_e32 v231, 0xbfb8aa3b, v231
	v_max_f32_e32 v232, v232, v232
	v_max_f32_e32 v233, v233, v233
	v_max_f32_e32 v234, v234, v234
	v_max_f32_e32 v235, v235, v235
	v_max_f32_e32 v236, v236, v236
	v_max_f32_e32 v237, v237, v237
	v_max_f32_e32 v238, v238, v238
	v_max_f32_e32 v239, v239, v239
	v_exp_f32_e32 v224, v224
	v_exp_f32_e32 v225, v225
	v_exp_f32_e32 v226, v226
	v_exp_f32_e32 v227, v227
	v_exp_f32_e32 v228, v228
	v_exp_f32_e32 v229, v229
	v_exp_f32_e32 v230, v230
	v_exp_f32_e32 v231, v231
	v_med3_f32 v232, v232, s48, v192
	v_med3_f32 v233, v233, s48, v192
	v_med3_f32 v234, v234, s48, v192
	v_med3_f32 v235, v235, s48, v192
	v_med3_f32 v236, v236, s48, v192
	v_med3_f32 v237, v237, s48, v192
	v_med3_f32 v238, v238, s48, v192
	v_med3_f32 v239, v239, s48, v192
	v_add_f32_e32 v224, 1.0, v224
	v_add_f32_e32 v225, 1.0, v225
	v_add_f32_e32 v226, 1.0, v226
	v_add_f32_e32 v227, 1.0, v227
	v_add_f32_e32 v228, 1.0, v228
	v_add_f32_e32 v229, 1.0, v229
	v_add_f32_e32 v230, 1.0, v230
	v_add_f32_e32 v231, 1.0, v231
	v_mul_f32_e32 v232, 0xbfb8aa3b, v232
	v_mul_f32_e32 v233, 0xbfb8aa3b, v233
	v_mul_f32_e32 v234, 0xbfb8aa3b, v234
	v_mul_f32_e32 v235, 0xbfb8aa3b, v235
	v_mul_f32_e32 v236, 0xbfb8aa3b, v236
	v_mul_f32_e32 v237, 0xbfb8aa3b, v237
	v_mul_f32_e32 v238, 0xbfb8aa3b, v238
	v_mul_f32_e32 v239, 0xbfb8aa3b, v239
	v_rcp_f32_e32 v224, v224
	v_rcp_f32_e32 v225, v225
	v_rcp_f32_e32 v226, v226
	v_rcp_f32_e32 v227, v227
	v_rcp_f32_e32 v228, v228
	v_rcp_f32_e32 v229, v229
	v_rcp_f32_e32 v230, v230
	v_rcp_f32_e32 v231, v231
	v_exp_f32_e32 v232, v232
	v_exp_f32_e32 v233, v233
	v_exp_f32_e32 v234, v234
	v_exp_f32_e32 v235, v235
	v_exp_f32_e32 v236, v236
	v_exp_f32_e32 v237, v237
	v_exp_f32_e32 v238, v238
	v_exp_f32_e32 v239, v239
	v_mul_f32_e32 v96, v96, v224
	v_mul_f32_e32 v97, v97, v225
	v_mul_f32_e32 v98, v98, v226
	v_mul_f32_e32 v99, v99, v227
	v_mul_f32_e32 v100, v100, v228
	v_mul_f32_e32 v101, v101, v229
	v_mul_f32_e32 v102, v102, v230
	v_mul_f32_e32 v103, v103, v231
	v_add_f32_e32 v232, 1.0, v232
	v_add_f32_e32 v233, 1.0, v233
	v_add_f32_e32 v234, 1.0, v234
	v_add_f32_e32 v235, 1.0, v235
	v_add_f32_e32 v236, 1.0, v236
	v_add_f32_e32 v237, 1.0, v237
	v_add_f32_e32 v238, 1.0, v238
	v_add_f32_e32 v239, 1.0, v239
	v_mul_f32_e32 v96, v96, v232
	v_mul_f32_e32 v97, v97, v233
	v_mul_f32_e32 v98, v98, v234
	v_mul_f32_e32 v99, v99, v235
	v_mul_f32_e32 v100, v100, v236
	v_mul_f32_e32 v101, v101, v237
	v_mul_f32_e32 v102, v102, v238
	v_mul_f32_e32 v103, v103, v239
	s_mov_b64 s[0:1], 0x1b9b00
	v_lshl_add_u64 v[2:3], v[206:207], 0, s[0:1]
	global_load_dwordx4 v[216:219], v[2:3], off
	global_load_dwordx4 v[220:223], v[2:3], off offset:2048
	s_waitcnt vmcnt(12)
	v_lshlrev_b32_e32 v224, 16, v240
	v_and_b32_e32 v225, 0xffff0000, v240
	v_lshlrev_b32_e32 v226, 16, v241
	v_and_b32_e32 v227, 0xffff0000, v241
	v_lshlrev_b32_e32 v228, 16, v242
	v_and_b32_e32 v229, 0xffff0000, v242
	v_lshlrev_b32_e32 v230, 16, v243
	v_and_b32_e32 v231, 0xffff0000, v243
	v_lshlrev_b32_e32 v232, 16, v244
	v_and_b32_e32 v233, 0xffff0000, v244
	v_lshlrev_b32_e32 v234, 16, v245
	v_and_b32_e32 v235, 0xffff0000, v245
	v_lshlrev_b32_e32 v236, 16, v246
	v_and_b32_e32 v237, 0xffff0000, v246
	v_lshlrev_b32_e32 v238, 16, v247
	v_and_b32_e32 v239, 0xffff0000, v247
	v_mul_f32_e32 v224, 0xbfb8aa3b, v224
	v_mul_f32_e32 v225, 0xbfb8aa3b, v225
	v_mul_f32_e32 v226, 0xbfb8aa3b, v226
	v_mul_f32_e32 v227, 0xbfb8aa3b, v227
	v_mul_f32_e32 v228, 0xbfb8aa3b, v228
	v_mul_f32_e32 v229, 0xbfb8aa3b, v229
	v_mul_f32_e32 v230, 0xbfb8aa3b, v230
	v_mul_f32_e32 v231, 0xbfb8aa3b, v231
	v_max_f32_e32 v232, v232, v232
	v_max_f32_e32 v233, v233, v233
	v_max_f32_e32 v234, v234, v234
	v_max_f32_e32 v235, v235, v235
	v_max_f32_e32 v236, v236, v236
	v_max_f32_e32 v237, v237, v237
	v_max_f32_e32 v238, v238, v238
	v_max_f32_e32 v239, v239, v239
	v_exp_f32_e32 v224, v224
	v_exp_f32_e32 v225, v225
	v_exp_f32_e32 v226, v226
	v_exp_f32_e32 v227, v227
	v_exp_f32_e32 v228, v228
	v_exp_f32_e32 v229, v229
	v_exp_f32_e32 v230, v230
	v_exp_f32_e32 v231, v231
	v_med3_f32 v232, v232, s48, v192
	v_med3_f32 v233, v233, s48, v192
	v_med3_f32 v234, v234, s48, v192
	v_med3_f32 v235, v235, s48, v192
	v_med3_f32 v236, v236, s48, v192
	v_med3_f32 v237, v237, s48, v192
	v_med3_f32 v238, v238, s48, v192
	v_med3_f32 v239, v239, s48, v192
	v_add_f32_e32 v224, 1.0, v224
	v_add_f32_e32 v225, 1.0, v225
	v_add_f32_e32 v226, 1.0, v226
	v_add_f32_e32 v227, 1.0, v227
	v_add_f32_e32 v228, 1.0, v228
	v_add_f32_e32 v229, 1.0, v229
	v_add_f32_e32 v230, 1.0, v230
	v_add_f32_e32 v231, 1.0, v231
	v_mul_f32_e32 v232, 0xbfb8aa3b, v232
	v_mul_f32_e32 v233, 0xbfb8aa3b, v233
	v_mul_f32_e32 v234, 0xbfb8aa3b, v234
	v_mul_f32_e32 v235, 0xbfb8aa3b, v235
	v_mul_f32_e32 v236, 0xbfb8aa3b, v236
	v_mul_f32_e32 v237, 0xbfb8aa3b, v237
	v_mul_f32_e32 v238, 0xbfb8aa3b, v238
	v_mul_f32_e32 v239, 0xbfb8aa3b, v239
	v_rcp_f32_e32 v224, v224
	v_rcp_f32_e32 v225, v225
	v_rcp_f32_e32 v226, v226
	v_rcp_f32_e32 v227, v227
	v_rcp_f32_e32 v228, v228
	v_rcp_f32_e32 v229, v229
	v_rcp_f32_e32 v230, v230
	v_rcp_f32_e32 v231, v231
	v_exp_f32_e32 v232, v232
	v_exp_f32_e32 v233, v233
	v_exp_f32_e32 v234, v234
	v_exp_f32_e32 v235, v235
	v_exp_f32_e32 v236, v236
	v_exp_f32_e32 v237, v237
	v_exp_f32_e32 v238, v238
	v_exp_f32_e32 v239, v239
	v_mul_f32_e32 v72, v72, v224
	v_mul_f32_e32 v73, v73, v225
	v_mul_f32_e32 v74, v74, v226
	v_mul_f32_e32 v75, v75, v227
	v_mul_f32_e32 v76, v76, v228
	v_mul_f32_e32 v77, v77, v229
	v_mul_f32_e32 v78, v78, v230
	v_mul_f32_e32 v79, v79, v231
	v_add_f32_e32 v232, 1.0, v232
	v_add_f32_e32 v233, 1.0, v233
	v_add_f32_e32 v234, 1.0, v234
	v_add_f32_e32 v235, 1.0, v235
	v_add_f32_e32 v236, 1.0, v236
	v_add_f32_e32 v237, 1.0, v237
	v_add_f32_e32 v238, 1.0, v238
	v_add_f32_e32 v239, 1.0, v239
	v_mul_f32_e32 v72, v72, v232
	v_mul_f32_e32 v73, v73, v233
	v_mul_f32_e32 v74, v74, v234
	v_mul_f32_e32 v75, v75, v235
	v_mul_f32_e32 v76, v76, v236
	v_mul_f32_e32 v77, v77, v237
	v_mul_f32_e32 v78, v78, v238
	v_mul_f32_e32 v79, v79, v239
	s_mov_b64 s[0:1], 0x1b9c00
	v_lshl_add_u64 v[2:3], v[206:207], 0, s[0:1]
	global_load_dwordx4 v[240:243], v[2:3], off
	global_load_dwordx4 v[244:247], v[2:3], off offset:2048
	s_waitcnt vmcnt(12)
; __device__ __forceinline__ float sigmoidf_(float x) { return __builtin_amdgcn_rcpf(1.0f + __expf(-x)); }
; __device__ __forceinline__ void unpack8(const uint4 u, float (&f)[8]) { f[0] = bflo(u.x); f[1] = bfhi(u.x); f[2] = bflo(u.y); f[3] = bfhi(u.y); f[4] = bflo(u.z); f[5] = bfhi(u.z); f[6] = bflo(u.w); f[7] = bfhi(u.w); }
;     __device__ __forceinline__ void mid(f32x4 (&acc)[2][2][4][2], const Unit& u, int wr, int wc, int fr, int fq) const {
;     ...
;             for (int m = 0; m < 4; ++m) { const bf16_t* gp = gate + (size_t)(row0 + ai * HALF + m * 16) * LDP + col8;
; #pragma unroll
;                 for (int bj = 0; bj < 2; ++bj) { float gc[8], gr[8]; unpack8(*(const uint4*)(gp + C_GC + bj * HALF), gc); unpack8(*(const uint4*)(gp + C_GR + bj * HALF), gr);
; #pragma unroll
;                     for (int e = 0; e < 4; ++e) { acc[ai][bj][m][0][e] *= sigmoidf_(gc[e]) * (1.0f + __expf(-fminf(fmaxf(gr[e], -30.f), 30.f)));
;                         acc[ai][bj][m][1][e] *= sigmoidf_(gc[4 + e]) * (1.0f + __expf(-fminf(fmaxf(gr[4 + e], -30.f), 30.f))); } } }
	v_lshlrev_b32_e32 v224, 16, v132
	v_and_b32_e32 v225, 0xffff0000, v132
	v_lshlrev_b32_e32 v226, 16, v133
	v_and_b32_e32 v227, 0xffff0000, v133
	v_lshlrev_b32_e32 v228, 16, v134
	v_and_b32_e32 v229, 0xffff0000, v134
	v_lshlrev_b32_e32 v230, 16, v135
	v_and_b32_e32 v231, 0xffff0000, v135
	v_lshlrev_b32_e32 v232, 16, v136
	v_and_b32_e32 v233, 0xffff0000, v136
	v_lshlrev_b32_e32 v234, 16, v137
	v_and_b32_e32 v235, 0xffff0000, v137
	v_lshlrev_b32_e32 v236, 16, v138
	v_and_b32_e32 v237, 0xffff0000, v138
	v_lshlrev_b32_e32 v238, 16, v139
	v_and_b32_e32 v239, 0xffff0000, v139
	v_mul_f32_e32 v224, 0xbfb8aa3b, v224
	v_mul_f32_e32 v225, 0xbfb8aa3b, v225
	v_mul_f32_e32 v226, 0xbfb8aa3b, v226
	v_mul_f32_e32 v227, 0xbfb8aa3b, v227
	v_mul_f32_e32 v228, 0xbfb8aa3b, v228
	v_mul_f32_e32 v229, 0xbfb8aa3b, v229
	v_mul_f32_e32 v230, 0xbfb8aa3b, v230
	v_mul_f32_e32 v231, 0xbfb8aa3b, v231
	v_max_f32_e32 v232, v232, v232
	v_max_f32_e32 v233, v233, v233
	v_max_f32_e32 v234, v234, v234
	v_max_f32_e32 v235, v235, v235
	v_max_f32_e32 v236, v236, v236
	v_max_f32_e32 v237, v237, v237
	v_max_f32_e32 v238, v238, v238
	v_max_f32_e32 v239, v239, v239
	v_exp_f32_e32 v224, v224
	v_exp_f32_e32 v225, v225
	v_exp_f32_e32 v226, v226
	v_exp_f32_e32 v227, v227
	v_exp_f32_e32 v228, v228
	v_exp_f32_e32 v229, v229
	v_exp_f32_e32 v230, v230
	v_exp_f32_e32 v231, v231
	v_med3_f32 v232, v232, s48, v192
	v_med3_f32 v233, v233, s48, v192
	v_med3_f32 v234, v234, s48, v192
	v_med3_f32 v235, v235, s48, v192
	v_med3_f32 v236, v236, s48, v192
	v_med3_f32 v237, v237, s48, v192
	v_med3_f32 v238, v238, s48, v192
	v_med3_f32 v239, v239, s48, v192
	v_add_f32_e32 v224, 1.0, v224
	v_add_f32_e32 v225, 1.0, v225
	v_add_f32_e32 v226, 1.0, v226
	v_add_f32_e32 v227, 1.0, v227
	v_add_f32_e32 v228, 1.0, v228
	v_add_f32_e32 v229, 1.0, v229
	v_add_f32_e32 v230, 1.0, v230
	v_add_f32_e32 v231, 1.0, v231
	v_mul_f32_e32 v232, 0xbfb8aa3b, v232
	v_mul_f32_e32 v233, 0xbfb8aa3b, v233
	v_mul_f32_e32 v234, 0xbfb8aa3b, v234
	v_mul_f32_e32 v235, 0xbfb8aa3b, v235
	v_mul_f32_e32 v236, 0xbfb8aa3b, v236
	v_mul_f32_e32 v237, 0xbfb8aa3b, v237
	v_mul_f32_e32 v238, 0xbfb8aa3b, v238
	v_mul_f32_e32 v239, 0xbfb8aa3b, v239
	v_rcp_f32_e32 v224, v224
	v_rcp_f32_e32 v225, v225
	v_rcp_f32_e32 v226, v226
	v_rcp_f32_e32 v227, v227
	v_rcp_f32_e32 v228, v228
	v_rcp_f32_e32 v229, v229
	v_rcp_f32_e32 v230, v230
	v_rcp_f32_e32 v231, v231
	v_exp_f32_e32 v232, v232
	v_exp_f32_e32 v233, v233
	v_exp_f32_e32 v234, v234
	v_exp_f32_e32 v235, v235
	v_exp_f32_e32 v236, v236
	v_exp_f32_e32 v237, v237
	v_exp_f32_e32 v238, v238
	v_exp_f32_e32 v239, v239
	v_mul_f32_e32 v104, v104, v224
	v_mul_f32_e32 v105, v105, v225
	v_mul_f32_e32 v106, v106, v226
	v_mul_f32_e32 v107, v107, v227
	v_mul_f32_e32 v108, v108, v228
	v_mul_f32_e32 v109, v109, v229
	v_mul_f32_e32 v110, v110, v230
	v_mul_f32_e32 v111, v111, v231
	v_add_f32_e32 v232, 1.0, v232
	v_add_f32_e32 v233, 1.0, v233
	v_add_f32_e32 v234, 1.0, v234
	v_add_f32_e32 v235, 1.0, v235
	v_add_f32_e32 v236, 1.0, v236
	v_add_f32_e32 v237, 1.0, v237
	v_add_f32_e32 v238, 1.0, v238
	v_add_f32_e32 v239, 1.0, v239
	v_mul_f32_e32 v104, v104, v232
	v_mul_f32_e32 v105, v105, v233
	v_mul_f32_e32 v106, v106, v234
	v_mul_f32_e32 v107, v107, v235
	v_mul_f32_e32 v108, v108, v236
	v_mul_f32_e32 v109, v109, v237
	v_mul_f32_e32 v110, v110, v238
	v_mul_f32_e32 v111, v111, v239
	s_mov_b64 s[0:1], 0x1e5b00
	v_lshl_add_u64 v[2:3], v[206:207], 0, s[0:1]
	global_load_dwordx4 v[132:135], v[2:3], off
	global_load_dwordx4 v[136:139], v[2:3], off offset:2048
	s_waitcnt vmcnt(12)
	v_lshlrev_b32_e32 v224, 16, v140
	v_and_b32_e32 v225, 0xffff0000, v140
	v_lshlrev_b32_e32 v226, 16, v141
	v_and_b32_e32 v227, 0xffff0000, v141
	v_lshlrev_b32_e32 v228, 16, v142
	v_and_b32_e32 v229, 0xffff0000, v142
	v_lshlrev_b32_e32 v230, 16, v143
	v_and_b32_e32 v231, 0xffff0000, v143
	v_lshlrev_b32_e32 v232, 16, v144
	v_and_b32_e32 v233, 0xffff0000, v144
	v_lshlrev_b32_e32 v234, 16, v145
	v_and_b32_e32 v235, 0xffff0000, v145
	v_lshlrev_b32_e32 v236, 16, v146
	v_and_b32_e32 v237, 0xffff0000, v146
	v_lshlrev_b32_e32 v238, 16, v147
	v_and_b32_e32 v239, 0xffff0000, v147
	v_mul_f32_e32 v224, 0xbfb8aa3b, v224
	v_mul_f32_e32 v225, 0xbfb8aa3b, v225
	v_mul_f32_e32 v226, 0xbfb8aa3b, v226
	v_mul_f32_e32 v227, 0xbfb8aa3b, v227
	v_mul_f32_e32 v228, 0xbfb8aa3b, v228
	v_mul_f32_e32 v229, 0xbfb8aa3b, v229
	v_mul_f32_e32 v230, 0xbfb8aa3b, v230
	v_mul_f32_e32 v231, 0xbfb8aa3b, v231
	v_max_f32_e32 v232, v232, v232
	v_max_f32_e32 v233, v233, v233
	v_max_f32_e32 v234, v234, v234
	v_max_f32_e32 v235, v235, v235
	v_max_f32_e32 v236, v236, v236
	v_max_f32_e32 v237, v237, v237
	v_max_f32_e32 v238, v238, v238
	v_max_f32_e32 v239, v239, v239
	v_exp_f32_e32 v224, v224
	v_exp_f32_e32 v225, v225
	v_exp_f32_e32 v226, v226
	v_exp_f32_e32 v227, v227
	v_exp_f32_e32 v228, v228
	v_exp_f32_e32 v229, v229
	v_exp_f32_e32 v230, v230
	v_exp_f32_e32 v231, v231
	v_med3_f32 v232, v232, s48, v192
	v_med3_f32 v233, v233, s48, v192
	v_med3_f32 v234, v234, s48, v192
	v_med3_f32 v235, v235, s48, v192
	v_med3_f32 v236, v236, s48, v192
	v_med3_f32 v237, v237, s48, v192
	v_med3_f32 v238, v238, s48, v192
	v_med3_f32 v239, v239, s48, v192
	v_add_f32_e32 v224, 1.0, v224
	v_add_f32_e32 v225, 1.0, v225
	v_add_f32_e32 v226, 1.0, v226
	v_add_f32_e32 v227, 1.0, v227
	v_add_f32_e32 v228, 1.0, v228
	v_add_f32_e32 v229, 1.0, v229
	v_add_f32_e32 v230, 1.0, v230
	v_add_f32_e32 v231, 1.0, v231
	v_mul_f32_e32 v232, 0xbfb8aa3b, v232
	v_mul_f32_e32 v233, 0xbfb8aa3b, v233
	v_mul_f32_e32 v234, 0xbfb8aa3b, v234
	v_mul_f32_e32 v235, 0xbfb8aa3b, v235
	v_mul_f32_e32 v236, 0xbfb8aa3b, v236
	v_mul_f32_e32 v237, 0xbfb8aa3b, v237
; __device__ __forceinline__ float sigmoidf_(float x) { return __builtin_amdgcn_rcpf(1.0f + __expf(-x)); }
; __device__ __forceinline__ void unpack8(const uint4 u, float (&f)[8]) { f[0] = bflo(u.x); f[1] = bfhi(u.x); f[2] = bflo(u.y); f[3] = bfhi(u.y); f[4] = bflo(u.z); f[5] = bfhi(u.z); f[6] = bflo(u.w); f[7] = bfhi(u.w); }
;     __device__ __forceinline__ void mid(f32x4 (&acc)[2][2][4][2], const Unit& u, int wr, int wc, int fr, int fq) const {
;     ...
;             for (int m = 0; m < 4; ++m) { const bf16_t* gp = gate + (size_t)(row0 + ai * HALF + m * 16) * LDP + col8;
; #pragma unroll
;                 for (int bj = 0; bj < 2; ++bj) { float gc[8], gr[8]; unpack8(*(const uint4*)(gp + C_GC + bj * HALF), gc); unpack8(*(const uint4*)(gp + C_GR + bj * HALF), gr);
; #pragma unroll
;                     for (int e = 0; e < 4; ++e) { acc[ai][bj][m][0][e] *= sigmoidf_(gc[e]) * (1.0f + __expf(-fminf(fmaxf(gr[e], -30.f), 30.f)));
;                         acc[ai][bj][m][1][e] *= sigmoidf_(gc[4 + e]) * (1.0f + __expf(-fminf(fmaxf(gr[4 + e], -30.f), 30.f))); } } }
	v_mul_f32_e32 v238, 0xbfb8aa3b, v238
	v_mul_f32_e32 v239, 0xbfb8aa3b, v239
	v_rcp_f32_e32 v224, v224
	v_rcp_f32_e32 v225, v225
	v_rcp_f32_e32 v226, v226
	v_rcp_f32_e32 v227, v227
	v_rcp_f32_e32 v228, v228
	v_rcp_f32_e32 v229, v229
	v_rcp_f32_e32 v230, v230
	v_rcp_f32_e32 v231, v231
	v_exp_f32_e32 v232, v232
	v_exp_f32_e32 v233, v233
	v_exp_f32_e32 v234, v234
	v_exp_f32_e32 v235, v235
	v_exp_f32_e32 v236, v236
	v_exp_f32_e32 v237, v237
	v_exp_f32_e32 v238, v238
	v_exp_f32_e32 v239, v239
	v_mul_f32_e32 v112, v112, v224
	v_mul_f32_e32 v113, v113, v225
	v_mul_f32_e32 v114, v114, v226
	v_mul_f32_e32 v115, v115, v227
	v_mul_f32_e32 v116, v116, v228
	v_mul_f32_e32 v117, v117, v229
	v_mul_f32_e32 v118, v118, v230
	v_mul_f32_e32 v119, v119, v231
	v_add_f32_e32 v232, 1.0, v232
	v_add_f32_e32 v233, 1.0, v233
	v_add_f32_e32 v234, 1.0, v234
	v_add_f32_e32 v235, 1.0, v235
	v_add_f32_e32 v236, 1.0, v236
	v_add_f32_e32 v237, 1.0, v237
	v_add_f32_e32 v238, 1.0, v238
	v_add_f32_e32 v239, 1.0, v239
	v_mul_f32_e32 v112, v112, v232
	v_mul_f32_e32 v113, v113, v233
	v_mul_f32_e32 v114, v114, v234
	v_mul_f32_e32 v115, v115, v235
	v_mul_f32_e32 v116, v116, v236
	v_mul_f32_e32 v117, v117, v237
	v_mul_f32_e32 v118, v118, v238
	v_mul_f32_e32 v119, v119, v239
	s_mov_b64 s[0:1], 0x1e5c00
	v_lshl_add_u64 v[2:3], v[206:207], 0, s[0:1]
	global_load_dwordx4 v[140:143], v[2:3], off
	global_load_dwordx4 v[144:147], v[2:3], off offset:2048
	s_waitcnt vmcnt(12)
	v_lshlrev_b32_e32 v224, 16, v148
	v_and_b32_e32 v225, 0xffff0000, v148
	v_lshlrev_b32_e32 v226, 16, v149
	v_and_b32_e32 v227, 0xffff0000, v149
	v_lshlrev_b32_e32 v228, 16, v150
	v_and_b32_e32 v229, 0xffff0000, v150
	v_lshlrev_b32_e32 v230, 16, v151
	v_and_b32_e32 v231, 0xffff0000, v151
	v_lshlrev_b32_e32 v232, 16, v152
	v_and_b32_e32 v233, 0xffff0000, v152
	v_lshlrev_b32_e32 v234, 16, v153
	v_and_b32_e32 v235, 0xffff0000, v153
	v_lshlrev_b32_e32 v236, 16, v154
	v_and_b32_e32 v237, 0xffff0000, v154
	v_lshlrev_b32_e32 v238, 16, v155
	v_and_b32_e32 v239, 0xffff0000, v155
	v_mul_f32_e32 v224, 0xbfb8aa3b, v224
	v_mul_f32_e32 v225, 0xbfb8aa3b, v225
	v_mul_f32_e32 v226, 0xbfb8aa3b, v226
	v_mul_f32_e32 v227, 0xbfb8aa3b, v227
	v_mul_f32_e32 v228, 0xbfb8aa3b, v228
	v_mul_f32_e32 v229, 0xbfb8aa3b, v229
	v_mul_f32_e32 v230, 0xbfb8aa3b, v230
	v_mul_f32_e32 v231, 0xbfb8aa3b, v231
	v_max_f32_e32 v232, v232, v232
	v_max_f32_e32 v233, v233, v233
	v_max_f32_e32 v234, v234, v234
	v_max_f32_e32 v235, v235, v235
	v_max_f32_e32 v236, v236, v236
	v_max_f32_e32 v237, v237, v237
	v_max_f32_e32 v238, v238, v238
	v_max_f32_e32 v239, v239, v239
	v_exp_f32_e32 v224, v224
	v_exp_f32_e32 v225, v225
	v_exp_f32_e32 v226, v226
	v_exp_f32_e32 v227, v227
	v_exp_f32_e32 v228, v228
	v_exp_f32_e32 v229, v229
	v_exp_f32_e32 v230, v230
	v_exp_f32_e32 v231, v231
	v_med3_f32 v232, v232, s48, v192
	v_med3_f32 v233, v233, s48, v192
	v_med3_f32 v234, v234, s48, v192
	v_med3_f32 v235, v235, s48, v192
	v_med3_f32 v236, v236, s48, v192
	v_med3_f32 v237, v237, s48, v192
	v_med3_f32 v238, v238, s48, v192
	v_med3_f32 v239, v239, s48, v192
	v_add_f32_e32 v224, 1.0, v224
	v_add_f32_e32 v225, 1.0, v225
	v_add_f32_e32 v226, 1.0, v226
	v_add_f32_e32 v227, 1.0, v227
	v_add_f32_e32 v228, 1.0, v228
	v_add_f32_e32 v229, 1.0, v229
	v_add_f32_e32 v230, 1.0, v230
	v_add_f32_e32 v231, 1.0, v231
	v_mul_f32_e32 v232, 0xbfb8aa3b, v232
	v_mul_f32_e32 v233, 0xbfb8aa3b, v233
	v_mul_f32_e32 v234, 0xbfb8aa3b, v234
	v_mul_f32_e32 v235, 0xbfb8aa3b, v235
	v_mul_f32_e32 v236, 0xbfb8aa3b, v236
	v_mul_f32_e32 v237, 0xbfb8aa3b, v237
	v_mul_f32_e32 v238, 0xbfb8aa3b, v238
	v_mul_f32_e32 v239, 0xbfb8aa3b, v239
	v_rcp_f32_e32 v224, v224
	v_rcp_f32_e32 v225, v225
	v_rcp_f32_e32 v226, v226
	v_rcp_f32_e32 v227, v227
	v_rcp_f32_e32 v228, v228
	v_rcp_f32_e32 v229, v229
	v_rcp_f32_e32 v230, v230
	v_rcp_f32_e32 v231, v231
	v_exp_f32_e32 v232, v232
	v_exp_f32_e32 v233, v233
	v_exp_f32_e32 v234, v234
	v_exp_f32_e32 v235, v235
	v_exp_f32_e32 v236, v236
	v_exp_f32_e32 v237, v237
	v_exp_f32_e32 v238, v238
	v_exp_f32_e32 v239, v239
	v_mul_f32_e32 v4, v4, v224
	v_mul_f32_e32 v5, v5, v225
	v_mul_f32_e32 v6, v6, v226
	v_mul_f32_e32 v7, v7, v227
	v_mul_f32_e32 v8, v8, v228
	v_mul_f32_e32 v9, v9, v229
	v_mul_f32_e32 v10, v10, v230
	v_mul_f32_e32 v11, v11, v231
	v_add_f32_e32 v232, 1.0, v232
	v_add_f32_e32 v233, 1.0, v233
	v_add_f32_e32 v234, 1.0, v234
	v_add_f32_e32 v235, 1.0, v235
	v_add_f32_e32 v236, 1.0, v236
	v_add_f32_e32 v237, 1.0, v237
	v_add_f32_e32 v238, 1.0, v238
	v_add_f32_e32 v239, 1.0, v239
	v_mul_f32_e32 v4, v4, v232
	v_mul_f32_e32 v5, v5, v233
	v_mul_f32_e32 v6, v6, v234
	v_mul_f32_e32 v7, v7, v235
	v_mul_f32_e32 v8, v8, v236
	v_mul_f32_e32 v9, v9, v237
	v_mul_f32_e32 v10, v10, v238
	v_mul_f32_e32 v11, v11, v239
	s_waitcnt vmcnt(10)
; __device__ __forceinline__ float sigmoidf_(float x) { return __builtin_amdgcn_rcpf(1.0f + __expf(-x)); }
; __device__ __forceinline__ void unpack8(const uint4 u, float (&f)[8]) { f[0] = bflo(u.x); f[1] = bfhi(u.x); f[2] = bflo(u.y); f[3] = bfhi(u.y); f[4] = bflo(u.z); f[5] = bfhi(u.z); f[6] = bflo(u.w); f[7] = bfhi(u.w); }
;     __device__ __forceinline__ void mid(f32x4 (&acc)[2][2][4][2], const Unit& u, int wr, int wc, int fr, int fq) const {
;     ...
;             for (int m = 0; m < 4; ++m) { const bf16_t* gp = gate + (size_t)(row0 + ai * HALF + m * 16) * LDP + col8;
; #pragma unroll
;                 for (int bj = 0; bj < 2; ++bj) { float gc[8], gr[8]; unpack8(*(const uint4*)(gp + C_GC + bj * HALF), gc); unpack8(*(const uint4*)(gp + C_GR + bj * HALF), gr);
; #pragma unroll
;                     for (int e = 0; e < 4; ++e) { acc[ai][bj][m][0][e] *= sigmoidf_(gc[e]) * (1.0f + __expf(-fminf(fmaxf(gr[e], -30.f), 30.f)));
;                         acc[ai][bj][m][1][e] *= sigmoidf_(gc[4 + e]) * (1.0f + __expf(-fminf(fmaxf(gr[4 + e], -30.f), 30.f))); } } }
	v_lshlrev_b32_e32 v224, 16, v156
	v_and_b32_e32 v225, 0xffff0000, v156
	v_lshlrev_b32_e32 v226, 16, v157
	v_and_b32_e32 v227, 0xffff0000, v157
	v_lshlrev_b32_e32 v228, 16, v158
	v_and_b32_e32 v229, 0xffff0000, v158
	v_lshlrev_b32_e32 v230, 16, v159
	v_and_b32_e32 v231, 0xffff0000, v159
	v_lshlrev_b32_e32 v232, 16, v160
	v_and_b32_e32 v233, 0xffff0000, v160
	v_lshlrev_b32_e32 v234, 16, v161
	v_and_b32_e32 v235, 0xffff0000, v161
	v_lshlrev_b32_e32 v236, 16, v162
	v_and_b32_e32 v237, 0xffff0000, v162
	v_lshlrev_b32_e32 v238, 16, v163
	v_and_b32_e32 v239, 0xffff0000, v163
	v_mul_f32_e32 v224, 0xbfb8aa3b, v224
	v_mul_f32_e32 v225, 0xbfb8aa3b, v225
	v_mul_f32_e32 v226, 0xbfb8aa3b, v226
	v_mul_f32_e32 v227, 0xbfb8aa3b, v227
	v_mul_f32_e32 v228, 0xbfb8aa3b, v228
	v_mul_f32_e32 v229, 0xbfb8aa3b, v229
	v_mul_f32_e32 v230, 0xbfb8aa3b, v230
	v_mul_f32_e32 v231, 0xbfb8aa3b, v231
	v_max_f32_e32 v232, v232, v232
	v_max_f32_e32 v233, v233, v233
	v_max_f32_e32 v234, v234, v234
	v_max_f32_e32 v235, v235, v235
	v_max_f32_e32 v236, v236, v236
	v_max_f32_e32 v237, v237, v237
	v_max_f32_e32 v238, v238, v238
	v_max_f32_e32 v239, v239, v239
	v_exp_f32_e32 v224, v224
	v_exp_f32_e32 v225, v225
	v_exp_f32_e32 v226, v226
	v_exp_f32_e32 v227, v227
	v_exp_f32_e32 v228, v228
	v_exp_f32_e32 v229, v229
	v_exp_f32_e32 v230, v230
	v_exp_f32_e32 v231, v231
	v_med3_f32 v232, v232, s48, v192
	v_med3_f32 v233, v233, s48, v192
	v_med3_f32 v234, v234, s48, v192
	v_med3_f32 v235, v235, s48, v192
	v_med3_f32 v236, v236, s48, v192
	v_med3_f32 v237, v237, s48, v192
	v_med3_f32 v238, v238, s48, v192
	v_med3_f32 v239, v239, s48, v192
	v_add_f32_e32 v224, 1.0, v224
	v_add_f32_e32 v225, 1.0, v225
	v_add_f32_e32 v226, 1.0, v226
	v_add_f32_e32 v227, 1.0, v227
	v_add_f32_e32 v228, 1.0, v228
	v_add_f32_e32 v229, 1.0, v229
	v_add_f32_e32 v230, 1.0, v230
	v_add_f32_e32 v231, 1.0, v231
	v_mul_f32_e32 v232, 0xbfb8aa3b, v232
	v_mul_f32_e32 v233, 0xbfb8aa3b, v233
	v_mul_f32_e32 v234, 0xbfb8aa3b, v234
	v_mul_f32_e32 v235, 0xbfb8aa3b, v235
	v_mul_f32_e32 v236, 0xbfb8aa3b, v236
	v_mul_f32_e32 v237, 0xbfb8aa3b, v237
	v_mul_f32_e32 v238, 0xbfb8aa3b, v238
	v_mul_f32_e32 v239, 0xbfb8aa3b, v239
	v_rcp_f32_e32 v224, v224
	v_rcp_f32_e32 v225, v225
	v_rcp_f32_e32 v226, v226
	v_rcp_f32_e32 v227, v227
	v_rcp_f32_e32 v228, v228
	v_rcp_f32_e32 v229, v229
	v_rcp_f32_e32 v230, v230
	v_rcp_f32_e32 v231, v231
	v_exp_f32_e32 v232, v232
	v_exp_f32_e32 v233, v233
	v_exp_f32_e32 v234, v234
	v_exp_f32_e32 v235, v235
	v_exp_f32_e32 v236, v236
	v_exp_f32_e32 v237, v237
	v_exp_f32_e32 v238, v238
	v_exp_f32_e32 v239, v239
	v_mul_f32_e32 v120, v120, v224
	v_mul_f32_e32 v121, v121, v225
	v_mul_f32_e32 v122, v122, v226
	v_mul_f32_e32 v123, v123, v227
	v_mul_f32_e32 v124, v124, v228
	v_mul_f32_e32 v125, v125, v229
	v_mul_f32_e32 v126, v126, v230
	v_mul_f32_e32 v127, v127, v231
	v_add_f32_e32 v232, 1.0, v232
	v_add_f32_e32 v233, 1.0, v233
	v_add_f32_e32 v234, 1.0, v234
	v_add_f32_e32 v235, 1.0, v235
	v_add_f32_e32 v236, 1.0, v236
	v_add_f32_e32 v237, 1.0, v237
	v_add_f32_e32 v238, 1.0, v238
	v_add_f32_e32 v239, 1.0, v239
	v_mul_f32_e32 v120, v120, v232
	v_mul_f32_e32 v121, v121, v233
	v_mul_f32_e32 v122, v122, v234
	v_mul_f32_e32 v123, v123, v235
	v_mul_f32_e32 v124, v124, v236
	v_mul_f32_e32 v125, v125, v237
	v_mul_f32_e32 v126, v126, v238
	v_mul_f32_e32 v127, v127, v239
	s_waitcnt vmcnt(8)
	v_lshlrev_b32_e32 v224, 16, v208
	v_and_b32_e32 v225, 0xffff0000, v208
	v_lshlrev_b32_e32 v226, 16, v209
	v_and_b32_e32 v227, 0xffff0000, v209
	v_lshlrev_b32_e32 v228, 16, v210
	v_and_b32_e32 v229, 0xffff0000, v210
	v_lshlrev_b32_e32 v230, 16, v211
	v_and_b32_e32 v231, 0xffff0000, v211
	v_lshlrev_b32_e32 v232, 16, v212
	v_and_b32_e32 v233, 0xffff0000, v212
	v_lshlrev_b32_e32 v234, 16, v213
	v_and_b32_e32 v235, 0xffff0000, v213
	v_lshlrev_b32_e32 v236, 16, v214
	v_and_b32_e32 v237, 0xffff0000, v214
	v_lshlrev_b32_e32 v238, 16, v215
	v_and_b32_e32 v239, 0xffff0000, v215
	v_mul_f32_e32 v224, 0xbfb8aa3b, v224
	v_mul_f32_e32 v225, 0xbfb8aa3b, v225
	v_mul_f32_e32 v226, 0xbfb8aa3b, v226
	v_mul_f32_e32 v227, 0xbfb8aa3b, v227
	v_mul_f32_e32 v228, 0xbfb8aa3b, v228
	v_mul_f32_e32 v229, 0xbfb8aa3b, v229
	v_mul_f32_e32 v230, 0xbfb8aa3b, v230
	v_mul_f32_e32 v231, 0xbfb8aa3b, v231
	v_max_f32_e32 v232, v232, v232
	v_max_f32_e32 v233, v233, v233
	v_max_f32_e32 v234, v234, v234
	v_max_f32_e32 v235, v235, v235
	v_max_f32_e32 v236, v236, v236
	v_max_f32_e32 v237, v237, v237
	v_max_f32_e32 v238, v238, v238
	v_max_f32_e32 v239, v239, v239
	v_exp_f32_e32 v224, v224
	v_exp_f32_e32 v225, v225
	v_exp_f32_e32 v226, v226
	v_exp_f32_e32 v227, v227
	v_exp_f32_e32 v228, v228
	v_exp_f32_e32 v229, v229
	v_exp_f32_e32 v230, v230
	v_exp_f32_e32 v231, v231
	v_med3_f32 v232, v232, s48, v192
	v_med3_f32 v233, v233, s48, v192
	v_med3_f32 v234, v234, s48, v192
	v_med3_f32 v235, v235, s48, v192
	v_med3_f32 v236, v236, s48, v192
	v_med3_f32 v237, v237, s48, v192
	v_med3_f32 v238, v238, s48, v192
	v_med3_f32 v239, v239, s48, v192
	v_add_f32_e32 v224, 1.0, v224
	v_add_f32_e32 v225, 1.0, v225
	v_add_f32_e32 v226, 1.0, v226
	v_add_f32_e32 v227, 1.0, v227
	v_add_f32_e32 v228, 1.0, v228
	v_add_f32_e32 v229, 1.0, v229
	v_add_f32_e32 v230, 1.0, v230
	v_add_f32_e32 v231, 1.0, v231
	v_mul_f32_e32 v232, 0xbfb8aa3b, v232
	v_mul_f32_e32 v233, 0xbfb8aa3b, v233
	v_mul_f32_e32 v234, 0xbfb8aa3b, v234
	v_mul_f32_e32 v235, 0xbfb8aa3b, v235
	v_mul_f32_e32 v236, 0xbfb8aa3b, v236
	v_mul_f32_e32 v237, 0xbfb8aa3b, v237
	v_mul_f32_e32 v238, 0xbfb8aa3b, v238
	v_mul_f32_e32 v239, 0xbfb8aa3b, v239
	v_rcp_f32_e32 v224, v224
	v_rcp_f32_e32 v225, v225
	v_rcp_f32_e32 v226, v226
	v_rcp_f32_e32 v227, v227
	v_rcp_f32_e32 v228, v228
	v_rcp_f32_e32 v229, v229
	v_rcp_f32_e32 v230, v230
	v_rcp_f32_e32 v231, v231
	v_exp_f32_e32 v232, v232
	v_exp_f32_e32 v233, v233
	v_exp_f32_e32 v234, v234
	v_exp_f32_e32 v235, v235
	v_exp_f32_e32 v236, v236
	v_exp_f32_e32 v237, v237
	v_exp_f32_e32 v238, v238
	v_exp_f32_e32 v239, v239
	v_mul_f32_e32 v12, v12, v224
	v_mul_f32_e32 v13, v13, v225
	v_mul_f32_e32 v14, v14, v226
	v_mul_f32_e32 v15, v15, v227
	v_mul_f32_e32 v16, v16, v228
	v_mul_f32_e32 v17, v17, v229
	v_mul_f32_e32 v18, v18, v230
	v_mul_f32_e32 v19, v19, v231
	v_add_f32_e32 v232, 1.0, v232
	v_add_f32_e32 v233, 1.0, v233
	v_add_f32_e32 v234, 1.0, v234
	v_add_f32_e32 v235, 1.0, v235
	v_add_f32_e32 v236, 1.0, v236
	v_add_f32_e32 v237, 1.0, v237
	v_add_f32_e32 v238, 1.0, v238
	v_add_f32_e32 v239, 1.0, v239
	v_mul_f32_e32 v12, v12, v232
	v_mul_f32_e32 v13, v13, v233
	v_mul_f32_e32 v14, v14, v234
	v_mul_f32_e32 v15, v15, v235
	v_mul_f32_e32 v16, v16, v236
	v_mul_f32_e32 v17, v17, v237
	v_mul_f32_e32 v18, v18, v238
	v_mul_f32_e32 v19, v19, v239
	s_waitcnt vmcnt(6)
; __device__ __forceinline__ float sigmoidf_(float x) { return __builtin_amdgcn_rcpf(1.0f + __expf(-x)); }
; __device__ __forceinline__ void unpack8(const uint4 u, float (&f)[8]) { f[0] = bflo(u.x); f[1] = bfhi(u.x); f[2] = bflo(u.y); f[3] = bfhi(u.y); f[4] = bflo(u.z); f[5] = bfhi(u.z); f[6] = bflo(u.w); f[7] = bfhi(u.w); }
;     __device__ __forceinline__ void mid(f32x4 (&acc)[2][2][4][2], const Unit& u, int wr, int wc, int fr, int fq) const {
;     ...
;             for (int m = 0; m < 4; ++m) { const bf16_t* gp = gate + (size_t)(row0 + ai * HALF + m * 16) * LDP + col8;
; #pragma unroll
;                 for (int bj = 0; bj < 2; ++bj) { float gc[8], gr[8]; unpack8(*(const uint4*)(gp + C_GC + bj * HALF), gc); unpack8(*(const uint4*)(gp + C_GR + bj * HALF), gr);
; #pragma unroll
;                     for (int e = 0; e < 4; ++e) { acc[ai][bj][m][0][e] *= sigmoidf_(gc[e]) * (1.0f + __expf(-fminf(fmaxf(gr[e], -30.f), 30.f)));
;                         acc[ai][bj][m][1][e] *= sigmoidf_(gc[4 + e]) * (1.0f + __expf(-fminf(fmaxf(gr[4 + e], -30.f), 30.f))); } } }
	v_lshlrev_b32_e32 v224, 16, v216
	v_and_b32_e32 v225, 0xffff0000, v216
	v_lshlrev_b32_e32 v226, 16, v217
	v_and_b32_e32 v227, 0xffff0000, v217
	v_lshlrev_b32_e32 v228, 16, v218
	v_and_b32_e32 v229, 0xffff0000, v218
	v_lshlrev_b32_e32 v230, 16, v219
	v_and_b32_e32 v231, 0xffff0000, v219
	v_lshlrev_b32_e32 v232, 16, v220
	v_and_b32_e32 v233, 0xffff0000, v220
	v_lshlrev_b32_e32 v234, 16, v221
	v_and_b32_e32 v235, 0xffff0000, v221
	v_lshlrev_b32_e32 v236, 16, v222
	v_and_b32_e32 v237, 0xffff0000, v222
	v_lshlrev_b32_e32 v238, 16, v223
	v_and_b32_e32 v239, 0xffff0000, v223
	v_mul_f32_e32 v224, 0xbfb8aa3b, v224
	v_mul_f32_e32 v225, 0xbfb8aa3b, v225
	v_mul_f32_e32 v226, 0xbfb8aa3b, v226
	v_mul_f32_e32 v227, 0xbfb8aa3b, v227
	v_mul_f32_e32 v228, 0xbfb8aa3b, v228
	v_mul_f32_e32 v229, 0xbfb8aa3b, v229
	v_mul_f32_e32 v230, 0xbfb8aa3b, v230
	v_mul_f32_e32 v231, 0xbfb8aa3b, v231
	v_max_f32_e32 v232, v232, v232
	v_max_f32_e32 v233, v233, v233
	v_max_f32_e32 v234, v234, v234
	v_max_f32_e32 v235, v235, v235
	v_max_f32_e32 v236, v236, v236
	v_max_f32_e32 v237, v237, v237
	v_max_f32_e32 v238, v238, v238
	v_max_f32_e32 v239, v239, v239
	v_exp_f32_e32 v224, v224
	v_exp_f32_e32 v225, v225
	v_exp_f32_e32 v226, v226
	v_exp_f32_e32 v227, v227
	v_exp_f32_e32 v228, v228
	v_exp_f32_e32 v229, v229
	v_exp_f32_e32 v230, v230
	v_exp_f32_e32 v231, v231
	v_med3_f32 v232, v232, s48, v192
	v_med3_f32 v233, v233, s48, v192
	v_med3_f32 v234, v234, s48, v192
	v_med3_f32 v235, v235, s48, v192
	v_med3_f32 v236, v236, s48, v192
	v_med3_f32 v237, v237, s48, v192
	v_med3_f32 v238, v238, s48, v192
	v_med3_f32 v239, v239, s48, v192
	v_add_f32_e32 v224, 1.0, v224
	v_add_f32_e32 v225, 1.0, v225
	v_add_f32_e32 v226, 1.0, v226
	v_add_f32_e32 v227, 1.0, v227
	v_add_f32_e32 v228, 1.0, v228
	v_add_f32_e32 v229, 1.0, v229
	v_add_f32_e32 v230, 1.0, v230
	v_add_f32_e32 v231, 1.0, v231
	v_mul_f32_e32 v232, 0xbfb8aa3b, v232
	v_mul_f32_e32 v233, 0xbfb8aa3b, v233
	v_mul_f32_e32 v234, 0xbfb8aa3b, v234
	v_mul_f32_e32 v235, 0xbfb8aa3b, v235
	v_mul_f32_e32 v236, 0xbfb8aa3b, v236
	v_mul_f32_e32 v237, 0xbfb8aa3b, v237
	v_mul_f32_e32 v238, 0xbfb8aa3b, v238
	v_mul_f32_e32 v239, 0xbfb8aa3b, v239
	v_rcp_f32_e32 v224, v224
	v_rcp_f32_e32 v225, v225
	v_rcp_f32_e32 v226, v226
	v_rcp_f32_e32 v227, v227
	v_rcp_f32_e32 v228, v228
	v_rcp_f32_e32 v229, v229
	v_rcp_f32_e32 v230, v230
	v_rcp_f32_e32 v231, v231
	v_exp_f32_e32 v232, v232
	v_exp_f32_e32 v233, v233
	v_exp_f32_e32 v234, v234
	v_exp_f32_e32 v235, v235
	v_exp_f32_e32 v236, v236
	v_exp_f32_e32 v237, v237
	v_exp_f32_e32 v238, v238
	v_exp_f32_e32 v239, v239
	v_mul_f32_e32 v128, v128, v224
	v_mul_f32_e32 v129, v129, v225
	v_mul_f32_e32 v130, v130, v226
	v_mul_f32_e32 v131, v131, v227
	v_mul_f32_e32 v36, v36, v228
	v_mul_f32_e32 v37, v37, v229
	v_mul_f32_e32 v38, v38, v230
	v_mul_f32_e32 v39, v39, v231
	v_add_f32_e32 v232, 1.0, v232
	v_add_f32_e32 v233, 1.0, v233
	v_add_f32_e32 v234, 1.0, v234
	v_add_f32_e32 v235, 1.0, v235
	v_add_f32_e32 v236, 1.0, v236
	v_add_f32_e32 v237, 1.0, v237
	v_add_f32_e32 v238, 1.0, v238
	v_add_f32_e32 v239, 1.0, v239
	v_mul_f32_e32 v128, v128, v232
	v_mul_f32_e32 v129, v129, v233
	v_mul_f32_e32 v130, v130, v234
	v_mul_f32_e32 v131, v131, v235
	v_mul_f32_e32 v36, v36, v236
	v_mul_f32_e32 v37, v37, v237
	v_mul_f32_e32 v38, v38, v238
	v_mul_f32_e32 v39, v39, v239
	s_waitcnt vmcnt(4)
	v_lshlrev_b32_e32 v224, 16, v240
	v_and_b32_e32 v225, 0xffff0000, v240
	v_lshlrev_b32_e32 v226, 16, v241
	v_and_b32_e32 v227, 0xffff0000, v241
	v_lshlrev_b32_e32 v228, 16, v242
	v_and_b32_e32 v229, 0xffff0000, v242
	v_lshlrev_b32_e32 v230, 16, v243
	v_and_b32_e32 v231, 0xffff0000, v243
	v_lshlrev_b32_e32 v232, 16, v244
	v_and_b32_e32 v233, 0xffff0000, v244
	v_lshlrev_b32_e32 v234, 16, v245
	v_and_b32_e32 v235, 0xffff0000, v245
	v_lshlrev_b32_e32 v236, 16, v246
	v_and_b32_e32 v237, 0xffff0000, v246
	v_lshlrev_b32_e32 v238, 16, v247
	v_and_b32_e32 v239, 0xffff0000, v247
	v_mul_f32_e32 v224, 0xbfb8aa3b, v224
	v_mul_f32_e32 v225, 0xbfb8aa3b, v225
	v_mul_f32_e32 v226, 0xbfb8aa3b, v226
	v_mul_f32_e32 v227, 0xbfb8aa3b, v227
	v_mul_f32_e32 v228, 0xbfb8aa3b, v228
	v_mul_f32_e32 v229, 0xbfb8aa3b, v229
	v_mul_f32_e32 v230, 0xbfb8aa3b, v230
	v_mul_f32_e32 v231, 0xbfb8aa3b, v231
	v_max_f32_e32 v232, v232, v232
	v_max_f32_e32 v233, v233, v233
	v_max_f32_e32 v234, v234, v234
	v_max_f32_e32 v235, v235, v235
	v_max_f32_e32 v236, v236, v236
	v_max_f32_e32 v237, v237, v237
	v_max_f32_e32 v238, v238, v238
	v_max_f32_e32 v239, v239, v239
	v_exp_f32_e32 v224, v224
	v_exp_f32_e32 v225, v225
	v_exp_f32_e32 v226, v226
	v_exp_f32_e32 v227, v227
	v_exp_f32_e32 v228, v228
	v_exp_f32_e32 v229, v229
	v_exp_f32_e32 v230, v230
	v_exp_f32_e32 v231, v231
	v_med3_f32 v232, v232, s48, v192
	v_med3_f32 v233, v233, s48, v192
	v_med3_f32 v234, v234, s48, v192
	v_med3_f32 v235, v235, s48, v192
	v_med3_f32 v236, v236, s48, v192
	v_med3_f32 v237, v237, s48, v192
	v_med3_f32 v238, v238, s48, v192
	v_med3_f32 v239, v239, s48, v192
	v_add_f32_e32 v224, 1.0, v224
	v_add_f32_e32 v225, 1.0, v225
	v_add_f32_e32 v226, 1.0, v226
	v_add_f32_e32 v227, 1.0, v227
	v_add_f32_e32 v228, 1.0, v228
	v_add_f32_e32 v229, 1.0, v229
	v_add_f32_e32 v230, 1.0, v230
	v_add_f32_e32 v231, 1.0, v231
	v_mul_f32_e32 v232, 0xbfb8aa3b, v232
	v_mul_f32_e32 v233, 0xbfb8aa3b, v233
	v_mul_f32_e32 v234, 0xbfb8aa3b, v234
	v_mul_f32_e32 v235, 0xbfb8aa3b, v235
	v_mul_f32_e32 v236, 0xbfb8aa3b, v236
	v_mul_f32_e32 v237, 0xbfb8aa3b, v237
	v_mul_f32_e32 v238, 0xbfb8aa3b, v238
	v_mul_f32_e32 v239, 0xbfb8aa3b, v239
	v_rcp_f32_e32 v224, v224
	v_rcp_f32_e32 v225, v225
	v_rcp_f32_e32 v226, v226
	v_rcp_f32_e32 v227, v227
	v_rcp_f32_e32 v228, v228
	v_rcp_f32_e32 v229, v229
	v_rcp_f32_e32 v230, v230
	v_rcp_f32_e32 v231, v231
	v_exp_f32_e32 v232, v232
	v_exp_f32_e32 v233, v233
	v_exp_f32_e32 v234, v234
	v_exp_f32_e32 v235, v235
	v_exp_f32_e32 v236, v236
	v_exp_f32_e32 v237, v237
	v_exp_f32_e32 v238, v238
	v_exp_f32_e32 v239, v239
	v_mul_f32_e32 v20, v20, v224
	v_mul_f32_e32 v21, v21, v225
	v_mul_f32_e32 v22, v22, v226
	v_mul_f32_e32 v23, v23, v227
	v_mul_f32_e32 v24, v24, v228
	v_mul_f32_e32 v25, v25, v229
	v_mul_f32_e32 v26, v26, v230
	v_mul_f32_e32 v27, v27, v231
	v_add_f32_e32 v232, 1.0, v232
	v_add_f32_e32 v233, 1.0, v233
	v_add_f32_e32 v234, 1.0, v234
	v_add_f32_e32 v235, 1.0, v235
	v_add_f32_e32 v236, 1.0, v236
	v_add_f32_e32 v237, 1.0, v237
	v_add_f32_e32 v238, 1.0, v238
	v_add_f32_e32 v239, 1.0, v239
	v_mul_f32_e32 v20, v20, v232
	v_mul_f32_e32 v21, v21, v233
	v_mul_f32_e32 v22, v22, v234
	v_mul_f32_e32 v23, v23, v235
	v_mul_f32_e32 v24, v24, v236
	v_mul_f32_e32 v25, v25, v237
	v_mul_f32_e32 v26, v26, v238
	v_mul_f32_e32 v27, v27, v239
	s_waitcnt vmcnt(2)
; __device__ __forceinline__ float sigmoidf_(float x) { return __builtin_amdgcn_rcpf(1.0f + __expf(-x)); }
; __device__ __forceinline__ void unpack8(const uint4 u, float (&f)[8]) { f[0] = bflo(u.x); f[1] = bfhi(u.x); f[2] = bflo(u.y); f[3] = bfhi(u.y); f[4] = bflo(u.z); f[5] = bfhi(u.z); f[6] = bflo(u.w); f[7] = bfhi(u.w); }
;     __device__ __forceinline__ void mid(f32x4 (&acc)[2][2][4][2], const Unit& u, int wr, int wc, int fr, int fq) const {
;     ...
;             for (int m = 0; m < 4; ++m) { const bf16_t* gp = gate + (size_t)(row0 + ai * HALF + m * 16) * LDP + col8;
; #pragma unroll
;                 for (int bj = 0; bj < 2; ++bj) { float gc[8], gr[8]; unpack8(*(const uint4*)(gp + C_GC + bj * HALF), gc); unpack8(*(const uint4*)(gp + C_GR + bj * HALF), gr);
; #pragma unroll
;                     for (int e = 0; e < 4; ++e) { acc[ai][bj][m][0][e] *= sigmoidf_(gc[e]) * (1.0f + __expf(-fminf(fmaxf(gr[e], -30.f), 30.f)));
;                         acc[ai][bj][m][1][e] *= sigmoidf_(gc[4 + e]) * (1.0f + __expf(-fminf(fmaxf(gr[4 + e], -30.f), 30.f))); } } }
	v_lshlrev_b32_e32 v224, 16, v132
	v_and_b32_e32 v225, 0xffff0000, v132
	v_lshlrev_b32_e32 v226, 16, v133
	v_and_b32_e32 v227, 0xffff0000, v133
	v_lshlrev_b32_e32 v228, 16, v134
	v_and_b32_e32 v229, 0xffff0000, v134
	v_lshlrev_b32_e32 v230, 16, v135
	v_and_b32_e32 v231, 0xffff0000, v135
	v_lshlrev_b32_e32 v232, 16, v136
	v_and_b32_e32 v233, 0xffff0000, v136
	v_lshlrev_b32_e32 v234, 16, v137
	v_and_b32_e32 v235, 0xffff0000, v137
	v_lshlrev_b32_e32 v236, 16, v138
	v_and_b32_e32 v237, 0xffff0000, v138
	v_lshlrev_b32_e32 v238, 16, v139
	v_and_b32_e32 v239, 0xffff0000, v139
	v_mul_f32_e32 v224, 0xbfb8aa3b, v224
	v_mul_f32_e32 v225, 0xbfb8aa3b, v225
	v_mul_f32_e32 v226, 0xbfb8aa3b, v226
	v_mul_f32_e32 v227, 0xbfb8aa3b, v227
	v_mul_f32_e32 v228, 0xbfb8aa3b, v228
	v_mul_f32_e32 v229, 0xbfb8aa3b, v229
	v_mul_f32_e32 v230, 0xbfb8aa3b, v230
	v_mul_f32_e32 v231, 0xbfb8aa3b, v231
	v_max_f32_e32 v232, v232, v232
	v_max_f32_e32 v233, v233, v233
	v_max_f32_e32 v234, v234, v234
	v_max_f32_e32 v235, v235, v235
	v_max_f32_e32 v236, v236, v236
	v_max_f32_e32 v237, v237, v237
	v_max_f32_e32 v238, v238, v238
	v_max_f32_e32 v239, v239, v239
	v_exp_f32_e32 v224, v224
	v_exp_f32_e32 v225, v225
	v_exp_f32_e32 v226, v226
	v_exp_f32_e32 v227, v227
	v_exp_f32_e32 v228, v228
	v_exp_f32_e32 v229, v229
	v_exp_f32_e32 v230, v230
	v_exp_f32_e32 v231, v231
	v_med3_f32 v232, v232, s48, v192
	v_med3_f32 v233, v233, s48, v192
	v_med3_f32 v234, v234, s48, v192
	v_med3_f32 v235, v235, s48, v192
	v_med3_f32 v236, v236, s48, v192
	v_med3_f32 v237, v237, s48, v192
	v_med3_f32 v238, v238, s48, v192
	v_med3_f32 v239, v239, s48, v192
	v_add_f32_e32 v224, 1.0, v224
	v_add_f32_e32 v225, 1.0, v225
	v_add_f32_e32 v226, 1.0, v226
	v_add_f32_e32 v227, 1.0, v227
	v_add_f32_e32 v228, 1.0, v228
	v_add_f32_e32 v229, 1.0, v229
	v_add_f32_e32 v230, 1.0, v230
	v_add_f32_e32 v231, 1.0, v231
	v_mul_f32_e32 v232, 0xbfb8aa3b, v232
	v_mul_f32_e32 v233, 0xbfb8aa3b, v233
	v_mul_f32_e32 v234, 0xbfb8aa3b, v234
	v_mul_f32_e32 v235, 0xbfb8aa3b, v235
	v_mul_f32_e32 v236, 0xbfb8aa3b, v236
	v_mul_f32_e32 v237, 0xbfb8aa3b, v237
	v_mul_f32_e32 v238, 0xbfb8aa3b, v238
	v_mul_f32_e32 v239, 0xbfb8aa3b, v239
	v_rcp_f32_e32 v224, v224
	v_rcp_f32_e32 v225, v225
	v_rcp_f32_e32 v226, v226
	v_rcp_f32_e32 v227, v227
	v_rcp_f32_e32 v228, v228
	v_rcp_f32_e32 v229, v229
	v_rcp_f32_e32 v230, v230
	v_rcp_f32_e32 v231, v231
	v_exp_f32_e32 v232, v232
	v_exp_f32_e32 v233, v233
	v_exp_f32_e32 v234, v234
	v_exp_f32_e32 v235, v235
	v_exp_f32_e32 v236, v236
	v_exp_f32_e32 v237, v237
	v_exp_f32_e32 v238, v238
	v_exp_f32_e32 v239, v239
	v_mul_f32_e32 v40, v40, v224
	v_mul_f32_e32 v41, v41, v225
	v_mul_f32_e32 v42, v42, v226
	v_mul_f32_e32 v43, v43, v227
	v_mul_f32_e32 v44, v44, v228
	v_mul_f32_e32 v45, v45, v229
	v_mul_f32_e32 v46, v46, v230
	v_mul_f32_e32 v47, v47, v231
	v_add_f32_e32 v232, 1.0, v232
	v_add_f32_e32 v233, 1.0, v233
	v_add_f32_e32 v234, 1.0, v234
	v_add_f32_e32 v235, 1.0, v235
	v_add_f32_e32 v236, 1.0, v236
	v_add_f32_e32 v237, 1.0, v237
	v_add_f32_e32 v238, 1.0, v238
	v_add_f32_e32 v239, 1.0, v239
	v_mul_f32_e32 v40, v40, v232
	v_mul_f32_e32 v41, v41, v233
	v_mul_f32_e32 v42, v42, v234
	v_mul_f32_e32 v43, v43, v235
	v_mul_f32_e32 v44, v44, v236
	v_mul_f32_e32 v45, v45, v237
	v_mul_f32_e32 v46, v46, v238
	v_mul_f32_e32 v47, v47, v239
	s_waitcnt vmcnt(0)
	v_lshlrev_b32_e32 v224, 16, v140
	v_and_b32_e32 v225, 0xffff0000, v140
	v_lshlrev_b32_e32 v226, 16, v141
	v_and_b32_e32 v227, 0xffff0000, v141
	v_lshlrev_b32_e32 v228, 16, v142
	v_and_b32_e32 v229, 0xffff0000, v142
	v_lshlrev_b32_e32 v230, 16, v143
	v_and_b32_e32 v231, 0xffff0000, v143
	v_lshlrev_b32_e32 v232, 16, v144
	v_and_b32_e32 v233, 0xffff0000, v144
	v_lshlrev_b32_e32 v234, 16, v145
	v_and_b32_e32 v235, 0xffff0000, v145
	v_lshlrev_b32_e32 v236, 16, v146
	v_and_b32_e32 v237, 0xffff0000, v146
	v_lshlrev_b32_e32 v238, 16, v147
	v_and_b32_e32 v239, 0xffff0000, v147
	v_mul_f32_e32 v224, 0xbfb8aa3b, v224
	v_mul_f32_e32 v225, 0xbfb8aa3b, v225
	v_mul_f32_e32 v226, 0xbfb8aa3b, v226
	v_mul_f32_e32 v227, 0xbfb8aa3b, v227
	v_mul_f32_e32 v228, 0xbfb8aa3b, v228
	v_mul_f32_e32 v229, 0xbfb8aa3b, v229
	v_mul_f32_e32 v230, 0xbfb8aa3b, v230
	v_mul_f32_e32 v231, 0xbfb8aa3b, v231
	v_max_f32_e32 v232, v232, v232
	v_max_f32_e32 v233, v233, v233
	v_max_f32_e32 v234, v234, v234
	v_max_f32_e32 v235, v235, v235
	v_max_f32_e32 v236, v236, v236
	v_max_f32_e32 v237, v237, v237
	v_max_f32_e32 v238, v238, v238
	v_max_f32_e32 v239, v239, v239
	v_exp_f32_e32 v224, v224
	v_exp_f32_e32 v225, v225
	v_exp_f32_e32 v226, v226
	v_exp_f32_e32 v227, v227
	v_exp_f32_e32 v228, v228
	v_exp_f32_e32 v229, v229
	v_exp_f32_e32 v230, v230
	v_exp_f32_e32 v231, v231
	v_med3_f32 v232, v232, s48, v192
	v_med3_f32 v233, v233, s48, v192
	v_med3_f32 v234, v234, s48, v192
	v_med3_f32 v235, v235, s48, v192
	v_med3_f32 v236, v236, s48, v192
	v_med3_f32 v237, v237, s48, v192
	v_med3_f32 v238, v238, s48, v192
	v_med3_f32 v239, v239, s48, v192
	v_add_f32_e32 v224, 1.0, v224
	v_add_f32_e32 v225, 1.0, v225
	v_add_f32_e32 v226, 1.0, v226
	v_add_f32_e32 v227, 1.0, v227
	v_add_f32_e32 v228, 1.0, v228
	v_add_f32_e32 v229, 1.0, v229
	v_add_f32_e32 v230, 1.0, v230
	v_add_f32_e32 v231, 1.0, v231
	v_mul_f32_e32 v232, 0xbfb8aa3b, v232
	v_mul_f32_e32 v233, 0xbfb8aa3b, v233
	v_mul_f32_e32 v234, 0xbfb8aa3b, v234
	v_mul_f32_e32 v235, 0xbfb8aa3b, v235
	v_mul_f32_e32 v236, 0xbfb8aa3b, v236
	v_mul_f32_e32 v237, 0xbfb8aa3b, v237
	v_mul_f32_e32 v238, 0xbfb8aa3b, v238
	v_mul_f32_e32 v239, 0xbfb8aa3b, v239
	v_rcp_f32_e32 v224, v224
	v_rcp_f32_e32 v225, v225
	v_rcp_f32_e32 v226, v226
	v_rcp_f32_e32 v227, v227
	v_rcp_f32_e32 v228, v228
	v_rcp_f32_e32 v229, v229
	v_rcp_f32_e32 v230, v230
	v_rcp_f32_e32 v231, v231
	v_exp_f32_e32 v232, v232
	v_exp_f32_e32 v233, v233
	v_exp_f32_e32 v234, v234
	v_exp_f32_e32 v235, v235
	v_exp_f32_e32 v236, v236
	v_exp_f32_e32 v237, v237
	v_exp_f32_e32 v238, v238
	v_exp_f32_e32 v239, v239
	v_mul_f32_e32 v28, v28, v224
	v_mul_f32_e32 v29, v29, v225
	v_mul_f32_e32 v30, v30, v226
	v_mul_f32_e32 v31, v31, v227
	v_mul_f32_e32 v32, v32, v228
	v_mul_f32_e32 v33, v33, v229
	v_mul_f32_e32 v34, v34, v230
	v_mul_f32_e32 v35, v35, v231
	v_add_f32_e32 v232, 1.0, v232
	v_add_f32_e32 v233, 1.0, v233
	v_add_f32_e32 v234, 1.0, v234
	v_add_f32_e32 v235, 1.0, v235
	v_add_f32_e32 v236, 1.0, v236
	v_add_f32_e32 v237, 1.0, v237
	v_add_f32_e32 v238, 1.0, v238
	v_add_f32_e32 v239, 1.0, v239
	v_mul_f32_e32 v28, v28, v232
	v_mul_f32_e32 v29, v29, v233
	v_mul_f32_e32 v30, v30, v234
	v_mul_f32_e32 v31, v31, v235
	v_mul_f32_e32 v32, v32, v236
	v_mul_f32_e32 v33, v33, v237
	v_mul_f32_e32 v34, v34, v238
	v_mul_f32_e32 v35, v35, v239
	s_and_b64 vcc, exec, s[10:11]
	s_mov_b64 s[0:1], -1
	s_cbranch_vccnz .LBB0_266
